# write-through sc1 payload stores replace buffer_wbl2 release fences on phase2-4 hand-offs; P2.5 load batching; P3 scratch prefetch
# speedup vs baseline: 1.0963x; 1.0736x over previous
; DEV u32x2 pk4(f32x4 v) { u32x2 r = {pk_bf16(v[0], v[1]), pk_bf16(v[2], v[3])}; return r; }
; DEV f32x4 unpk4(u32x2 u) { f32x4 r = {bf_lo(u[0]), bf_hi(u[0]), bf_lo(u[1]), bf_hi(u[1])}; return r; }
; DEV void gla_block(const Params& p, int g) {
;     ...
;     if (dkh == 0) {
;       u32x2* o_ = (u32x2*)(p.ws + OFF_OP0) + ((((size_t)((b * 32 + c) * 4 + h) * 16 + vs) * 2) * 4) * 64 + lane;
; #pragma unroll
;       for (int q = 0; q < 4; ++q) {
;         const f32x4 a0 = {o0[4 * q], o0[4 * q + 1], o0[4 * q + 2], o0[4 * q + 3]}, a1 = {o1[4 * q], o1[4 * q + 1], o1[4 * q + 2], o1[4 * q + 3]};
;         o_[q * 64] = pk4(a0 + unpk4(xch[q * 64])); o_[(4 + q) * 64] = pk4(a1 + unpk4(xch[(4 + q) * 64]));
;       }
;     }
.LBB0_418:
	s_waitcnt vmcnt(0)
	s_andn2_b64 vcc, exec, s[24:25]
	s_waitcnt lgkmcnt(0)
	s_barrier
	s_cbranch_vccnz .LBB0_395
	ds_read2st64_b64 v[114:117], v176 offset1:1
	s_ashr_i32 s27, s26, 31
	s_lshl_b64 s[28:29], s[26:27], 16
	v_lshl_add_u64 v[112:113], v[182:183], 0, s[28:29]
	s_waitcnt lgkmcnt(0)
	v_lshlrev_b32_e32 v118, 16, v114
	v_and_b32_e32 v119, 0xffff0000, v114
	v_lshlrev_b32_e32 v114, 16, v115
	v_and_b32_e32 v115, 0xffff0000, v115
	v_pk_add_f32 v[82:83], v[82:83], v[114:115]
	v_pk_add_f32 v[80:81], v[80:81], v[118:119]
	s_nop 0
	v_cvt_pk_bf16_f32 v80, v80, v81
	v_cvt_pk_bf16_f32 v81, v82, v83
	global_store_dwordx2 v[112:113], v[80:81], off sc1
	ds_read2st64_b64 v[80:83], v176 offset0:4 offset1:5
	s_waitcnt lgkmcnt(0)
	v_lshlrev_b32_e32 v114, 16, v80
	v_and_b32_e32 v115, 0xffff0000, v80
	v_lshlrev_b32_e32 v80, 16, v81
	v_and_b32_e32 v81, 0xffff0000, v81
	v_pk_add_f32 v[66:67], v[66:67], v[80:81]
	v_pk_add_f32 v[64:65], v[64:65], v[114:115]
	s_nop 0
	v_cvt_pk_bf16_f32 v64, v64, v65
	v_cvt_pk_bf16_f32 v65, v66, v67
	global_store_dwordx2 v[112:113], v[64:65], off offset:2048 sc1
	v_lshlrev_b32_e32 v64, 16, v116
	v_and_b32_e32 v65, 0xffff0000, v116
	v_lshlrev_b32_e32 v66, 16, v117
	v_and_b32_e32 v67, 0xffff0000, v117
	v_pk_add_f32 v[66:67], v[86:87], v[66:67]
	v_pk_add_f32 v[64:65], v[84:85], v[64:65]
	s_nop 0
	v_cvt_pk_bf16_f32 v64, v64, v65
	v_cvt_pk_bf16_f32 v65, v66, v67
	global_store_dwordx2 v[112:113], v[64:65], off offset:512 sc1
	v_lshlrev_b32_e32 v64, 16, v82
	v_and_b32_e32 v65, 0xffff0000, v82
	v_lshlrev_b32_e32 v66, 16, v83
	v_and_b32_e32 v67, 0xffff0000, v83
	v_pk_add_f32 v[66:67], v[70:71], v[66:67]
	v_pk_add_f32 v[64:65], v[68:69], v[64:65]
	s_nop 0
	v_cvt_pk_bf16_f32 v64, v64, v65
	v_cvt_pk_bf16_f32 v65, v66, v67
	global_store_dwordx2 v[112:113], v[64:65], off offset:2560 sc1
	ds_read2st64_b64 v[64:67], v176 offset0:2 offset1:3
	s_waitcnt lgkmcnt(0)
	v_lshlrev_b32_e32 v68, 16, v64
	v_and_b32_e32 v69, 0xffff0000, v64
	v_lshlrev_b32_e32 v64, 16, v65
	v_and_b32_e32 v65, 0xffff0000, v65
	v_pk_add_f32 v[64:65], v[90:91], v[64:65]
	v_pk_add_f32 v[68:69], v[88:89], v[68:69]
	s_nop 0
	v_cvt_pk_bf16_f32 v68, v68, v69
	v_cvt_pk_bf16_f32 v69, v64, v65
	global_store_dwordx2 v[112:113], v[68:69], off offset:1024 sc1
	ds_read2st64_b64 v[68:71], v176 offset0:6 offset1:7
	s_waitcnt lgkmcnt(0)
	v_lshlrev_b32_e32 v64, 16, v68
	v_and_b32_e32 v65, 0xffff0000, v68
	v_lshlrev_b32_e32 v68, 16, v69
	v_and_b32_e32 v69, 0xffff0000, v69
	v_pk_add_f32 v[68:69], v[74:75], v[68:69]
	v_pk_add_f32 v[64:65], v[72:73], v[64:65]
	s_nop 0
	v_cvt_pk_bf16_f32 v64, v64, v65
	v_cvt_pk_bf16_f32 v65, v68, v69
	global_store_dwordx2 v[112:113], v[64:65], off offset:3072 sc1
	v_lshlrev_b32_e32 v64, 16, v66
	v_and_b32_e32 v65, 0xffff0000, v66
	v_lshlrev_b32_e32 v66, 16, v67
	v_and_b32_e32 v67, 0xffff0000, v67
	v_pk_add_f32 v[66:67], v[94:95], v[66:67]
	v_pk_add_f32 v[64:65], v[92:93], v[64:65]
	s_nop 0
	v_cvt_pk_bf16_f32 v64, v64, v65
	v_cvt_pk_bf16_f32 v65, v66, v67
	global_store_dwordx2 v[112:113], v[64:65], off offset:1536 sc1
	v_lshlrev_b32_e32 v64, 16, v70
	v_and_b32_e32 v65, 0xffff0000, v70
	v_lshlrev_b32_e32 v66, 16, v71
	v_and_b32_e32 v67, 0xffff0000, v71
	v_pk_add_f32 v[66:67], v[78:79], v[66:67]
	v_pk_add_f32 v[64:65], v[76:77], v[64:65]
	s_nop 0
	v_cvt_pk_bf16_f32 v64, v64, v65
	v_cvt_pk_bf16_f32 v65, v66, v67
	global_store_dwordx2 v[112:113], v[64:65], off offset:3584 sc1
	s_branch .LBB0_395

; DEV void panel_publish(unsigned* cnt, const int tidx) {
;   asm volatile("s_waitcnt vmcnt(0)" ::: "memory");
;   __syncthreads();
;   if (tidx == 0) {
;     __builtin_amdgcn_fence(__ATOMIC_RELEASE, "agent");
;     asm volatile("s_waitcnt vmcnt(0)" ::: "memory");
;     __hip_atomic_fetch_add(cnt, 1u, __ATOMIC_RELAXED, __HIP_MEMORY_SCOPE_AGENT);
;   }
; }
.LBB0_436:
	s_waitcnt vmcnt(0)
	s_barrier
	s_waitcnt vmcnt(0)
	v_cmp_eq_u32_e32 vcc, 0, v224
	s_barrier
	s_and_saveexec_b64 s[4:5], vcc
	s_cbranch_execz .LBB0_350
	s_mov_b64 s[6:7], exec
	v_mbcnt_lo_u32_b32 v0, s6, 0
	s_waitcnt vmcnt(0)
	s_waitcnt vmcnt(0)
	v_mbcnt_hi_u32_b32 v0, s7, v0
	v_cmp_eq_u32_e32 vcc, 0, v0
	s_and_b64 s[8:9], exec, vcc
	s_mov_b64 exec, s[8:9]
	s_cbranch_execz .LBB0_350
	s_ashr_i32 s1, s0, 31
	s_lshl_b64 s[0:1], s[0:1], 2
	v_readlane_b32 s8, v253, 29
	s_add_u32 s0, s8, s0
	v_readlane_b32 s8, v253, 30
	s_addc_u32 s1, s8, s1
	s_bcnt1_i32_b64 s6, s[6:7]
	v_mov_b32_e32 v0, s6
	global_atomic_add v177, v0, s[0:1]
	s_branch .LBB0_350

; DEV f32x16 mfma32(bf16x8 a, bf16x8 b, f32x16 c) { return __builtin_amdgcn_mfma_f32_32x32x16_bf16(a, b, c, 0, 0, 0); }
; DEV void mem_block(const Params& p, int item) {
;     ...
;   for (int n = 8; n < 16; ++n) {
;     if (n == 8) asm volatile("s_waitcnt vmcnt(4)" ::: "memory");
;     else if (n == 9) asm volatile("s_waitcnt vmcnt(8)" ::: "memory");
;     else asm volatile("s_waitcnt vmcnt(12)" ::: "memory");
;     __builtin_amdgcn_s_barrier();
;     asm volatile("" ::: "memory");
;     const int nb = buf >= 1 ? buf - 1 : 2;
;     { const int nn = n + 2 < 16 ? n + 2 : 15; MEM_DMA(nn, nb); }
;     const char* lf = smem + buf * 32768;
;     int vf0 = VF0;
;     asm volatile("" : "+v"(vf0));
;     char* lw = smem + 98304 + wave * 4096;
; #pragma unroll
;     for (int dd = 0; dd < 2; ++dd) {
;       f32x16 o;
;       for (int g = 0; g < 16; ++g) o[g] = 0.f;
; #pragma unroll
;       for (int t = 0; t < 8; ++t) { o = mfma32(*(const bf16x8*)(lf + dd * 16384 + (vf0 ^ (64 * t))), pf[t][0], o); o = mfma32(*(const bf16x8*)(lf + dd * 16384 + (vf0 ^ (64 * t + 32))), pf[t][1], o); }
.LBB0_459:
	s_min_u32 s7, s5, 13
	s_lshl_b32 s7, s7, 6
	s_lshl_b32 s9, s23, 15
	s_addk_i32 s7, 0xfe80
	s_add_i32 s11, s9, 0xffff8000
	s_cmp_gt_i32 s23, 0
	s_cselect_b32 s11, s11, 0x10000
	s_add_i32 s12, s7, s4
	s_ashr_i32 s13, s12, 31
	v_add_u32_e32 v2, s11, v195
	s_lshl_b64 s[12:13], s[12:13], 9
	v_lshl_add_u64 v[0:1], v[82:83], 0, s[12:13]
	v_add_u32_e32 v3, s19, v2
	s_add_i32 s12, s7, s6
	v_readfirstlane_b32 s11, v3
	s_ashr_i32 s13, s12, 31
	s_barrier
	s_mov_b32 m0, s11
	s_lshl_b64 s[12:13], s[12:13], 9
	global_load_lds_dwordx4 v[0:1], off
	v_lshl_add_u64 v[0:1], v[84:85], 0, s[12:13]
	v_add_u32_e32 v3, s20, v2
	s_add_i32 s12, s7, s8
	v_readfirstlane_b32 s11, v3
	s_ashr_i32 s13, s12, 31
	s_mov_b32 m0, s11
	s_lshl_b64 s[12:13], s[12:13], 9
	global_load_lds_dwordx4 v[0:1], off
	v_lshl_add_u64 v[0:1], v[86:87], 0, s[12:13]
	v_add_u32_e32 v3, s21, v2
	s_add_i32 s12, s7, s10
	v_readfirstlane_b32 s11, v3
	s_ashr_i32 s13, s12, 31
	v_add_u32_e32 v2, s22, v2
	s_mov_b32 m0, s11
	s_lshl_b64 s[12:13], s[12:13], 9
	v_readfirstlane_b32 s7, v2
	global_load_lds_dwordx4 v[0:1], off
	v_lshl_add_u64 v[0:1], v[88:89], 0, s[12:13]
	s_mov_b32 m0, s7
	s_add_i32 s7, s9, 0
	v_mov_b32_e32 v107, v92
	global_load_lds_dwordx4 v[0:1], off
	s_nop 0
	v_add_u32_e32 v112, s7, v107
	ds_read_b128 v[0:3], v112
	v_xad_u32 v113, v107, 32, s7
	ds_read_b128 v[108:111], v113
	s_waitcnt lgkmcnt(0)
	v_mfma_f32_32x32x16_bf16 v[0:15], v[0:3], v[16:19], 0
	v_xad_u32 v114, v107, 64, s7
	v_mfma_f32_32x32x16_bf16 v[0:15], v[108:111], v[20:23], v[0:15]
	ds_read_b128 v[108:111], v114
	s_waitcnt lgkmcnt(0)
	v_mfma_f32_32x32x16_bf16 v[0:15], v[108:111], v[24:27], v[0:15]
	v_xor_b32_e32 v108, 0x60, v107
	v_add_u32_e32 v115, s7, v108
	ds_read_b128 v[108:111], v115
	s_waitcnt lgkmcnt(0)
	v_mfma_f32_32x32x16_bf16 v[0:15], v[108:111], v[28:31], v[0:15]
	v_xor_b32_e32 v108, 0x80, v107
	v_add_u32_e32 v116, s7, v108
	ds_read_b128 v[108:111], v116
	s_waitcnt lgkmcnt(0)
	v_mfma_f32_32x32x16_bf16 v[0:15], v[108:111], v[32:35], v[0:15]
	v_xor_b32_e32 v108, 0xa0, v107
	v_add_u32_e32 v117, s7, v108
	ds_read_b128 v[108:111], v117
	s_waitcnt lgkmcnt(0)
	v_mfma_f32_32x32x16_bf16 v[0:15], v[108:111], v[36:39], v[0:15]
	v_xor_b32_e32 v108, 0xc0, v107
	v_add_u32_e32 v118, s7, v108
	ds_read_b128 v[108:111], v118
	s_waitcnt lgkmcnt(0)
	v_mfma_f32_32x32x16_bf16 v[0:15], v[108:111], v[40:43], v[0:15]
	v_xor_b32_e32 v108, 0xe0, v107
	v_add_u32_e32 v119, s7, v108
	ds_read_b128 v[108:111], v119
	s_waitcnt lgkmcnt(0)
	v_mfma_f32_32x32x16_bf16 v[0:15], v[108:111], v[44:47], v[0:15]
	v_xor_b32_e32 v108, 0x100, v107
	v_add_u32_e32 v120, s7, v108
	ds_read_b128 v[108:111], v120
	s_waitcnt lgkmcnt(0)
	v_mfma_f32_32x32x16_bf16 v[0:15], v[108:111], v[48:51], v[0:15]
	v_xor_b32_e32 v108, 0x120, v107
	v_add_u32_e32 v121, s7, v108
	ds_read_b128 v[108:111], v121
	s_waitcnt lgkmcnt(0)
	v_mfma_f32_32x32x16_bf16 v[0:15], v[108:111], v[52:55], v[0:15]
	v_xor_b32_e32 v108, 0x140, v107
	v_add_u32_e32 v122, s7, v108
	ds_read_b128 v[108:111], v122
	s_waitcnt lgkmcnt(0)
	v_mfma_f32_32x32x16_bf16 v[0:15], v[108:111], v[56:59], v[0:15]
	v_xor_b32_e32 v108, 0x160, v107
	v_add_u32_e32 v123, s7, v108
	ds_read_b128 v[108:111], v123
	s_waitcnt lgkmcnt(0)
	v_mfma_f32_32x32x16_bf16 v[0:15], v[108:111], v[60:63], v[0:15]
	v_xor_b32_e32 v108, 0x180, v107
	v_add_u32_e32 v124, s7, v108
	ds_read_b128 v[108:111], v124
	s_waitcnt lgkmcnt(0)
	v_mfma_f32_32x32x16_bf16 v[0:15], v[108:111], v[64:67], v[0:15]
	v_xor_b32_e32 v108, 0x1a0, v107
	v_add_u32_e32 v125, s7, v108
	ds_read_b128 v[108:111], v125
	s_waitcnt lgkmcnt(0)
	v_mfma_f32_32x32x16_bf16 v[0:15], v[108:111], v[68:71], v[0:15]
	v_xor_b32_e32 v108, 0x1c0, v107
	v_add_u32_e32 v126, s7, v108
	ds_read_b128 v[108:111], v126
	v_xor_b32_e32 v107, 0x1e0, v107
	v_add_u32_e32 v107, s7, v107
	s_mov_b32 s7, 0xac00000
	s_waitcnt lgkmcnt(0)
	v_mfma_f32_32x32x16_bf16 v[0:15], v[108:111], v[72:75], v[0:15]
	ds_read_b128 v[108:111], v107
	s_waitcnt lgkmcnt(0)
; DEV f32x16 mfma32(bf16x8 a, bf16x8 b, f32x16 c) { return __builtin_amdgcn_mfma_f32_32x32x16_bf16(a, b, c, 0, 0, 0); }
; DEV u32x2 pk4(f32x4 v) { u32x2 r = {pk_bf16(v[0], v[1]), pk_bf16(v[2], v[3])}; return r; }
; DEV void mem_block(const Params& p, int item) {
;     ...
;       for (int t = 0; t < 8; ++t) { o = mfma32(*(const bf16x8*)(lf + dd * 16384 + (vf0 ^ (64 * t))), pf[t][0], o); o = mfma32(*(const bf16x8*)(lf + dd * 16384 + (vf0 ^ (64 * t + 32))), pf[t][1], o); }
; #pragma unroll
;       for (int q = 0; q < 4; ++q) {
;         f32x4 v = {o[4 * q] * inv, o[4 * q + 1] * inv, o[4 * q + 2] * inv, o[4 * q + 3] * inv};
;         *(u32x2*)(lw + l31 * 128 + (((4 * dd + q) ^ (l31 & 7)) * 16) + hh * 8) = pk4(v);
;       }
;     }
;     asm volatile("s_waitcnt lgkmcnt(0)" ::: "memory");
; #pragma unroll
;     for (int i = 0; i < 4; ++i) {
;       const int id = i * 64 + lane, r = id >> 3, pos = id & 7, c = pos ^ (r & 7);
;       *(u32x4*)(om + ((size_t)qt * 32 + r) * 2048 + h * 512 + 64 * (n - 8) + 8 * c) = *(const u32x4*)(lw + r * 128 + pos * 16);
;     }
	v_mfma_f32_32x32x16_bf16 v[0:15], v[108:111], v[76:79], v[0:15]
	s_nop 11
	v_pk_mul_f32 v[0:1], v[80:81], v[0:1]
	v_pk_mul_f32 v[2:3], v[80:81], v[2:3]
	v_cvt_pk_bf16_f32 v0, v0, v1
	v_cvt_pk_bf16_f32 v1, v2, v3
	v_add_u32_e32 v2, v93, v94
	ds_write_b64 v2, v[0:1]
	v_pk_mul_f32 v[0:1], v[80:81], v[4:5]
	v_pk_mul_f32 v[2:3], v[80:81], v[6:7]
	v_cvt_pk_bf16_f32 v0, v0, v1
	v_cvt_pk_bf16_f32 v1, v2, v3
	ds_write_b64 v97, v[0:1]
	v_pk_mul_f32 v[0:1], v[80:81], v[8:9]
	v_pk_mul_f32 v[2:3], v[80:81], v[10:11]
	v_cvt_pk_bf16_f32 v0, v0, v1
	v_cvt_pk_bf16_f32 v1, v2, v3
	ds_write_b64 v98, v[0:1]
	v_pk_mul_f32 v[0:1], v[80:81], v[12:13]
	v_pk_mul_f32 v[2:3], v[80:81], v[14:15]
	v_cvt_pk_bf16_f32 v0, v0, v1
	v_cvt_pk_bf16_f32 v1, v2, v3
	ds_write_b64 v99, v[0:1]
	ds_read_b128 v[0:3], v112 offset:16384
	ds_read_b128 v[108:111], v113 offset:16384
	s_waitcnt lgkmcnt(0)
	v_mfma_f32_32x32x16_bf16 v[0:15], v[0:3], v[16:19], 0
	v_mfma_f32_32x32x16_bf16 v[0:15], v[108:111], v[20:23], v[0:15]
	ds_read_b128 v[108:111], v114 offset:16384
	s_waitcnt lgkmcnt(0)
	v_mfma_f32_32x32x16_bf16 v[0:15], v[108:111], v[24:27], v[0:15]
	ds_read_b128 v[108:111], v115 offset:16384
	s_waitcnt lgkmcnt(0)
	v_mfma_f32_32x32x16_bf16 v[0:15], v[108:111], v[28:31], v[0:15]
	ds_read_b128 v[108:111], v116 offset:16384
	s_waitcnt lgkmcnt(0)
	v_mfma_f32_32x32x16_bf16 v[0:15], v[108:111], v[32:35], v[0:15]
	ds_read_b128 v[108:111], v117 offset:16384
	s_waitcnt lgkmcnt(0)
	v_mfma_f32_32x32x16_bf16 v[0:15], v[108:111], v[36:39], v[0:15]
	ds_read_b128 v[108:111], v118 offset:16384
	s_waitcnt lgkmcnt(0)
	v_mfma_f32_32x32x16_bf16 v[0:15], v[108:111], v[40:43], v[0:15]
	ds_read_b128 v[108:111], v119 offset:16384
	s_waitcnt lgkmcnt(0)
	v_mfma_f32_32x32x16_bf16 v[0:15], v[108:111], v[44:47], v[0:15]
	ds_read_b128 v[108:111], v120 offset:16384
	s_waitcnt lgkmcnt(0)
	v_mfma_f32_32x32x16_bf16 v[0:15], v[108:111], v[48:51], v[0:15]
	ds_read_b128 v[108:111], v121 offset:16384
	s_waitcnt lgkmcnt(0)
	v_mfma_f32_32x32x16_bf16 v[0:15], v[108:111], v[52:55], v[0:15]
	ds_read_b128 v[108:111], v122 offset:16384
	s_waitcnt lgkmcnt(0)
	v_mfma_f32_32x32x16_bf16 v[0:15], v[108:111], v[56:59], v[0:15]
	ds_read_b128 v[108:111], v123 offset:16384
	s_waitcnt lgkmcnt(0)
	v_mfma_f32_32x32x16_bf16 v[0:15], v[108:111], v[60:63], v[0:15]
	ds_read_b128 v[108:111], v124 offset:16384
	s_waitcnt lgkmcnt(0)
	v_mfma_f32_32x32x16_bf16 v[0:15], v[108:111], v[64:67], v[0:15]
	ds_read_b128 v[108:111], v125 offset:16384
	s_waitcnt lgkmcnt(0)
	v_mfma_f32_32x32x16_bf16 v[0:15], v[108:111], v[68:71], v[0:15]
	ds_read_b128 v[108:111], v126 offset:16384
	s_waitcnt lgkmcnt(0)
	v_mfma_f32_32x32x16_bf16 v[0:15], v[108:111], v[72:75], v[0:15]
	ds_read_b128 v[108:111], v107 offset:16384
	s_waitcnt lgkmcnt(0)
	v_mfma_f32_32x32x16_bf16 v[0:15], v[108:111], v[76:79], v[0:15]
	s_nop 11
	v_pk_mul_f32 v[0:1], v[80:81], v[0:1]
	v_pk_mul_f32 v[2:3], v[80:81], v[2:3]
	v_cvt_pk_bf16_f32 v0, v0, v1
	v_cvt_pk_bf16_f32 v1, v2, v3
	ds_write_b64 v100, v[0:1]
	v_pk_mul_f32 v[0:1], v[80:81], v[4:5]
	v_pk_mul_f32 v[2:3], v[80:81], v[6:7]
	v_cvt_pk_bf16_f32 v0, v0, v1
	v_cvt_pk_bf16_f32 v1, v2, v3
	ds_write_b64 v101, v[0:1]
	v_pk_mul_f32 v[0:1], v[80:81], v[8:9]
	v_pk_mul_f32 v[2:3], v[80:81], v[10:11]
	v_cvt_pk_bf16_f32 v0, v0, v1
	v_cvt_pk_bf16_f32 v1, v2, v3
	ds_write_b64 v102, v[0:1]
	v_pk_mul_f32 v[0:1], v[80:81], v[12:13]
	v_pk_mul_f32 v[2:3], v[80:81], v[14:15]
	v_cvt_pk_bf16_f32 v0, v0, v1
	v_cvt_pk_bf16_f32 v1, v2, v3
	ds_write_b64 v103, v[0:1]
	s_waitcnt lgkmcnt(0)
	v_add_u32_e32 v0, v95, v96
	ds_read_b128 v[0:3], v0
	v_lshl_add_u64 v[4:5], v[90:91], 0, s[0:1]
	v_add_co_u32_e32 v6, vcc, s7, v4
	s_mov_b32 s7, 0xac08000
	s_nop 0
	v_addc_co_u32_e32 v7, vcc, 0, v5, vcc
	s_waitcnt lgkmcnt(0)
	global_store_dwordx4 v[6:7], v[0:3], off sc1
	ds_read_b128 v[0:3], v104
	v_add_co_u32_e32 v6, vcc, s7, v4
	s_mov_b32 s7, 0xac10000
	s_nop 0
	v_addc_co_u32_e32 v7, vcc, 0, v5, vcc
	s_waitcnt lgkmcnt(0)
	global_store_dwordx4 v[6:7], v[0:3], off sc1
	ds_read_b128 v[0:3], v105
	v_add_co_u32_e32 v6, vcc, s7, v4
	s_mov_b32 s7, 0xac18000
	s_nop 0
	v_addc_co_u32_e32 v7, vcc, 0, v5, vcc
	s_waitcnt lgkmcnt(0)
	global_store_dwordx4 v[6:7], v[0:3], off sc1
	ds_read_b128 v[0:3], v106
	v_add_co_u32_e32 v4, vcc, s7, v4
	s_add_i32 s7, s23, 1
	s_nop 0
	v_addc_co_u32_e32 v5, vcc, 0, v5, vcc
	s_cmp_lg_u32 s23, 2
	s_waitcnt lgkmcnt(0)
	global_store_dwordx4 v[4:5], v[0:3], off sc1
	s_cselect_b32 s23, s7, 0
	s_add_i32 s5, s5, 1
	s_add_u32 s0, s0, 0x80
	s_addc_u32 s1, s1, 0
	s_cmpk_eq_i32 s0, 0x400
	s_cbranch_scc1 .LBB0_470

; DEV void panel_publish(unsigned* cnt, const int tidx) {
;   asm volatile("s_waitcnt vmcnt(0)" ::: "memory");
;   __syncthreads();
;   if (tidx == 0) {
;     __builtin_amdgcn_fence(__ATOMIC_RELEASE, "agent");
;     asm volatile("s_waitcnt vmcnt(0)" ::: "memory");
;     __hip_atomic_fetch_add(cnt, 1u, __ATOMIC_RELAXED, __HIP_MEMORY_SCOPE_AGENT);
;   }
; }
.LBB0_470:
	s_waitcnt vmcnt(0)
	v_cmp_eq_u32_e32 vcc, 0, v194
	s_waitcnt vmcnt(0)
	s_barrier
	s_and_saveexec_b64 s[0:1], vcc
	s_cbranch_execz .LBB0_473
	s_mov_b64 s[4:5], exec
	v_mbcnt_lo_u32_b32 v0, s4, 0
	s_waitcnt vmcnt(0)
	v_mbcnt_hi_u32_b32 v0, s5, v0
	v_cmp_eq_u32_e32 vcc, 0, v0
	s_and_b64 s[6:7], exec, vcc
	s_mov_b64 exec, s[6:7]
	s_cbranch_execz .LBB0_473
	s_bcnt1_i32_b64 s4, s[4:5]
	s_lshl_b32 s6, s18, 2
	v_mov_b32_e32 v1, s4
	v_readlane_b32 s4, v253, 42
	v_mov_b32_e32 v0, s6
	v_readlane_b32 s5, v253, 43
	s_nop 4
	global_atomic_add v0, v1, s[4:5]

; DEV void sb_block(const Params& p, int item) {
;     ...
;   {
;     char* lw = smem + wave * 16384;
; #pragma unroll
;     for (int d = 0; d < 4; ++d)
; #pragma unroll
;       for (int q = 0; q < 4; ++q) {
;         const f32x4 o = {O[d][4 * q], O[d][4 * q + 1], O[d][4 * q + 2], O[d][4 * q + 3]};
;         *(f32x4*)(lw + l31 * 512 + (((8 * d + 2 * q + hh) ^ l31) * 16)) = o;
;       }
;     asm volatile("s_waitcnt lgkmcnt(0)" ::: "memory");
;     const size_t tok0 = row0 + qt * 32;
;     u32x2 gv[16];
; #pragma unroll
;     for (int i = 0; i < 16; ++i) { const int r = 2 * i + hh, c = l31 ^ r; gv[i] = __builtin_nontemporal_load((const u32x2*)(ssg + (tok0 + r) * 2048 + h * 128 + 4 * c)); }
.LBB0_571:
	v_readlane_b32 s0, v252, 13
	s_lshl_b32 s0, s0, 14
	s_add_i32 s4, s0, 0
	v_lshl_add_u32 v64, v203, 9, s4
	v_xor_b32_e32 v65, v202, v203
	v_lshl_add_u32 v66, v65, 4, v64
	s_waitcnt vmcnt(0)
	s_waitcnt vmcnt(0) lgkmcnt(0)
	s_barrier
	ds_write_b128 v66, v[48:51]
	v_bitop3_b32 v48, v202, v203, 2 bitop3:0x36
	v_lshl_add_u32 v49, v48, 4, v64
	ds_write_b128 v49, v[52:55]
	v_bitop3_b32 v49, v202, v203, 4 bitop3:0x36
	v_lshl_add_u32 v50, v49, 4, v64
	ds_write_b128 v50, v[56:59]
	v_bitop3_b32 v50, v202, v203, 6 bitop3:0x36
	v_lshl_add_u32 v51, v50, 4, v64
	ds_write_b128 v51, v[60:63]
	v_bitop3_b32 v51, v202, v203, 8 bitop3:0x36
	v_lshl_add_u32 v52, v51, 4, v64
	ds_write_b128 v52, v[32:35]
	v_bitop3_b32 v32, v202, v203, 10 bitop3:0x36
	v_lshl_add_u32 v33, v32, 4, v64
	ds_write_b128 v33, v[36:39]
	v_bitop3_b32 v33, v202, v203, 12 bitop3:0x36
	v_lshl_add_u32 v34, v33, 4, v64
	ds_write_b128 v34, v[40:43]
	v_bitop3_b32 v34, v202, v203, 14 bitop3:0x36
	v_lshl_add_u32 v35, v34, 4, v64
	ds_write_b128 v35, v[44:47]
	v_bitop3_b32 v35, v202, v203, 16 bitop3:0x36
	v_lshl_add_u32 v36, v35, 4, v64
	ds_write_b128 v36, v[16:19]
	v_bitop3_b32 v16, v202, v203, 18 bitop3:0x36
	v_lshl_add_u32 v17, v16, 4, v64
	ds_write_b128 v17, v[20:23]
	v_bitop3_b32 v17, v202, v203, 20 bitop3:0x36
	v_lshl_add_u32 v18, v17, 4, v64
	v_bitop3_b32 v20, v202, v203, 22 bitop3:0x36
	ds_write_b128 v18, v[24:27]
	v_lshl_add_u32 v18, v20, 4, v64
	v_bitop3_b32 v24, v202, v203, 24 bitop3:0x36
	ds_write_b128 v18, v[28:31]
	v_lshl_add_u32 v18, v24, 4, v64
	v_bitop3_b32 v98, v202, v203, 26 bitop3:0x36
	ds_write_b128 v18, v[0:3]
	v_lshl_add_u32 v0, v98, 4, v64
	ds_write_b128 v0, v[4:7]
	v_bitop3_b32 v4, v202, v203, 28 bitop3:0x36
	v_readlane_b32 s6, v252, 0
	v_lshl_add_u32 v0, v4, 4, v64
	v_bitop3_b32 v104, v202, v203, 30 bitop3:0x36
	v_readlane_b32 s7, v252, 1
	ds_write_b128 v0, v[8:11]
	v_lshl_add_u32 v0, v104, 4, v64
	v_readlane_b32 s0, v253, 48
	v_readlane_b32 s5, v254, 62
	v_readlane_b32 s7, v254, 63
	ds_write_b128 v0, v[12:15]
	v_readlane_b32 s1, v253, 49
	s_add_u32 s0, s0, s6
	v_or_b32_e32 v0, s5, v202
	v_mov_b32_e32 v1, s7
	s_addc_u32 s1, s1, 0
	v_lshlrev_b64 v[108:109], 12, v[0:1]
	v_lshl_add_u64 v[2:3], s[0:1], 0, v[108:109]
	v_lshlrev_b32_e32 v176, 3, v65
	s_waitcnt lgkmcnt(0)
	v_lshl_add_u64 v[2:3], v[2:3], 0, v[176:177]
	global_load_dwordx2 v[110:111], v[2:3], off nt
	v_or_b32_e32 v103, 2, v202
	v_or_b32_e32 v0, s5, v103
	v_lshlrev_b64 v[78:79], 12, v[0:1]
	v_lshl_add_u64 v[2:3], s[0:1], 0, v[78:79]
	v_lshlrev_b32_e32 v84, 3, v48
	v_mov_b32_e32 v85, v177
	v_lshl_add_u64 v[2:3], v[2:3], 0, v[84:85]
	global_load_dwordx2 v[88:89], v[2:3], off nt
	v_or_b32_e32 v114, 4, v202
	v_or_b32_e32 v0, s5, v114
	v_lshlrev_b64 v[80:81], 12, v[0:1]
	v_lshl_add_u64 v[2:3], s[0:1], 0, v[80:81]
	v_lshlrev_b32_e32 v82, 3, v49
	v_mov_b32_e32 v83, v177
	v_lshl_add_u64 v[2:3], v[2:3], 0, v[82:83]
	global_load_dwordx2 v[86:87], v[2:3], off nt
	v_or_b32_e32 v115, 6, v202
	v_or_b32_e32 v0, s5, v115
	v_lshlrev_b64 v[66:67], 12, v[0:1]
	v_lshl_add_u64 v[2:3], s[0:1], 0, v[66:67]
	v_lshlrev_b32_e32 v68, 3, v50
	v_mov_b32_e32 v69, v177
	v_lshl_add_u64 v[2:3], v[2:3], 0, v[68:69]
	global_load_dwordx2 v[76:77], v[2:3], off nt
	v_or_b32_e32 v102, 8, v202
	v_or_b32_e32 v0, s5, v102
	v_lshlrev_b64 v[70:71], 12, v[0:1]
	v_lshl_add_u64 v[2:3], s[0:1], 0, v[70:71]
	v_lshlrev_b32_e32 v72, 3, v51
	v_mov_b32_e32 v73, v177
	v_lshl_add_u64 v[2:3], v[2:3], 0, v[72:73]
	global_load_dwordx2 v[74:75], v[2:3], off nt
	v_or_b32_e32 v101, 10, v202
	v_or_b32_e32 v0, s5, v101
	v_lshlrev_b64 v[54:55], 12, v[0:1]
	v_lshl_add_u64 v[2:3], s[0:1], 0, v[54:55]
	v_lshlrev_b32_e32 v60, 3, v32
	v_mov_b32_e32 v61, v177
	v_lshl_add_u64 v[2:3], v[2:3], 0, v[60:61]
	global_load_dwordx2 v[64:65], v[2:3], off nt
	v_or_b32_e32 v100, 12, v202
	v_or_b32_e32 v0, s5, v100
	v_lshlrev_b64 v[56:57], 12, v[0:1]
	v_lshl_add_u64 v[2:3], s[0:1], 0, v[56:57]
	v_lshlrev_b32_e32 v58, 3, v33
	v_mov_b32_e32 v59, v177
	v_lshl_add_u64 v[2:3], v[2:3], 0, v[58:59]
	global_load_dwordx2 v[62:63], v[2:3], off nt
	v_or_b32_e32 v99, 14, v202
	v_or_b32_e32 v0, s5, v99
	v_lshlrev_b64 v[42:43], 12, v[0:1]
	v_lshl_add_u64 v[2:3], s[0:1], 0, v[42:43]
	v_lshlrev_b32_e32 v44, 3, v34
	v_mov_b32_e32 v45, v177
	v_lshl_add_u64 v[2:3], v[2:3], 0, v[44:45]
	global_load_dwordx2 v[52:53], v[2:3], off nt
	v_or_b32_e32 v97, 16, v202
	v_or_b32_e32 v0, s5, v97
	v_or_b32_e32 v96, 18, v202
	v_lshlrev_b64 v[46:47], 12, v[0:1]
	v_lshl_add_u64 v[2:3], s[0:1], 0, v[46:47]
	v_lshlrev_b32_e32 v48, 3, v35
	v_mov_b32_e32 v49, v177
	v_or_b32_e32 v0, s5, v96
	v_or_b32_e32 v95, 20, v202
	v_lshl_add_u64 v[2:3], v[2:3], 0, v[48:49]
	v_lshlrev_b64 v[30:31], 12, v[0:1]
	global_load_dwordx2 v[50:51], v[2:3], off nt
	v_lshl_add_u64 v[2:3], s[0:1], 0, v[30:31]
	v_lshlrev_b32_e32 v36, 3, v16
	v_mov_b32_e32 v37, v177
	v_or_b32_e32 v0, s5, v95
	v_or_b32_e32 v94, 22, v202
	v_lshl_add_u64 v[2:3], v[2:3], 0, v[36:37]
	v_lshlrev_b64 v[32:33], 12, v[0:1]
	global_load_dwordx2 v[40:41], v[2:3], off nt
	v_lshl_add_u64 v[2:3], s[0:1], 0, v[32:33]
	v_lshlrev_b32_e32 v34, 3, v17
	v_mov_b32_e32 v35, v177
	v_or_b32_e32 v0, s5, v94
	v_or_b32_e32 v93, 24, v202
	v_lshl_add_u64 v[2:3], v[2:3], 0, v[34:35]
	v_lshlrev_b64 v[18:19], 12, v[0:1]
	global_load_dwordx2 v[38:39], v[2:3], off nt
	v_lshl_add_u64 v[2:3], s[0:1], 0, v[18:19]
	v_lshlrev_b32_e32 v20, 3, v20
	v_mov_b32_e32 v21, v177
	v_or_b32_e32 v0, s5, v93
	v_or_b32_e32 v92, 26, v202
	v_lshl_add_u64 v[2:3], v[2:3], 0, v[20:21]
	v_lshlrev_b64 v[22:23], 12, v[0:1]
	global_load_dwordx2 v[28:29], v[2:3], off nt
	v_lshl_add_u64 v[2:3], s[0:1], 0, v[22:23]
	v_lshlrev_b32_e32 v24, 3, v24
	v_mov_b32_e32 v25, v177
	v_or_b32_e32 v0, s5, v92
	v_or_b32_e32 v91, 28, v202
	v_lshl_add_u64 v[2:3], v[2:3], 0, v[24:25]
	v_lshlrev_b64 v[6:7], 12, v[0:1]
	global_load_dwordx2 v[26:27], v[2:3], off nt
	v_lshl_add_u64 v[2:3], s[0:1], 0, v[6:7]
	v_lshlrev_b32_e32 v12, 3, v98
	v_mov_b32_e32 v13, v177
	v_or_b32_e32 v0, s5, v91
	v_lshl_add_u64 v[2:3], v[2:3], 0, v[12:13]
	v_lshlrev_b64 v[8:9], 12, v[0:1]
	global_load_dwordx2 v[16:17], v[2:3], off nt
	v_lshl_add_u64 v[2:3], s[0:1], 0, v[8:9]
	v_lshlrev_b32_e32 v10, 3, v4
	v_mov_b32_e32 v11, v177
	v_lshl_add_u64 v[2:3], v[2:3], 0, v[10:11]
	v_lshl_add_u32 v98, v203, 4, s4
	global_load_dwordx2 v[14:15], v[2:3], off nt
	v_lshlrev_b32_e32 v2, 3, v104
	v_lshl_add_u32 v104, v202, 9, v98
	v_or_b32_e32 v90, 30, v202
	ds_read_b128 v[104:107], v104
	v_or_b32_e32 v0, s5, v90
	v_lshlrev_b64 v[0:1], 12, v[0:1]
	v_lshl_add_u64 v[4:5], s[0:1], 0, v[0:1]
	v_readlane_b32 s0, v253, 52
	v_readlane_b32 s1, v253, 53
	s_add_u32 s0, s0, s6
	s_waitcnt vmcnt(14)
; DEV u32x2 pk4(f32x4 v) { u32x2 r = {pk_bf16(v[0], v[1]), pk_bf16(v[2], v[3])}; return r; }
; DEV f32x4 unpk4(u32x2 u) { f32x4 r = {bf_lo(u[0]), bf_hi(u[0]), bf_lo(u[1]), bf_hi(u[1])}; return r; }
; DEV void sb_block(const Params& p, int item) {
;     ...
; #pragma unroll
;     for (int i = 0; i < 16; ++i) {
;       const int r = 2 * i + hh, c = l31 ^ r;
;       const f32x4 o = *(const f32x4*)(lw + r * 512 + l31 * 16);
;       *(u32x2*)(ob + (tok0 + r) * 2048 + h * 128 + 4 * c) = pk4(o * unpk4(gv[i]));
;     }
	v_lshlrev_b32_e32 v112, 16, v110
	v_and_b32_e32 v113, 0xffff0000, v110
	v_lshlrev_b32_e32 v110, 16, v111
	v_and_b32_e32 v111, 0xffff0000, v111
	s_addc_u32 s1, s1, 0
	s_waitcnt lgkmcnt(0)
	v_pk_mul_f32 v[106:107], v[106:107], v[110:111]
	v_pk_mul_f32 v[104:105], v[104:105], v[112:113]
	v_mov_b32_e32 v3, v177
	v_cvt_pk_bf16_f32 v104, v104, v105
	v_cvt_pk_bf16_f32 v105, v106, v107
	v_lshl_add_u64 v[106:107], s[0:1], 0, v[108:109]
	v_lshl_add_u64 v[4:5], v[4:5], 0, v[2:3]
	v_lshl_add_u64 v[106:107], v[106:107], 0, v[176:177]
	v_lshl_add_u32 v103, v103, 9, v98
	global_load_dwordx2 v[4:5], v[4:5], off nt
	s_waitcnt vmcnt(14)
	v_lshlrev_b32_e32 v108, 16, v88
	global_store_dwordx2 v[106:107], v[104:105], off sc1
	ds_read_b128 v[104:107], v103
	v_and_b32_e32 v109, 0xffff0000, v88
	v_lshlrev_b32_e32 v88, 16, v89
	v_and_b32_e32 v89, 0xffff0000, v89
	v_lshl_add_u64 v[78:79], s[0:1], 0, v[78:79]
	s_waitcnt lgkmcnt(0)
	v_pk_mul_f32 v[88:89], v[106:107], v[88:89]
	v_pk_mul_f32 v[104:105], v[104:105], v[108:109]
	v_lshl_add_u64 v[78:79], v[78:79], 0, v[84:85]
	v_cvt_pk_bf16_f32 v104, v104, v105
	v_cvt_pk_bf16_f32 v105, v88, v89
	global_store_dwordx2 v[78:79], v[104:105], off sc1
	v_lshl_add_u32 v78, v114, 9, v98
	ds_read_b128 v[104:107], v78
	s_waitcnt vmcnt(15)
	v_lshlrev_b32_e32 v78, 16, v86
	v_and_b32_e32 v79, 0xffff0000, v86
	v_lshlrev_b32_e32 v84, 16, v87
	v_and_b32_e32 v85, 0xffff0000, v87
	s_waitcnt lgkmcnt(0)
	v_pk_mul_f32 v[84:85], v[106:107], v[84:85]
	v_pk_mul_f32 v[78:79], v[104:105], v[78:79]
	v_lshl_add_u64 v[80:81], s[0:1], 0, v[80:81]
	v_cvt_pk_bf16_f32 v78, v78, v79
	v_cvt_pk_bf16_f32 v79, v84, v85
	v_lshl_add_u64 v[80:81], v[80:81], 0, v[82:83]
	global_store_dwordx2 v[80:81], v[78:79], off sc1
	v_lshl_add_u32 v78, v115, 9, v98
	ds_read_b128 v[78:81], v78
	s_waitcnt vmcnt(15)
	v_lshlrev_b32_e32 v82, 16, v76
	v_and_b32_e32 v83, 0xffff0000, v76
	v_lshlrev_b32_e32 v76, 16, v77
	v_and_b32_e32 v77, 0xffff0000, v77
	s_waitcnt lgkmcnt(0)
	v_pk_mul_f32 v[76:77], v[80:81], v[76:77]
	v_pk_mul_f32 v[78:79], v[78:79], v[82:83]
	v_lshl_add_u64 v[66:67], s[0:1], 0, v[66:67]
	v_cvt_pk_bf16_f32 v78, v78, v79
	v_cvt_pk_bf16_f32 v79, v76, v77
	v_lshl_add_u64 v[66:67], v[66:67], 0, v[68:69]
	global_store_dwordx2 v[66:67], v[78:79], off sc1
	v_lshl_add_u32 v66, v102, 9, v98
	ds_read_b128 v[66:69], v66
	s_waitcnt vmcnt(15)
	v_lshlrev_b32_e32 v76, 16, v74
	v_and_b32_e32 v77, 0xffff0000, v74
	v_lshlrev_b32_e32 v74, 16, v75
	v_and_b32_e32 v75, 0xffff0000, v75
	s_waitcnt lgkmcnt(0)
	v_pk_mul_f32 v[68:69], v[68:69], v[74:75]
	v_pk_mul_f32 v[66:67], v[66:67], v[76:77]
	v_lshl_add_u64 v[54:55], s[0:1], 0, v[54:55]
	v_cvt_pk_bf16_f32 v66, v66, v67
	v_cvt_pk_bf16_f32 v67, v68, v69
	v_lshl_add_u64 v[68:69], s[0:1], 0, v[70:71]
	v_lshl_add_u64 v[68:69], v[68:69], 0, v[72:73]
	global_store_dwordx2 v[68:69], v[66:67], off sc1
	v_lshl_add_u32 v66, v101, 9, v98
	ds_read_b128 v[66:69], v66
	s_waitcnt vmcnt(15)
	v_lshlrev_b32_e32 v70, 16, v64
	v_and_b32_e32 v71, 0xffff0000, v64
	v_lshlrev_b32_e32 v64, 16, v65
	v_and_b32_e32 v65, 0xffff0000, v65
	s_waitcnt lgkmcnt(0)
	v_pk_mul_f32 v[64:65], v[68:69], v[64:65]
	v_pk_mul_f32 v[66:67], v[66:67], v[70:71]
	v_lshl_add_u64 v[54:55], v[54:55], 0, v[60:61]
	v_cvt_pk_bf16_f32 v66, v66, v67
	v_cvt_pk_bf16_f32 v67, v64, v65
	global_store_dwordx2 v[54:55], v[66:67], off sc1
	v_lshl_add_u32 v54, v100, 9, v98
	ds_read_b128 v[64:67], v54
	s_waitcnt vmcnt(15)
	v_lshlrev_b32_e32 v54, 16, v62
	v_and_b32_e32 v55, 0xffff0000, v62
	v_lshlrev_b32_e32 v60, 16, v63
	v_and_b32_e32 v61, 0xffff0000, v63
	s_waitcnt lgkmcnt(0)
	v_pk_mul_f32 v[60:61], v[66:67], v[60:61]
	v_pk_mul_f32 v[54:55], v[64:65], v[54:55]
	v_lshl_add_u64 v[56:57], s[0:1], 0, v[56:57]
	v_cvt_pk_bf16_f32 v54, v54, v55
	v_cvt_pk_bf16_f32 v55, v60, v61
	v_lshl_add_u64 v[56:57], v[56:57], 0, v[58:59]
	global_store_dwordx2 v[56:57], v[54:55], off sc1
	v_lshl_add_u32 v54, v99, 9, v98
	ds_read_b128 v[54:57], v54
	s_waitcnt vmcnt(15)
	v_lshlrev_b32_e32 v58, 16, v52
	v_and_b32_e32 v59, 0xffff0000, v52
	v_lshlrev_b32_e32 v52, 16, v53
	v_and_b32_e32 v53, 0xffff0000, v53
	s_waitcnt lgkmcnt(0)
	v_pk_mul_f32 v[52:53], v[56:57], v[52:53]
	v_pk_mul_f32 v[54:55], v[54:55], v[58:59]
	v_lshl_add_u64 v[42:43], s[0:1], 0, v[42:43]
	v_cvt_pk_bf16_f32 v54, v54, v55
	v_cvt_pk_bf16_f32 v55, v52, v53
	v_lshl_add_u64 v[42:43], v[42:43], 0, v[44:45]
	global_store_dwordx2 v[42:43], v[54:55], off sc1
	v_lshl_add_u32 v42, v97, 9, v98
	ds_read_b128 v[42:45], v42
	s_waitcnt vmcnt(15)
	v_lshlrev_b32_e32 v52, 16, v50
	v_and_b32_e32 v53, 0xffff0000, v50
	v_lshlrev_b32_e32 v50, 16, v51
	v_and_b32_e32 v51, 0xffff0000, v51
	s_waitcnt lgkmcnt(0)
; DEV u32x2 pk4(f32x4 v) { u32x2 r = {pk_bf16(v[0], v[1]), pk_bf16(v[2], v[3])}; return r; }
; DEV f32x4 unpk4(u32x2 u) { f32x4 r = {bf_lo(u[0]), bf_hi(u[0]), bf_lo(u[1]), bf_hi(u[1])}; return r; }
; DEV void sb_block(const Params& p, int item) {
;     ...
;     for (int i = 0; i < 16; ++i) {
;       const int r = 2 * i + hh, c = l31 ^ r;
;       const f32x4 o = *(const f32x4*)(lw + r * 512 + l31 * 16);
;       *(u32x2*)(ob + (tok0 + r) * 2048 + h * 128 + 4 * c) = pk4(o * unpk4(gv[i]));
;     }
;   }
;   panel_publish((unsigned*)(p.ws + OFF_MISC + 2048 + 896) + (b * 8 + qb), tidx);
	v_pk_mul_f32 v[44:45], v[44:45], v[50:51]
	v_pk_mul_f32 v[42:43], v[42:43], v[52:53]
	v_lshl_add_u64 v[30:31], s[0:1], 0, v[30:31]
	v_cvt_pk_bf16_f32 v42, v42, v43
	v_cvt_pk_bf16_f32 v43, v44, v45
	v_lshl_add_u64 v[44:45], s[0:1], 0, v[46:47]
	v_lshl_add_u64 v[44:45], v[44:45], 0, v[48:49]
	global_store_dwordx2 v[44:45], v[42:43], off sc1
	v_lshl_add_u32 v42, v96, 9, v98
	ds_read_b128 v[42:45], v42
	s_waitcnt vmcnt(15)
	v_lshlrev_b32_e32 v46, 16, v40
	v_and_b32_e32 v47, 0xffff0000, v40
	v_lshlrev_b32_e32 v40, 16, v41
	v_and_b32_e32 v41, 0xffff0000, v41
	s_waitcnt lgkmcnt(0)
	v_pk_mul_f32 v[40:41], v[44:45], v[40:41]
	v_pk_mul_f32 v[42:43], v[42:43], v[46:47]
	v_lshl_add_u64 v[30:31], v[30:31], 0, v[36:37]
	v_cvt_pk_bf16_f32 v42, v42, v43
	v_cvt_pk_bf16_f32 v43, v40, v41
	global_store_dwordx2 v[30:31], v[42:43], off sc1
	v_lshl_add_u32 v30, v95, 9, v98
	ds_read_b128 v[40:43], v30
	s_waitcnt vmcnt(15)
	v_lshlrev_b32_e32 v30, 16, v38
	v_and_b32_e32 v31, 0xffff0000, v38
	v_lshlrev_b32_e32 v36, 16, v39
	v_and_b32_e32 v37, 0xffff0000, v39
	s_waitcnt lgkmcnt(0)
	v_pk_mul_f32 v[36:37], v[42:43], v[36:37]
	v_pk_mul_f32 v[30:31], v[40:41], v[30:31]
	v_lshl_add_u64 v[32:33], s[0:1], 0, v[32:33]
	v_cvt_pk_bf16_f32 v30, v30, v31
	v_cvt_pk_bf16_f32 v31, v36, v37
	v_lshl_add_u64 v[32:33], v[32:33], 0, v[34:35]
	global_store_dwordx2 v[32:33], v[30:31], off sc1
	v_lshl_add_u32 v30, v94, 9, v98
	ds_read_b128 v[30:33], v30
	s_waitcnt vmcnt(15)
	v_lshlrev_b32_e32 v34, 16, v28
	v_and_b32_e32 v35, 0xffff0000, v28
	v_lshlrev_b32_e32 v28, 16, v29
	v_and_b32_e32 v29, 0xffff0000, v29
	s_waitcnt lgkmcnt(0)
	v_pk_mul_f32 v[28:29], v[32:33], v[28:29]
	v_pk_mul_f32 v[30:31], v[30:31], v[34:35]
	v_lshl_add_u64 v[18:19], s[0:1], 0, v[18:19]
	v_cvt_pk_bf16_f32 v30, v30, v31
	v_cvt_pk_bf16_f32 v31, v28, v29
	v_lshl_add_u64 v[18:19], v[18:19], 0, v[20:21]
	global_store_dwordx2 v[18:19], v[30:31], off sc1
	v_lshl_add_u32 v18, v93, 9, v98
	ds_read_b128 v[18:21], v18
	s_waitcnt vmcnt(15)
	v_lshlrev_b32_e32 v28, 16, v26
	v_and_b32_e32 v29, 0xffff0000, v26
	v_lshlrev_b32_e32 v26, 16, v27
	v_and_b32_e32 v27, 0xffff0000, v27
	s_waitcnt lgkmcnt(0)
	v_pk_mul_f32 v[20:21], v[20:21], v[26:27]
	v_pk_mul_f32 v[18:19], v[18:19], v[28:29]
	v_lshl_add_u64 v[6:7], s[0:1], 0, v[6:7]
	v_cvt_pk_bf16_f32 v18, v18, v19
	v_cvt_pk_bf16_f32 v19, v20, v21
	v_lshl_add_u64 v[20:21], s[0:1], 0, v[22:23]
	v_lshl_add_u64 v[20:21], v[20:21], 0, v[24:25]
	global_store_dwordx2 v[20:21], v[18:19], off sc1
	v_lshl_add_u32 v18, v92, 9, v98
	ds_read_b128 v[18:21], v18
	s_waitcnt vmcnt(15)
	v_lshlrev_b32_e32 v22, 16, v16
	v_and_b32_e32 v23, 0xffff0000, v16
	v_lshlrev_b32_e32 v16, 16, v17
	v_and_b32_e32 v17, 0xffff0000, v17
	s_waitcnt lgkmcnt(0)
	v_pk_mul_f32 v[16:17], v[20:21], v[16:17]
	v_pk_mul_f32 v[18:19], v[18:19], v[22:23]
	v_lshl_add_u64 v[6:7], v[6:7], 0, v[12:13]
	v_cvt_pk_bf16_f32 v18, v18, v19
	v_cvt_pk_bf16_f32 v19, v16, v17
	global_store_dwordx2 v[6:7], v[18:19], off sc1
	v_lshl_add_u32 v6, v91, 9, v98
	ds_read_b128 v[16:19], v6
	s_waitcnt vmcnt(15)
	v_lshlrev_b32_e32 v6, 16, v14
	v_and_b32_e32 v7, 0xffff0000, v14
	v_lshlrev_b32_e32 v12, 16, v15
	v_and_b32_e32 v13, 0xffff0000, v15
	s_waitcnt lgkmcnt(0)
	v_pk_mul_f32 v[12:13], v[18:19], v[12:13]
	v_pk_mul_f32 v[6:7], v[16:17], v[6:7]
	v_lshl_add_u64 v[8:9], s[0:1], 0, v[8:9]
	v_cvt_pk_bf16_f32 v6, v6, v7
	v_cvt_pk_bf16_f32 v7, v12, v13
	v_lshl_add_u64 v[8:9], v[8:9], 0, v[10:11]
	global_store_dwordx2 v[8:9], v[6:7], off sc1
	v_lshl_add_u32 v6, v90, 9, v98
	ds_read_b128 v[6:9], v6
	s_waitcnt vmcnt(15)
	v_lshlrev_b32_e32 v10, 16, v4
	v_and_b32_e32 v11, 0xffff0000, v4
	v_lshlrev_b32_e32 v4, 16, v5
	v_and_b32_e32 v5, 0xffff0000, v5
	s_waitcnt lgkmcnt(0)
	v_pk_mul_f32 v[4:5], v[8:9], v[4:5]
	v_pk_mul_f32 v[6:7], v[6:7], v[10:11]
	v_lshl_add_u64 v[0:1], s[0:1], 0, v[0:1]
	v_cvt_pk_bf16_f32 v6, v6, v7
	v_cvt_pk_bf16_f32 v7, v4, v5
	v_lshl_add_u64 v[0:1], v[0:1], 0, v[2:3]
	global_store_dwordx2 v[0:1], v[6:7], off sc1
	s_waitcnt vmcnt(0)
	v_cmp_eq_u32_e32 vcc, 0, v201
	s_barrier
	s_and_saveexec_b64 s[0:1], vcc
	s_cbranch_execz .LBB0_574
	s_mov_b64 s[4:5], exec
	v_mbcnt_lo_u32_b32 v0, s4, 0
	s_waitcnt vmcnt(0)
	s_waitcnt vmcnt(0)
	v_mbcnt_hi_u32_b32 v0, s5, v0
	v_cmp_eq_u32_e32 vcc, 0, v0
	s_and_b64 s[6:7], exec, vcc
	s_mov_b64 exec, s[6:7]
	s_cbranch_execz .LBB0_574
	v_readlane_b32 s6, v254, 61
	s_lshl_b32 s6, s6, 3
	v_readlane_b32 s7, v252, 6
	s_add_i32 s6, s6, s7
	s_bcnt1_i32_b64 s4, s[4:5]
	s_lshl_b32 s6, s6, 2
	v_mov_b32_e32 v1, s4
	v_readlane_b32 s4, v253, 42
	v_mov_b32_e32 v0, s6
	v_readlane_b32 s5, v253, 43
	s_nop 4
	global_atomic_add v0, v1, s[4:5]

; DEV u32x2 pk4(f32x4 v) { u32x2 r = {pk_bf16(v[0], v[1]), pk_bf16(v[2], v[3])}; return r; }
; DEV int sig4(int x) { return ((x & 1) << 1) | (x >> 1); }
;   DEV void operator()(f32x4 (&acc)[2][2][4][2], int brow, int bcol, int wr, int wc, int fr, int fq) const {
;     ...
; #pragma unroll
;     for (int ai = 0; ai < 2; ++ai)
; #pragma unroll
;       for (int m = 0; m < 4; ++m) {
;         const int tposl = ai * 128 + wr * 64 + m * 16 + 4 * sig4(fq);
; #pragma unroll
;         for (int bj = 0; bj < 2; ++bj)
; #pragma unroll
;           for (int n = 0; n < 2; ++n) tile_put4(bj * 128 + wc * 32 + n * 16 + fr, tposl, pk4(acc[ai][bj][m][n]));
;       }
; DEV void phase2(const Params& p, int rerun) {
;     ...
;       phase1(p, 2816 + it);
;       __threadfence();
;       __syncthreads();
;       if (tidx == 0) atomicAdd(mkv_done, 1u);
.LBB0_578:
	s_waitcnt vmcnt(0)
	buffer_inv sc1
	s_barrier
	s_and_saveexec_b64 s[0:1], s[66:67]
	s_xor_b64 s[0:1], exec, s[0:1]
	s_mov_b64 s[26:27], 0x200
	s_cbranch_execz .LBB0_441
	s_mov_b64 s[4:5], exec
	v_mbcnt_lo_u32_b32 v0, s4, 0
	v_mbcnt_hi_u32_b32 v0, s5, v0
	v_cmp_eq_u32_e32 vcc, 0, v0
	s_and_saveexec_b64 s[6:7], vcc
	s_xor_b64 s[6:7], exec, s[6:7]
	s_cbranch_execz .LBB0_440
	s_bcnt1_i32_b64 s4, s[4:5]
	v_mov_b32_e32 v0, s4
	v_readlane_b32 s4, v253, 33
	v_readlane_b32 s5, v253, 34
	s_nop 4
	global_atomic_add v177, v0, s[4:5]
	s_branch .LBB0_440
.LBB0_581:
	s_or_b64 exec, exec, s[0:1]
	v_cvt_pk_bf16_f32 v116, v116, v117
	v_lshrrev_b32_e32 v130, 4, v140
	v_ashrrev_i32_e32 v132, 2, v140
	v_lshrrev_b32_e32 v133, 3, v140
	v_bfe_u32 v130, v130, 1, 1
	v_and_b32_e32 v132, 0xffffffc0, v132
	v_and_or_b32 v133, v133, 2, v130
	v_bfe_u32 v129, v140, 6, 2
	v_and_b32_e32 v128, 15, v140
	v_lshl_or_b32 v132, v133, 2, v132
	v_ashrrev_i32_e32 v134, 3, v132
	v_cvt_pk_bf16_f32 v117, v118, v119
	v_lshlrev_b32_e32 v118, 14, v129
	v_lshlrev_b32_e32 v119, 9, v128
	v_add3_u32 v118, 0, v118, v119
	v_bitop3_b32 v119, v134, v140, 15 bitop3:0x78
	v_cvt_pk_bf16_f32 v112, v112, v113
	v_cvt_pk_bf16_f32 v113, v114, v115
	v_bitop3_b32 v114, v134, v128, 16 bitop3:0x1e
	v_lshlrev_b32_e32 v130, 3, v130
	v_lshlrev_b32_e32 v119, 4, v119
	v_lshlrev_b32_e32 v114, 4, v114
	v_add3_u32 v135, v118, v119, v130
	v_add3_u32 v115, v118, v114, v130
	v_or_b32_e32 v133, 16, v128
	ds_write_b64 v135, v[116:117]
	ds_write_b64 v115, v[112:113] offset:8192
	v_add_u32_e32 v115, 0x10000, v118
	v_cvt_pk_bf16_f32 v112, v124, v125
	v_cvt_pk_bf16_f32 v113, v126, v127
	v_add3_u32 v116, v115, v119, v130
	v_cvt_pk_bf16_f32 v100, v100, v101
	v_cvt_pk_bf16_f32 v101, v102, v103
	v_bitop3_b32 v102, v134, v128, 2 bitop3:0x36
	v_cvt_pk_bf16_f32 v96, v96, v97
	v_cvt_pk_bf16_f32 v97, v98, v99
	v_bitop3_b32 v98, v134, v133, 2 bitop3:0x36
	ds_write_b64 v116, v[112:113]
	v_add_u32_e32 v116, 0x12000, v118
	v_lshlrev_b32_e32 v102, 4, v102
	v_lshlrev_b32_e32 v98, 4, v98
	v_cvt_pk_bf16_f32 v112, v120, v121
	v_cvt_pk_bf16_f32 v113, v122, v123
	v_add3_u32 v114, v116, v114, v130
	v_add3_u32 v103, v118, v102, v130
	v_add3_u32 v99, v118, v98, v130
	v_cvt_pk_bf16_f32 v84, v84, v85
	v_cvt_pk_bf16_f32 v85, v86, v87
	v_bitop3_b32 v86, v134, v128, 4 bitop3:0x36
	v_cvt_pk_bf16_f32 v80, v80, v81
	v_cvt_pk_bf16_f32 v81, v82, v83
	v_bitop3_b32 v82, v134, v133, 4 bitop3:0x36
	ds_write_b64 v114, v[112:113]
	ds_write_b64 v103, v[100:101]
	ds_write_b64 v99, v[96:97] offset:8192
	v_cvt_pk_bf16_f32 v96, v108, v109
	v_cvt_pk_bf16_f32 v97, v110, v111
	v_add3_u32 v99, v115, v102, v130
	v_lshlrev_b32_e32 v86, 4, v86
	v_lshlrev_b32_e32 v82, 4, v82
	ds_write_b64 v99, v[96:97]
	v_cvt_pk_bf16_f32 v96, v104, v105
	v_cvt_pk_bf16_f32 v97, v106, v107
	v_add3_u32 v98, v116, v98, v130
	v_add3_u32 v87, v118, v86, v130
	v_add3_u32 v83, v118, v82, v130
	v_cvt_pk_bf16_f32 v52, v52, v53
	v_cvt_pk_bf16_f32 v53, v54, v55
	v_bitop3_b32 v54, v134, v128, 6 bitop3:0x36
	v_cvt_pk_bf16_f32 v48, v48, v49
	v_cvt_pk_bf16_f32 v49, v50, v51
	v_bitop3_b32 v50, v134, v133, 6 bitop3:0x36
	ds_write_b64 v98, v[96:97]
	ds_write_b64 v87, v[84:85]
	ds_write_b64 v83, v[80:81] offset:8192
	v_cvt_pk_bf16_f32 v80, v92, v93
	v_cvt_pk_bf16_f32 v81, v94, v95
	v_add3_u32 v83, v115, v86, v130
	v_lshlrev_b32_e32 v54, 4, v54
	v_lshlrev_b32_e32 v50, 4, v50
	ds_write_b64 v83, v[80:81]
	v_cvt_pk_bf16_f32 v80, v88, v89
	v_cvt_pk_bf16_f32 v81, v90, v91
	v_add3_u32 v82, v116, v82, v130
	v_add3_u32 v55, v118, v54, v130
	v_add3_u32 v51, v118, v50, v130
	ds_write_b64 v82, v[80:81]
	ds_write_b64 v55, v[52:53]
	ds_write_b64 v51, v[48:49] offset:8192
	v_cvt_pk_bf16_f32 v48, v64, v65
	v_cvt_pk_bf16_f32 v49, v66, v67
	v_add3_u32 v51, v115, v54, v130
	ds_write_b64 v51, v[48:49]
	v_cvt_pk_bf16_f32 v48, v56, v57
	v_cvt_pk_bf16_f32 v49, v58, v59
	v_add3_u32 v50, v116, v50, v130
	ds_write_b64 v50, v[48:49]
	v_add_u32_e32 v48, 0x80, v132
	v_ashrrev_i32_e32 v50, 3, v48
	v_bitop3_b32 v51, v50, v140, 15 bitop3:0x78
	v_lshlrev_b32_e32 v51, 4, v51
	v_bitop3_b32 v50, v50, v128, 16 bitop3:0x1e
	v_cvt_pk_bf16_f32 v48, v72, v73
	v_cvt_pk_bf16_f32 v49, v74, v75
	v_add3_u32 v52, v118, v51, v130
	v_lshlrev_b32_e32 v50, 4, v50
	ds_write_b64 v52, v[48:49]
	v_cvt_pk_bf16_f32 v48, v60, v61
	v_cvt_pk_bf16_f32 v49, v62, v63
	v_add3_u32 v52, v118, v50, v130
	ds_write_b64 v52, v[48:49] offset:8192
	v_cvt_pk_bf16_f32 v48, v76, v77
	v_cvt_pk_bf16_f32 v49, v78, v79
	v_add3_u32 v51, v115, v51, v130
	ds_write_b64 v51, v[48:49]
	v_cvt_pk_bf16_f32 v48, v68, v69
	v_cvt_pk_bf16_f32 v49, v70, v71
	v_add3_u32 v50, v116, v50, v130
	ds_write_b64 v50, v[48:49]
	v_add_u32_e32 v48, 0x90, v132
	v_ashrrev_i32_e32 v48, 3, v48
	v_cvt_pk_bf16_f32 v40, v40, v41
	v_cvt_pk_bf16_f32 v41, v42, v43
	v_bitop3_b32 v42, v48, v140, 15 bitop3:0x78
	v_cvt_pk_bf16_f32 v32, v32, v33
	v_cvt_pk_bf16_f32 v33, v34, v35
	v_bitop3_b32 v34, v48, v128, 16 bitop3:0x1e
	v_lshlrev_b32_e32 v42, 4, v42
	v_lshlrev_b32_e32 v34, 4, v34
	v_add3_u32 v43, v118, v42, v130
	v_add3_u32 v35, v118, v34, v130
	ds_write_b64 v43, v[40:41]
	ds_write_b64 v35, v[32:33] offset:8192
	v_cvt_pk_bf16_f32 v32, v44, v45
	v_cvt_pk_bf16_f32 v33, v46, v47
	v_add3_u32 v35, v115, v42, v130
	ds_write_b64 v35, v[32:33]
	v_cvt_pk_bf16_f32 v32, v36, v37
	v_cvt_pk_bf16_f32 v33, v38, v39
	v_add3_u32 v34, v116, v34, v130
	ds_write_b64 v34, v[32:33]
	v_add_u32_e32 v32, 0xa0, v132
	v_ashrrev_i32_e32 v32, 3, v32
	v_cvt_pk_bf16_f32 v24, v24, v25
	v_cvt_pk_bf16_f32 v25, v26, v27
	v_bitop3_b32 v26, v32, v140, 15 bitop3:0x78
	v_cvt_pk_bf16_f32 v16, v16, v17
	v_cvt_pk_bf16_f32 v17, v18, v19
; DEV u32x2 pk4(f32x4 v) { u32x2 r = {pk_bf16(v[0], v[1]), pk_bf16(v[2], v[3])}; return r; }
;   DEV void operator()(f32x4 (&acc)[2][2][4][2], int brow, int bcol, int wr, int wc, int fr, int fq) const {
;     ...
;           for (int n = 0; n < 2; ++n) tile_put4(bj * 128 + wc * 32 + n * 16 + fr, tposl, pk4(acc[ai][bj][m][n]));
;       }
;     __syncthreads();
;     const int bt = brow >> tshift, tl0 = brow & (T - 1);
;     tile_rows_out<true>(out + ((size_t)(bt * nch + (bcol - segstart)) << tshift) + tl0, (size_t)T, (wr * 4 + wc) * 64 + fq * 16 + fr);
	v_bitop3_b32 v18, v32, v128, 16 bitop3:0x1e
	v_lshlrev_b32_e32 v26, 4, v26
	v_lshlrev_b32_e32 v18, 4, v18
	v_add3_u32 v27, v118, v26, v130
	v_add3_u32 v19, v118, v18, v130
	ds_write_b64 v27, v[24:25]
	ds_write_b64 v19, v[16:17] offset:8192
	v_cvt_pk_bf16_f32 v16, v28, v29
	v_cvt_pk_bf16_f32 v17, v30, v31
	v_add3_u32 v19, v115, v26, v130
	ds_write_b64 v19, v[16:17]
	v_cvt_pk_bf16_f32 v16, v20, v21
	v_cvt_pk_bf16_f32 v17, v22, v23
	v_add3_u32 v18, v116, v18, v130
	ds_write_b64 v18, v[16:17]
	v_add_u32_e32 v16, 0xb0, v132
	v_ashrrev_i32_e32 v16, 3, v16
	v_cvt_pk_bf16_f32 v8, v8, v9
	v_cvt_pk_bf16_f32 v9, v10, v11
	v_bitop3_b32 v10, v16, v140, 15 bitop3:0x78
	v_cvt_pk_bf16_f32 v0, v0, v1
	v_cvt_pk_bf16_f32 v1, v2, v3
	v_bitop3_b32 v2, v16, v128, 16 bitop3:0x1e
	v_lshlrev_b32_e32 v10, 4, v10
	v_lshlrev_b32_e32 v2, 4, v2
	v_add3_u32 v11, v118, v10, v130
	v_add3_u32 v3, v118, v2, v130
	s_ashr_i32 s0, s6, s40
	s_lshl_b32 s1, -1, s40
	ds_write_b64 v11, v[8:9]
	ds_write_b64 v3, v[0:1] offset:8192
	v_cvt_pk_bf16_f32 v0, v12, v13
	v_cvt_pk_bf16_f32 v1, v14, v15
	v_add3_u32 v3, v115, v10, v130
	s_andn2_b32 s6, s6, s1
	s_lshl_b32 s0, s0, 11
	s_add_i32 s1, s8, s41
	v_bfe_u32 v131, v140, 4, 2
	ds_write_b64 v3, v[0:1]
	v_cvt_pk_bf16_f32 v0, v4, v5
	v_cvt_pk_bf16_f32 v1, v6, v7
	v_add3_u32 v2, v116, v2, v130
	s_add_i32 s0, s1, s0
	ds_write_b64 v2, v[0:1]
	s_ashr_i32 s1, s0, 31
	v_and_b32_e32 v0, 0xffffff00, v140
	v_lshlrev_b32_e32 v1, 6, v129
	v_lshlrev_b32_e32 v2, 4, v131
	s_lshl_b64 s[0:1], s[0:1], s40
	v_or3_b32 v12, v1, v0, v2
	s_lshl_b64 s[0:1], s[0:1], 1
	v_or_b32_e32 v0, v12, v128
	s_add_u32 s0, s4, s0
	v_lshlrev_b32_e32 v0, 4, v0
	s_addc_u32 s1, s5, s1
	s_lshl_b32 s4, s6, 1
	v_and_b32_e32 v0, 0x1f0, v0
	v_ashrrev_i32_e32 v4, 5, v12
	s_add_u32 s0, s0, s4
	v_add_u32_e32 v13, 0, v0
	v_bitop3_b32 v6, v4, v12, v128 bitop3:0x1e
	v_ashrrev_i32_e32 v5, 31, v4
	s_addc_u32 s1, s1, 0
	v_lshl_add_u32 v0, v4, 9, v13
	v_lshlrev_b64 v[4:5], s40, v[4:5]
	v_lshlrev_b32_e32 v6, 4, v6
	s_waitcnt vmcnt(0) lgkmcnt(0)
	s_barrier
; template <bool NT = false>
; DEV void tile_rows_out(bf16_t* __restrict__ out0, const size_t ld, const int tid) {
; #pragma unroll
;   for (int i = 0; i < 16; ++i) {
;     const int id = i * 512 + tid, r = id >> 5, pos = id & 31, c = pos ^ (r & 31);
;     const u32x4 v = *(const u32x4*)(smem + r * 512 + pos * 16);
;     if (NT) __builtin_nontemporal_store(v, (u32x4*)(out0 + (size_t)r * ld + 8 * c)); else *(u32x4*)(out0 + (size_t)r * ld + 8 * c) = v;
;   }
	ds_read_b128 v[0:3], v0
	v_lshl_add_u64 v[4:5], v[4:5], 1, s[0:1]
	v_and_b32_e32 v176, 0x1f0, v6
	v_lshl_add_u64 v[8:9], v[4:5], 0, v[176:177]
	v_add_u32_e32 v4, 0x200, v12
	v_ashrrev_i32_e32 v10, 5, v4
	v_lshl_add_u32 v4, v10, 9, v13
	ds_read_b128 v[4:7], v4
	s_waitcnt lgkmcnt(1)
	global_store_dwordx4 v[8:9], v[0:3], off sc1
	v_ashrrev_i32_e32 v11, 31, v10
	s_nop 0
	v_bitop3_b32 v2, v10, v12, v128 bitop3:0x1e
	v_lshlrev_b64 v[0:1], s40, v[10:11]
	v_lshlrev_b32_e32 v2, 4, v2
	v_lshl_add_u64 v[0:1], v[0:1], 1, s[0:1]
	v_and_b32_e32 v176, 0x1f0, v2
	v_lshl_add_u64 v[0:1], v[0:1], 0, v[176:177]
	s_waitcnt lgkmcnt(0)
	global_store_dwordx4 v[0:1], v[4:7], off sc1
	v_add_u32_e32 v0, 0x400, v12
	s_nop 0
	v_ashrrev_i32_e32 v4, 5, v0
	v_bitop3_b32 v6, v4, v12, v128 bitop3:0x1e
	v_ashrrev_i32_e32 v5, 31, v4
	v_lshl_add_u32 v0, v4, 9, v13
	v_lshlrev_b64 v[4:5], s40, v[4:5]
	v_lshlrev_b32_e32 v6, 4, v6
	ds_read_b128 v[0:3], v0
	v_lshl_add_u64 v[4:5], v[4:5], 1, s[0:1]
	v_and_b32_e32 v176, 0x1f0, v6
	v_lshl_add_u64 v[8:9], v[4:5], 0, v[176:177]
	v_add_u32_e32 v4, 0x600, v12
	v_ashrrev_i32_e32 v10, 5, v4
	v_lshl_add_u32 v4, v10, 9, v13
	ds_read_b128 v[4:7], v4
	s_waitcnt lgkmcnt(1)
	global_store_dwordx4 v[8:9], v[0:3], off sc1
	v_ashrrev_i32_e32 v11, 31, v10
	s_nop 0
	v_bitop3_b32 v2, v10, v12, v128 bitop3:0x1e
	v_lshlrev_b64 v[0:1], s40, v[10:11]
	v_lshlrev_b32_e32 v2, 4, v2
	v_lshl_add_u64 v[0:1], v[0:1], 1, s[0:1]
	v_and_b32_e32 v176, 0x1f0, v2
	v_lshl_add_u64 v[0:1], v[0:1], 0, v[176:177]
	s_waitcnt lgkmcnt(0)
	global_store_dwordx4 v[0:1], v[4:7], off sc1
	v_add_u32_e32 v0, 0x800, v12
	s_nop 0
	v_ashrrev_i32_e32 v4, 5, v0
	v_bitop3_b32 v6, v4, v12, v128 bitop3:0x1e
	v_ashrrev_i32_e32 v5, 31, v4
	v_lshl_add_u32 v0, v4, 9, v13
	v_lshlrev_b64 v[4:5], s40, v[4:5]
	v_lshlrev_b32_e32 v6, 4, v6
	ds_read_b128 v[0:3], v0
	v_lshl_add_u64 v[4:5], v[4:5], 1, s[0:1]
	v_and_b32_e32 v176, 0x1f0, v6
	v_lshl_add_u64 v[8:9], v[4:5], 0, v[176:177]
	v_add_u32_e32 v4, 0xa00, v12
	v_ashrrev_i32_e32 v10, 5, v4
	v_lshl_add_u32 v4, v10, 9, v13
	ds_read_b128 v[4:7], v4
	s_waitcnt lgkmcnt(1)
	global_store_dwordx4 v[8:9], v[0:3], off sc1
	v_ashrrev_i32_e32 v11, 31, v10
	s_nop 0
	v_bitop3_b32 v2, v10, v12, v128 bitop3:0x1e
	v_lshlrev_b64 v[0:1], s40, v[10:11]
	v_lshlrev_b32_e32 v2, 4, v2
	v_lshl_add_u64 v[0:1], v[0:1], 1, s[0:1]
	v_and_b32_e32 v176, 0x1f0, v2
	v_lshl_add_u64 v[0:1], v[0:1], 0, v[176:177]
	s_waitcnt lgkmcnt(0)
	global_store_dwordx4 v[0:1], v[4:7], off sc1
	v_add_u32_e32 v0, 0xc00, v12
	s_nop 0
	v_ashrrev_i32_e32 v4, 5, v0
	v_bitop3_b32 v6, v4, v12, v128 bitop3:0x1e
	v_ashrrev_i32_e32 v5, 31, v4
	v_lshl_add_u32 v0, v4, 9, v13
	v_lshlrev_b64 v[4:5], s40, v[4:5]
	v_lshlrev_b32_e32 v6, 4, v6
	ds_read_b128 v[0:3], v0
	v_lshl_add_u64 v[4:5], v[4:5], 1, s[0:1]
	v_and_b32_e32 v176, 0x1f0, v6
	v_lshl_add_u64 v[8:9], v[4:5], 0, v[176:177]
	v_add_u32_e32 v4, 0xe00, v12
	v_ashrrev_i32_e32 v10, 5, v4
	v_lshl_add_u32 v4, v10, 9, v13
	ds_read_b128 v[4:7], v4
	s_waitcnt lgkmcnt(1)
	global_store_dwordx4 v[8:9], v[0:3], off sc1
	v_ashrrev_i32_e32 v11, 31, v10
	s_nop 0
	v_bitop3_b32 v2, v10, v12, v128 bitop3:0x1e
	v_lshlrev_b64 v[0:1], s40, v[10:11]
	v_lshlrev_b32_e32 v2, 4, v2
	v_lshl_add_u64 v[0:1], v[0:1], 1, s[0:1]
	v_and_b32_e32 v176, 0x1f0, v2
	v_lshl_add_u64 v[0:1], v[0:1], 0, v[176:177]
	s_waitcnt lgkmcnt(0)
	global_store_dwordx4 v[0:1], v[4:7], off sc1
	v_add_u32_e32 v0, 0x1000, v12
	s_nop 0
	v_ashrrev_i32_e32 v4, 5, v0
	v_bitop3_b32 v6, v4, v12, v128 bitop3:0x1e
	v_ashrrev_i32_e32 v5, 31, v4
	v_lshl_add_u32 v0, v4, 9, v13
	v_lshlrev_b64 v[4:5], s40, v[4:5]
	v_lshlrev_b32_e32 v6, 4, v6
	ds_read_b128 v[0:3], v0
	v_lshl_add_u64 v[4:5], v[4:5], 1, s[0:1]
	v_and_b32_e32 v176, 0x1f0, v6
	v_lshl_add_u64 v[8:9], v[4:5], 0, v[176:177]
	v_add_u32_e32 v4, 0x1200, v12
	v_ashrrev_i32_e32 v10, 5, v4
	v_lshl_add_u32 v4, v10, 9, v13
	ds_read_b128 v[4:7], v4
	s_waitcnt lgkmcnt(1)
	global_store_dwordx4 v[8:9], v[0:3], off sc1
	v_ashrrev_i32_e32 v11, 31, v10
	s_nop 0
	v_bitop3_b32 v2, v10, v12, v128 bitop3:0x1e
	v_lshlrev_b64 v[0:1], s40, v[10:11]
	v_lshlrev_b32_e32 v2, 4, v2
	v_lshl_add_u64 v[0:1], v[0:1], 1, s[0:1]
	v_and_b32_e32 v176, 0x1f0, v2
	v_lshl_add_u64 v[0:1], v[0:1], 0, v[176:177]
	s_waitcnt lgkmcnt(0)
	global_store_dwordx4 v[0:1], v[4:7], off sc1
	v_add_u32_e32 v0, 0x1400, v12
	s_nop 0
	v_ashrrev_i32_e32 v4, 5, v0
	v_bitop3_b32 v6, v4, v12, v128 bitop3:0x1e
	v_ashrrev_i32_e32 v5, 31, v4
	v_lshl_add_u32 v0, v4, 9, v13
	v_lshlrev_b64 v[4:5], s40, v[4:5]
	v_lshlrev_b32_e32 v6, 4, v6
	ds_read_b128 v[0:3], v0
	v_lshl_add_u64 v[4:5], v[4:5], 1, s[0:1]
	v_and_b32_e32 v176, 0x1f0, v6
	v_lshl_add_u64 v[8:9], v[4:5], 0, v[176:177]
	v_add_u32_e32 v4, 0x1600, v12
	v_ashrrev_i32_e32 v10, 5, v4
	v_lshl_add_u32 v4, v10, 9, v13
	ds_read_b128 v[4:7], v4
	s_waitcnt lgkmcnt(1)
	global_store_dwordx4 v[8:9], v[0:3], off sc1
	v_ashrrev_i32_e32 v11, 31, v10
	s_nop 0
	v_bitop3_b32 v2, v10, v12, v128 bitop3:0x1e
	v_lshlrev_b64 v[0:1], s40, v[10:11]
	v_lshlrev_b32_e32 v2, 4, v2
	v_lshl_add_u64 v[0:1], v[0:1], 1, s[0:1]
	v_and_b32_e32 v176, 0x1f0, v2
	v_lshl_add_u64 v[0:1], v[0:1], 0, v[176:177]
	s_waitcnt lgkmcnt(0)
	global_store_dwordx4 v[0:1], v[4:7], off sc1
	v_add_u32_e32 v0, 0x1800, v12
	s_nop 0
	v_ashrrev_i32_e32 v4, 5, v0
	v_bitop3_b32 v6, v4, v12, v128 bitop3:0x1e
	v_ashrrev_i32_e32 v5, 31, v4
	v_lshl_add_u32 v0, v4, 9, v13
	v_lshlrev_b64 v[4:5], s40, v[4:5]
	v_lshlrev_b32_e32 v6, 4, v6
	ds_read_b128 v[0:3], v0
	v_lshl_add_u64 v[4:5], v[4:5], 1, s[0:1]
	v_and_b32_e32 v176, 0x1f0, v6
	v_lshl_add_u64 v[8:9], v[4:5], 0, v[176:177]
	v_add_u32_e32 v4, 0x1a00, v12
	v_ashrrev_i32_e32 v10, 5, v4
	v_lshl_add_u32 v4, v10, 9, v13
	ds_read_b128 v[4:7], v4
	s_waitcnt lgkmcnt(1)
	global_store_dwordx4 v[8:9], v[0:3], off sc1
	v_ashrrev_i32_e32 v11, 31, v10
	s_nop 0
	v_bitop3_b32 v2, v10, v12, v128 bitop3:0x1e
	v_lshlrev_b64 v[0:1], s40, v[10:11]
	v_lshlrev_b32_e32 v2, 4, v2
	v_lshl_add_u64 v[0:1], v[0:1], 1, s[0:1]
	v_and_b32_e32 v176, 0x1f0, v2
	v_lshl_add_u64 v[0:1], v[0:1], 0, v[176:177]
	s_waitcnt lgkmcnt(0)
	global_store_dwordx4 v[0:1], v[4:7], off sc1
	v_add_u32_e32 v0, 0x1c00, v12
	s_nop 0
	v_ashrrev_i32_e32 v4, 5, v0
	v_bitop3_b32 v6, v4, v12, v128 bitop3:0x1e
	v_ashrrev_i32_e32 v5, 31, v4
	v_lshl_add_u32 v0, v4, 9, v13
	v_lshlrev_b64 v[4:5], s40, v[4:5]
	v_lshlrev_b32_e32 v6, 4, v6
	ds_read_b128 v[0:3], v0
	v_lshl_add_u64 v[4:5], v[4:5], 1, s[0:1]
	v_and_b32_e32 v176, 0x1f0, v6
	v_lshl_add_u64 v[8:9], v[4:5], 0, v[176:177]
	v_add_u32_e32 v4, 0x1e00, v12
	v_ashrrev_i32_e32 v10, 5, v4
	v_lshl_add_u32 v4, v10, 9, v13
	ds_read_b128 v[4:7], v4
	s_waitcnt lgkmcnt(1)
	global_store_dwordx4 v[8:9], v[0:3], off sc1
	v_ashrrev_i32_e32 v11, 31, v10
	s_nop 0
	v_bitop3_b32 v2, v10, v12, v128 bitop3:0x1e
	v_lshlrev_b64 v[0:1], s40, v[10:11]
	v_lshlrev_b32_e32 v2, 4, v2
	v_lshl_add_u64 v[0:1], v[0:1], 1, s[0:1]
	v_and_b32_e32 v176, 0x1f0, v2
	v_lshl_add_u64 v[0:1], v[0:1], 0, v[176:177]
	s_waitcnt lgkmcnt(0)
	global_store_dwordx4 v[0:1], v[4:7], off sc1

; template <bool NT = false>
; DEV void tile_rows_out(bf16_t* __restrict__ out0, const size_t ld, const int tid) {
; #pragma unroll
;   for (int i = 0; i < 16; ++i) {
;     const int id = i * 512 + tid, r = id >> 5, pos = id & 31, c = pos ^ (r & 31);
;     const u32x4 v = *(const u32x4*)(smem + r * 512 + pos * 16);
;     if (NT) __builtin_nontemporal_store(v, (u32x4*)(out0 + (size_t)r * ld + 8 * c)); else *(u32x4*)(out0 + (size_t)r * ld + 8 * c) = v;
;   }
.LBB0_1132:
	s_ashr_i32 s0, s7, 31
	s_mul_hi_u32 s1, s14, s7
	s_mul_i32 s0, s14, s0
	s_add_i32 s0, s1, s0
	s_mul_i32 s1, s15, s7
	s_waitcnt vmcnt(0)
	v_and_b32_e32 v128, 0xffffff00, v198
	v_lshlrev_b32_e32 v129, 6, v138
	v_lshlrev_b32_e32 v130, 4, v139
	s_add_i32 s1, s0, s1
	s_mul_i32 s0, s14, s7
	v_or3_b32 v133, v129, v128, v130
	s_lshl_b64 s[0:1], s[0:1], 1
	v_or_b32_e32 v128, v133, v202
	s_add_u32 s20, s18, s0
	v_lshlrev_b32_e32 v128, 4, v128
	s_addc_u32 s21, s19, s1
	s_sub_i32 s18, s9, s42
	v_and_b32_e32 v128, 0x1f0, v128
	s_ashr_i32 s19, s18, 31
	v_add_u32_e32 v199, 0, v128
	v_ashrrev_i32_e32 v128, 5, v133
	s_lshl_b64 s[0:1], s[18:19], 1
	v_lshlrev_b32_e32 v129, 9, v128
	s_add_u32 s0, s20, s0
	v_bitop3_b32 v140, v128, v133, v202 bitop3:0x1e
	v_add_u32_e32 v205, v199, v129
	v_ashrrev_i32_e32 v129, 31, v128
	s_addc_u32 s1, s21, s1
	v_mul_lo_u32 v141, s14, v129
	v_mul_lo_u32 v142, s15, v128
	v_mad_u64_u32 v[130:131], s[20:21], s14, v128, 0
	v_lshlrev_b32_e32 v140, 3, v140
	v_add3_u32 v131, v131, v141, v142
	v_and_b32_e32 v140, 0xf8, v140
	s_waitcnt lgkmcnt(0)
	s_barrier
	ds_read_b128 v[136:139], v205
	v_lshl_add_u64 v[130:131], v[130:131], 1, s[0:1]
	v_lshlrev_b32_e32 v176, 1, v140
	v_lshl_add_u64 v[144:145], v[130:131], 0, v[176:177]
	v_add_u32_e32 v130, 0x200, v133
	v_ashrrev_i32_e32 v130, 5, v130
	v_lshlrev_b32_e32 v131, 9, v130
	v_add_u32_e32 v206, v199, v131
	v_ashrrev_i32_e32 v131, 31, v130
	ds_read_b128 v[140:143], v206
	s_waitcnt lgkmcnt(1)
	global_store_dwordx4 v[144:145], v[136:139], off sc1
	v_bitop3_b32 v144, v130, v133, v202 bitop3:0x1e
	s_andn2_b64 vcc, exec, s[16:17]
	v_mul_lo_u32 v138, s14, v131
	v_mul_lo_u32 v139, s15, v130
	v_mad_u64_u32 v[136:137], s[20:21], s14, v130, 0
	v_add3_u32 v137, v137, v138, v139
	v_lshl_add_u64 v[138:139], v[136:137], 1, s[0:1]
	v_lshlrev_b32_e32 v136, 3, v144
	v_and_b32_e32 v136, 0xf8, v136
	v_lshlrev_b32_e32 v136, 1, v136
	v_mov_b32_e32 v137, v177
	v_lshl_add_u64 v[138:139], v[138:139], 0, v[136:137]
	s_waitcnt lgkmcnt(0)
	global_store_dwordx4 v[138:139], v[140:143], off sc1
	v_add_u32_e32 v138, 0x400, v133
	v_ashrrev_i32_e32 v138, 5, v138
	v_lshlrev_b32_e32 v139, 9, v138
	v_bitop3_b32 v142, v138, v133, v202 bitop3:0x1e
	v_add_u32_e32 v207, v199, v139
	v_ashrrev_i32_e32 v139, 31, v138
	v_mul_lo_u32 v143, s14, v139
	v_mul_lo_u32 v148, s15, v138
	v_mad_u64_u32 v[140:141], s[20:21], s14, v138, 0
	v_lshlrev_b32_e32 v142, 3, v142
	v_add3_u32 v141, v141, v143, v148
	v_and_b32_e32 v142, 0xf8, v142
	ds_read_b128 v[144:147], v207
	v_lshl_add_u64 v[140:141], v[140:141], 1, s[0:1]
	v_lshlrev_b32_e32 v142, 1, v142
	v_mov_b32_e32 v143, v177
	v_lshl_add_u64 v[152:153], v[140:141], 0, v[142:143]
	v_add_u32_e32 v140, 0x600, v133
	v_ashrrev_i32_e32 v140, 5, v140
	v_lshlrev_b32_e32 v141, 9, v140
	v_add_u32_e32 v208, v199, v141
	v_ashrrev_i32_e32 v141, 31, v140
	ds_read_b128 v[148:151], v208
	s_waitcnt lgkmcnt(1)
	global_store_dwordx4 v[152:153], v[144:147], off sc1
	v_bitop3_b32 v152, v140, v133, v202 bitop3:0x1e
	s_nop 0
	v_mul_lo_u32 v146, s14, v141
	v_mul_lo_u32 v147, s15, v140
	v_mad_u64_u32 v[144:145], s[20:21], s14, v140, 0
	v_add3_u32 v145, v145, v146, v147
	v_lshl_add_u64 v[146:147], v[144:145], 1, s[0:1]
	v_lshlrev_b32_e32 v144, 3, v152
	v_and_b32_e32 v144, 0xf8, v144
	v_lshlrev_b32_e32 v144, 1, v144
	v_mov_b32_e32 v145, v177
	v_lshl_add_u64 v[146:147], v[146:147], 0, v[144:145]
	s_waitcnt lgkmcnt(0)
	global_store_dwordx4 v[146:147], v[148:151], off sc1
	v_add_u32_e32 v146, 0x800, v133
	v_ashrrev_i32_e32 v146, 5, v146
	v_lshlrev_b32_e32 v147, 9, v146
	v_bitop3_b32 v150, v146, v133, v202 bitop3:0x1e
	v_add_u32_e32 v209, v199, v147
	v_ashrrev_i32_e32 v147, 31, v146
	v_mul_lo_u32 v151, s14, v147
	v_mul_lo_u32 v156, s15, v146
	v_mad_u64_u32 v[148:149], s[20:21], s14, v146, 0
	v_lshlrev_b32_e32 v150, 3, v150
	v_add3_u32 v149, v149, v151, v156
	v_and_b32_e32 v150, 0xf8, v150
	ds_read_b128 v[152:155], v209
	v_lshl_add_u64 v[148:149], v[148:149], 1, s[0:1]
	v_lshlrev_b32_e32 v150, 1, v150
	v_mov_b32_e32 v151, v177
	v_lshl_add_u64 v[160:161], v[148:149], 0, v[150:151]
	v_add_u32_e32 v148, 0xa00, v133
	v_ashrrev_i32_e32 v148, 5, v148
	v_lshlrev_b32_e32 v149, 9, v148
	v_add_u32_e32 v210, v199, v149
	v_ashrrev_i32_e32 v149, 31, v148
	ds_read_b128 v[156:159], v210
	s_waitcnt lgkmcnt(1)
	global_store_dwordx4 v[160:161], v[152:155], off sc1
	v_bitop3_b32 v160, v148, v133, v202 bitop3:0x1e
	s_nop 0
	v_mul_lo_u32 v154, s14, v149
	v_mul_lo_u32 v155, s15, v148
	v_mad_u64_u32 v[152:153], s[20:21], s14, v148, 0
	v_add3_u32 v153, v153, v154, v155
	v_lshl_add_u64 v[154:155], v[152:153], 1, s[0:1]
	v_lshlrev_b32_e32 v152, 3, v160
	v_and_b32_e32 v152, 0xf8, v152
	v_lshlrev_b32_e32 v152, 1, v152
	v_mov_b32_e32 v153, v177
	v_lshl_add_u64 v[154:155], v[154:155], 0, v[152:153]
	s_waitcnt lgkmcnt(0)
	global_store_dwordx4 v[154:155], v[156:159], off sc1
	v_add_u32_e32 v154, 0xc00, v133
	v_ashrrev_i32_e32 v154, 5, v154
	v_lshlrev_b32_e32 v155, 9, v154
	v_bitop3_b32 v158, v154, v133, v202 bitop3:0x1e
	v_add_u32_e32 v211, v199, v155
	v_ashrrev_i32_e32 v155, 31, v154
	v_mul_lo_u32 v159, s14, v155
	v_mul_lo_u32 v164, s15, v154
	v_mad_u64_u32 v[156:157], s[20:21], s14, v154, 0
	v_lshlrev_b32_e32 v158, 3, v158
	v_add3_u32 v157, v157, v159, v164
	v_and_b32_e32 v158, 0xf8, v158
	ds_read_b128 v[160:163], v211
	v_lshl_add_u64 v[156:157], v[156:157], 1, s[0:1]
	v_lshlrev_b32_e32 v158, 1, v158
	v_mov_b32_e32 v159, v177
	v_lshl_add_u64 v[168:169], v[156:157], 0, v[158:159]
	v_add_u32_e32 v156, 0xe00, v133
	v_ashrrev_i32_e32 v156, 5, v156
	v_lshlrev_b32_e32 v157, 9, v156
	v_add_u32_e32 v212, v199, v157
	v_ashrrev_i32_e32 v157, 31, v156
	ds_read_b128 v[164:167], v212
	s_waitcnt lgkmcnt(1)
; template <bool NT = false>
; DEV void tile_rows_out(bf16_t* __restrict__ out0, const size_t ld, const int tid) {
; #pragma unroll
;   for (int i = 0; i < 16; ++i) {
;     const int id = i * 512 + tid, r = id >> 5, pos = id & 31, c = pos ^ (r & 31);
;     const u32x4 v = *(const u32x4*)(smem + r * 512 + pos * 16);
;     if (NT) __builtin_nontemporal_store(v, (u32x4*)(out0 + (size_t)r * ld + 8 * c)); else *(u32x4*)(out0 + (size_t)r * ld + 8 * c) = v;
;   }
; }
;   DEV void operator()(f32x4 (&acc)[2][2][4][2], int brow, int bcol, int wr, int wc, int fr, int fq) const {
;     ...
;     __syncthreads();
;     tile_rows_out<true>(out + (size_t)brow * ld + (bcol - segstart), (size_t)ld, (wr * 4 + wc) * 64 + fq * 16 + fr);
	global_store_dwordx4 v[168:169], v[160:163], off sc1
	v_bitop3_b32 v168, v156, v133, v202 bitop3:0x1e
	s_nop 0
	v_mul_lo_u32 v162, s14, v157
	v_mul_lo_u32 v163, s15, v156
	v_mad_u64_u32 v[160:161], s[20:21], s14, v156, 0
	v_add3_u32 v161, v161, v162, v163
	v_lshl_add_u64 v[162:163], v[160:161], 1, s[0:1]
	v_lshlrev_b32_e32 v160, 3, v168
	v_and_b32_e32 v160, 0xf8, v160
	v_lshlrev_b32_e32 v160, 1, v160
	v_mov_b32_e32 v161, v177
	v_lshl_add_u64 v[162:163], v[162:163], 0, v[160:161]
	s_waitcnt lgkmcnt(0)
	global_store_dwordx4 v[162:163], v[164:167], off sc1
	v_add_u32_e32 v162, 0x1000, v133
	v_ashrrev_i32_e32 v162, 5, v162
	v_lshlrev_b32_e32 v163, 9, v162
	v_bitop3_b32 v166, v162, v133, v202 bitop3:0x1e
	v_add_u32_e32 v213, v199, v163
	v_ashrrev_i32_e32 v163, 31, v162
	v_mul_lo_u32 v167, s14, v163
	v_mul_lo_u32 v172, s15, v162
	v_mad_u64_u32 v[164:165], s[20:21], s14, v162, 0
	v_lshlrev_b32_e32 v166, 3, v166
	v_add3_u32 v165, v165, v167, v172
	v_and_b32_e32 v166, 0xf8, v166
	ds_read_b128 v[168:171], v213
	v_lshl_add_u64 v[164:165], v[164:165], 1, s[0:1]
	v_lshlrev_b32_e32 v166, 1, v166
	v_mov_b32_e32 v167, v177
	v_lshl_add_u64 v[180:181], v[164:165], 0, v[166:167]
	v_add_u32_e32 v164, 0x1200, v133
	v_ashrrev_i32_e32 v164, 5, v164
	v_lshlrev_b32_e32 v165, 9, v164
	v_add_u32_e32 v214, v199, v165
	v_ashrrev_i32_e32 v165, 31, v164
	ds_read_b128 v[172:175], v214
	s_waitcnt lgkmcnt(1)
	global_store_dwordx4 v[180:181], v[168:171], off sc1
	v_bitop3_b32 v180, v164, v133, v202 bitop3:0x1e
	s_nop 0
	v_mul_lo_u32 v170, s14, v165
	v_mul_lo_u32 v171, s15, v164
	v_mad_u64_u32 v[168:169], s[20:21], s14, v164, 0
	v_add3_u32 v169, v169, v170, v171
	v_lshl_add_u64 v[170:171], v[168:169], 1, s[0:1]
	v_lshlrev_b32_e32 v168, 3, v180
	v_and_b32_e32 v168, 0xf8, v168
	v_lshlrev_b32_e32 v168, 1, v168
	v_mov_b32_e32 v169, v177
	v_lshl_add_u64 v[170:171], v[170:171], 0, v[168:169]
	s_waitcnt lgkmcnt(0)
	global_store_dwordx4 v[170:171], v[172:175], off sc1
	v_add_u32_e32 v170, 0x1400, v133
	v_ashrrev_i32_e32 v170, 5, v170
	v_lshlrev_b32_e32 v171, 9, v170
	v_bitop3_b32 v174, v170, v133, v202 bitop3:0x1e
	v_add_u32_e32 v215, v199, v171
	v_ashrrev_i32_e32 v171, 31, v170
	v_mul_lo_u32 v175, s14, v171
	v_mul_lo_u32 v184, s15, v170
	v_mad_u64_u32 v[172:173], s[20:21], s14, v170, 0
	v_lshlrev_b32_e32 v174, 3, v174
	v_add3_u32 v173, v173, v175, v184
	v_and_b32_e32 v174, 0xf8, v174
	ds_read_b128 v[180:183], v215
	v_lshl_add_u64 v[172:173], v[172:173], 1, s[0:1]
	v_lshlrev_b32_e32 v174, 1, v174
	v_mov_b32_e32 v175, v177
	v_lshl_add_u64 v[188:189], v[172:173], 0, v[174:175]
	v_add_u32_e32 v172, 0x1600, v133
	v_ashrrev_i32_e32 v172, 5, v172
	v_lshlrev_b32_e32 v173, 9, v172
	v_add_u32_e32 v216, v199, v173
	v_ashrrev_i32_e32 v173, 31, v172
	ds_read_b128 v[184:187], v216
	s_waitcnt lgkmcnt(1)
	global_store_dwordx4 v[188:189], v[180:183], off sc1
	v_bitop3_b32 v188, v172, v133, v202 bitop3:0x1e
	s_nop 0
	v_mul_lo_u32 v182, s14, v173
	v_mul_lo_u32 v183, s15, v172
	v_mad_u64_u32 v[180:181], s[20:21], s14, v172, 0
	v_add3_u32 v181, v181, v182, v183
	v_lshl_add_u64 v[182:183], v[180:181], 1, s[0:1]
	v_lshlrev_b32_e32 v180, 3, v188
	v_and_b32_e32 v180, 0xf8, v180
	v_lshlrev_b32_e32 v180, 1, v180
	v_mov_b32_e32 v181, v177
	v_lshl_add_u64 v[182:183], v[182:183], 0, v[180:181]
	s_waitcnt lgkmcnt(0)
	global_store_dwordx4 v[182:183], v[184:187], off sc1
	v_add_u32_e32 v182, 0x1800, v133
	v_ashrrev_i32_e32 v182, 5, v182
	v_lshlrev_b32_e32 v183, 9, v182
	v_bitop3_b32 v186, v182, v133, v202 bitop3:0x1e
	v_add_u32_e32 v217, v199, v183
	v_ashrrev_i32_e32 v183, 31, v182
	v_mul_lo_u32 v187, s14, v183
	v_mul_lo_u32 v192, s15, v182
	v_mad_u64_u32 v[184:185], s[20:21], s14, v182, 0
	v_lshlrev_b32_e32 v186, 3, v186
	v_add3_u32 v185, v185, v187, v192
	v_and_b32_e32 v186, 0xf8, v186
	ds_read_b128 v[188:191], v217
	v_lshl_add_u64 v[184:185], v[184:185], 1, s[0:1]
	v_lshlrev_b32_e32 v186, 1, v186
	v_mov_b32_e32 v187, v177
	v_lshl_add_u64 v[196:197], v[184:185], 0, v[186:187]
	v_add_u32_e32 v184, 0x1a00, v133
	v_ashrrev_i32_e32 v184, 5, v184
	v_lshlrev_b32_e32 v185, 9, v184
	v_add_u32_e32 v223, v199, v185
	v_ashrrev_i32_e32 v185, 31, v184
	ds_read_b128 v[192:195], v223
	s_waitcnt lgkmcnt(1)
	global_store_dwordx4 v[196:197], v[188:191], off sc1
	v_bitop3_b32 v196, v184, v133, v202 bitop3:0x1e
	s_nop 0
	v_mul_lo_u32 v190, s14, v185
	v_mul_lo_u32 v191, s15, v184
	v_mad_u64_u32 v[188:189], s[20:21], s14, v184, 0
	v_add3_u32 v189, v189, v190, v191
	v_lshl_add_u64 v[190:191], v[188:189], 1, s[0:1]
	v_lshlrev_b32_e32 v188, 3, v196
	v_and_b32_e32 v188, 0xf8, v188
	v_lshlrev_b32_e32 v188, 1, v188
	v_mov_b32_e32 v189, v177
	v_lshl_add_u64 v[190:191], v[190:191], 0, v[188:189]
	s_waitcnt lgkmcnt(0)
	global_store_dwordx4 v[190:191], v[192:195], off sc1
	v_add_u32_e32 v190, 0x1c00, v133
	v_ashrrev_i32_e32 v190, 5, v190
	v_lshlrev_b32_e32 v191, 9, v190
	v_bitop3_b32 v194, v190, v133, v202 bitop3:0x1e
	v_add_u32_e32 v224, v199, v191
	v_ashrrev_i32_e32 v191, 31, v190
	v_mul_lo_u32 v195, s14, v191
	v_mul_lo_u32 v196, s15, v190
	v_mad_u64_u32 v[192:193], s[20:21], s14, v190, 0
	v_lshlrev_b32_e32 v194, 3, v194
	v_add3_u32 v193, v193, v195, v196
	v_and_b32_e32 v194, 0xf8, v194
	v_lshl_add_u64 v[192:193], v[192:193], 1, s[0:1]
	v_lshlrev_b32_e32 v194, 1, v194
	v_mov_b32_e32 v195, v177
	ds_read_b128 v[226:229], v224
	v_lshl_add_u64 v[196:197], v[192:193], 0, v[194:195]
	v_add_u32_e32 v192, 0x1e00, v133
	v_ashrrev_i32_e32 v192, 5, v192
	v_lshlrev_b32_e32 v193, 9, v192
	v_add_u32_e32 v225, v199, v193
	ds_read_b128 v[230:233], v225
	v_bitop3_b32 v133, v192, v133, v202 bitop3:0x1e
	v_ashrrev_i32_e32 v193, 31, v192
	s_waitcnt lgkmcnt(1)
	global_store_dwordx4 v[196:197], v[226:229], off sc1
	v_mul_lo_u32 v199, s14, v193
	v_lshlrev_b32_e32 v133, 3, v133
	v_mul_lo_u32 v226, s15, v192
	v_mad_u64_u32 v[196:197], s[14:15], s14, v192, 0
	v_add3_u32 v197, v197, v199, v226
	v_and_b32_e32 v133, 0xf8, v133
	v_lshl_add_u64 v[226:227], v[196:197], 1, s[0:1]
	v_lshlrev_b32_e32 v196, 1, v133
	v_mov_b32_e32 v197, v177
	v_lshl_add_u64 v[226:227], v[226:227], 0, v[196:197]
	s_waitcnt lgkmcnt(0)
	global_store_dwordx4 v[226:227], v[230:233], off sc1
	s_cbranch_vccnz .LBB0_1134
; DEV u32x2 pk4(f32x4 v) { u32x2 r = {pk_bf16(v[0], v[1]), pk_bf16(v[2], v[3])}; return r; }
;   DEV void operator()(f32x4 (&acc)[2][2][4][2], int brow, int bcol, int wr, int wc, int fr, int fq) const {
;     ...
;     if (mode == 4) {
;       __syncthreads();
; #pragma unroll
;       for (int ai = 0; ai < 2; ++ai)
; #pragma unroll
;         for (int m = 0; m < 4; ++m) {
;           const int rl = ai * 128 + wr * 64 + m * 16 + fr, tok = brow + rl;
;           const int tposl = (rl & ~15) + sig16(rl & 15);
; #pragma unroll
;           for (int bj = 0; bj < 2; ++bj)
; #pragma unroll
;             for (int n = 0; n < 2; ++n) {
;               const int cl = bj * 128 + wc * 32 + n * 16 + fq * 4, lc = bcol - segstart + cl;
;               const f32x4 v = acc[ai][bj][m][n];
;               const f32x4 b4 = *(const f32x4*)(bmat + (size_t)tok * 1024 + lc);
;               const f32x4 bl = *(const f32x4*)(bmat + (size_t)(tok | 63) * 1024 + lc);
;               const u32x2 kk = pk4((f32x4){v[0] * __expf(bl[0] - b4[0]), v[1] * __expf(bl[1] - b4[1]), v[2] * __expf(bl[2] - b4[2]), v[3] * __expf(bl[3] - b4[3])});
; #pragma unroll
;               for (int j = 0; j < 4; ++j) {
;                 const int row = cl + j;
;                 const unsigned short val = (unsigned short)((j & 1) ? (kk[j >> 1] >> 16) : (kk[j >> 1] & 0xffff));
;                 *(unsigned short*)(smem + row * 512 + (((tposl >> 3) ^ (row & 31)) * 16) + (tposl & 7) * 2) = val;
;               }
;             }
	v_lshlrev_b32_e32 v133, 1, v202
	v_or_b32_e32 v132, 63, v132
	v_and_b32_e32 v232, 8, v133
	v_and_b32_e32 v226, 6, v133
	v_readlane_b32 s0, v253, 54
	v_ashrrev_i32_e32 v133, 31, v132
	v_readlane_b32 s1, v253, 55
	v_lshlrev_b64 v[132:133], 12, v[132:133]
	v_and_b32_e32 v227, 8, v198
	v_lshl_add_u64 v[198:199], s[0:1], 0, v[132:133]
	v_add_u32_e32 v132, s18, v204
	v_ashrrev_i32_e32 v133, 31, v132
	v_or_b32_e32 v228, v232, v203
	v_lshl_add_u64 v[134:135], s[0:1], 0, v[134:135]
	v_lshlrev_b64 v[132:133], 2, v[132:133]
	v_ashrrev_i32_e32 v238, 3, v228
	v_lshl_add_u64 v[228:229], v[134:135], 0, v[132:133]
	v_lshl_add_u64 v[234:235], v[198:199], 0, v[132:133]
	s_barrier
	global_load_dwordx4 v[228:231], v[228:229], off
	s_and_b32 s9, s7, 0x7ff
	global_load_dwordx4 v[234:237], v[234:235], off
	v_readlane_b32 s14, v253, 25
	v_readlane_b32 s15, v253, 26
	s_waitcnt vmcnt(0)
	v_sub_f32_e32 v228, v234, v228
	v_sub_f32_e32 v229, v235, v229
	v_mul_f32_e32 v228, 0x3fb8aa3b, v228
	v_mul_f32_e32 v229, 0x3fb8aa3b, v229
	v_exp_f32_e32 v228, v228
	v_exp_f32_e32 v229, v229
	s_nop 0
	v_pk_mul_f32 v[124:125], v[124:125], v[228:229]
	v_sub_f32_e32 v228, v236, v230
	v_sub_f32_e32 v229, v237, v231
	v_mul_f32_e32 v228, 0x3fb8aa3b, v228
	v_mul_f32_e32 v229, 0x3fb8aa3b, v229
	v_exp_f32_e32 v228, v228
	v_exp_f32_e32 v229, v229
	v_cvt_pk_bf16_f32 v124, v124, v125
	v_pk_mul_f32 v[126:127], v[126:127], v[228:229]
	s_nop 0
	v_cvt_pk_bf16_f32 v125, v126, v127
	v_xor_b32_e32 v127, v238, v201
	v_lshl_add_u32 v126, v204, 9, 0
	v_lshlrev_b32_e32 v244, 4, v127
	v_add_u32_e32 v127, v126, v244
	v_add3_u32 v127, v127, v227, v226
	ds_write_b16 v127, v124
	v_bitop3_b32 v127, v238, v201, 1 bitop3:0x1e
	v_lshlrev_b32_e32 v245, 4, v127
	v_add_u32_e32 v127, v126, v245
	v_add3_u32 v127, v127, v227, v226
	ds_write_b16_d16_hi v127, v124 offset:512
	v_bitop3_b32 v124, v238, v201, 2 bitop3:0x1e
	v_lshlrev_b32_e32 v246, 4, v124
	v_add_u32_e32 v124, v126, v246
	v_add3_u32 v124, v124, v227, v226
	ds_write_b16 v124, v125 offset:1024
	v_bitop3_b32 v124, v238, v201, 3 bitop3:0x1e
	v_lshlrev_b32_e32 v247, 4, v124
	v_add_u32_e32 v124, v126, v247
	v_add3_u32 v124, v124, v227, v226
	v_or_b32_e32 v127, 16, v204
	ds_write_b16_d16_hi v124, v125 offset:1536
	v_add_u32_e32 v124, s18, v127
	v_ashrrev_i32_e32 v125, 31, v124
	v_lshlrev_b64 v[124:125], 2, v[124:125]
	v_lshl_add_u64 v[228:229], v[134:135], 0, v[124:125]
	v_lshl_add_u64 v[234:235], v[198:199], 0, v[124:125]
	global_load_dwordx4 v[228:231], v[228:229], off
	s_nop 0
	global_load_dwordx4 v[234:237], v[234:235], off
	s_waitcnt vmcnt(0)
	v_sub_f32_e32 v228, v234, v228
	v_sub_f32_e32 v229, v235, v229
	v_mul_f32_e32 v228, 0x3fb8aa3b, v228
	v_mul_f32_e32 v229, 0x3fb8aa3b, v229
	v_exp_f32_e32 v228, v228
	v_exp_f32_e32 v229, v229
	s_nop 0
	v_pk_mul_f32 v[120:121], v[120:121], v[228:229]
	v_sub_f32_e32 v228, v236, v230
	v_sub_f32_e32 v229, v237, v231
	v_mul_f32_e32 v228, 0x3fb8aa3b, v228
	v_mul_f32_e32 v229, 0x3fb8aa3b, v229
	v_exp_f32_e32 v228, v228
	v_exp_f32_e32 v229, v229
	v_cvt_pk_bf16_f32 v120, v120, v121
	v_lshl_add_u32 v231, v127, 9, 0
	v_add_u32_e32 v230, 0x10600, v126
	v_pk_mul_f32 v[122:123], v[122:123], v[228:229]
	s_nop 0
	v_cvt_pk_bf16_f32 v121, v122, v123
	v_bitop3_b32 v122, v238, v201, 16 bitop3:0x1e
	v_lshlrev_b32_e32 v122, 4, v122
	v_add_u32_e32 v123, v231, v122
	v_add3_u32 v123, v123, v227, v226
	ds_write_b16 v123, v120
	v_bitop3_b32 v123, v238, v201, 17 bitop3:0x1e
	v_lshlrev_b32_e32 v123, 4, v123
	v_add_u32_e32 v127, v126, v123
	v_add3_u32 v127, v127, v227, v226
	ds_write_b16_d16_hi v127, v120 offset:8704
	v_bitop3_b32 v120, v238, v201, 18 bitop3:0x1e
	v_lshlrev_b32_e32 v233, 4, v120
	v_add_u32_e32 v120, v126, v233
	v_add3_u32 v120, v120, v227, v226
	ds_write_b16 v120, v121 offset:9216
	v_bitop3_b32 v120, v238, v201, 19 bitop3:0x1e
	v_lshlrev_b32_e32 v234, 4, v120
	v_add_u32_e32 v120, v126, v234
	v_add3_u32 v120, v120, v227, v226
	v_or_b32_e32 v127, 0x80, v204
	ds_write_b16_d16_hi v120, v121 offset:9728
	v_add_u32_e32 v120, s18, v127
	v_ashrrev_i32_e32 v121, 31, v120
	v_lshlrev_b64 v[120:121], 2, v[120:121]
	v_lshl_add_u64 v[228:229], v[134:135], 0, v[120:121]
	global_load_dwordx4 v[236:239], v[228:229], off
	v_lshl_add_u64 v[228:229], v[198:199], 0, v[120:121]
	global_load_dwordx4 v[240:243], v[228:229], off
	v_lshl_add_u32 v127, v127, 9, 0
	v_or_b32_e32 v204, 0x90, v204
	s_waitcnt vmcnt(0)
	v_sub_f32_e32 v228, v240, v236
	v_sub_f32_e32 v229, v241, v237
	v_mul_f32_e32 v228, 0x3fb8aa3b, v228
	v_mul_f32_e32 v229, 0x3fb8aa3b, v229
	v_exp_f32_e32 v228, v228
	v_exp_f32_e32 v229, v229
	s_nop 0
	v_pk_mul_f32 v[116:117], v[116:117], v[228:229]
	v_sub_f32_e32 v228, v242, v238
	v_sub_f32_e32 v229, v243, v239
	v_mul_f32_e32 v228, 0x3fb8aa3b, v228
	v_mul_f32_e32 v229, 0x3fb8aa3b, v229
	v_exp_f32_e32 v228, v228
	v_exp_f32_e32 v229, v229
	v_cvt_pk_bf16_f32 v116, v116, v117
	v_pk_mul_f32 v[118:119], v[118:119], v[228:229]
	s_nop 0
	v_cvt_pk_bf16_f32 v117, v118, v119
	v_add_u32_e32 v118, v127, v244
	v_add3_u32 v118, v118, v227, v226
	v_add_u32_e32 v228, 0x10200, v126
	ds_write_b16 v118, v116
	v_add_u32_e32 v118, v228, v245
	v_add3_u32 v118, v118, v227, v226
	v_add_u32_e32 v229, 0x10400, v126
	ds_write_b16_d16_hi v118, v116
	v_add_u32_e32 v116, v229, v246
	v_add3_u32 v116, v116, v227, v226
	ds_write_b16 v116, v117
	v_add_u32_e32 v116, v230, v247
	v_add3_u32 v116, v116, v227, v226
	ds_write_b16_d16_hi v116, v117
	v_add_u32_e32 v116, s18, v204
	v_ashrrev_i32_e32 v117, 31, v116
	v_lshlrev_b64 v[116:117], 2, v[116:117]
	v_lshl_add_u64 v[118:119], v[134:135], 0, v[116:117]
	global_load_dwordx4 v[236:239], v[118:119], off
	v_lshl_add_u64 v[118:119], v[198:199], 0, v[116:117]
	global_load_dwordx4 v[240:243], v[118:119], off
	s_waitcnt vmcnt(0)
; DEV u32x2 pk4(f32x4 v) { u32x2 r = {pk_bf16(v[0], v[1]), pk_bf16(v[2], v[3])}; return r; }
;   DEV void operator()(f32x4 (&acc)[2][2][4][2], int brow, int bcol, int wr, int wc, int fr, int fq) const {
;     ...
; #pragma unroll
;       for (int ai = 0; ai < 2; ++ai)
; #pragma unroll
;         for (int m = 0; m < 4; ++m) {
;           const int rl = ai * 128 + wr * 64 + m * 16 + fr, tok = brow + rl;
;           const int tposl = (rl & ~15) + sig16(rl & 15);
; #pragma unroll
;           for (int bj = 0; bj < 2; ++bj)
; #pragma unroll
;             for (int n = 0; n < 2; ++n) {
;               const int cl = bj * 128 + wc * 32 + n * 16 + fq * 4, lc = bcol - segstart + cl;
;               const f32x4 v = acc[ai][bj][m][n];
;               const f32x4 b4 = *(const f32x4*)(bmat + (size_t)tok * 1024 + lc);
;               const f32x4 bl = *(const f32x4*)(bmat + (size_t)(tok | 63) * 1024 + lc);
;               const u32x2 kk = pk4((f32x4){v[0] * __expf(bl[0] - b4[0]), v[1] * __expf(bl[1] - b4[1]), v[2] * __expf(bl[2] - b4[2]), v[3] * __expf(bl[3] - b4[3])});
; #pragma unroll
;               for (int j = 0; j < 4; ++j) {
;                 const int row = cl + j;
;                 const unsigned short val = (unsigned short)((j & 1) ? (kk[j >> 1] >> 16) : (kk[j >> 1] & 0xffff));
;                 *(unsigned short*)(smem + row * 512 + (((tposl >> 3) ^ (row & 31)) * 16) + (tposl & 7) * 2) = val;
;               }
;             }
	v_sub_f32_e32 v118, v240, v236
	v_sub_f32_e32 v119, v241, v237
	v_mul_f32_e32 v118, 0x3fb8aa3b, v118
	v_mul_f32_e32 v119, 0x3fb8aa3b, v119
	v_exp_f32_e32 v118, v118
	v_exp_f32_e32 v119, v119
	s_nop 0
	v_pk_mul_f32 v[112:113], v[112:113], v[118:119]
	v_sub_f32_e32 v118, v242, v238
	v_sub_f32_e32 v119, v243, v239
	v_mul_f32_e32 v118, 0x3fb8aa3b, v118
	v_mul_f32_e32 v119, 0x3fb8aa3b, v119
	v_exp_f32_e32 v118, v118
	v_exp_f32_e32 v119, v119
	v_cvt_pk_bf16_f32 v112, v112, v113
	v_pk_mul_f32 v[114:115], v[114:115], v[118:119]
	v_lshl_add_u32 v118, v204, 9, 0
	v_cvt_pk_bf16_f32 v113, v114, v115
	v_add_u32_e32 v114, v118, v122
	v_add3_u32 v114, v114, v227, v226
	v_add_u32_e32 v119, 0x12200, v126
	ds_write_b16 v114, v112
	v_add_u32_e32 v114, v119, v123
	v_add3_u32 v114, v114, v227, v226
	v_add_u32_e32 v122, 0x12400, v126
	ds_write_b16_d16_hi v114, v112
	v_add_u32_e32 v112, v122, v233
	v_add3_u32 v112, v112, v227, v226
	v_add_u32_e32 v123, 0x12600, v126
	ds_write_b16 v112, v113
	v_add_u32_e32 v112, v123, v234
	v_add3_u32 v112, v112, v227, v226
	ds_write_b16_d16_hi v112, v113
	v_or_b32_e32 v112, 16, v203
	v_or_b32_e32 v113, v112, v202
	v_add_u32_e32 v114, s7, v113
	v_ashrrev_i32_e32 v115, 31, v114
	v_or_b32_e32 v134, v112, v232
	v_lshlrev_b64 v[112:113], 12, v[114:115]
	v_or_b32_e32 v114, 63, v114
	v_ashrrev_i32_e32 v115, 31, v114
	v_lshl_add_u64 v[112:113], s[0:1], 0, v[112:113]
	v_lshlrev_b64 v[114:115], 12, v[114:115]
	v_lshl_add_u64 v[114:115], s[0:1], 0, v[114:115]
	v_ashrrev_i32_e32 v198, 3, v134
	v_lshl_add_u64 v[134:135], v[112:113], 0, v[132:133]
	global_load_dwordx4 v[234:237], v[134:135], off
	v_lshl_add_u64 v[134:135], v[114:115], 0, v[132:133]
	global_load_dwordx4 v[238:241], v[134:135], off
	s_waitcnt vmcnt(0)
	v_sub_f32_e32 v134, v238, v234
	v_sub_f32_e32 v135, v239, v235
	v_mul_f32_e32 v134, 0x3fb8aa3b, v134
	v_mul_f32_e32 v135, 0x3fb8aa3b, v135
	v_exp_f32_e32 v134, v134
	v_exp_f32_e32 v135, v135
	s_nop 0
	v_pk_mul_f32 v[108:109], v[108:109], v[134:135]
	v_sub_f32_e32 v134, v240, v236
	v_sub_f32_e32 v135, v241, v237
	v_mul_f32_e32 v134, 0x3fb8aa3b, v134
	v_mul_f32_e32 v135, 0x3fb8aa3b, v135
	v_exp_f32_e32 v134, v134
	v_exp_f32_e32 v135, v135
	s_nop 0
	v_pk_mul_f32 v[110:111], v[110:111], v[134:135]
	v_cvt_pk_bf16_f32 v134, v108, v109
	v_xor_b32_e32 v108, v198, v201
	v_lshlrev_b32_e32 v108, 4, v108
	v_add_u32_e32 v109, v126, v108
	v_add3_u32 v109, v109, v227, v226
	ds_write_b16 v109, v134
	v_bitop3_b32 v109, v198, v201, 1 bitop3:0x1e
	v_lshlrev_b32_e32 v109, 4, v109
	v_cvt_pk_bf16_f32 v135, v110, v111
	v_add_u32_e32 v110, v126, v109
	v_add3_u32 v110, v110, v227, v226
	ds_write_b16_d16_hi v110, v134 offset:512
	v_bitop3_b32 v110, v198, v201, 2 bitop3:0x1e
	v_lshlrev_b32_e32 v110, 4, v110
	v_add_u32_e32 v111, v126, v110
	v_add3_u32 v111, v111, v227, v226
	ds_write_b16 v111, v135 offset:1024
	v_bitop3_b32 v111, v198, v201, 3 bitop3:0x1e
	v_lshlrev_b32_e32 v111, 4, v111
	v_add_u32_e32 v134, v126, v111
	v_add3_u32 v134, v134, v227, v226
	ds_write_b16_d16_hi v134, v135 offset:1536
	v_lshl_add_u64 v[134:135], v[112:113], 0, v[124:125]
	global_load_dwordx4 v[234:237], v[134:135], off
	v_lshl_add_u64 v[134:135], v[114:115], 0, v[124:125]
	global_load_dwordx4 v[238:241], v[134:135], off
	s_waitcnt vmcnt(0)
	v_sub_f32_e32 v134, v238, v234
	v_sub_f32_e32 v135, v239, v235
	v_mul_f32_e32 v134, 0x3fb8aa3b, v134
	v_mul_f32_e32 v135, 0x3fb8aa3b, v135
	v_exp_f32_e32 v134, v134
	v_exp_f32_e32 v135, v135
	s_nop 0
	v_pk_mul_f32 v[104:105], v[104:105], v[134:135]
	v_sub_f32_e32 v134, v240, v236
	v_sub_f32_e32 v135, v241, v237
	v_mul_f32_e32 v134, 0x3fb8aa3b, v134
	v_mul_f32_e32 v135, 0x3fb8aa3b, v135
	v_exp_f32_e32 v134, v134
	v_exp_f32_e32 v135, v135
	s_nop 0
	v_pk_mul_f32 v[106:107], v[106:107], v[134:135]
	v_cvt_pk_bf16_f32 v134, v104, v105
	v_bitop3_b32 v104, v198, v201, 16 bitop3:0x1e
	v_lshlrev_b32_e32 v104, 4, v104
	v_add_u32_e32 v105, v231, v104
	v_add3_u32 v105, v105, v227, v226
	ds_write_b16 v105, v134
	v_bitop3_b32 v105, v198, v201, 17 bitop3:0x1e
	v_lshlrev_b32_e32 v105, 4, v105
	v_cvt_pk_bf16_f32 v135, v106, v107
	v_add_u32_e32 v106, v126, v105
	v_add3_u32 v106, v106, v227, v226
	ds_write_b16_d16_hi v106, v134 offset:8704
	v_bitop3_b32 v106, v198, v201, 18 bitop3:0x1e
	v_lshlrev_b32_e32 v106, 4, v106
	v_add_u32_e32 v107, v126, v106
	v_add3_u32 v107, v107, v227, v226
	ds_write_b16 v107, v135 offset:9216
	v_bitop3_b32 v107, v198, v201, 19 bitop3:0x1e
	v_lshlrev_b32_e32 v107, 4, v107
	v_add_u32_e32 v134, v126, v107
	v_add3_u32 v134, v134, v227, v226
	ds_write_b16_d16_hi v134, v135 offset:9728
	v_lshl_add_u64 v[134:135], v[112:113], 0, v[120:121]
	global_load_dwordx4 v[234:237], v[134:135], off
	v_lshl_add_u64 v[134:135], v[114:115], 0, v[120:121]
	global_load_dwordx4 v[238:241], v[134:135], off
	s_waitcnt vmcnt(0)
	v_sub_f32_e32 v134, v238, v234
	v_sub_f32_e32 v135, v239, v235
	v_mul_f32_e32 v134, 0x3fb8aa3b, v134
	v_mul_f32_e32 v135, 0x3fb8aa3b, v135
	v_exp_f32_e32 v134, v134
	v_exp_f32_e32 v135, v135
	s_nop 0
	v_pk_mul_f32 v[100:101], v[100:101], v[134:135]
	v_sub_f32_e32 v134, v240, v236
	v_sub_f32_e32 v135, v241, v237
	v_mul_f32_e32 v134, 0x3fb8aa3b, v134
	v_mul_f32_e32 v135, 0x3fb8aa3b, v135
	v_exp_f32_e32 v134, v134
	v_exp_f32_e32 v135, v135
	v_cvt_pk_bf16_f32 v100, v100, v101
	v_pk_mul_f32 v[102:103], v[102:103], v[134:135]
	s_nop 0
	v_cvt_pk_bf16_f32 v101, v102, v103
	v_add_u32_e32 v102, v127, v108
	v_add3_u32 v102, v102, v227, v226
	ds_write_b16 v102, v100
	v_add_u32_e32 v102, v228, v109
	v_add3_u32 v102, v102, v227, v226
	ds_write_b16_d16_hi v102, v100
	v_add_u32_e32 v100, v229, v110
	v_add3_u32 v100, v100, v227, v226
	ds_write_b16 v100, v101
	v_add_u32_e32 v100, v230, v111
	v_add3_u32 v100, v100, v227, v226
	ds_write_b16_d16_hi v100, v101
	v_lshl_add_u64 v[100:101], v[112:113], 0, v[116:117]
	v_lshl_add_u64 v[108:109], v[114:115], 0, v[116:117]
	global_load_dwordx4 v[100:103], v[100:101], off
	s_nop 0
	global_load_dwordx4 v[108:111], v[108:109], off
	s_waitcnt vmcnt(0)
; DEV u32x2 pk4(f32x4 v) { u32x2 r = {pk_bf16(v[0], v[1]), pk_bf16(v[2], v[3])}; return r; }
;   DEV void operator()(f32x4 (&acc)[2][2][4][2], int brow, int bcol, int wr, int wc, int fr, int fq) const {
;     ...
; #pragma unroll
;       for (int ai = 0; ai < 2; ++ai)
; #pragma unroll
;         for (int m = 0; m < 4; ++m) {
;           const int rl = ai * 128 + wr * 64 + m * 16 + fr, tok = brow + rl;
;           const int tposl = (rl & ~15) + sig16(rl & 15);
; #pragma unroll
;           for (int bj = 0; bj < 2; ++bj)
; #pragma unroll
;             for (int n = 0; n < 2; ++n) {
;               const int cl = bj * 128 + wc * 32 + n * 16 + fq * 4, lc = bcol - segstart + cl;
;               const f32x4 v = acc[ai][bj][m][n];
;               const f32x4 b4 = *(const f32x4*)(bmat + (size_t)tok * 1024 + lc);
;               const f32x4 bl = *(const f32x4*)(bmat + (size_t)(tok | 63) * 1024 + lc);
;               const u32x2 kk = pk4((f32x4){v[0] * __expf(bl[0] - b4[0]), v[1] * __expf(bl[1] - b4[1]), v[2] * __expf(bl[2] - b4[2]), v[3] * __expf(bl[3] - b4[3])});
; #pragma unroll
;               for (int j = 0; j < 4; ++j) {
;                 const int row = cl + j;
;                 const unsigned short val = (unsigned short)((j & 1) ? (kk[j >> 1] >> 16) : (kk[j >> 1] & 0xffff));
;                 *(unsigned short*)(smem + row * 512 + (((tposl >> 3) ^ (row & 31)) * 16) + (tposl & 7) * 2) = val;
;               }
;             }
	v_sub_f32_e32 v100, v108, v100
	v_sub_f32_e32 v101, v109, v101
	v_mul_f32_e32 v100, 0x3fb8aa3b, v100
	v_mul_f32_e32 v101, 0x3fb8aa3b, v101
	v_exp_f32_e32 v100, v100
	v_exp_f32_e32 v101, v101
	s_nop 0
	v_pk_mul_f32 v[96:97], v[96:97], v[100:101]
	v_sub_f32_e32 v100, v110, v102
	v_sub_f32_e32 v101, v111, v103
	v_mul_f32_e32 v100, 0x3fb8aa3b, v100
	v_mul_f32_e32 v101, 0x3fb8aa3b, v101
	v_exp_f32_e32 v100, v100
	v_exp_f32_e32 v101, v101
	v_cvt_pk_bf16_f32 v96, v96, v97
	v_pk_mul_f32 v[98:99], v[98:99], v[100:101]
	s_nop 0
	v_cvt_pk_bf16_f32 v97, v98, v99
	v_add_u32_e32 v98, v118, v104
	v_add3_u32 v98, v98, v227, v226
	ds_write_b16 v98, v96
	v_add_u32_e32 v98, v119, v105
	v_add3_u32 v98, v98, v227, v226
	ds_write_b16_d16_hi v98, v96
	v_add_u32_e32 v96, v122, v106
	v_add3_u32 v96, v96, v227, v226
	ds_write_b16 v96, v97
	v_add_u32_e32 v96, v123, v107
	v_add3_u32 v96, v96, v227, v226
	ds_write_b16_d16_hi v96, v97
	v_or_b32_e32 v96, 32, v203
	v_or_b32_e32 v97, v96, v202
	v_add_u32_e32 v98, s7, v97
	v_ashrrev_i32_e32 v99, 31, v98
	v_or_b32_e32 v100, v96, v232
	v_lshlrev_b64 v[96:97], 12, v[98:99]
	v_or_b32_e32 v98, 63, v98
	v_ashrrev_i32_e32 v99, 31, v98
	v_lshlrev_b64 v[98:99], 12, v[98:99]
	v_lshl_add_u64 v[96:97], s[0:1], 0, v[96:97]
	v_lshl_add_u64 v[98:99], s[0:1], 0, v[98:99]
	v_ashrrev_i32_e32 v108, 3, v100
	v_lshl_add_u64 v[100:101], v[96:97], 0, v[132:133]
	v_lshl_add_u64 v[104:105], v[98:99], 0, v[132:133]
	global_load_dwordx4 v[100:103], v[100:101], off
	s_nop 0
	global_load_dwordx4 v[104:107], v[104:105], off
	s_waitcnt vmcnt(0)
	v_sub_f32_e32 v100, v104, v100
	v_sub_f32_e32 v101, v105, v101
	v_mul_f32_e32 v100, 0x3fb8aa3b, v100
	v_mul_f32_e32 v101, 0x3fb8aa3b, v101
	v_exp_f32_e32 v100, v100
	v_exp_f32_e32 v101, v101
	v_lshl_add_u64 v[104:105], v[98:99], 0, v[124:125]
	v_pk_mul_f32 v[92:93], v[92:93], v[100:101]
	v_sub_f32_e32 v100, v106, v102
	v_sub_f32_e32 v101, v107, v103
	v_mul_f32_e32 v100, 0x3fb8aa3b, v100
	v_mul_f32_e32 v101, 0x3fb8aa3b, v101
	v_exp_f32_e32 v100, v100
	v_exp_f32_e32 v101, v101
	global_load_dwordx4 v[104:107], v[104:105], off
	v_pk_mul_f32 v[94:95], v[94:95], v[100:101]
	v_cvt_pk_bf16_f32 v100, v92, v93
	v_xor_b32_e32 v92, v108, v201
	v_lshlrev_b32_e32 v92, 4, v92
	v_add_u32_e32 v93, v126, v92
	v_add3_u32 v93, v93, v227, v226
	ds_write_b16 v93, v100
	v_bitop3_b32 v93, v108, v201, 1 bitop3:0x1e
	v_lshlrev_b32_e32 v93, 4, v93
	v_cvt_pk_bf16_f32 v101, v94, v95
	v_add_u32_e32 v94, v126, v93
	v_add3_u32 v94, v94, v227, v226
	ds_write_b16_d16_hi v94, v100 offset:512
	v_bitop3_b32 v94, v108, v201, 2 bitop3:0x1e
	v_lshlrev_b32_e32 v94, 4, v94
	v_add_u32_e32 v95, v126, v94
	v_add3_u32 v95, v95, v227, v226
	ds_write_b16 v95, v101 offset:1024
	v_bitop3_b32 v95, v108, v201, 3 bitop3:0x1e
	v_lshlrev_b32_e32 v95, 4, v95
	v_add_u32_e32 v100, v126, v95
	v_add3_u32 v100, v100, v227, v226
	ds_write_b16_d16_hi v100, v101 offset:1536
	v_lshl_add_u64 v[100:101], v[96:97], 0, v[124:125]
	global_load_dwordx4 v[100:103], v[100:101], off
	s_waitcnt vmcnt(0)
	v_sub_f32_e32 v100, v104, v100
	v_sub_f32_e32 v101, v105, v101
	v_mul_f32_e32 v100, 0x3fb8aa3b, v100
	v_mul_f32_e32 v101, 0x3fb8aa3b, v101
	v_exp_f32_e32 v100, v100
	v_exp_f32_e32 v101, v101
	v_lshl_add_u64 v[104:105], v[98:99], 0, v[120:121]
	v_pk_mul_f32 v[88:89], v[88:89], v[100:101]
	v_sub_f32_e32 v100, v106, v102
	v_sub_f32_e32 v101, v107, v103
	v_mul_f32_e32 v100, 0x3fb8aa3b, v100
	v_mul_f32_e32 v101, 0x3fb8aa3b, v101
	v_exp_f32_e32 v100, v100
	v_exp_f32_e32 v101, v101
	global_load_dwordx4 v[104:107], v[104:105], off
	v_pk_mul_f32 v[90:91], v[90:91], v[100:101]
	v_cvt_pk_bf16_f32 v100, v88, v89
	v_bitop3_b32 v88, v108, v201, 16 bitop3:0x1e
	v_lshlrev_b32_e32 v88, 4, v88
	v_add_u32_e32 v89, v231, v88
	v_add3_u32 v89, v89, v227, v226
	ds_write_b16 v89, v100
	v_bitop3_b32 v89, v108, v201, 17 bitop3:0x1e
	v_lshlrev_b32_e32 v89, 4, v89
	v_cvt_pk_bf16_f32 v101, v90, v91
	v_add_u32_e32 v90, v126, v89
	v_add3_u32 v90, v90, v227, v226
	ds_write_b16_d16_hi v90, v100 offset:8704
	v_bitop3_b32 v90, v108, v201, 18 bitop3:0x1e
	v_lshlrev_b32_e32 v90, 4, v90
	v_add_u32_e32 v91, v126, v90
	v_add3_u32 v91, v91, v227, v226
	ds_write_b16 v91, v101 offset:9216
	v_bitop3_b32 v91, v108, v201, 19 bitop3:0x1e
	v_lshlrev_b32_e32 v91, 4, v91
	v_add_u32_e32 v100, v126, v91
	v_add3_u32 v100, v100, v227, v226
	ds_write_b16_d16_hi v100, v101 offset:9728
	v_lshl_add_u64 v[100:101], v[96:97], 0, v[120:121]
	global_load_dwordx4 v[100:103], v[100:101], off
	s_waitcnt vmcnt(0)
	v_sub_f32_e32 v100, v104, v100
	v_sub_f32_e32 v101, v105, v101
	v_mul_f32_e32 v100, 0x3fb8aa3b, v100
	v_mul_f32_e32 v101, 0x3fb8aa3b, v101
	v_exp_f32_e32 v100, v100
	v_exp_f32_e32 v101, v101
	s_nop 0
	v_pk_mul_f32 v[84:85], v[84:85], v[100:101]
	v_sub_f32_e32 v100, v106, v102
	v_sub_f32_e32 v101, v107, v103
	v_mul_f32_e32 v100, 0x3fb8aa3b, v100
	v_mul_f32_e32 v101, 0x3fb8aa3b, v101
	v_exp_f32_e32 v100, v100
	v_exp_f32_e32 v101, v101
	v_cvt_pk_bf16_f32 v84, v84, v85
	v_pk_mul_f32 v[86:87], v[86:87], v[100:101]
	s_nop 0
	v_cvt_pk_bf16_f32 v85, v86, v87
	v_add_u32_e32 v86, v127, v92
	v_add3_u32 v86, v86, v227, v226
	ds_write_b16 v86, v84
	v_add_u32_e32 v86, v228, v93
	v_add3_u32 v86, v86, v227, v226
	ds_write_b16_d16_hi v86, v84
	v_add_u32_e32 v84, v229, v94
	v_add3_u32 v84, v84, v227, v226
	ds_write_b16 v84, v85
	v_add_u32_e32 v84, v230, v95
	v_add3_u32 v84, v84, v227, v226
	ds_write_b16_d16_hi v84, v85
	v_lshl_add_u64 v[84:85], v[96:97], 0, v[116:117]
	v_lshl_add_u64 v[92:93], v[98:99], 0, v[116:117]
	global_load_dwordx4 v[84:87], v[84:85], off
	s_nop 0
	global_load_dwordx4 v[92:95], v[92:93], off
	s_waitcnt vmcnt(0)
; DEV u32x2 pk4(f32x4 v) { u32x2 r = {pk_bf16(v[0], v[1]), pk_bf16(v[2], v[3])}; return r; }
;   DEV void operator()(f32x4 (&acc)[2][2][4][2], int brow, int bcol, int wr, int wc, int fr, int fq) const {
;     ...
; #pragma unroll
;       for (int ai = 0; ai < 2; ++ai)
; #pragma unroll
;         for (int m = 0; m < 4; ++m) {
;           const int rl = ai * 128 + wr * 64 + m * 16 + fr, tok = brow + rl;
;           const int tposl = (rl & ~15) + sig16(rl & 15);
; #pragma unroll
;           for (int bj = 0; bj < 2; ++bj)
; #pragma unroll
;             for (int n = 0; n < 2; ++n) {
;               const int cl = bj * 128 + wc * 32 + n * 16 + fq * 4, lc = bcol - segstart + cl;
;               const f32x4 v = acc[ai][bj][m][n];
;               const f32x4 b4 = *(const f32x4*)(bmat + (size_t)tok * 1024 + lc);
;               const f32x4 bl = *(const f32x4*)(bmat + (size_t)(tok | 63) * 1024 + lc);
;               const u32x2 kk = pk4((f32x4){v[0] * __expf(bl[0] - b4[0]), v[1] * __expf(bl[1] - b4[1]), v[2] * __expf(bl[2] - b4[2]), v[3] * __expf(bl[3] - b4[3])});
; #pragma unroll
;               for (int j = 0; j < 4; ++j) {
;                 const int row = cl + j;
;                 const unsigned short val = (unsigned short)((j & 1) ? (kk[j >> 1] >> 16) : (kk[j >> 1] & 0xffff));
;                 *(unsigned short*)(smem + row * 512 + (((tposl >> 3) ^ (row & 31)) * 16) + (tposl & 7) * 2) = val;
;               }
;             }
	v_sub_f32_e32 v84, v92, v84
	v_sub_f32_e32 v85, v93, v85
	v_mul_f32_e32 v84, 0x3fb8aa3b, v84
	v_mul_f32_e32 v85, 0x3fb8aa3b, v85
	v_exp_f32_e32 v84, v84
	v_exp_f32_e32 v85, v85
	s_nop 0
	v_pk_mul_f32 v[80:81], v[80:81], v[84:85]
	v_sub_f32_e32 v84, v94, v86
	v_sub_f32_e32 v85, v95, v87
	v_mul_f32_e32 v84, 0x3fb8aa3b, v84
	v_mul_f32_e32 v85, 0x3fb8aa3b, v85
	v_exp_f32_e32 v84, v84
	v_exp_f32_e32 v85, v85
	v_cvt_pk_bf16_f32 v80, v80, v81
	v_pk_mul_f32 v[82:83], v[82:83], v[84:85]
	s_nop 0
	v_cvt_pk_bf16_f32 v81, v82, v83
	v_add_u32_e32 v82, v118, v88
	v_add3_u32 v82, v82, v227, v226
	ds_write_b16 v82, v80
	v_add_u32_e32 v82, v119, v89
	v_add3_u32 v82, v82, v227, v226
	ds_write_b16_d16_hi v82, v80
	v_add_u32_e32 v80, v122, v90
	v_add3_u32 v80, v80, v227, v226
	ds_write_b16 v80, v81
	v_add_u32_e32 v80, v123, v91
	v_add3_u32 v80, v80, v227, v226
	ds_write_b16_d16_hi v80, v81
	v_or_b32_e32 v80, 48, v203
	v_or_b32_e32 v81, v80, v202
	v_add_u32_e32 v82, s7, v81
	v_ashrrev_i32_e32 v83, 31, v82
	v_or_b32_e32 v84, v80, v232
	v_lshlrev_b64 v[80:81], 12, v[82:83]
	v_or_b32_e32 v82, 63, v82
	v_ashrrev_i32_e32 v83, 31, v82
	v_lshlrev_b64 v[82:83], 12, v[82:83]
	v_lshl_add_u64 v[80:81], s[0:1], 0, v[80:81]
	v_lshl_add_u64 v[82:83], s[0:1], 0, v[82:83]
	v_ashrrev_i32_e32 v92, 3, v84
	v_lshl_add_u64 v[84:85], v[80:81], 0, v[132:133]
	v_lshl_add_u64 v[88:89], v[82:83], 0, v[132:133]
	global_load_dwordx4 v[84:87], v[84:85], off
	s_nop 0
	global_load_dwordx4 v[88:91], v[88:89], off
	s_waitcnt vmcnt(0)
	v_sub_f32_e32 v84, v88, v84
	v_sub_f32_e32 v85, v89, v85
	v_mul_f32_e32 v84, 0x3fb8aa3b, v84
	v_mul_f32_e32 v85, 0x3fb8aa3b, v85
	v_exp_f32_e32 v84, v84
	v_exp_f32_e32 v85, v85
	v_lshl_add_u64 v[88:89], v[82:83], 0, v[124:125]
	v_pk_mul_f32 v[76:77], v[76:77], v[84:85]
	v_sub_f32_e32 v84, v90, v86
	v_sub_f32_e32 v85, v91, v87
	v_mul_f32_e32 v84, 0x3fb8aa3b, v84
	v_mul_f32_e32 v85, 0x3fb8aa3b, v85
	v_exp_f32_e32 v84, v84
	v_exp_f32_e32 v85, v85
	global_load_dwordx4 v[88:91], v[88:89], off
	v_pk_mul_f32 v[78:79], v[78:79], v[84:85]
	v_cvt_pk_bf16_f32 v84, v76, v77
	v_xor_b32_e32 v76, v92, v201
	v_lshlrev_b32_e32 v76, 4, v76
	v_add_u32_e32 v77, v126, v76
	v_add3_u32 v77, v77, v227, v226
	ds_write_b16 v77, v84
	v_bitop3_b32 v77, v92, v201, 1 bitop3:0x1e
	v_lshlrev_b32_e32 v77, 4, v77
	v_cvt_pk_bf16_f32 v85, v78, v79
	v_add_u32_e32 v78, v126, v77
	v_add3_u32 v78, v78, v227, v226
	ds_write_b16_d16_hi v78, v84 offset:512
	v_bitop3_b32 v78, v92, v201, 2 bitop3:0x1e
	v_lshlrev_b32_e32 v78, 4, v78
	v_add_u32_e32 v79, v126, v78
	v_add3_u32 v79, v79, v227, v226
	ds_write_b16 v79, v85 offset:1024
	v_bitop3_b32 v79, v92, v201, 3 bitop3:0x1e
	v_lshlrev_b32_e32 v79, 4, v79
	v_add_u32_e32 v84, v126, v79
	v_add3_u32 v84, v84, v227, v226
	ds_write_b16_d16_hi v84, v85 offset:1536
	v_lshl_add_u64 v[84:85], v[80:81], 0, v[124:125]
	global_load_dwordx4 v[84:87], v[84:85], off
	s_waitcnt vmcnt(0)
	v_sub_f32_e32 v84, v88, v84
	v_sub_f32_e32 v85, v89, v85
	v_mul_f32_e32 v84, 0x3fb8aa3b, v84
	v_mul_f32_e32 v85, 0x3fb8aa3b, v85
	v_exp_f32_e32 v84, v84
	v_exp_f32_e32 v85, v85
	v_lshl_add_u64 v[88:89], v[82:83], 0, v[120:121]
	v_pk_mul_f32 v[72:73], v[72:73], v[84:85]
	v_sub_f32_e32 v84, v90, v86
	v_sub_f32_e32 v85, v91, v87
	v_mul_f32_e32 v84, 0x3fb8aa3b, v84
	v_mul_f32_e32 v85, 0x3fb8aa3b, v85
	v_exp_f32_e32 v84, v84
	v_exp_f32_e32 v85, v85
	global_load_dwordx4 v[88:91], v[88:89], off
	v_pk_mul_f32 v[74:75], v[74:75], v[84:85]
	v_cvt_pk_bf16_f32 v84, v72, v73
	v_bitop3_b32 v72, v92, v201, 16 bitop3:0x1e
	v_lshlrev_b32_e32 v72, 4, v72
	v_add_u32_e32 v73, v231, v72
	v_add3_u32 v73, v73, v227, v226
	ds_write_b16 v73, v84
	v_bitop3_b32 v73, v92, v201, 17 bitop3:0x1e
	v_lshlrev_b32_e32 v73, 4, v73
	v_cvt_pk_bf16_f32 v85, v74, v75
	v_add_u32_e32 v74, v126, v73
	v_add3_u32 v74, v74, v227, v226
	ds_write_b16_d16_hi v74, v84 offset:8704
	v_bitop3_b32 v74, v92, v201, 18 bitop3:0x1e
	v_lshlrev_b32_e32 v74, 4, v74
	v_add_u32_e32 v75, v126, v74
	v_add3_u32 v75, v75, v227, v226
	ds_write_b16 v75, v85 offset:9216
	v_bitop3_b32 v75, v92, v201, 19 bitop3:0x1e
	v_lshlrev_b32_e32 v75, 4, v75
	v_add_u32_e32 v84, v126, v75
	v_add3_u32 v84, v84, v227, v226
	ds_write_b16_d16_hi v84, v85 offset:9728
	v_lshl_add_u64 v[84:85], v[80:81], 0, v[120:121]
	global_load_dwordx4 v[84:87], v[84:85], off
	s_waitcnt vmcnt(0)
	v_sub_f32_e32 v84, v88, v84
	v_sub_f32_e32 v85, v89, v85
	v_mul_f32_e32 v84, 0x3fb8aa3b, v84
	v_mul_f32_e32 v85, 0x3fb8aa3b, v85
	v_exp_f32_e32 v84, v84
	v_exp_f32_e32 v85, v85
	s_nop 0
	v_pk_mul_f32 v[68:69], v[68:69], v[84:85]
	v_sub_f32_e32 v84, v90, v86
	v_sub_f32_e32 v85, v91, v87
	v_mul_f32_e32 v84, 0x3fb8aa3b, v84
	v_mul_f32_e32 v85, 0x3fb8aa3b, v85
	v_exp_f32_e32 v84, v84
	v_exp_f32_e32 v85, v85
	v_cvt_pk_bf16_f32 v68, v68, v69
	v_pk_mul_f32 v[70:71], v[70:71], v[84:85]
	s_nop 0
	v_cvt_pk_bf16_f32 v69, v70, v71
	v_add_u32_e32 v70, v127, v76
	v_add3_u32 v70, v70, v227, v226
	ds_write_b16 v70, v68
	v_add_u32_e32 v70, v228, v77
	v_add3_u32 v70, v70, v227, v226
	ds_write_b16_d16_hi v70, v68
	v_add_u32_e32 v68, v229, v78
	v_add3_u32 v68, v68, v227, v226
	ds_write_b16 v68, v69
	v_add_u32_e32 v68, v230, v79
	v_add3_u32 v68, v68, v227, v226
	ds_write_b16_d16_hi v68, v69
	v_lshl_add_u64 v[68:69], v[80:81], 0, v[116:117]
	v_lshl_add_u64 v[76:77], v[82:83], 0, v[116:117]
	global_load_dwordx4 v[68:71], v[68:69], off
	s_nop 0
	global_load_dwordx4 v[76:79], v[76:77], off
	s_waitcnt vmcnt(0)
; DEV u32x2 pk4(f32x4 v) { u32x2 r = {pk_bf16(v[0], v[1]), pk_bf16(v[2], v[3])}; return r; }
;   DEV void operator()(f32x4 (&acc)[2][2][4][2], int brow, int bcol, int wr, int wc, int fr, int fq) const {
;     ...
; #pragma unroll
;       for (int ai = 0; ai < 2; ++ai)
; #pragma unroll
;         for (int m = 0; m < 4; ++m) {
;           const int rl = ai * 128 + wr * 64 + m * 16 + fr, tok = brow + rl;
;           const int tposl = (rl & ~15) + sig16(rl & 15);
; #pragma unroll
;           for (int bj = 0; bj < 2; ++bj)
; #pragma unroll
;             for (int n = 0; n < 2; ++n) {
;               const int cl = bj * 128 + wc * 32 + n * 16 + fq * 4, lc = bcol - segstart + cl;
;               const f32x4 v = acc[ai][bj][m][n];
;               const f32x4 b4 = *(const f32x4*)(bmat + (size_t)tok * 1024 + lc);
;               const f32x4 bl = *(const f32x4*)(bmat + (size_t)(tok | 63) * 1024 + lc);
;               const u32x2 kk = pk4((f32x4){v[0] * __expf(bl[0] - b4[0]), v[1] * __expf(bl[1] - b4[1]), v[2] * __expf(bl[2] - b4[2]), v[3] * __expf(bl[3] - b4[3])});
; #pragma unroll
;               for (int j = 0; j < 4; ++j) {
;                 const int row = cl + j;
;                 const unsigned short val = (unsigned short)((j & 1) ? (kk[j >> 1] >> 16) : (kk[j >> 1] & 0xffff));
;                 *(unsigned short*)(smem + row * 512 + (((tposl >> 3) ^ (row & 31)) * 16) + (tposl & 7) * 2) = val;
;               }
;             }
	v_sub_f32_e32 v68, v76, v68
	v_sub_f32_e32 v69, v77, v69
	v_mul_f32_e32 v68, 0x3fb8aa3b, v68
	v_mul_f32_e32 v69, 0x3fb8aa3b, v69
	v_exp_f32_e32 v68, v68
	v_exp_f32_e32 v69, v69
	s_nop 0
	v_pk_mul_f32 v[64:65], v[64:65], v[68:69]
	v_sub_f32_e32 v68, v78, v70
	v_sub_f32_e32 v69, v79, v71
	v_mul_f32_e32 v68, 0x3fb8aa3b, v68
	v_mul_f32_e32 v69, 0x3fb8aa3b, v69
	v_exp_f32_e32 v68, v68
	v_exp_f32_e32 v69, v69
	v_cvt_pk_bf16_f32 v64, v64, v65
	v_pk_mul_f32 v[66:67], v[66:67], v[68:69]
	s_nop 0
	v_cvt_pk_bf16_f32 v65, v66, v67
	v_add_u32_e32 v66, v118, v72
	v_add3_u32 v66, v66, v227, v226
	ds_write_b16 v66, v64
	v_add_u32_e32 v66, v119, v73
	v_add3_u32 v66, v66, v227, v226
	ds_write_b16_d16_hi v66, v64
	v_add_u32_e32 v64, v122, v74
	v_add3_u32 v64, v64, v227, v226
	ds_write_b16 v64, v65
	v_add_u32_e32 v64, v123, v75
	v_add3_u32 v64, v64, v227, v226
	ds_write_b16_d16_hi v64, v65
	v_add_u32_e32 v64, 0x80, v203
	v_or_b32_e32 v65, v64, v202
	v_add_u32_e32 v66, s7, v65
	v_ashrrev_i32_e32 v67, 31, v66
	v_or_b32_e32 v68, v64, v232
	v_lshlrev_b64 v[64:65], 12, v[66:67]
	v_or_b32_e32 v66, 63, v66
	v_ashrrev_i32_e32 v67, 31, v66
	v_lshlrev_b64 v[66:67], 12, v[66:67]
	v_lshl_add_u64 v[64:65], s[0:1], 0, v[64:65]
	v_lshl_add_u64 v[66:67], s[0:1], 0, v[66:67]
	v_ashrrev_i32_e32 v76, 3, v68
	v_lshl_add_u64 v[68:69], v[64:65], 0, v[132:133]
	v_lshl_add_u64 v[72:73], v[66:67], 0, v[132:133]
	global_load_dwordx4 v[68:71], v[68:69], off
	s_nop 0
	global_load_dwordx4 v[72:75], v[72:73], off
	s_waitcnt vmcnt(0)
	v_sub_f32_e32 v68, v72, v68
	v_sub_f32_e32 v69, v73, v69
	v_mul_f32_e32 v68, 0x3fb8aa3b, v68
	v_mul_f32_e32 v69, 0x3fb8aa3b, v69
	v_exp_f32_e32 v68, v68
	v_exp_f32_e32 v69, v69
	v_lshl_add_u64 v[72:73], v[66:67], 0, v[124:125]
	v_pk_mul_f32 v[60:61], v[60:61], v[68:69]
	v_sub_f32_e32 v68, v74, v70
	v_sub_f32_e32 v69, v75, v71
	v_mul_f32_e32 v68, 0x3fb8aa3b, v68
	v_mul_f32_e32 v69, 0x3fb8aa3b, v69
	v_exp_f32_e32 v68, v68
	v_exp_f32_e32 v69, v69
	global_load_dwordx4 v[72:75], v[72:73], off
	v_pk_mul_f32 v[62:63], v[62:63], v[68:69]
	v_cvt_pk_bf16_f32 v68, v60, v61
	v_xor_b32_e32 v60, v76, v201
	v_lshlrev_b32_e32 v60, 4, v60
	v_add_u32_e32 v61, v126, v60
	v_add3_u32 v61, v61, v227, v226
	ds_write_b16 v61, v68
	v_bitop3_b32 v61, v76, v201, 1 bitop3:0x1e
	v_lshlrev_b32_e32 v61, 4, v61
	v_cvt_pk_bf16_f32 v69, v62, v63
	v_add_u32_e32 v62, v126, v61
	v_add3_u32 v62, v62, v227, v226
	ds_write_b16_d16_hi v62, v68 offset:512
	v_bitop3_b32 v62, v76, v201, 2 bitop3:0x1e
	v_lshlrev_b32_e32 v62, 4, v62
	v_add_u32_e32 v63, v126, v62
	v_add3_u32 v63, v63, v227, v226
	ds_write_b16 v63, v69 offset:1024
	v_bitop3_b32 v63, v76, v201, 3 bitop3:0x1e
	v_lshlrev_b32_e32 v63, 4, v63
	v_add_u32_e32 v68, v126, v63
	v_add3_u32 v68, v68, v227, v226
	ds_write_b16_d16_hi v68, v69 offset:1536
	v_lshl_add_u64 v[68:69], v[64:65], 0, v[124:125]
	global_load_dwordx4 v[68:71], v[68:69], off
	s_waitcnt vmcnt(0)
	v_sub_f32_e32 v68, v72, v68
	v_sub_f32_e32 v69, v73, v69
	v_mul_f32_e32 v68, 0x3fb8aa3b, v68
	v_mul_f32_e32 v69, 0x3fb8aa3b, v69
	v_exp_f32_e32 v68, v68
	v_exp_f32_e32 v69, v69
	v_lshl_add_u64 v[72:73], v[66:67], 0, v[120:121]
	v_pk_mul_f32 v[56:57], v[56:57], v[68:69]
	v_sub_f32_e32 v68, v74, v70
	v_sub_f32_e32 v69, v75, v71
	v_mul_f32_e32 v68, 0x3fb8aa3b, v68
	v_mul_f32_e32 v69, 0x3fb8aa3b, v69
	v_exp_f32_e32 v68, v68
	v_exp_f32_e32 v69, v69
	global_load_dwordx4 v[72:75], v[72:73], off
	v_pk_mul_f32 v[58:59], v[58:59], v[68:69]
	v_cvt_pk_bf16_f32 v68, v56, v57
	v_bitop3_b32 v56, v76, v201, 16 bitop3:0x1e
	v_lshlrev_b32_e32 v56, 4, v56
	v_add_u32_e32 v57, v231, v56
	v_add3_u32 v57, v57, v227, v226
	ds_write_b16 v57, v68
	v_bitop3_b32 v57, v76, v201, 17 bitop3:0x1e
	v_lshlrev_b32_e32 v57, 4, v57
	v_cvt_pk_bf16_f32 v69, v58, v59
	v_add_u32_e32 v58, v126, v57
	v_add3_u32 v58, v58, v227, v226
	ds_write_b16_d16_hi v58, v68 offset:8704
	v_bitop3_b32 v58, v76, v201, 18 bitop3:0x1e
	v_lshlrev_b32_e32 v58, 4, v58
	v_add_u32_e32 v59, v126, v58
	v_add3_u32 v59, v59, v227, v226
	ds_write_b16 v59, v69 offset:9216
	v_bitop3_b32 v59, v76, v201, 19 bitop3:0x1e
	v_lshlrev_b32_e32 v59, 4, v59
	v_add_u32_e32 v68, v126, v59
	v_add3_u32 v68, v68, v227, v226
	ds_write_b16_d16_hi v68, v69 offset:9728
	v_lshl_add_u64 v[68:69], v[64:65], 0, v[120:121]
	global_load_dwordx4 v[68:71], v[68:69], off
	s_waitcnt vmcnt(0)
	v_sub_f32_e32 v68, v72, v68
	v_sub_f32_e32 v69, v73, v69
	v_mul_f32_e32 v68, 0x3fb8aa3b, v68
	v_mul_f32_e32 v69, 0x3fb8aa3b, v69
	v_exp_f32_e32 v68, v68
	v_exp_f32_e32 v69, v69
	s_nop 0
	v_pk_mul_f32 v[52:53], v[52:53], v[68:69]
	v_sub_f32_e32 v68, v74, v70
	v_sub_f32_e32 v69, v75, v71
	v_mul_f32_e32 v68, 0x3fb8aa3b, v68
	v_mul_f32_e32 v69, 0x3fb8aa3b, v69
	v_exp_f32_e32 v68, v68
	v_exp_f32_e32 v69, v69
	v_cvt_pk_bf16_f32 v52, v52, v53
	v_pk_mul_f32 v[54:55], v[54:55], v[68:69]
	s_nop 0
	v_cvt_pk_bf16_f32 v53, v54, v55
	v_add_u32_e32 v54, v127, v60
	v_add3_u32 v54, v54, v227, v226
	ds_write_b16 v54, v52
	v_add_u32_e32 v54, v228, v61
	v_add3_u32 v54, v54, v227, v226
	ds_write_b16_d16_hi v54, v52
	v_add_u32_e32 v52, v229, v62
	v_add3_u32 v52, v52, v227, v226
	ds_write_b16 v52, v53
	v_add_u32_e32 v52, v230, v63
	v_add3_u32 v52, v52, v227, v226
	ds_write_b16_d16_hi v52, v53
	v_lshl_add_u64 v[52:53], v[64:65], 0, v[116:117]
	v_lshl_add_u64 v[60:61], v[66:67], 0, v[116:117]
	global_load_dwordx4 v[52:55], v[52:53], off
	s_nop 0
	global_load_dwordx4 v[60:63], v[60:61], off
	s_waitcnt vmcnt(0)
; DEV u32x2 pk4(f32x4 v) { u32x2 r = {pk_bf16(v[0], v[1]), pk_bf16(v[2], v[3])}; return r; }
;   DEV void operator()(f32x4 (&acc)[2][2][4][2], int brow, int bcol, int wr, int wc, int fr, int fq) const {
;     ...
; #pragma unroll
;       for (int ai = 0; ai < 2; ++ai)
; #pragma unroll
;         for (int m = 0; m < 4; ++m) {
;           const int rl = ai * 128 + wr * 64 + m * 16 + fr, tok = brow + rl;
;           const int tposl = (rl & ~15) + sig16(rl & 15);
; #pragma unroll
;           for (int bj = 0; bj < 2; ++bj)
; #pragma unroll
;             for (int n = 0; n < 2; ++n) {
;               const int cl = bj * 128 + wc * 32 + n * 16 + fq * 4, lc = bcol - segstart + cl;
;               const f32x4 v = acc[ai][bj][m][n];
;               const f32x4 b4 = *(const f32x4*)(bmat + (size_t)tok * 1024 + lc);
;               const f32x4 bl = *(const f32x4*)(bmat + (size_t)(tok | 63) * 1024 + lc);
;               const u32x2 kk = pk4((f32x4){v[0] * __expf(bl[0] - b4[0]), v[1] * __expf(bl[1] - b4[1]), v[2] * __expf(bl[2] - b4[2]), v[3] * __expf(bl[3] - b4[3])});
; #pragma unroll
;               for (int j = 0; j < 4; ++j) {
;                 const int row = cl + j;
;                 const unsigned short val = (unsigned short)((j & 1) ? (kk[j >> 1] >> 16) : (kk[j >> 1] & 0xffff));
;                 *(unsigned short*)(smem + row * 512 + (((tposl >> 3) ^ (row & 31)) * 16) + (tposl & 7) * 2) = val;
;               }
;             }
	v_sub_f32_e32 v52, v60, v52
	v_sub_f32_e32 v53, v61, v53
	v_mul_f32_e32 v52, 0x3fb8aa3b, v52
	v_mul_f32_e32 v53, 0x3fb8aa3b, v53
	v_exp_f32_e32 v52, v52
	v_exp_f32_e32 v53, v53
	s_nop 0
	v_pk_mul_f32 v[48:49], v[48:49], v[52:53]
	v_sub_f32_e32 v52, v62, v54
	v_sub_f32_e32 v53, v63, v55
	v_mul_f32_e32 v52, 0x3fb8aa3b, v52
	v_mul_f32_e32 v53, 0x3fb8aa3b, v53
	v_exp_f32_e32 v52, v52
	v_exp_f32_e32 v53, v53
	v_cvt_pk_bf16_f32 v48, v48, v49
	v_pk_mul_f32 v[50:51], v[50:51], v[52:53]
	s_nop 0
	v_cvt_pk_bf16_f32 v49, v50, v51
	v_add_u32_e32 v50, v118, v56
	v_add3_u32 v50, v50, v227, v226
	ds_write_b16 v50, v48
	v_add_u32_e32 v50, v119, v57
	v_add3_u32 v50, v50, v227, v226
	ds_write_b16_d16_hi v50, v48
	v_add_u32_e32 v48, v122, v58
	v_add3_u32 v48, v48, v227, v226
	ds_write_b16 v48, v49
	v_add_u32_e32 v48, v123, v59
	v_add3_u32 v48, v48, v227, v226
	ds_write_b16_d16_hi v48, v49
	v_add_u32_e32 v48, 0x90, v203
	v_or_b32_e32 v49, v48, v202
	v_add_u32_e32 v50, s7, v49
	v_ashrrev_i32_e32 v51, 31, v50
	v_or_b32_e32 v52, v48, v232
	v_lshlrev_b64 v[48:49], 12, v[50:51]
	v_or_b32_e32 v50, 63, v50
	v_ashrrev_i32_e32 v51, 31, v50
	v_lshlrev_b64 v[50:51], 12, v[50:51]
	v_lshl_add_u64 v[48:49], s[0:1], 0, v[48:49]
	v_lshl_add_u64 v[50:51], s[0:1], 0, v[50:51]
	v_ashrrev_i32_e32 v60, 3, v52
	v_lshl_add_u64 v[52:53], v[48:49], 0, v[132:133]
	v_lshl_add_u64 v[56:57], v[50:51], 0, v[132:133]
	global_load_dwordx4 v[52:55], v[52:53], off
	s_nop 0
	global_load_dwordx4 v[56:59], v[56:57], off
	s_waitcnt vmcnt(0)
	v_sub_f32_e32 v52, v56, v52
	v_sub_f32_e32 v53, v57, v53
	v_mul_f32_e32 v52, 0x3fb8aa3b, v52
	v_mul_f32_e32 v53, 0x3fb8aa3b, v53
	v_exp_f32_e32 v52, v52
	v_exp_f32_e32 v53, v53
	v_lshl_add_u64 v[56:57], v[50:51], 0, v[124:125]
	v_pk_mul_f32 v[44:45], v[44:45], v[52:53]
	v_sub_f32_e32 v52, v58, v54
	v_sub_f32_e32 v53, v59, v55
	v_mul_f32_e32 v52, 0x3fb8aa3b, v52
	v_mul_f32_e32 v53, 0x3fb8aa3b, v53
	v_exp_f32_e32 v52, v52
	v_exp_f32_e32 v53, v53
	global_load_dwordx4 v[56:59], v[56:57], off
	v_pk_mul_f32 v[46:47], v[46:47], v[52:53]
	v_cvt_pk_bf16_f32 v52, v44, v45
	v_xor_b32_e32 v44, v60, v201
	v_lshlrev_b32_e32 v44, 4, v44
	v_add_u32_e32 v45, v126, v44
	v_add3_u32 v45, v45, v227, v226
	ds_write_b16 v45, v52
	v_bitop3_b32 v45, v60, v201, 1 bitop3:0x1e
	v_lshlrev_b32_e32 v45, 4, v45
	v_cvt_pk_bf16_f32 v53, v46, v47
	v_add_u32_e32 v46, v126, v45
	v_add3_u32 v46, v46, v227, v226
	ds_write_b16_d16_hi v46, v52 offset:512
	v_bitop3_b32 v46, v60, v201, 2 bitop3:0x1e
	v_lshlrev_b32_e32 v46, 4, v46
	v_add_u32_e32 v47, v126, v46
	v_add3_u32 v47, v47, v227, v226
	ds_write_b16 v47, v53 offset:1024
	v_bitop3_b32 v47, v60, v201, 3 bitop3:0x1e
	v_lshlrev_b32_e32 v47, 4, v47
	v_add_u32_e32 v52, v126, v47
	v_add3_u32 v52, v52, v227, v226
	ds_write_b16_d16_hi v52, v53 offset:1536
	v_lshl_add_u64 v[52:53], v[48:49], 0, v[124:125]
	global_load_dwordx4 v[52:55], v[52:53], off
	s_waitcnt vmcnt(0)
	v_sub_f32_e32 v52, v56, v52
	v_sub_f32_e32 v53, v57, v53
	v_mul_f32_e32 v52, 0x3fb8aa3b, v52
	v_mul_f32_e32 v53, 0x3fb8aa3b, v53
	v_exp_f32_e32 v52, v52
	v_exp_f32_e32 v53, v53
	v_lshl_add_u64 v[56:57], v[50:51], 0, v[120:121]
	v_pk_mul_f32 v[40:41], v[40:41], v[52:53]
	v_sub_f32_e32 v52, v58, v54
	v_sub_f32_e32 v53, v59, v55
	v_mul_f32_e32 v52, 0x3fb8aa3b, v52
	v_mul_f32_e32 v53, 0x3fb8aa3b, v53
	v_exp_f32_e32 v52, v52
	v_exp_f32_e32 v53, v53
	global_load_dwordx4 v[56:59], v[56:57], off
	v_pk_mul_f32 v[42:43], v[42:43], v[52:53]
	v_cvt_pk_bf16_f32 v52, v40, v41
	v_bitop3_b32 v40, v60, v201, 16 bitop3:0x1e
	v_lshlrev_b32_e32 v40, 4, v40
	v_add_u32_e32 v41, v231, v40
	v_add3_u32 v41, v41, v227, v226
	ds_write_b16 v41, v52
	v_bitop3_b32 v41, v60, v201, 17 bitop3:0x1e
	v_lshlrev_b32_e32 v41, 4, v41
	v_cvt_pk_bf16_f32 v53, v42, v43
	v_add_u32_e32 v42, v126, v41
	v_add3_u32 v42, v42, v227, v226
	ds_write_b16_d16_hi v42, v52 offset:8704
	v_bitop3_b32 v42, v60, v201, 18 bitop3:0x1e
	v_lshlrev_b32_e32 v42, 4, v42
	v_add_u32_e32 v43, v126, v42
	v_add3_u32 v43, v43, v227, v226
	ds_write_b16 v43, v53 offset:9216
	v_bitop3_b32 v43, v60, v201, 19 bitop3:0x1e
	v_lshlrev_b32_e32 v43, 4, v43
	v_add_u32_e32 v52, v126, v43
	v_add3_u32 v52, v52, v227, v226
	ds_write_b16_d16_hi v52, v53 offset:9728
	v_lshl_add_u64 v[52:53], v[48:49], 0, v[120:121]
	global_load_dwordx4 v[52:55], v[52:53], off
	s_waitcnt vmcnt(0)
	v_sub_f32_e32 v52, v56, v52
	v_sub_f32_e32 v53, v57, v53
	v_mul_f32_e32 v52, 0x3fb8aa3b, v52
	v_mul_f32_e32 v53, 0x3fb8aa3b, v53
	v_exp_f32_e32 v52, v52
	v_exp_f32_e32 v53, v53
	s_nop 0
	v_pk_mul_f32 v[36:37], v[36:37], v[52:53]
	v_sub_f32_e32 v52, v58, v54
	v_sub_f32_e32 v53, v59, v55
	v_mul_f32_e32 v52, 0x3fb8aa3b, v52
	v_mul_f32_e32 v53, 0x3fb8aa3b, v53
	v_exp_f32_e32 v52, v52
	v_exp_f32_e32 v53, v53
	v_cvt_pk_bf16_f32 v36, v36, v37
	v_pk_mul_f32 v[38:39], v[38:39], v[52:53]
	s_nop 0
	v_cvt_pk_bf16_f32 v37, v38, v39
	v_add_u32_e32 v38, v127, v44
	v_add3_u32 v38, v38, v227, v226
	ds_write_b16 v38, v36
	v_add_u32_e32 v38, v228, v45
	v_add3_u32 v38, v38, v227, v226
	ds_write_b16_d16_hi v38, v36
	v_add_u32_e32 v36, v229, v46
	v_add3_u32 v36, v36, v227, v226
	ds_write_b16 v36, v37
	v_add_u32_e32 v36, v230, v47
	v_add3_u32 v36, v36, v227, v226
	ds_write_b16_d16_hi v36, v37
	v_lshl_add_u64 v[36:37], v[48:49], 0, v[116:117]
	v_lshl_add_u64 v[44:45], v[50:51], 0, v[116:117]
	global_load_dwordx4 v[36:39], v[36:37], off
	s_nop 0
	global_load_dwordx4 v[44:47], v[44:45], off
	s_waitcnt vmcnt(0)
; DEV u32x2 pk4(f32x4 v) { u32x2 r = {pk_bf16(v[0], v[1]), pk_bf16(v[2], v[3])}; return r; }
;   DEV void operator()(f32x4 (&acc)[2][2][4][2], int brow, int bcol, int wr, int wc, int fr, int fq) const {
;     ...
; #pragma unroll
;       for (int ai = 0; ai < 2; ++ai)
; #pragma unroll
;         for (int m = 0; m < 4; ++m) {
;           const int rl = ai * 128 + wr * 64 + m * 16 + fr, tok = brow + rl;
;           const int tposl = (rl & ~15) + sig16(rl & 15);
; #pragma unroll
;           for (int bj = 0; bj < 2; ++bj)
; #pragma unroll
;             for (int n = 0; n < 2; ++n) {
;               const int cl = bj * 128 + wc * 32 + n * 16 + fq * 4, lc = bcol - segstart + cl;
;               const f32x4 v = acc[ai][bj][m][n];
;               const f32x4 b4 = *(const f32x4*)(bmat + (size_t)tok * 1024 + lc);
;               const f32x4 bl = *(const f32x4*)(bmat + (size_t)(tok | 63) * 1024 + lc);
;               const u32x2 kk = pk4((f32x4){v[0] * __expf(bl[0] - b4[0]), v[1] * __expf(bl[1] - b4[1]), v[2] * __expf(bl[2] - b4[2]), v[3] * __expf(bl[3] - b4[3])});
; #pragma unroll
;               for (int j = 0; j < 4; ++j) {
;                 const int row = cl + j;
;                 const unsigned short val = (unsigned short)((j & 1) ? (kk[j >> 1] >> 16) : (kk[j >> 1] & 0xffff));
;                 *(unsigned short*)(smem + row * 512 + (((tposl >> 3) ^ (row & 31)) * 16) + (tposl & 7) * 2) = val;
;               }
;             }
	v_sub_f32_e32 v36, v44, v36
	v_sub_f32_e32 v37, v45, v37
	v_mul_f32_e32 v36, 0x3fb8aa3b, v36
	v_mul_f32_e32 v37, 0x3fb8aa3b, v37
	v_exp_f32_e32 v36, v36
	v_exp_f32_e32 v37, v37
	s_nop 0
	v_pk_mul_f32 v[32:33], v[32:33], v[36:37]
	v_sub_f32_e32 v36, v46, v38
	v_sub_f32_e32 v37, v47, v39
	v_mul_f32_e32 v36, 0x3fb8aa3b, v36
	v_mul_f32_e32 v37, 0x3fb8aa3b, v37
	v_exp_f32_e32 v36, v36
	v_exp_f32_e32 v37, v37
	v_cvt_pk_bf16_f32 v32, v32, v33
	v_pk_mul_f32 v[34:35], v[34:35], v[36:37]
	s_nop 0
	v_cvt_pk_bf16_f32 v33, v34, v35
	v_add_u32_e32 v34, v118, v40
	v_add3_u32 v34, v34, v227, v226
	ds_write_b16 v34, v32
	v_add_u32_e32 v34, v119, v41
	v_add3_u32 v34, v34, v227, v226
	ds_write_b16_d16_hi v34, v32
	v_add_u32_e32 v32, v122, v42
	v_add3_u32 v32, v32, v227, v226
	ds_write_b16 v32, v33
	v_add_u32_e32 v32, v123, v43
	v_add3_u32 v32, v32, v227, v226
	ds_write_b16_d16_hi v32, v33
	v_add_u32_e32 v32, 0xa0, v203
	v_or_b32_e32 v33, v32, v202
	v_add_u32_e32 v34, s7, v33
	v_ashrrev_i32_e32 v35, 31, v34
	v_or_b32_e32 v36, v32, v232
	v_lshlrev_b64 v[32:33], 12, v[34:35]
	v_or_b32_e32 v34, 63, v34
	v_ashrrev_i32_e32 v35, 31, v34
	v_lshlrev_b64 v[34:35], 12, v[34:35]
	v_lshl_add_u64 v[32:33], s[0:1], 0, v[32:33]
	v_lshl_add_u64 v[34:35], s[0:1], 0, v[34:35]
	v_ashrrev_i32_e32 v44, 3, v36
	v_lshl_add_u64 v[36:37], v[32:33], 0, v[132:133]
	v_lshl_add_u64 v[40:41], v[34:35], 0, v[132:133]
	global_load_dwordx4 v[36:39], v[36:37], off
	s_nop 0
	global_load_dwordx4 v[40:43], v[40:41], off
	s_waitcnt vmcnt(0)
	v_sub_f32_e32 v36, v40, v36
	v_sub_f32_e32 v37, v41, v37
	v_mul_f32_e32 v36, 0x3fb8aa3b, v36
	v_mul_f32_e32 v37, 0x3fb8aa3b, v37
	v_exp_f32_e32 v36, v36
	v_exp_f32_e32 v37, v37
	v_lshl_add_u64 v[40:41], v[34:35], 0, v[124:125]
	v_pk_mul_f32 v[28:29], v[28:29], v[36:37]
	v_sub_f32_e32 v36, v42, v38
	v_sub_f32_e32 v37, v43, v39
	v_mul_f32_e32 v36, 0x3fb8aa3b, v36
	v_mul_f32_e32 v37, 0x3fb8aa3b, v37
	v_exp_f32_e32 v36, v36
	v_exp_f32_e32 v37, v37
	global_load_dwordx4 v[40:43], v[40:41], off
	v_pk_mul_f32 v[30:31], v[30:31], v[36:37]
	v_cvt_pk_bf16_f32 v36, v28, v29
	v_xor_b32_e32 v28, v44, v201
	v_lshlrev_b32_e32 v28, 4, v28
	v_add_u32_e32 v29, v126, v28
	v_add3_u32 v29, v29, v227, v226
	ds_write_b16 v29, v36
	v_bitop3_b32 v29, v44, v201, 1 bitop3:0x1e
	v_lshlrev_b32_e32 v29, 4, v29
	v_cvt_pk_bf16_f32 v37, v30, v31
	v_add_u32_e32 v30, v126, v29
	v_add3_u32 v30, v30, v227, v226
	ds_write_b16_d16_hi v30, v36 offset:512
	v_bitop3_b32 v30, v44, v201, 2 bitop3:0x1e
	v_lshlrev_b32_e32 v30, 4, v30
	v_add_u32_e32 v31, v126, v30
	v_add3_u32 v31, v31, v227, v226
	ds_write_b16 v31, v37 offset:1024
	v_bitop3_b32 v31, v44, v201, 3 bitop3:0x1e
	v_lshlrev_b32_e32 v31, 4, v31
	v_add_u32_e32 v36, v126, v31
	v_add3_u32 v36, v36, v227, v226
	ds_write_b16_d16_hi v36, v37 offset:1536
	v_lshl_add_u64 v[36:37], v[32:33], 0, v[124:125]
	global_load_dwordx4 v[36:39], v[36:37], off
	s_waitcnt vmcnt(0)
	v_sub_f32_e32 v36, v40, v36
	v_sub_f32_e32 v37, v41, v37
	v_mul_f32_e32 v36, 0x3fb8aa3b, v36
	v_mul_f32_e32 v37, 0x3fb8aa3b, v37
	v_exp_f32_e32 v36, v36
	v_exp_f32_e32 v37, v37
	v_lshl_add_u64 v[40:41], v[34:35], 0, v[120:121]
	v_pk_mul_f32 v[24:25], v[24:25], v[36:37]
	v_sub_f32_e32 v36, v42, v38
	v_sub_f32_e32 v37, v43, v39
	v_mul_f32_e32 v36, 0x3fb8aa3b, v36
	v_mul_f32_e32 v37, 0x3fb8aa3b, v37
	v_exp_f32_e32 v36, v36
	v_exp_f32_e32 v37, v37
	global_load_dwordx4 v[40:43], v[40:41], off
	v_pk_mul_f32 v[26:27], v[26:27], v[36:37]
	v_cvt_pk_bf16_f32 v36, v24, v25
	v_bitop3_b32 v24, v44, v201, 16 bitop3:0x1e
	v_lshlrev_b32_e32 v24, 4, v24
	v_add_u32_e32 v25, v231, v24
	v_add3_u32 v25, v25, v227, v226
	ds_write_b16 v25, v36
	v_bitop3_b32 v25, v44, v201, 17 bitop3:0x1e
	v_lshlrev_b32_e32 v25, 4, v25
	v_cvt_pk_bf16_f32 v37, v26, v27
	v_add_u32_e32 v26, v126, v25
	v_add3_u32 v26, v26, v227, v226
	ds_write_b16_d16_hi v26, v36 offset:8704
	v_bitop3_b32 v26, v44, v201, 18 bitop3:0x1e
	v_lshlrev_b32_e32 v26, 4, v26
	v_add_u32_e32 v27, v126, v26
	v_add3_u32 v27, v27, v227, v226
	ds_write_b16 v27, v37 offset:9216
	v_bitop3_b32 v27, v44, v201, 19 bitop3:0x1e
	v_lshlrev_b32_e32 v27, 4, v27
	v_add_u32_e32 v36, v126, v27
	v_add3_u32 v36, v36, v227, v226
	ds_write_b16_d16_hi v36, v37 offset:9728
	v_lshl_add_u64 v[36:37], v[32:33], 0, v[120:121]
	global_load_dwordx4 v[36:39], v[36:37], off
	s_waitcnt vmcnt(0)
	v_sub_f32_e32 v36, v40, v36
	v_sub_f32_e32 v37, v41, v37
	v_mul_f32_e32 v36, 0x3fb8aa3b, v36
	v_mul_f32_e32 v37, 0x3fb8aa3b, v37
	v_exp_f32_e32 v36, v36
	v_exp_f32_e32 v37, v37
	s_nop 0
	v_pk_mul_f32 v[20:21], v[20:21], v[36:37]
	v_sub_f32_e32 v36, v42, v38
	v_sub_f32_e32 v37, v43, v39
	v_mul_f32_e32 v36, 0x3fb8aa3b, v36
	v_mul_f32_e32 v37, 0x3fb8aa3b, v37
	v_exp_f32_e32 v36, v36
	v_exp_f32_e32 v37, v37
	v_cvt_pk_bf16_f32 v20, v20, v21
	v_pk_mul_f32 v[22:23], v[22:23], v[36:37]
	s_nop 0
	v_cvt_pk_bf16_f32 v21, v22, v23
	v_add_u32_e32 v22, v127, v28
	v_add3_u32 v22, v22, v227, v226
	ds_write_b16 v22, v20
	v_add_u32_e32 v22, v228, v29
	v_add3_u32 v22, v22, v227, v226
	ds_write_b16_d16_hi v22, v20
	v_add_u32_e32 v20, v229, v30
	v_add3_u32 v20, v20, v227, v226
	ds_write_b16 v20, v21
	v_add_u32_e32 v20, v230, v31
	v_add3_u32 v20, v20, v227, v226
	ds_write_b16_d16_hi v20, v21
	v_lshl_add_u64 v[20:21], v[32:33], 0, v[116:117]
	v_lshl_add_u64 v[28:29], v[34:35], 0, v[116:117]
	global_load_dwordx4 v[20:23], v[20:21], off
	s_nop 0
	global_load_dwordx4 v[28:31], v[28:29], off
	s_waitcnt vmcnt(0)
; DEV u32x2 pk4(f32x4 v) { u32x2 r = {pk_bf16(v[0], v[1]), pk_bf16(v[2], v[3])}; return r; }
;   DEV void operator()(f32x4 (&acc)[2][2][4][2], int brow, int bcol, int wr, int wc, int fr, int fq) const {
;     ...
; #pragma unroll
;       for (int ai = 0; ai < 2; ++ai)
; #pragma unroll
;         for (int m = 0; m < 4; ++m) {
;           const int rl = ai * 128 + wr * 64 + m * 16 + fr, tok = brow + rl;
;           const int tposl = (rl & ~15) + sig16(rl & 15);
; #pragma unroll
;           for (int bj = 0; bj < 2; ++bj)
; #pragma unroll
;             for (int n = 0; n < 2; ++n) {
;               const int cl = bj * 128 + wc * 32 + n * 16 + fq * 4, lc = bcol - segstart + cl;
;               const f32x4 v = acc[ai][bj][m][n];
;               const f32x4 b4 = *(const f32x4*)(bmat + (size_t)tok * 1024 + lc);
;               const f32x4 bl = *(const f32x4*)(bmat + (size_t)(tok | 63) * 1024 + lc);
;               const u32x2 kk = pk4((f32x4){v[0] * __expf(bl[0] - b4[0]), v[1] * __expf(bl[1] - b4[1]), v[2] * __expf(bl[2] - b4[2]), v[3] * __expf(bl[3] - b4[3])});
; #pragma unroll
;               for (int j = 0; j < 4; ++j) {
;                 const int row = cl + j;
;                 const unsigned short val = (unsigned short)((j & 1) ? (kk[j >> 1] >> 16) : (kk[j >> 1] & 0xffff));
;                 *(unsigned short*)(smem + row * 512 + (((tposl >> 3) ^ (row & 31)) * 16) + (tposl & 7) * 2) = val;
;               }
;             }
;         }
;       __syncthreads();
;       const int bt = brow >> 11, tl0 = brow & 2047, hd = (bcol - segstart) >> 8;
;       tile_rows_out<true>(keT + ((size_t)((bt * 4 + hd) * 256)) * 2048 + tl0, 2048, (wr * 4 + wc) * 64 + fq * 16 + fr);
	v_sub_f32_e32 v20, v28, v20
	v_sub_f32_e32 v21, v29, v21
	v_mul_f32_e32 v20, 0x3fb8aa3b, v20
	v_mul_f32_e32 v21, 0x3fb8aa3b, v21
	v_exp_f32_e32 v20, v20
	v_exp_f32_e32 v21, v21
	s_nop 0
	v_pk_mul_f32 v[16:17], v[16:17], v[20:21]
	v_sub_f32_e32 v20, v30, v22
	v_sub_f32_e32 v21, v31, v23
	v_mul_f32_e32 v20, 0x3fb8aa3b, v20
	v_mul_f32_e32 v21, 0x3fb8aa3b, v21
	v_exp_f32_e32 v20, v20
	v_exp_f32_e32 v21, v21
	v_cvt_pk_bf16_f32 v16, v16, v17
	v_pk_mul_f32 v[18:19], v[18:19], v[20:21]
	s_nop 0
	v_cvt_pk_bf16_f32 v17, v18, v19
	v_add_u32_e32 v18, v118, v24
	v_add3_u32 v18, v18, v227, v226
	ds_write_b16 v18, v16
	v_add_u32_e32 v18, v119, v25
	v_add3_u32 v18, v18, v227, v226
	ds_write_b16_d16_hi v18, v16
	v_add_u32_e32 v16, v122, v26
	v_add3_u32 v16, v16, v227, v226
	ds_write_b16 v16, v17
	v_add_u32_e32 v16, v123, v27
	v_add3_u32 v16, v16, v227, v226
	ds_write_b16_d16_hi v16, v17
	v_add_u32_e32 v16, 0xb0, v203
	v_or_b32_e32 v17, v16, v202
	v_add_u32_e32 v18, s7, v17
	v_ashrrev_i32_e32 v19, 31, v18
	v_or_b32_e32 v20, v16, v232
	v_lshlrev_b64 v[16:17], 12, v[18:19]
	v_or_b32_e32 v18, 63, v18
	v_ashrrev_i32_e32 v19, 31, v18
	v_lshlrev_b64 v[18:19], 12, v[18:19]
	v_lshl_add_u64 v[16:17], s[0:1], 0, v[16:17]
	v_lshl_add_u64 v[18:19], s[0:1], 0, v[18:19]
	v_ashrrev_i32_e32 v28, 3, v20
	v_lshl_add_u64 v[20:21], v[16:17], 0, v[132:133]
	v_lshl_add_u64 v[24:25], v[18:19], 0, v[132:133]
	global_load_dwordx4 v[20:23], v[20:21], off
	s_ashr_i32 s0, s7, 1
	global_load_dwordx4 v[24:27], v[24:25], off
	s_and_b32 s0, s0, 0xfffffc00
	s_add_i32 s0, s0, s18
	s_and_b32 s0, s0, 0xffffff00
	s_ashr_i32 s1, s0, 31
	s_lshl_b64 s[0:1], s[0:1], 12
	s_add_u32 s0, s14, s0
	s_addc_u32 s1, s15, s1
	s_lshl_b32 s7, s9, 1
	s_add_u32 s0, s0, s7
	s_addc_u32 s1, s1, 0
	s_waitcnt vmcnt(0)
	v_sub_f32_e32 v20, v24, v20
	v_sub_f32_e32 v21, v25, v21
	v_mul_f32_e32 v20, 0x3fb8aa3b, v20
	v_mul_f32_e32 v21, 0x3fb8aa3b, v21
	v_exp_f32_e32 v20, v20
	v_exp_f32_e32 v21, v21
	v_lshl_add_u64 v[24:25], v[18:19], 0, v[124:125]
	v_pk_mul_f32 v[12:13], v[12:13], v[20:21]
	v_sub_f32_e32 v20, v26, v22
	v_sub_f32_e32 v21, v27, v23
	v_mul_f32_e32 v20, 0x3fb8aa3b, v20
	v_mul_f32_e32 v21, 0x3fb8aa3b, v21
	v_exp_f32_e32 v20, v20
	v_exp_f32_e32 v21, v21
	v_cvt_pk_bf16_f32 v12, v12, v13
	global_load_dwordx4 v[24:27], v[24:25], off
	v_pk_mul_f32 v[14:15], v[14:15], v[20:21]
	s_nop 0
	v_cvt_pk_bf16_f32 v13, v14, v15
	v_xor_b32_e32 v14, v28, v201
	v_lshlrev_b32_e32 v20, 4, v14
	v_add_u32_e32 v14, v126, v20
	v_add3_u32 v14, v14, v227, v226
	ds_write_b16 v14, v12
	v_bitop3_b32 v14, v28, v201, 1 bitop3:0x1e
	v_lshlrev_b32_e32 v21, 4, v14
	v_add_u32_e32 v14, v126, v21
	v_add3_u32 v14, v14, v227, v226
	ds_write_b16_d16_hi v14, v12 offset:512
	v_bitop3_b32 v12, v28, v201, 2 bitop3:0x1e
	v_lshlrev_b32_e32 v22, 4, v12
	v_add_u32_e32 v12, v126, v22
	v_add3_u32 v12, v12, v227, v226
	ds_write_b16 v12, v13 offset:1024
	v_bitop3_b32 v12, v28, v201, 3 bitop3:0x1e
	v_lshlrev_b32_e32 v23, 4, v12
	v_add_u32_e32 v12, v126, v23
	v_add3_u32 v12, v12, v227, v226
	ds_write_b16_d16_hi v12, v13 offset:1536
	v_lshl_add_u64 v[12:13], v[16:17], 0, v[124:125]
	global_load_dwordx4 v[12:15], v[12:13], off
	s_waitcnt vmcnt(0)
	v_sub_f32_e32 v12, v24, v12
	v_sub_f32_e32 v13, v25, v13
	v_mul_f32_e32 v12, 0x3fb8aa3b, v12
	v_mul_f32_e32 v13, 0x3fb8aa3b, v13
	v_exp_f32_e32 v12, v12
	v_exp_f32_e32 v13, v13
	v_lshl_add_u64 v[24:25], v[18:19], 0, v[120:121]
	v_pk_mul_f32 v[8:9], v[8:9], v[12:13]
	v_sub_f32_e32 v12, v26, v14
	v_sub_f32_e32 v13, v27, v15
	v_mul_f32_e32 v12, 0x3fb8aa3b, v12
	v_mul_f32_e32 v13, 0x3fb8aa3b, v13
	v_exp_f32_e32 v12, v12
	v_exp_f32_e32 v13, v13
	v_cvt_pk_bf16_f32 v8, v8, v9
	global_load_dwordx4 v[24:27], v[24:25], off
	v_pk_mul_f32 v[10:11], v[10:11], v[12:13]
	s_nop 0
	v_cvt_pk_bf16_f32 v9, v10, v11
	v_bitop3_b32 v10, v28, v201, 16 bitop3:0x1e
	v_lshlrev_b32_e32 v12, 4, v10
	v_add_u32_e32 v10, v231, v12
	v_add3_u32 v10, v10, v227, v226
	ds_write_b16 v10, v8
	v_bitop3_b32 v10, v28, v201, 17 bitop3:0x1e
	v_lshlrev_b32_e32 v13, 4, v10
	v_add_u32_e32 v10, v126, v13
	v_add3_u32 v10, v10, v227, v226
	ds_write_b16_d16_hi v10, v8 offset:8704
	v_bitop3_b32 v8, v28, v201, 18 bitop3:0x1e
	v_lshlrev_b32_e32 v14, 4, v8
	v_add_u32_e32 v8, v126, v14
	v_add3_u32 v8, v8, v227, v226
	ds_write_b16 v8, v9 offset:9216
	v_bitop3_b32 v8, v28, v201, 19 bitop3:0x1e
	v_lshlrev_b32_e32 v15, 4, v8
	v_add_u32_e32 v8, v126, v15
	v_add3_u32 v8, v8, v227, v226
	ds_write_b16_d16_hi v8, v9 offset:9728
	v_lshl_add_u64 v[8:9], v[16:17], 0, v[120:121]
	global_load_dwordx4 v[8:11], v[8:9], off
	s_waitcnt vmcnt(0)
	v_sub_f32_e32 v8, v24, v8
	v_sub_f32_e32 v9, v25, v9
	v_mul_f32_e32 v8, 0x3fb8aa3b, v8
	v_mul_f32_e32 v9, 0x3fb8aa3b, v9
	v_exp_f32_e32 v8, v8
	v_exp_f32_e32 v9, v9
	s_nop 0
	v_pk_mul_f32 v[4:5], v[4:5], v[8:9]
	v_sub_f32_e32 v8, v26, v10
	v_sub_f32_e32 v9, v27, v11
	v_mul_f32_e32 v8, 0x3fb8aa3b, v8
	v_mul_f32_e32 v9, 0x3fb8aa3b, v9
	v_exp_f32_e32 v8, v8
	v_exp_f32_e32 v9, v9
	v_cvt_pk_bf16_f32 v4, v4, v5
	v_pk_mul_f32 v[6:7], v[6:7], v[8:9]
	s_nop 0
	v_cvt_pk_bf16_f32 v5, v6, v7
	v_add_u32_e32 v6, v127, v20
	v_add3_u32 v6, v6, v227, v226
	ds_write_b16 v6, v4
	v_add_u32_e32 v6, v228, v21
	v_add3_u32 v6, v6, v227, v226
	ds_write_b16_d16_hi v6, v4
	v_add_u32_e32 v4, v229, v22
	v_add3_u32 v4, v4, v227, v226
	ds_write_b16 v4, v5
	v_add_u32_e32 v4, v230, v23
	v_add3_u32 v4, v4, v227, v226
	ds_write_b16_d16_hi v4, v5
	v_lshl_add_u64 v[4:5], v[16:17], 0, v[116:117]
	v_lshl_add_u64 v[8:9], v[18:19], 0, v[116:117]
	global_load_dwordx4 v[4:7], v[4:5], off
	s_nop 0
	global_load_dwordx4 v[8:11], v[8:9], off
	s_waitcnt vmcnt(0)
	v_sub_f32_e32 v4, v8, v4
	v_sub_f32_e32 v5, v9, v5
	v_mul_f32_e32 v4, 0x3fb8aa3b, v4
	v_mul_f32_e32 v5, 0x3fb8aa3b, v5
	v_exp_f32_e32 v4, v4
	v_exp_f32_e32 v5, v5
	s_nop 0
	v_pk_mul_f32 v[0:1], v[0:1], v[4:5]
	v_sub_f32_e32 v4, v10, v6
	v_sub_f32_e32 v5, v11, v7
	v_mul_f32_e32 v4, 0x3fb8aa3b, v4
	v_mul_f32_e32 v5, 0x3fb8aa3b, v5
	v_exp_f32_e32 v4, v4
	v_exp_f32_e32 v5, v5
	v_cvt_pk_bf16_f32 v0, v0, v1
	v_pk_mul_f32 v[2:3], v[2:3], v[4:5]
	s_nop 0
	v_cvt_pk_bf16_f32 v1, v2, v3
	v_add_u32_e32 v2, v118, v12
	v_add3_u32 v2, v2, v227, v226
	ds_write_b16 v2, v0
	v_add_u32_e32 v2, v119, v13
	v_add3_u32 v2, v2, v227, v226
	ds_write_b16_d16_hi v2, v0
	v_add_u32_e32 v0, v122, v14
	v_add3_u32 v0, v0, v227, v226
	ds_write_b16 v0, v1
	v_add_u32_e32 v0, v123, v15
	v_add3_u32 v0, v0, v227, v226
	ds_write_b16_d16_hi v0, v1
	s_waitcnt lgkmcnt(0)
	s_barrier
; template <bool NT = false>
; DEV void tile_rows_out(bf16_t* __restrict__ out0, const size_t ld, const int tid) {
; #pragma unroll
;   for (int i = 0; i < 16; ++i) {
;     const int id = i * 512 + tid, r = id >> 5, pos = id & 31, c = pos ^ (r & 31);
;     const u32x4 v = *(const u32x4*)(smem + r * 512 + pos * 16);
;     if (NT) __builtin_nontemporal_store(v, (u32x4*)(out0 + (size_t)r * ld + 8 * c)); else *(u32x4*)(out0 + (size_t)r * ld + 8 * c) = v;
;   }
; }
;   DEV void operator()(f32x4 (&acc)[2][2][4][2], int brow, int bcol, int wr, int wc, int fr, int fq) const {
;     ...
;       const int bt = brow >> 11, tl0 = brow & 2047, hd = (bcol - segstart) >> 8;
;       tile_rows_out<true>(keT + ((size_t)((bt * 4 + hd) * 256)) * 2048 + tl0, 2048, (wr * 4 + wc) * 64 + fq * 16 + fr);
	ds_read_b128 v[0:3], v205
	v_lshlrev_b64 v[4:5], 12, v[128:129]
	v_lshl_add_u64 v[4:5], s[0:1], 0, v[4:5]
	v_lshl_add_u64 v[4:5], v[4:5], 0, v[176:177]
	s_waitcnt lgkmcnt(0)
	global_store_dwordx4 v[4:5], v[0:3], off sc1
	ds_read_b128 v[0:3], v206
	v_lshlrev_b64 v[4:5], 12, v[130:131]
	v_lshl_add_u64 v[4:5], s[0:1], 0, v[4:5]
	v_lshl_add_u64 v[4:5], v[4:5], 0, v[136:137]
	s_waitcnt lgkmcnt(0)
	global_store_dwordx4 v[4:5], v[0:3], off sc1
	ds_read_b128 v[0:3], v207
	v_lshlrev_b64 v[4:5], 12, v[138:139]
	v_lshl_add_u64 v[4:5], s[0:1], 0, v[4:5]
	v_lshl_add_u64 v[4:5], v[4:5], 0, v[142:143]
	s_waitcnt lgkmcnt(0)
	global_store_dwordx4 v[4:5], v[0:3], off sc1
	ds_read_b128 v[0:3], v208
	v_lshlrev_b64 v[4:5], 12, v[140:141]
	v_lshl_add_u64 v[4:5], s[0:1], 0, v[4:5]
	v_lshl_add_u64 v[4:5], v[4:5], 0, v[144:145]
	s_waitcnt lgkmcnt(0)
	global_store_dwordx4 v[4:5], v[0:3], off sc1
	ds_read_b128 v[0:3], v209
	v_lshlrev_b64 v[4:5], 12, v[146:147]
	v_lshl_add_u64 v[4:5], s[0:1], 0, v[4:5]
	v_lshl_add_u64 v[4:5], v[4:5], 0, v[150:151]
	s_waitcnt lgkmcnt(0)
	global_store_dwordx4 v[4:5], v[0:3], off sc1
	ds_read_b128 v[0:3], v210
	v_lshlrev_b64 v[4:5], 12, v[148:149]
	v_lshl_add_u64 v[4:5], s[0:1], 0, v[4:5]
	v_lshl_add_u64 v[4:5], v[4:5], 0, v[152:153]
	s_waitcnt lgkmcnt(0)
	global_store_dwordx4 v[4:5], v[0:3], off sc1
	ds_read_b128 v[0:3], v211
	v_lshlrev_b64 v[4:5], 12, v[154:155]
	v_lshl_add_u64 v[4:5], s[0:1], 0, v[4:5]
	v_lshl_add_u64 v[4:5], v[4:5], 0, v[158:159]
	s_waitcnt lgkmcnt(0)
	global_store_dwordx4 v[4:5], v[0:3], off sc1
	ds_read_b128 v[0:3], v212
	v_lshlrev_b64 v[4:5], 12, v[156:157]
	v_lshl_add_u64 v[4:5], s[0:1], 0, v[4:5]
	v_lshl_add_u64 v[4:5], v[4:5], 0, v[160:161]
	s_waitcnt lgkmcnt(0)
	global_store_dwordx4 v[4:5], v[0:3], off sc1
	ds_read_b128 v[0:3], v213
	v_lshlrev_b64 v[4:5], 12, v[162:163]
	v_lshl_add_u64 v[4:5], s[0:1], 0, v[4:5]
	v_lshl_add_u64 v[4:5], v[4:5], 0, v[166:167]
	s_waitcnt lgkmcnt(0)
	global_store_dwordx4 v[4:5], v[0:3], off sc1
	ds_read_b128 v[0:3], v214
	v_lshlrev_b64 v[4:5], 12, v[164:165]
	v_lshl_add_u64 v[4:5], s[0:1], 0, v[4:5]
	v_lshl_add_u64 v[4:5], v[4:5], 0, v[168:169]
	s_waitcnt lgkmcnt(0)
	global_store_dwordx4 v[4:5], v[0:3], off sc1
	ds_read_b128 v[0:3], v215
	v_lshlrev_b64 v[4:5], 12, v[170:171]
	v_lshl_add_u64 v[4:5], s[0:1], 0, v[4:5]
	v_lshl_add_u64 v[4:5], v[4:5], 0, v[174:175]
	s_waitcnt lgkmcnt(0)
	global_store_dwordx4 v[4:5], v[0:3], off sc1
	ds_read_b128 v[0:3], v216
	v_lshlrev_b64 v[4:5], 12, v[172:173]
	v_lshl_add_u64 v[4:5], s[0:1], 0, v[4:5]
	v_lshl_add_u64 v[4:5], v[4:5], 0, v[180:181]
	s_waitcnt lgkmcnt(0)
	global_store_dwordx4 v[4:5], v[0:3], off sc1
	ds_read_b128 v[0:3], v217
	v_lshlrev_b64 v[4:5], 12, v[182:183]
	v_lshl_add_u64 v[4:5], s[0:1], 0, v[4:5]
	v_lshl_add_u64 v[4:5], v[4:5], 0, v[186:187]
	s_waitcnt lgkmcnt(0)
	global_store_dwordx4 v[4:5], v[0:3], off sc1
	ds_read_b128 v[0:3], v223
	v_lshlrev_b64 v[4:5], 12, v[184:185]
	v_lshl_add_u64 v[4:5], s[0:1], 0, v[4:5]
	v_lshl_add_u64 v[4:5], v[4:5], 0, v[188:189]
	s_waitcnt lgkmcnt(0)
	global_store_dwordx4 v[4:5], v[0:3], off sc1
	ds_read_b128 v[0:3], v224
	v_lshlrev_b64 v[4:5], 12, v[190:191]
	v_lshl_add_u64 v[4:5], s[0:1], 0, v[4:5]
	v_lshl_add_u64 v[4:5], v[4:5], 0, v[194:195]
	s_waitcnt lgkmcnt(0)
	global_store_dwordx4 v[4:5], v[0:3], off sc1
	ds_read_b128 v[0:3], v225
	v_lshlrev_b64 v[4:5], 12, v[192:193]
	v_lshl_add_u64 v[4:5], s[0:1], 0, v[4:5]
	v_lshl_add_u64 v[4:5], v[4:5], 0, v[196:197]
	s_waitcnt lgkmcnt(0)
	global_store_dwordx4 v[4:5], v[0:3], off sc1

; DEV u32x2 pk4(f32x4 v) { u32x2 r = {pk_bf16(v[0], v[1]), pk_bf16(v[2], v[3])}; return r; }
; DEV f32x4 unpk4(u32x2 u) { f32x4 r = {bf_lo(u[0]), bf_hi(u[0]), bf_lo(u[1]), bf_hi(u[1])}; return r; }
; DEV void sb_block(const Params& p, int item) {
;     ...
;   asm volatile("s_waitcnt vmcnt(0)" ::: "memory");
;     ...
;   __syncthreads();
;   {
;     char* lw = smem + wave * 16384;
; #pragma unroll
;     for (int d = 0; d < 4; ++d)
; #pragma unroll
;       for (int q = 0; q < 4; ++q) {
;         const f32x4 o = {O[d][4 * q], O[d][4 * q + 1], O[d][4 * q + 2], O[d][4 * q + 3]};
;         *(f32x4*)(lw + l31 * 512 + (((8 * d + 2 * q + hh) ^ l31) * 16)) = o;
;       }
;     asm volatile("s_waitcnt lgkmcnt(0)" ::: "memory");
;     const size_t tok0 = row0 + qt * 32;
;     u32x2 gv[16];
; #pragma unroll
;     for (int i = 0; i < 16; ++i) { const int r = 2 * i + hh, c = l31 ^ r; gv[i] = __builtin_nontemporal_load((const u32x2*)(ssg + (tok0 + r) * 2048 + h * 128 + 4 * c)); }
; #pragma unroll
;     for (int i = 0; i < 16; ++i) {
;       const int r = 2 * i + hh, c = l31 ^ r;
;       const f32x4 o = *(const f32x4*)(lw + r * 512 + l31 * 16);
;       *(u32x2*)(ob + (tok0 + r) * 2048 + h * 128 + 4 * c) = pk4(o * unpk4(gv[i]));
.LBB0_1223:
	s_lshl_b32 s0, s91, 14
	s_add_i32 s4, s0, 0
	v_lshl_add_u32 v64, v203, 9, s4
	v_xor_b32_e32 v65, v202, v203
	v_lshl_add_u32 v66, v65, 4, v64
	s_waitcnt vmcnt(0)
	s_waitcnt vmcnt(0) lgkmcnt(0)
	s_barrier
	ds_write_b128 v66, v[48:51]
	v_bitop3_b32 v48, v202, v203, 2 bitop3:0x36
	v_lshl_add_u32 v49, v48, 4, v64
	ds_write_b128 v49, v[52:55]
	v_bitop3_b32 v49, v202, v203, 4 bitop3:0x36
	v_lshl_add_u32 v50, v49, 4, v64
	ds_write_b128 v50, v[56:59]
	v_bitop3_b32 v50, v202, v203, 6 bitop3:0x36
	v_lshl_add_u32 v51, v50, 4, v64
	ds_write_b128 v51, v[60:63]
	v_bitop3_b32 v51, v202, v203, 8 bitop3:0x36
	v_lshl_add_u32 v52, v51, 4, v64
	ds_write_b128 v52, v[32:35]
	v_bitop3_b32 v32, v202, v203, 10 bitop3:0x36
	v_lshl_add_u32 v33, v32, 4, v64
	ds_write_b128 v33, v[36:39]
	v_bitop3_b32 v33, v202, v203, 12 bitop3:0x36
	v_lshl_add_u32 v34, v33, 4, v64
	ds_write_b128 v34, v[40:43]
	v_bitop3_b32 v34, v202, v203, 14 bitop3:0x36
	v_lshl_add_u32 v35, v34, 4, v64
	ds_write_b128 v35, v[44:47]
	v_bitop3_b32 v35, v202, v203, 16 bitop3:0x36
	v_lshl_add_u32 v36, v35, 4, v64
	ds_write_b128 v36, v[16:19]
	v_bitop3_b32 v16, v202, v203, 18 bitop3:0x36
	v_lshl_add_u32 v17, v16, 4, v64
	ds_write_b128 v17, v[20:23]
	v_bitop3_b32 v17, v202, v203, 20 bitop3:0x36
	v_lshl_add_u32 v18, v17, 4, v64
	v_bitop3_b32 v20, v202, v203, 22 bitop3:0x36
	ds_write_b128 v18, v[24:27]
	v_lshl_add_u32 v18, v20, 4, v64
	v_bitop3_b32 v24, v202, v203, 24 bitop3:0x36
	ds_write_b128 v18, v[28:31]
	v_lshl_add_u32 v18, v24, 4, v64
	v_bitop3_b32 v98, v202, v203, 26 bitop3:0x36
	ds_write_b128 v18, v[0:3]
	v_lshl_add_u32 v0, v98, 4, v64
	ds_write_b128 v0, v[4:7]
	v_bitop3_b32 v4, v202, v203, 28 bitop3:0x36
	v_lshl_add_u32 v0, v4, 4, v64
	v_bitop3_b32 v104, v202, v203, 30 bitop3:0x36
	ds_write_b128 v0, v[8:11]
	v_lshl_add_u32 v0, v104, 4, v64
	v_readlane_b32 s0, v253, 48
	v_readlane_b32 s6, v252, 0
	v_readlane_b32 s91, v254, 63
	v_readlane_b32 s5, v254, 62
	ds_write_b128 v0, v[12:15]
	v_readlane_b32 s1, v253, 49
	s_add_u32 s0, s0, s6
	v_or_b32_e32 v0, s91, v202
	v_mov_b32_e32 v1, s5
	s_addc_u32 s1, s1, 0
	v_lshlrev_b64 v[108:109], 12, v[0:1]
	v_lshl_add_u64 v[2:3], s[0:1], 0, v[108:109]
	v_lshlrev_b32_e32 v176, 3, v65
	s_waitcnt lgkmcnt(0)
	v_lshl_add_u64 v[2:3], v[2:3], 0, v[176:177]
	global_load_dwordx2 v[110:111], v[2:3], off nt
	v_or_b32_e32 v103, 2, v202
	v_or_b32_e32 v0, s91, v103
	v_lshlrev_b64 v[78:79], 12, v[0:1]
	v_lshl_add_u64 v[2:3], s[0:1], 0, v[78:79]
	v_lshlrev_b32_e32 v84, 3, v48
	v_mov_b32_e32 v85, v177
	v_lshl_add_u64 v[2:3], v[2:3], 0, v[84:85]
	global_load_dwordx2 v[88:89], v[2:3], off nt
	v_or_b32_e32 v114, 4, v202
	v_or_b32_e32 v0, s91, v114
	v_lshlrev_b64 v[80:81], 12, v[0:1]
	v_lshl_add_u64 v[2:3], s[0:1], 0, v[80:81]
	v_lshlrev_b32_e32 v82, 3, v49
	v_mov_b32_e32 v83, v177
	v_lshl_add_u64 v[2:3], v[2:3], 0, v[82:83]
	global_load_dwordx2 v[86:87], v[2:3], off nt
	v_or_b32_e32 v115, 6, v202
	v_or_b32_e32 v0, s91, v115
	v_lshlrev_b64 v[66:67], 12, v[0:1]
	v_lshl_add_u64 v[2:3], s[0:1], 0, v[66:67]
	v_lshlrev_b32_e32 v68, 3, v50
	v_mov_b32_e32 v69, v177
	v_lshl_add_u64 v[2:3], v[2:3], 0, v[68:69]
	global_load_dwordx2 v[76:77], v[2:3], off nt
	v_or_b32_e32 v102, 8, v202
	v_or_b32_e32 v0, s91, v102
	v_lshlrev_b64 v[70:71], 12, v[0:1]
	v_lshl_add_u64 v[2:3], s[0:1], 0, v[70:71]
	v_lshlrev_b32_e32 v72, 3, v51
	v_mov_b32_e32 v73, v177
	v_lshl_add_u64 v[2:3], v[2:3], 0, v[72:73]
	global_load_dwordx2 v[74:75], v[2:3], off nt
	v_or_b32_e32 v101, 10, v202
	v_or_b32_e32 v0, s91, v101
	v_lshlrev_b64 v[54:55], 12, v[0:1]
	v_lshl_add_u64 v[2:3], s[0:1], 0, v[54:55]
	v_lshlrev_b32_e32 v60, 3, v32
	v_mov_b32_e32 v61, v177
	v_lshl_add_u64 v[2:3], v[2:3], 0, v[60:61]
	global_load_dwordx2 v[64:65], v[2:3], off nt
	v_or_b32_e32 v100, 12, v202
	v_or_b32_e32 v0, s91, v100
	v_lshlrev_b64 v[56:57], 12, v[0:1]
	v_lshl_add_u64 v[2:3], s[0:1], 0, v[56:57]
	v_lshlrev_b32_e32 v58, 3, v33
	v_mov_b32_e32 v59, v177
	v_lshl_add_u64 v[2:3], v[2:3], 0, v[58:59]
	global_load_dwordx2 v[62:63], v[2:3], off nt
	v_or_b32_e32 v99, 14, v202
	v_or_b32_e32 v0, s91, v99
	v_lshlrev_b64 v[42:43], 12, v[0:1]
	v_lshl_add_u64 v[2:3], s[0:1], 0, v[42:43]
	v_lshlrev_b32_e32 v44, 3, v34
	v_mov_b32_e32 v45, v177
	v_lshl_add_u64 v[2:3], v[2:3], 0, v[44:45]
	global_load_dwordx2 v[52:53], v[2:3], off nt
	v_or_b32_e32 v97, 16, v202
	v_or_b32_e32 v0, s91, v97
	v_or_b32_e32 v96, 18, v202
	v_lshlrev_b64 v[46:47], 12, v[0:1]
	v_lshl_add_u64 v[2:3], s[0:1], 0, v[46:47]
	v_lshlrev_b32_e32 v48, 3, v35
	v_mov_b32_e32 v49, v177
	v_or_b32_e32 v0, s91, v96
	v_or_b32_e32 v95, 20, v202
	v_lshl_add_u64 v[2:3], v[2:3], 0, v[48:49]
	v_lshlrev_b64 v[30:31], 12, v[0:1]
	global_load_dwordx2 v[50:51], v[2:3], off nt
	v_lshl_add_u64 v[2:3], s[0:1], 0, v[30:31]
	v_lshlrev_b32_e32 v36, 3, v16
	v_mov_b32_e32 v37, v177
	v_or_b32_e32 v0, s91, v95
	v_or_b32_e32 v94, 22, v202
	v_lshl_add_u64 v[2:3], v[2:3], 0, v[36:37]
	v_lshlrev_b64 v[32:33], 12, v[0:1]
	global_load_dwordx2 v[40:41], v[2:3], off nt
	v_lshl_add_u64 v[2:3], s[0:1], 0, v[32:33]
	v_lshlrev_b32_e32 v34, 3, v17
	v_mov_b32_e32 v35, v177
	v_or_b32_e32 v0, s91, v94
	v_or_b32_e32 v93, 24, v202
	v_lshl_add_u64 v[2:3], v[2:3], 0, v[34:35]
	v_lshlrev_b64 v[18:19], 12, v[0:1]
	global_load_dwordx2 v[38:39], v[2:3], off nt
	v_lshl_add_u64 v[2:3], s[0:1], 0, v[18:19]
	v_lshlrev_b32_e32 v20, 3, v20
	v_mov_b32_e32 v21, v177
	v_or_b32_e32 v0, s91, v93
	v_or_b32_e32 v92, 26, v202
	v_lshl_add_u64 v[2:3], v[2:3], 0, v[20:21]
	v_lshlrev_b64 v[22:23], 12, v[0:1]
	global_load_dwordx2 v[28:29], v[2:3], off nt
	v_lshl_add_u64 v[2:3], s[0:1], 0, v[22:23]
	v_lshlrev_b32_e32 v24, 3, v24
	v_mov_b32_e32 v25, v177
	v_or_b32_e32 v0, s91, v92
	v_or_b32_e32 v91, 28, v202
	v_lshl_add_u64 v[2:3], v[2:3], 0, v[24:25]
	v_lshlrev_b64 v[6:7], 12, v[0:1]
	global_load_dwordx2 v[26:27], v[2:3], off nt
	v_lshl_add_u64 v[2:3], s[0:1], 0, v[6:7]
	v_lshlrev_b32_e32 v12, 3, v98
	v_mov_b32_e32 v13, v177
	v_or_b32_e32 v0, s91, v91
	v_lshl_add_u64 v[2:3], v[2:3], 0, v[12:13]
	v_lshlrev_b64 v[8:9], 12, v[0:1]
	global_load_dwordx2 v[16:17], v[2:3], off nt
	v_lshl_add_u64 v[2:3], s[0:1], 0, v[8:9]
	v_lshlrev_b32_e32 v10, 3, v4
	v_mov_b32_e32 v11, v177
	v_lshl_add_u64 v[2:3], v[2:3], 0, v[10:11]
	v_lshl_add_u32 v98, v203, 4, s4
	global_load_dwordx2 v[14:15], v[2:3], off nt
	v_lshlrev_b32_e32 v2, 3, v104
	v_lshl_add_u32 v104, v202, 9, v98
	v_or_b32_e32 v90, 30, v202
	ds_read_b128 v[104:107], v104
	v_or_b32_e32 v0, s91, v90
	v_lshlrev_b64 v[0:1], 12, v[0:1]
	v_lshl_add_u64 v[4:5], s[0:1], 0, v[0:1]
	v_readlane_b32 s0, v253, 52
	v_readlane_b32 s1, v253, 53
	s_add_u32 s0, s0, s6
	s_waitcnt vmcnt(14)
; DEV u32x2 pk4(f32x4 v) { u32x2 r = {pk_bf16(v[0], v[1]), pk_bf16(v[2], v[3])}; return r; }
; DEV f32x4 unpk4(u32x2 u) { f32x4 r = {bf_lo(u[0]), bf_hi(u[0]), bf_lo(u[1]), bf_hi(u[1])}; return r; }
; DEV void sb_block(const Params& p, int item) {
;     ...
; #pragma unroll
;     for (int i = 0; i < 16; ++i) {
;       const int r = 2 * i + hh, c = l31 ^ r;
;       const f32x4 o = *(const f32x4*)(lw + r * 512 + l31 * 16);
;       *(u32x2*)(ob + (tok0 + r) * 2048 + h * 128 + 4 * c) = pk4(o * unpk4(gv[i]));
;     }
	v_lshlrev_b32_e32 v112, 16, v110
	v_and_b32_e32 v113, 0xffff0000, v110
	v_lshlrev_b32_e32 v110, 16, v111
	v_and_b32_e32 v111, 0xffff0000, v111
	s_addc_u32 s1, s1, 0
	s_waitcnt lgkmcnt(0)
	v_pk_mul_f32 v[106:107], v[106:107], v[110:111]
	v_pk_mul_f32 v[104:105], v[104:105], v[112:113]
	v_mov_b32_e32 v3, v177
	v_cvt_pk_bf16_f32 v104, v104, v105
	v_cvt_pk_bf16_f32 v105, v106, v107
	v_lshl_add_u64 v[106:107], s[0:1], 0, v[108:109]
	v_lshl_add_u64 v[4:5], v[4:5], 0, v[2:3]
	v_lshl_add_u64 v[106:107], v[106:107], 0, v[176:177]
	v_lshl_add_u32 v103, v103, 9, v98
	global_load_dwordx2 v[4:5], v[4:5], off nt
	s_waitcnt vmcnt(14)
	v_lshlrev_b32_e32 v108, 16, v88
	global_store_dwordx2 v[106:107], v[104:105], off sc1
	ds_read_b128 v[104:107], v103
	v_and_b32_e32 v109, 0xffff0000, v88
	v_lshlrev_b32_e32 v88, 16, v89
	v_and_b32_e32 v89, 0xffff0000, v89
	v_lshl_add_u64 v[78:79], s[0:1], 0, v[78:79]
	s_waitcnt lgkmcnt(0)
	v_pk_mul_f32 v[88:89], v[106:107], v[88:89]
	v_pk_mul_f32 v[104:105], v[104:105], v[108:109]
	v_lshl_add_u64 v[78:79], v[78:79], 0, v[84:85]
	v_cvt_pk_bf16_f32 v104, v104, v105
	v_cvt_pk_bf16_f32 v105, v88, v89
	global_store_dwordx2 v[78:79], v[104:105], off sc1
	v_lshl_add_u32 v78, v114, 9, v98
	ds_read_b128 v[104:107], v78
	s_waitcnt vmcnt(15)
	v_lshlrev_b32_e32 v78, 16, v86
	v_and_b32_e32 v79, 0xffff0000, v86
	v_lshlrev_b32_e32 v84, 16, v87
	v_and_b32_e32 v85, 0xffff0000, v87
	s_waitcnt lgkmcnt(0)
	v_pk_mul_f32 v[84:85], v[106:107], v[84:85]
	v_pk_mul_f32 v[78:79], v[104:105], v[78:79]
	v_lshl_add_u64 v[80:81], s[0:1], 0, v[80:81]
	v_cvt_pk_bf16_f32 v78, v78, v79
	v_cvt_pk_bf16_f32 v79, v84, v85
	v_lshl_add_u64 v[80:81], v[80:81], 0, v[82:83]
	global_store_dwordx2 v[80:81], v[78:79], off sc1
	v_lshl_add_u32 v78, v115, 9, v98
	ds_read_b128 v[78:81], v78
	s_waitcnt vmcnt(15)
	v_lshlrev_b32_e32 v82, 16, v76
	v_and_b32_e32 v83, 0xffff0000, v76
	v_lshlrev_b32_e32 v76, 16, v77
	v_and_b32_e32 v77, 0xffff0000, v77
	s_waitcnt lgkmcnt(0)
	v_pk_mul_f32 v[76:77], v[80:81], v[76:77]
	v_pk_mul_f32 v[78:79], v[78:79], v[82:83]
	v_lshl_add_u64 v[66:67], s[0:1], 0, v[66:67]
	v_cvt_pk_bf16_f32 v78, v78, v79
	v_cvt_pk_bf16_f32 v79, v76, v77
	v_lshl_add_u64 v[66:67], v[66:67], 0, v[68:69]
	global_store_dwordx2 v[66:67], v[78:79], off sc1
	v_lshl_add_u32 v66, v102, 9, v98
	ds_read_b128 v[66:69], v66
	s_waitcnt vmcnt(15)
	v_lshlrev_b32_e32 v76, 16, v74
	v_and_b32_e32 v77, 0xffff0000, v74
	v_lshlrev_b32_e32 v74, 16, v75
	v_and_b32_e32 v75, 0xffff0000, v75
	s_waitcnt lgkmcnt(0)
	v_pk_mul_f32 v[68:69], v[68:69], v[74:75]
	v_pk_mul_f32 v[66:67], v[66:67], v[76:77]
	v_lshl_add_u64 v[54:55], s[0:1], 0, v[54:55]
	v_cvt_pk_bf16_f32 v66, v66, v67
	v_cvt_pk_bf16_f32 v67, v68, v69
	v_lshl_add_u64 v[68:69], s[0:1], 0, v[70:71]
	v_lshl_add_u64 v[68:69], v[68:69], 0, v[72:73]
	global_store_dwordx2 v[68:69], v[66:67], off sc1
	v_lshl_add_u32 v66, v101, 9, v98
	ds_read_b128 v[66:69], v66
	s_waitcnt vmcnt(15)
	v_lshlrev_b32_e32 v70, 16, v64
	v_and_b32_e32 v71, 0xffff0000, v64
	v_lshlrev_b32_e32 v64, 16, v65
	v_and_b32_e32 v65, 0xffff0000, v65
	s_waitcnt lgkmcnt(0)
	v_pk_mul_f32 v[64:65], v[68:69], v[64:65]
	v_pk_mul_f32 v[66:67], v[66:67], v[70:71]
	v_lshl_add_u64 v[54:55], v[54:55], 0, v[60:61]
	v_cvt_pk_bf16_f32 v66, v66, v67
	v_cvt_pk_bf16_f32 v67, v64, v65
	global_store_dwordx2 v[54:55], v[66:67], off sc1
	v_lshl_add_u32 v54, v100, 9, v98
	ds_read_b128 v[64:67], v54
	s_waitcnt vmcnt(15)
	v_lshlrev_b32_e32 v54, 16, v62
	v_and_b32_e32 v55, 0xffff0000, v62
	v_lshlrev_b32_e32 v60, 16, v63
	v_and_b32_e32 v61, 0xffff0000, v63
	s_waitcnt lgkmcnt(0)
	v_pk_mul_f32 v[60:61], v[66:67], v[60:61]
	v_pk_mul_f32 v[54:55], v[64:65], v[54:55]
	v_lshl_add_u64 v[56:57], s[0:1], 0, v[56:57]
	v_cvt_pk_bf16_f32 v54, v54, v55
	v_cvt_pk_bf16_f32 v55, v60, v61
	v_lshl_add_u64 v[56:57], v[56:57], 0, v[58:59]
	global_store_dwordx2 v[56:57], v[54:55], off sc1
	v_lshl_add_u32 v54, v99, 9, v98
	ds_read_b128 v[54:57], v54
	s_waitcnt vmcnt(15)
	v_lshlrev_b32_e32 v58, 16, v52
	v_and_b32_e32 v59, 0xffff0000, v52
	v_lshlrev_b32_e32 v52, 16, v53
	v_and_b32_e32 v53, 0xffff0000, v53
	s_waitcnt lgkmcnt(0)
	v_pk_mul_f32 v[52:53], v[56:57], v[52:53]
	v_pk_mul_f32 v[54:55], v[54:55], v[58:59]
	v_lshl_add_u64 v[42:43], s[0:1], 0, v[42:43]
	v_cvt_pk_bf16_f32 v54, v54, v55
	v_cvt_pk_bf16_f32 v55, v52, v53
	v_lshl_add_u64 v[42:43], v[42:43], 0, v[44:45]
	global_store_dwordx2 v[42:43], v[54:55], off sc1
	v_lshl_add_u32 v42, v97, 9, v98
	ds_read_b128 v[42:45], v42
	s_waitcnt vmcnt(15)
	v_lshlrev_b32_e32 v52, 16, v50
	v_and_b32_e32 v53, 0xffff0000, v50
	v_lshlrev_b32_e32 v50, 16, v51
	v_and_b32_e32 v51, 0xffff0000, v51
	s_waitcnt lgkmcnt(0)
; DEV u32x2 pk4(f32x4 v) { u32x2 r = {pk_bf16(v[0], v[1]), pk_bf16(v[2], v[3])}; return r; }
; DEV f32x4 unpk4(u32x2 u) { f32x4 r = {bf_lo(u[0]), bf_hi(u[0]), bf_lo(u[1]), bf_hi(u[1])}; return r; }
; DEV void panel_publish(unsigned* cnt, const int tidx) {
;   asm volatile("s_waitcnt vmcnt(0)" ::: "memory");
;   __syncthreads();
;   if (tidx == 0) {
;     __builtin_amdgcn_fence(__ATOMIC_RELEASE, "agent");
;     asm volatile("s_waitcnt vmcnt(0)" ::: "memory");
;     __hip_atomic_fetch_add(cnt, 1u, __ATOMIC_RELAXED, __HIP_MEMORY_SCOPE_AGENT);
;   }
; }
; DEV void sb_block(const Params& p, int item) {
;     ...
; #pragma unroll
;     for (int i = 0; i < 16; ++i) {
;       const int r = 2 * i + hh, c = l31 ^ r;
;       const f32x4 o = *(const f32x4*)(lw + r * 512 + l31 * 16);
;       *(u32x2*)(ob + (tok0 + r) * 2048 + h * 128 + 4 * c) = pk4(o * unpk4(gv[i]));
;     }
;   }
;   panel_publish((unsigned*)(p.ws + OFF_MISC + 2048 + 896) + (b * 8 + qb), tidx);
	v_pk_mul_f32 v[44:45], v[44:45], v[50:51]
	v_pk_mul_f32 v[42:43], v[42:43], v[52:53]
	v_lshl_add_u64 v[30:31], s[0:1], 0, v[30:31]
	v_cvt_pk_bf16_f32 v42, v42, v43
	v_cvt_pk_bf16_f32 v43, v44, v45
	v_lshl_add_u64 v[44:45], s[0:1], 0, v[46:47]
	v_lshl_add_u64 v[44:45], v[44:45], 0, v[48:49]
	global_store_dwordx2 v[44:45], v[42:43], off sc1
	v_lshl_add_u32 v42, v96, 9, v98
	ds_read_b128 v[42:45], v42
	s_waitcnt vmcnt(15)
	v_lshlrev_b32_e32 v46, 16, v40
	v_and_b32_e32 v47, 0xffff0000, v40
	v_lshlrev_b32_e32 v40, 16, v41
	v_and_b32_e32 v41, 0xffff0000, v41
	s_waitcnt lgkmcnt(0)
	v_pk_mul_f32 v[40:41], v[44:45], v[40:41]
	v_pk_mul_f32 v[42:43], v[42:43], v[46:47]
	v_lshl_add_u64 v[30:31], v[30:31], 0, v[36:37]
	v_cvt_pk_bf16_f32 v42, v42, v43
	v_cvt_pk_bf16_f32 v43, v40, v41
	global_store_dwordx2 v[30:31], v[42:43], off sc1
	v_lshl_add_u32 v30, v95, 9, v98
	ds_read_b128 v[40:43], v30
	s_waitcnt vmcnt(15)
	v_lshlrev_b32_e32 v30, 16, v38
	v_and_b32_e32 v31, 0xffff0000, v38
	v_lshlrev_b32_e32 v36, 16, v39
	v_and_b32_e32 v37, 0xffff0000, v39
	s_waitcnt lgkmcnt(0)
	v_pk_mul_f32 v[36:37], v[42:43], v[36:37]
	v_pk_mul_f32 v[30:31], v[40:41], v[30:31]
	v_lshl_add_u64 v[32:33], s[0:1], 0, v[32:33]
	v_cvt_pk_bf16_f32 v30, v30, v31
	v_cvt_pk_bf16_f32 v31, v36, v37
	v_lshl_add_u64 v[32:33], v[32:33], 0, v[34:35]
	global_store_dwordx2 v[32:33], v[30:31], off sc1
	v_lshl_add_u32 v30, v94, 9, v98
	ds_read_b128 v[30:33], v30
	s_waitcnt vmcnt(15)
	v_lshlrev_b32_e32 v34, 16, v28
	v_and_b32_e32 v35, 0xffff0000, v28
	v_lshlrev_b32_e32 v28, 16, v29
	v_and_b32_e32 v29, 0xffff0000, v29
	s_waitcnt lgkmcnt(0)
	v_pk_mul_f32 v[28:29], v[32:33], v[28:29]
	v_pk_mul_f32 v[30:31], v[30:31], v[34:35]
	v_lshl_add_u64 v[18:19], s[0:1], 0, v[18:19]
	v_cvt_pk_bf16_f32 v30, v30, v31
	v_cvt_pk_bf16_f32 v31, v28, v29
	v_lshl_add_u64 v[18:19], v[18:19], 0, v[20:21]
	global_store_dwordx2 v[18:19], v[30:31], off sc1
	v_lshl_add_u32 v18, v93, 9, v98
	ds_read_b128 v[18:21], v18
	s_waitcnt vmcnt(15)
	v_lshlrev_b32_e32 v28, 16, v26
	v_and_b32_e32 v29, 0xffff0000, v26
	v_lshlrev_b32_e32 v26, 16, v27
	v_and_b32_e32 v27, 0xffff0000, v27
	s_waitcnt lgkmcnt(0)
	v_pk_mul_f32 v[20:21], v[20:21], v[26:27]
	v_pk_mul_f32 v[18:19], v[18:19], v[28:29]
	v_lshl_add_u64 v[6:7], s[0:1], 0, v[6:7]
	v_cvt_pk_bf16_f32 v18, v18, v19
	v_cvt_pk_bf16_f32 v19, v20, v21
	v_lshl_add_u64 v[20:21], s[0:1], 0, v[22:23]
	v_lshl_add_u64 v[20:21], v[20:21], 0, v[24:25]
	global_store_dwordx2 v[20:21], v[18:19], off sc1
	v_lshl_add_u32 v18, v92, 9, v98
	ds_read_b128 v[18:21], v18
	s_waitcnt vmcnt(15)
	v_lshlrev_b32_e32 v22, 16, v16
	v_and_b32_e32 v23, 0xffff0000, v16
	v_lshlrev_b32_e32 v16, 16, v17
	v_and_b32_e32 v17, 0xffff0000, v17
	s_waitcnt lgkmcnt(0)
	v_pk_mul_f32 v[16:17], v[20:21], v[16:17]
	v_pk_mul_f32 v[18:19], v[18:19], v[22:23]
	v_lshl_add_u64 v[6:7], v[6:7], 0, v[12:13]
	v_cvt_pk_bf16_f32 v18, v18, v19
	v_cvt_pk_bf16_f32 v19, v16, v17
	global_store_dwordx2 v[6:7], v[18:19], off sc1
	v_lshl_add_u32 v6, v91, 9, v98
	ds_read_b128 v[16:19], v6
	s_waitcnt vmcnt(15)
	v_lshlrev_b32_e32 v6, 16, v14
	v_and_b32_e32 v7, 0xffff0000, v14
	v_lshlrev_b32_e32 v12, 16, v15
	v_and_b32_e32 v13, 0xffff0000, v15
	s_waitcnt lgkmcnt(0)
	v_pk_mul_f32 v[12:13], v[18:19], v[12:13]
	v_pk_mul_f32 v[6:7], v[16:17], v[6:7]
	v_lshl_add_u64 v[8:9], s[0:1], 0, v[8:9]
	v_cvt_pk_bf16_f32 v6, v6, v7
	v_cvt_pk_bf16_f32 v7, v12, v13
	v_lshl_add_u64 v[8:9], v[8:9], 0, v[10:11]
	global_store_dwordx2 v[8:9], v[6:7], off sc1
	v_lshl_add_u32 v6, v90, 9, v98
	ds_read_b128 v[6:9], v6
	s_waitcnt vmcnt(15)
	v_lshlrev_b32_e32 v10, 16, v4
	v_and_b32_e32 v11, 0xffff0000, v4
	v_lshlrev_b32_e32 v4, 16, v5
	v_and_b32_e32 v5, 0xffff0000, v5
	s_waitcnt lgkmcnt(0)
	v_pk_mul_f32 v[4:5], v[8:9], v[4:5]
	v_pk_mul_f32 v[6:7], v[6:7], v[10:11]
	v_lshl_add_u64 v[0:1], s[0:1], 0, v[0:1]
	v_cvt_pk_bf16_f32 v6, v6, v7
	v_cvt_pk_bf16_f32 v7, v4, v5
	v_lshl_add_u64 v[0:1], v[0:1], 0, v[2:3]
	global_store_dwordx2 v[0:1], v[6:7], off sc1
	s_waitcnt vmcnt(0)
	v_cmp_eq_u32_e32 vcc, 0, v201
	v_readlane_b32 s7, v252, 1
	s_barrier
	s_and_saveexec_b64 s[0:1], vcc
	v_readlane_b32 s66, v254, 59
	s_mov_b32 s65, 0x800000
	v_readlane_b32 s67, v254, 60
	s_cbranch_execz .LBB0_1226
	s_mov_b64 s[4:5], exec
	v_mbcnt_lo_u32_b32 v0, s4, 0
	s_waitcnt vmcnt(0)
	s_waitcnt vmcnt(0)
	v_mbcnt_hi_u32_b32 v0, s5, v0
	v_cmp_eq_u32_e32 vcc, 0, v0
	s_and_b64 s[6:7], exec, vcc
	s_mov_b64 exec, s[6:7]
	s_cbranch_execz .LBB0_1226
	v_readlane_b32 s6, v252, 6
	s_lshl_b32 s6, s6, 3
	v_readlane_b32 s7, v252, 13
	s_add_i32 s6, s6, s7
	s_bcnt1_i32_b64 s4, s[4:5]
	s_lshl_b32 s6, s6, 2
	v_mov_b32_e32 v1, s4
	v_readlane_b32 s4, v253, 42
	v_mov_b32_e32 v0, s6
	v_readlane_b32 s5, v253, 43
	s_nop 4
	global_atomic_add v0, v1, s[4:5]

; DEV f32x16 mfma32(bf16x8 a, bf16x8 b, f32x16 c) { return __builtin_amdgcn_mfma_f32_32x32x16_bf16(a, b, c, 0, 0, 0); }
; DEV void phase25(const Params& p, const bool fuse) {
;     ...
;     if (tidx < 64) ssL[tidx] = 0.f;
;     if (wave < 3) {
;       const int jt = (wave == 2) ? 1 : 0, i2 = (wave == 0) ? 0 : 1;
;       const bf16_t* kd = Kd + (grow + 32 * jt + l31) * 1024 + h * 256 + 8 * hh;
;       const bf16_t* q = Qp + (grow + 32 * i2 + l31) * 1024 + h * 256 + 8 * hh;
;       f32x16 X;
;       for (int g = 0; g < 16; ++g) X[g] = 0.f;
; #pragma unroll
;       for (int s = 0; s < 16; ++s) X = mfma32(ld16(kd + 16 * s), ld16(q + 16 * s), X);
;       if (jt == i2) {
; #pragma unroll
;         for (int g = 0; g < 16; ++g) { const int jl = (g & 3) + 8 * (g >> 2) + 4 * hh; if (jl > l31) X[g] = 0.f; }
;       }
.LBB0_1241:
	s_or_b64 exec, exec, s[8:9]
	s_barrier
	s_and_saveexec_b64 s[8:9], s[4:5]
	ds_write_b32 v87, v177
	s_or_b64 exec, exec, s[8:9]
	s_ashr_i32 s8, s69, 7
	s_and_b32 s88, s69, 31
	s_ashr_i32 s9, s8, 31
	s_and_b32 s33, s64, 3
	s_lshl_b32 s68, s88, 6
	s_lshl_b64 s[64:65], s[8:9], 11
	s_andn2_b64 vcc, exec, s[42:43]
	s_or_b32 s9, s64, s68
	s_cbranch_vccnz .LBB0_1247
	v_mov_b32_e32 v1, s65
	v_or_b32_e32 v0, s9, v86
	v_readlane_b32 s66, v253, 13
	v_lshlrev_b64 v[0:1], 11, v[0:1]
	v_readlane_b32 s67, v253, 14
	v_mov_b32_e32 v3, s65
	v_or_b32_e32 v2, s9, v88
	v_lshl_add_u64 v[0:1], s[66:67], 0, v[0:1]
	v_readlane_b32 s66, v253, 11
	s_lshl_b32 s92, s33, 9
	v_lshlrev_b64 v[2:3], 11, v[2:3]
	v_readlane_b32 s67, v253, 12
	v_lshl_add_u64 v[0:1], v[0:1], 0, s[92:93]
	v_lshl_add_u64 v[24:25], v[0:1], 0, v[176:177]
	v_lshl_add_u64 v[2:3], s[66:67], 0, v[2:3]
	v_lshl_add_u64 v[2:3], v[2:3], 0, s[92:93]
	v_lshl_add_u64 v[26:27], v[2:3], 0, v[176:177]
	s_andn2_b64 vcc, exec, s[44:45]
	global_load_dwordx4 v[16:19], v[24:25], off
	global_load_dwordx4 v[20:23], v[26:27], off
	global_load_dwordx4 v[28:31], v[24:25], off offset:32
	global_load_dwordx4 v[32:35], v[26:27], off offset:32
	global_load_dwordx4 v[36:39], v[24:25], off offset:64
	global_load_dwordx4 v[40:43], v[26:27], off offset:64
	global_load_dwordx4 v[44:47], v[24:25], off offset:96
	global_load_dwordx4 v[48:51], v[26:27], off offset:96
	global_load_dwordx4 v[52:55], v[24:25], off offset:128
	global_load_dwordx4 v[56:59], v[26:27], off offset:128
	global_load_dwordx4 v[60:63], v[24:25], off offset:160
	global_load_dwordx4 v[64:67], v[26:27], off offset:160
	global_load_dwordx4 v[68:71], v[24:25], off offset:192
	global_load_dwordx4 v[72:75], v[26:27], off offset:192
	global_load_dwordx4 v[76:79], v[24:25], off offset:224
	global_load_dwordx4 v[80:83], v[26:27], off offset:224
	s_waitcnt vmcnt(14)
	v_mfma_f32_32x32x16_bf16 v[0:15], v[16:19], v[20:23], 0
	global_load_dwordx4 v[16:19], v[24:25], off offset:256
	global_load_dwordx4 v[20:23], v[26:27], off offset:256
	s_waitcnt vmcnt(14)
	v_mfma_f32_32x32x16_bf16 v[0:15], v[28:31], v[32:35], v[0:15]
	global_load_dwordx4 v[28:31], v[24:25], off offset:288
	global_load_dwordx4 v[32:35], v[26:27], off offset:288
	s_waitcnt vmcnt(14)
	v_mfma_f32_32x32x16_bf16 v[0:15], v[36:39], v[40:43], v[0:15]
	global_load_dwordx4 v[36:39], v[24:25], off offset:320
	global_load_dwordx4 v[40:43], v[26:27], off offset:320
	s_waitcnt vmcnt(14)
	v_mfma_f32_32x32x16_bf16 v[0:15], v[44:47], v[48:51], v[0:15]
	global_load_dwordx4 v[44:47], v[24:25], off offset:352
	global_load_dwordx4 v[48:51], v[26:27], off offset:352
	s_waitcnt vmcnt(14)
	v_mfma_f32_32x32x16_bf16 v[0:15], v[52:55], v[56:59], v[0:15]
	global_load_dwordx4 v[52:55], v[24:25], off offset:384
	global_load_dwordx4 v[56:59], v[26:27], off offset:384
	s_waitcnt vmcnt(14)
	v_mfma_f32_32x32x16_bf16 v[0:15], v[60:63], v[64:67], v[0:15]
	global_load_dwordx4 v[60:63], v[24:25], off offset:416
	global_load_dwordx4 v[64:67], v[26:27], off offset:416
	s_waitcnt vmcnt(14)
	v_mfma_f32_32x32x16_bf16 v[0:15], v[68:71], v[72:75], v[0:15]
	global_load_dwordx4 v[68:71], v[24:25], off offset:448
	global_load_dwordx4 v[72:75], v[26:27], off offset:448
	s_waitcnt vmcnt(14)
	v_mfma_f32_32x32x16_bf16 v[0:15], v[76:79], v[80:83], v[0:15]
	global_load_dwordx4 v[76:79], v[24:25], off offset:480
	global_load_dwordx4 v[80:83], v[26:27], off offset:480
	s_waitcnt vmcnt(14)
	v_mfma_f32_32x32x16_bf16 v[0:15], v[16:19], v[20:23], v[0:15]
	s_waitcnt vmcnt(12)
	v_mfma_f32_32x32x16_bf16 v[0:15], v[28:31], v[32:35], v[0:15]
	s_waitcnt vmcnt(10)
	v_mfma_f32_32x32x16_bf16 v[0:15], v[36:39], v[40:43], v[0:15]
	s_waitcnt vmcnt(8)
	v_mfma_f32_32x32x16_bf16 v[0:15], v[44:47], v[48:51], v[0:15]
	s_waitcnt vmcnt(6)
	v_mfma_f32_32x32x16_bf16 v[0:15], v[52:55], v[56:59], v[0:15]
	s_waitcnt vmcnt(4)
	v_mfma_f32_32x32x16_bf16 v[0:15], v[60:63], v[64:67], v[0:15]
	s_waitcnt vmcnt(2)
	v_mfma_f32_32x32x16_bf16 v[0:15], v[68:71], v[72:75], v[0:15]
	s_waitcnt vmcnt(0)
	v_mfma_f32_32x32x16_bf16 v[0:15], v[76:79], v[80:83], v[0:15]
	s_cbranch_vccnz .LBB0_1246
	v_readlane_b32 s66, v252, 2
	v_readlane_b32 s67, v252, 3
	s_nop 8
	v_cndmask_b32_e64 v1, 0, v1, s[10:11]
	v_cndmask_b32_e64 v2, v2, 0, s[12:13]
	v_cndmask_b32_e64 v16, v0, 0, s[66:67]
	v_cndmask_b32_e64 v0, v16, v0, s[10:11]
	v_cndmask_b32_e64 v3, v3, 0, s[14:15]
	v_cndmask_b32_e64 v4, v4, 0, s[16:17]
	v_cndmask_b32_e64 v5, v5, 0, s[18:19]
	v_cndmask_b32_e64 v6, v6, 0, s[20:21]
	v_cndmask_b32_e64 v7, v7, 0, s[22:23]
	v_cndmask_b32_e64 v8, v8, 0, s[24:25]
	v_cndmask_b32_e64 v9, v9, 0, s[26:27]
	v_cndmask_b32_e64 v10, v10, 0, s[28:29]
	v_cndmask_b32_e64 v11, v11, 0, s[30:31]
	v_cndmask_b32_e64 v12, v12, 0, s[34:35]
	v_cndmask_b32_e64 v13, v13, 0, s[36:37]
	v_cndmask_b32_e64 v14, v14, 0, s[38:39]
	v_cndmask_b32_e64 v15, v15, 0, s[40:41]

; DEV void phase25(const Params& p, const bool fuse) {
;     ...
;     {
;       char* lw = smem + wave * 16384;
; #pragma unroll
;       for (int dt = 0; dt < 2; ++dt)
; #pragma unroll
;         for (int i2 = 0; i2 < 2; ++i2)
; #pragma unroll
;           for (int q = 0; q < 4; ++q) {
;             const f32x4 v = {o[dt][i2][4 * q], o[dt][i2][4 * q + 1], o[dt][i2][4 * q + 2], o[dt][i2][4 * q + 3]};
;             const int r = 32 * i2 + l31;
;             *(f32x4*)(lw + r * 256 + (((8 * dt + 2 * q + hh) ^ (r & 15)) * 16)) = v;
;           }
;       asm volatile("s_waitcnt lgkmcnt(0)" ::: "memory");
;       u32x2 sgv[16]; f32x4 ghv[16];
; #pragma unroll
;       for (int i = 0; i < 16; ++i) {
;         const int id = i * 64 + lane, r = id >> 4, pos = id & 15, c = pos ^ (r & 15);
;         const int dv = 64 * wave + 4 * c;
;         sgv[i] = __builtin_nontemporal_load((const u32x2*)(sgg + (grow + r) * 2048 + h * 512 + dv));
;         ghv[i] = *(const f32x4*)(p.g_head + dv);
;       }
; #pragma unroll
;       for (int i = 0; i < 16; ++i) {
;         const int id = i * 64 + lane, r = id >> 4, pos = id & 15, c = pos ^ (r & 15);
;         const f32x4 v = *(const f32x4*)(lw + r * 256 + pos * 16);
;         const float rstd = rsqrtf(ssL[r] * (1.f / 512.f) + 1e-6f);
.LBB0_1251:
	s_or_b64 exec, exec, s[66:67]
	s_lshl_b32 s33, s33, 1
	v_readlane_b32 s66, v253, 17
	s_waitcnt lgkmcnt(0)
	s_barrier
	ds_write_b128 v214, v[16:19]
	ds_write_b128 v215, v[20:23]
	ds_write_b128 v216, v[24:27]
	ds_write_b128 v217, v[28:31]
	ds_write_b128 v214, v[0:3] offset:8192
	ds_write_b128 v215, v[4:7] offset:8192
	ds_write_b128 v216, v[8:11] offset:8192
	ds_write_b128 v217, v[12:15] offset:8192
	ds_write_b128 v223, v[32:35]
	ds_write_b128 v224, v[36:39]
	ds_write_b128 v225, v[40:43]
	ds_write_b128 v226, v[44:47]
	ds_write_b128 v223, v[48:51] offset:8192
	ds_write_b128 v224, v[52:55] offset:8192
	ds_write_b128 v225, v[56:59] offset:8192
	ds_write_b128 v226, v[60:63] offset:8192
	v_readlane_b32 s67, v253, 18
	s_add_u32 s66, s66, s33
	v_mov_b32_e32 v1, s65
	v_or_b32_e32 v0, s9, v90
	s_addc_u32 s67, s67, 0
	v_lshlrev_b64 v[208:209], 12, v[0:1]
	v_lshl_add_u64 v[0:1], s[66:67], 0, v[208:209]
	s_waitcnt lgkmcnt(0)
	v_lshl_add_u64 v[0:1], v[0:1], 0, v[152:153]
	global_load_dwordx2 v[0:1], v[0:1], off nt
	s_nop 0
	global_load_dwordx4 v[4:7], v[126:127], off
	v_mov_b32_e32 v3, s65
	v_or_b32_e32 v2, s9, v92
	v_lshlrev_b64 v[204:205], 12, v[2:3]
	v_lshl_add_u64 v[2:3], s[66:67], 0, v[204:205]
	v_lshl_add_u64 v[2:3], v[2:3], 0, v[154:155]
	global_load_dwordx2 v[210:211], v[2:3], off nt
	global_load_dwordx4 v[48:51], v[128:129], off
	v_mov_b32_e32 v3, s65
	v_or_b32_e32 v2, s9, v94
	v_lshlrev_b64 v[200:201], 12, v[2:3]
	v_lshl_add_u64 v[2:3], s[66:67], 0, v[200:201]
	v_lshl_add_u64 v[2:3], v[2:3], 0, v[156:157]
	global_load_dwordx2 v[206:207], v[2:3], off nt
	global_load_dwordx4 v[44:47], v[130:131], off
	v_mov_b32_e32 v3, s65
	v_or_b32_e32 v2, s9, v96
	v_lshlrev_b64 v[196:197], 12, v[2:3]
	v_lshl_add_u64 v[2:3], s[66:67], 0, v[196:197]
	v_lshl_add_u64 v[2:3], v[2:3], 0, v[158:159]
	global_load_dwordx2 v[202:203], v[2:3], off nt
	global_load_dwordx4 v[40:43], v[132:133], off
	v_mov_b32_e32 v3, s65
	v_or_b32_e32 v2, s9, v98
	v_lshlrev_b64 v[194:195], 12, v[2:3]
	v_lshl_add_u64 v[2:3], s[66:67], 0, v[194:195]
	v_lshl_add_u64 v[2:3], v[2:3], 0, v[152:153]
	global_load_dwordx2 v[198:199], v[2:3], off nt
	v_mov_b32_e32 v3, s65
	v_or_b32_e32 v2, s9, v100
	v_lshlrev_b64 v[188:189], 12, v[2:3]
	v_lshl_add_u64 v[2:3], s[66:67], 0, v[188:189]
	v_lshl_add_u64 v[2:3], v[2:3], 0, v[160:161]
	global_load_dwordx2 v[192:193], v[2:3], off nt
	global_load_dwordx4 v[36:39], v[134:135], off
	v_mov_b32_e32 v3, s65
	v_or_b32_e32 v2, s9, v102
	v_lshlrev_b64 v[186:187], 12, v[2:3]
	v_lshl_add_u64 v[2:3], s[66:67], 0, v[186:187]
	v_lshl_add_u64 v[2:3], v[2:3], 0, v[162:163]
	global_load_dwordx2 v[190:191], v[2:3], off nt
	global_load_dwordx4 v[32:35], v[136:137], off
	v_mov_b32_e32 v3, s65
	v_or_b32_e32 v2, s9, v104
	v_lshlrev_b64 v[82:83], 12, v[2:3]
	v_lshl_add_u64 v[2:3], s[66:67], 0, v[82:83]
	v_lshl_add_u64 v[2:3], v[2:3], 0, v[164:165]
	global_load_dwordx2 v[184:185], v[2:3], off nt
	global_load_dwordx4 v[28:31], v[138:139], off
	v_mov_b32_e32 v3, s65
	v_or_b32_e32 v2, s9, v106
	v_lshlrev_b64 v[80:81], 12, v[2:3]
	v_lshl_add_u64 v[2:3], s[66:67], 0, v[80:81]
	v_lshl_add_u64 v[2:3], v[2:3], 0, v[152:153]
	global_load_dwordx2 v[182:183], v[2:3], off nt
	v_mov_b32_e32 v3, s65
	v_or_b32_e32 v2, s9, v108
	v_lshlrev_b64 v[74:75], 12, v[2:3]
	v_lshl_add_u64 v[2:3], s[66:67], 0, v[74:75]
	v_lshl_add_u64 v[2:3], v[2:3], 0, v[166:167]
	global_load_dwordx2 v[78:79], v[2:3], off nt
	global_load_dwordx4 v[24:27], v[140:141], off
	v_mov_b32_e32 v3, s65
	v_or_b32_e32 v2, s9, v110
	v_lshlrev_b64 v[70:71], 12, v[2:3]
	v_lshl_add_u64 v[2:3], s[66:67], 0, v[70:71]
	v_lshl_add_u64 v[2:3], v[2:3], 0, v[168:169]
	global_load_dwordx2 v[76:77], v[2:3], off nt
	global_load_dwordx4 v[20:23], v[142:143], off
	v_mov_b32_e32 v3, s65
	v_or_b32_e32 v2, s9, v112
	v_lshlrev_b64 v[66:67], 12, v[2:3]
	v_lshl_add_u64 v[2:3], s[66:67], 0, v[66:67]
	v_lshl_add_u64 v[2:3], v[2:3], 0, v[170:171]
	global_load_dwordx2 v[72:73], v[2:3], off nt
	global_load_dwordx4 v[16:19], v[144:145], off
	v_mov_b32_e32 v3, s65
	v_or_b32_e32 v2, s9, v114
	v_lshlrev_b64 v[64:65], 12, v[2:3]
	v_lshl_add_u64 v[2:3], s[66:67], 0, v[64:65]
	v_lshl_add_u64 v[2:3], v[2:3], 0, v[152:153]
	global_load_dwordx2 v[68:69], v[2:3], off nt
	v_mov_b32_e32 v3, s65
	v_or_b32_e32 v2, s9, v116
	v_lshlrev_b64 v[58:59], 12, v[2:3]
	v_lshl_add_u64 v[2:3], s[66:67], 0, v[58:59]
	v_lshl_add_u64 v[2:3], v[2:3], 0, v[172:173]
	global_load_dwordx2 v[62:63], v[2:3], off nt
	global_load_dwordx4 v[12:15], v[146:147], off
	ds_read_b32 v52, v95
	v_mov_b32_e32 v3, s65
	v_or_b32_e32 v2, s9, v118
	v_lshlrev_b64 v[56:57], 12, v[2:3]
	v_lshl_add_u64 v[2:3], s[66:67], 0, v[56:57]
	v_lshl_add_u64 v[2:3], v[2:3], 0, v[174:175]
	global_load_dwordx2 v[60:61], v[2:3], off nt
	global_load_dwordx4 v[8:11], v[148:149], off
	s_waitcnt lgkmcnt(0)
	v_fmamk_f32 v2, v52, 0x3b000000, v178
	s_mov_b32 s64, 0x800000
	v_cmp_gt_f32_e32 vcc, s64, v2
	v_mul_f32_e32 v52, 0x4b800000, v2
	ds_read_b128 v[244:247], v227
	ds_read_b32 v243, v97
	v_cndmask_b32_e32 v2, v2, v52, vcc
	v_rsq_f32_e32 v54, v2
	v_mov_b32_e32 v3, s65
	v_or_b32_e32 v2, s9, v120
	v_lshlrev_b64 v[52:53], 12, v[2:3]
	v_mul_f32_e32 v2, 0x45800000, v54
	v_cndmask_b32_e32 v2, v54, v2, vcc
	v_readlane_b32 s9, v253, 19
	s_waitcnt lgkmcnt(1)
	v_pk_mul_f32 v[246:247], v[246:247], v[2:3] op_sel_hi:[1,0]
	v_pk_mul_f32 v[2:3], v[244:245], v[2:3] op_sel_hi:[1,0]
	s_add_u32 s90, s9, s33
	v_readlane_b32 s9, v253, 20
	s_waitcnt vmcnt(26)
	v_lshlrev_b32_e32 v244, 16, v0
	v_and_b32_e32 v245, 0xffff0000, v0
	v_lshlrev_b32_e32 v0, 16, v1
	v_and_b32_e32 v1, 0xffff0000, v1
	s_waitcnt vmcnt(25)
; DEV u32x2 pk4(f32x4 v) { u32x2 r = {pk_bf16(v[0], v[1]), pk_bf16(v[2], v[3])}; return r; }
; DEV f32x4 unpk4(u32x2 u) { f32x4 r = {bf_lo(u[0]), bf_hi(u[0]), bf_lo(u[1]), bf_hi(u[1])}; return r; }
; DEV void phase25(const Params& p, const bool fuse) {
;     ...
;       for (int i = 0; i < 16; ++i) {
;         const int id = i * 64 + lane, r = id >> 4, pos = id & 15, c = pos ^ (r & 15);
;         const f32x4 v = *(const f32x4*)(lw + r * 256 + pos * 16);
;         const float rstd = rsqrtf(ssL[r] * (1.f / 512.f) + 1e-6f);
;         const int dv = 64 * wave + 4 * c;
;         *(u32x2*)(oa + (grow + r) * 2048 + h * 512 + dv) = pk4(v * rstd * ghv[i] * unpk4(sgv[i]));
;       }
	v_pk_mul_f32 v[2:3], v[4:5], v[2:3]
	v_pk_mul_f32 v[246:247], v[6:7], v[246:247]
	s_addc_u32 s91, s9, 0
	v_lshl_add_u64 v[54:55], s[66:67], 0, v[52:53]
	v_pk_mul_f32 v[246:247], v[246:247], v[0:1]
	v_pk_mul_f32 v[244:245], v[2:3], v[244:245]
	v_lshl_add_u64 v[208:209], s[90:91], 0, v[208:209]
	v_lshl_add_u64 v[54:55], v[54:55], 0, v[180:181]
	v_cvt_pk_bf16_f32 v244, v244, v245
	v_cvt_pk_bf16_f32 v245, v246, v247
	v_lshl_add_u64 v[208:209], v[208:209], 0, v[152:153]
	global_load_dwordx2 v[54:55], v[54:55], off nt
	v_lshl_add_u64 v[204:205], s[90:91], 0, v[204:205]
	global_load_dwordx4 v[0:3], v[150:151], off
	v_lshl_add_u64 v[204:205], v[204:205], 0, v[154:155]
	global_store_dwordx2 v[208:209], v[244:245], off sc1
	s_waitcnt lgkmcnt(0)
	v_fmamk_f32 v208, v243, 0x3b000000, v178
	v_cmp_gt_f32_e32 vcc, s64, v208
	v_mul_f32_e32 v209, 0x4b800000, v208
	ds_read_b128 v[244:247], v228
	v_cndmask_b32_e32 v208, v208, v209, vcc
	v_rsq_f32_e32 v208, v208
	s_nop 0
	v_mul_f32_e32 v209, 0x45800000, v208
	v_cndmask_b32_e32 v208, v208, v209, vcc
	s_waitcnt lgkmcnt(0)
	v_pk_mul_f32 v[246:247], v[246:247], v[208:209] op_sel_hi:[1,0]
	v_pk_mul_f32 v[208:209], v[244:245], v[208:209] op_sel_hi:[1,0]
	s_waitcnt vmcnt(26)
	v_pk_mul_f32 v[50:51], v[50:51], v[246:247]
	v_pk_mul_f32 v[48:49], v[48:49], v[208:209]
	v_lshlrev_b32_e32 v208, 16, v210
	v_and_b32_e32 v209, 0xffff0000, v210
	v_lshlrev_b32_e32 v210, 16, v211
	v_and_b32_e32 v211, 0xffff0000, v211
	v_pk_mul_f32 v[50:51], v[50:51], v[210:211]
	ds_read_b32 v210, v99
	v_pk_mul_f32 v[48:49], v[48:49], v[208:209]
	v_cvt_pk_bf16_f32 v209, v50, v51
	v_cvt_pk_bf16_f32 v208, v48, v49
	global_store_dwordx2 v[204:205], v[208:209], off sc1
	s_waitcnt lgkmcnt(0)
	v_fmamk_f32 v48, v210, 0x3b000000, v178
	v_cmp_gt_f32_e32 vcc, s64, v48
	v_mul_f32_e32 v49, 0x4b800000, v48
	s_nop 0
	v_cndmask_b32_e32 v48, v48, v49, vcc
	v_rsq_f32_e32 v210, v48
	ds_read_b128 v[48:51], v229
	v_mul_f32_e32 v204, 0x45800000, v210
	v_cndmask_b32_e32 v204, v210, v204, vcc
	s_waitcnt lgkmcnt(0)
	v_pk_mul_f32 v[50:51], v[50:51], v[204:205] op_sel_hi:[1,0]
	v_pk_mul_f32 v[48:49], v[48:49], v[204:205] op_sel_hi:[1,0]
	ds_read_b32 v204, v101
	s_waitcnt vmcnt(25)
	v_pk_mul_f32 v[44:45], v[44:45], v[48:49]
	v_lshlrev_b32_e32 v48, 16, v206
	v_and_b32_e32 v49, 0xffff0000, v206
	v_pk_mul_f32 v[44:45], v[44:45], v[48:49]
	v_pk_mul_f32 v[46:47], v[46:47], v[50:51]
	v_cvt_pk_bf16_f32 v48, v44, v45
	s_waitcnt lgkmcnt(0)
	v_fmamk_f32 v44, v204, 0x3b000000, v178
	v_cmp_gt_f32_e32 vcc, s64, v44
	v_mul_f32_e32 v45, 0x4b800000, v44
	v_lshlrev_b32_e32 v50, 16, v207
	v_and_b32_e32 v51, 0xffff0000, v207
	v_cndmask_b32_e32 v44, v44, v45, vcc
	v_pk_mul_f32 v[46:47], v[46:47], v[50:51]
	v_lshl_add_u64 v[50:51], s[90:91], 0, v[200:201]
	v_rsq_f32_e32 v200, v44
	v_cvt_pk_bf16_f32 v49, v46, v47
	ds_read_b128 v[44:47], v230
	v_lshl_add_u64 v[50:51], v[50:51], 0, v[156:157]
	global_store_dwordx2 v[50:51], v[48:49], off sc1
	v_mul_f32_e32 v48, 0x45800000, v200
	v_cndmask_b32_e32 v48, v200, v48, vcc
	s_waitcnt lgkmcnt(0)
	v_pk_mul_f32 v[46:47], v[46:47], v[48:49] op_sel_hi:[1,0]
	v_pk_mul_f32 v[44:45], v[44:45], v[48:49] op_sel_hi:[1,0]
	ds_read_b32 v48, v103
	s_waitcnt vmcnt(24)
	v_pk_mul_f32 v[40:41], v[40:41], v[44:45]
	v_lshlrev_b32_e32 v44, 16, v202
	v_and_b32_e32 v45, 0xffff0000, v202
	v_pk_mul_f32 v[40:41], v[40:41], v[44:45]
	v_pk_mul_f32 v[42:43], v[42:43], v[46:47]
	v_cvt_pk_bf16_f32 v44, v40, v41
	s_waitcnt lgkmcnt(0)
	v_fmamk_f32 v40, v48, 0x3b000000, v178
	v_cmp_gt_f32_e32 vcc, s64, v40
	v_mul_f32_e32 v41, 0x4b800000, v40
	v_lshlrev_b32_e32 v46, 16, v203
	v_cndmask_b32_e32 v40, v40, v41, vcc
	v_and_b32_e32 v47, 0xffff0000, v203
	v_rsq_f32_e32 v48, v40
	v_pk_mul_f32 v[42:43], v[42:43], v[46:47]
	v_lshl_add_u64 v[46:47], s[90:91], 0, v[196:197]
	v_cvt_pk_bf16_f32 v45, v42, v43
	ds_read_b128 v[40:43], v231
	v_lshl_add_u64 v[46:47], v[46:47], 0, v[158:159]
	global_store_dwordx2 v[46:47], v[44:45], off sc1
	v_mul_f32_e32 v44, 0x45800000, v48
	v_cndmask_b32_e32 v44, v48, v44, vcc
	ds_read_b32 v48, v105
	s_waitcnt lgkmcnt(1)
	v_pk_mul_f32 v[40:41], v[40:41], v[44:45] op_sel_hi:[1,0]
	v_pk_mul_f32 v[42:43], v[42:43], v[44:45] op_sel_hi:[1,0]
	v_pk_mul_f32 v[40:41], v[4:5], v[40:41]
	s_waitcnt vmcnt(24)
	v_lshlrev_b32_e32 v44, 16, v198
	v_and_b32_e32 v45, 0xffff0000, v198
	v_pk_mul_f32 v[40:41], v[40:41], v[44:45]
	v_pk_mul_f32 v[42:43], v[6:7], v[42:43]
	v_cvt_pk_bf16_f32 v44, v40, v41
	s_waitcnt lgkmcnt(0)
	v_fmamk_f32 v40, v48, 0x3b000000, v178
	v_cmp_gt_f32_e32 vcc, s64, v40
	v_mul_f32_e32 v41, 0x4b800000, v40
	v_lshlrev_b32_e32 v46, 16, v199
	v_and_b32_e32 v47, 0xffff0000, v199
	v_cndmask_b32_e32 v40, v40, v41, vcc
	v_pk_mul_f32 v[42:43], v[42:43], v[46:47]
	v_rsq_f32_e32 v48, v40
	v_cvt_pk_bf16_f32 v45, v42, v43
	ds_read_b128 v[40:43], v232
	v_lshl_add_u64 v[46:47], s[90:91], 0, v[194:195]
	v_lshl_add_u64 v[46:47], v[46:47], 0, v[152:153]
	global_store_dwordx2 v[46:47], v[44:45], off sc1
	v_mul_f32_e32 v44, 0x45800000, v48
	v_cndmask_b32_e32 v44, v48, v44, vcc
	s_waitcnt lgkmcnt(0)
	v_pk_mul_f32 v[42:43], v[42:43], v[44:45] op_sel_hi:[1,0]
	v_pk_mul_f32 v[40:41], v[40:41], v[44:45] op_sel_hi:[1,0]
	ds_read_b32 v44, v107
	s_waitcnt vmcnt(23)
	v_pk_mul_f32 v[36:37], v[36:37], v[40:41]
	v_lshlrev_b32_e32 v40, 16, v192
	v_and_b32_e32 v41, 0xffff0000, v192
	v_pk_mul_f32 v[36:37], v[36:37], v[40:41]
	v_pk_mul_f32 v[38:39], v[38:39], v[42:43]
	v_cvt_pk_bf16_f32 v40, v36, v37
	s_waitcnt lgkmcnt(0)
; DEV u32x2 pk4(f32x4 v) { u32x2 r = {pk_bf16(v[0], v[1]), pk_bf16(v[2], v[3])}; return r; }
; DEV f32x4 unpk4(u32x2 u) { f32x4 r = {bf_lo(u[0]), bf_hi(u[0]), bf_lo(u[1]), bf_hi(u[1])}; return r; }
; DEV void phase25(const Params& p, const bool fuse) {
;     ...
;       for (int i = 0; i < 16; ++i) {
;         const int id = i * 64 + lane, r = id >> 4, pos = id & 15, c = pos ^ (r & 15);
;         const f32x4 v = *(const f32x4*)(lw + r * 256 + pos * 16);
;         const float rstd = rsqrtf(ssL[r] * (1.f / 512.f) + 1e-6f);
;         const int dv = 64 * wave + 4 * c;
;         *(u32x2*)(oa + (grow + r) * 2048 + h * 512 + dv) = pk4(v * rstd * ghv[i] * unpk4(sgv[i]));
;       }
	v_fmamk_f32 v36, v44, 0x3b000000, v178
	v_cmp_gt_f32_e32 vcc, s64, v36
	v_mul_f32_e32 v37, 0x4b800000, v36
	v_lshlrev_b32_e32 v42, 16, v193
	v_and_b32_e32 v43, 0xffff0000, v193
	v_cndmask_b32_e32 v36, v36, v37, vcc
	v_pk_mul_f32 v[38:39], v[38:39], v[42:43]
	v_rsq_f32_e32 v44, v36
	v_cvt_pk_bf16_f32 v41, v38, v39
	ds_read_b128 v[36:39], v233
	v_lshl_add_u64 v[42:43], s[90:91], 0, v[188:189]
	v_lshl_add_u64 v[42:43], v[42:43], 0, v[160:161]
	global_store_dwordx2 v[42:43], v[40:41], off sc1
	v_mul_f32_e32 v40, 0x45800000, v44
	v_cndmask_b32_e32 v40, v44, v40, vcc
	s_waitcnt lgkmcnt(0)
	v_pk_mul_f32 v[38:39], v[38:39], v[40:41] op_sel_hi:[1,0]
	v_pk_mul_f32 v[36:37], v[36:37], v[40:41] op_sel_hi:[1,0]
	s_waitcnt vmcnt(22)
	v_pk_mul_f32 v[34:35], v[34:35], v[38:39]
	v_lshlrev_b32_e32 v38, 16, v191
	v_and_b32_e32 v39, 0xffff0000, v191
	v_pk_mul_f32 v[34:35], v[34:35], v[38:39]
	ds_read_b32 v38, v109
	v_pk_mul_f32 v[32:33], v[32:33], v[36:37]
	v_lshlrev_b32_e32 v36, 16, v190
	v_and_b32_e32 v37, 0xffff0000, v190
	v_pk_mul_f32 v[32:33], v[32:33], v[36:37]
	s_waitcnt lgkmcnt(0)
	v_fmamk_f32 v36, v38, 0x3b000000, v178
	v_cmp_gt_f32_e32 vcc, s64, v36
	v_mul_f32_e32 v37, 0x4b800000, v36
	v_cvt_pk_bf16_f32 v32, v32, v33
	v_cndmask_b32_e32 v36, v36, v37, vcc
	v_rsq_f32_e32 v36, v36
	v_cvt_pk_bf16_f32 v33, v34, v35
	v_lshl_add_u64 v[34:35], s[90:91], 0, v[186:187]
	ds_read_b128 v[38:41], v234
	v_lshl_add_u64 v[34:35], v[34:35], 0, v[162:163]
	global_store_dwordx2 v[34:35], v[32:33], off sc1
	v_mul_f32_e32 v32, 0x45800000, v36
	v_cndmask_b32_e32 v32, v36, v32, vcc
	ds_read_b32 v36, v111
	s_waitcnt lgkmcnt(1)
	v_pk_mul_f32 v[34:35], v[40:41], v[32:33] op_sel_hi:[1,0]
	v_pk_mul_f32 v[32:33], v[38:39], v[32:33] op_sel_hi:[1,0]
	s_waitcnt vmcnt(21)
	v_pk_mul_f32 v[30:31], v[30:31], v[34:35]
	v_pk_mul_f32 v[28:29], v[28:29], v[32:33]
	v_lshlrev_b32_e32 v32, 16, v184
	v_and_b32_e32 v33, 0xffff0000, v184
	v_pk_mul_f32 v[28:29], v[28:29], v[32:33]
	v_lshlrev_b32_e32 v34, 16, v185
	v_cvt_pk_bf16_f32 v32, v28, v29
	s_waitcnt lgkmcnt(0)
	v_fmamk_f32 v28, v36, 0x3b000000, v178
	v_cmp_gt_f32_e32 vcc, s64, v28
	v_mul_f32_e32 v29, 0x4b800000, v28
	v_and_b32_e32 v35, 0xffff0000, v185
	v_cndmask_b32_e32 v28, v28, v29, vcc
	v_rsq_f32_e32 v36, v28
	v_pk_mul_f32 v[30:31], v[30:31], v[34:35]
	v_lshl_add_u64 v[34:35], s[90:91], 0, v[82:83]
	v_cvt_pk_bf16_f32 v33, v30, v31
	ds_read_b128 v[28:31], v235
	v_lshl_add_u64 v[34:35], v[34:35], 0, v[164:165]
	global_store_dwordx2 v[34:35], v[32:33], off sc1
	v_mul_f32_e32 v32, 0x45800000, v36
	v_cndmask_b32_e32 v32, v36, v32, vcc
	ds_read_b32 v36, v113
	s_waitcnt lgkmcnt(1)
	v_pk_mul_f32 v[28:29], v[28:29], v[32:33] op_sel_hi:[1,0]
	v_pk_mul_f32 v[30:31], v[30:31], v[32:33] op_sel_hi:[1,0]
	v_pk_mul_f32 v[28:29], v[4:5], v[28:29]
	s_waitcnt vmcnt(21)
	v_lshlrev_b32_e32 v32, 16, v182
	v_and_b32_e32 v33, 0xffff0000, v182
	v_pk_mul_f32 v[28:29], v[28:29], v[32:33]
	v_pk_mul_f32 v[30:31], v[6:7], v[30:31]
	v_cvt_pk_bf16_f32 v32, v28, v29
	s_waitcnt lgkmcnt(0)
	v_fmamk_f32 v28, v36, 0x3b000000, v178
	v_cmp_gt_f32_e32 vcc, s64, v28
	v_mul_f32_e32 v29, 0x4b800000, v28
	v_lshlrev_b32_e32 v34, 16, v183
	v_and_b32_e32 v35, 0xffff0000, v183
	v_cndmask_b32_e32 v28, v28, v29, vcc
	v_pk_mul_f32 v[30:31], v[30:31], v[34:35]
	v_rsq_f32_e32 v36, v28
	v_cvt_pk_bf16_f32 v33, v30, v31
	ds_read_b128 v[28:31], v236
	v_lshl_add_u64 v[34:35], s[90:91], 0, v[80:81]
	v_lshl_add_u64 v[34:35], v[34:35], 0, v[152:153]
	global_store_dwordx2 v[34:35], v[32:33], off sc1
	v_mul_f32_e32 v32, 0x45800000, v36
	v_cndmask_b32_e32 v32, v36, v32, vcc
	s_waitcnt lgkmcnt(0)
	v_pk_mul_f32 v[30:31], v[30:31], v[32:33] op_sel_hi:[1,0]
	v_pk_mul_f32 v[28:29], v[28:29], v[32:33] op_sel_hi:[1,0]
	ds_read_b32 v32, v115
	s_waitcnt vmcnt(20)
	v_pk_mul_f32 v[24:25], v[24:25], v[28:29]
	v_lshlrev_b32_e32 v28, 16, v78
	v_and_b32_e32 v29, 0xffff0000, v78
	v_pk_mul_f32 v[24:25], v[24:25], v[28:29]
	v_pk_mul_f32 v[26:27], v[26:27], v[30:31]
	v_cvt_pk_bf16_f32 v28, v24, v25
	s_waitcnt lgkmcnt(0)
	v_fmamk_f32 v24, v32, 0x3b000000, v178
	v_cmp_gt_f32_e32 vcc, s64, v24
	v_mul_f32_e32 v25, 0x4b800000, v24
	v_lshlrev_b32_e32 v30, 16, v79
	v_and_b32_e32 v31, 0xffff0000, v79
	v_cndmask_b32_e32 v24, v24, v25, vcc
	v_pk_mul_f32 v[26:27], v[26:27], v[30:31]
	v_rsq_f32_e32 v32, v24
	v_cvt_pk_bf16_f32 v29, v26, v27
	ds_read_b128 v[24:27], v237
	v_lshl_add_u64 v[30:31], s[90:91], 0, v[74:75]
	v_lshl_add_u64 v[30:31], v[30:31], 0, v[166:167]
	global_store_dwordx2 v[30:31], v[28:29], off sc1
	v_mul_f32_e32 v28, 0x45800000, v32
	v_cndmask_b32_e32 v28, v32, v28, vcc
	s_waitcnt lgkmcnt(0)
	v_pk_mul_f32 v[26:27], v[26:27], v[28:29] op_sel_hi:[1,0]
	v_pk_mul_f32 v[24:25], v[24:25], v[28:29] op_sel_hi:[1,0]
	ds_read_b32 v28, v117
	s_waitcnt vmcnt(19)
	v_pk_mul_f32 v[20:21], v[20:21], v[24:25]
	v_lshlrev_b32_e32 v24, 16, v76
	v_and_b32_e32 v25, 0xffff0000, v76
	v_pk_mul_f32 v[20:21], v[20:21], v[24:25]
	v_pk_mul_f32 v[22:23], v[22:23], v[26:27]
	v_cvt_pk_bf16_f32 v24, v20, v21
	s_waitcnt lgkmcnt(0)
	v_fmamk_f32 v20, v28, 0x3b000000, v178
	v_cmp_gt_f32_e32 vcc, s64, v20
	v_mul_f32_e32 v21, 0x4b800000, v20
	v_lshlrev_b32_e32 v26, 16, v77
	v_and_b32_e32 v27, 0xffff0000, v77
	v_cndmask_b32_e32 v20, v20, v21, vcc
	v_pk_mul_f32 v[22:23], v[22:23], v[26:27]
	v_rsq_f32_e32 v28, v20
	v_cvt_pk_bf16_f32 v25, v22, v23
	ds_read_b128 v[20:23], v238
	v_lshl_add_u64 v[26:27], s[90:91], 0, v[70:71]
	v_lshl_add_u64 v[26:27], v[26:27], 0, v[168:169]
	global_store_dwordx2 v[26:27], v[24:25], off sc1
	v_mul_f32_e32 v24, 0x45800000, v28
	v_cndmask_b32_e32 v24, v28, v24, vcc
	s_waitcnt lgkmcnt(0)
; DEV u32x2 pk4(f32x4 v) { u32x2 r = {pk_bf16(v[0], v[1]), pk_bf16(v[2], v[3])}; return r; }
; DEV f32x4 unpk4(u32x2 u) { f32x4 r = {bf_lo(u[0]), bf_hi(u[0]), bf_lo(u[1]), bf_hi(u[1])}; return r; }
; DEV void panel_publish(unsigned* cnt, const int tidx) {
;   asm volatile("s_waitcnt vmcnt(0)" ::: "memory");
;   __syncthreads();
;   if (tidx == 0) {
;     __builtin_amdgcn_fence(__ATOMIC_RELEASE, "agent");
;     asm volatile("s_waitcnt vmcnt(0)" ::: "memory");
;     __hip_atomic_fetch_add(cnt, 1u, __ATOMIC_RELAXED, __HIP_MEMORY_SCOPE_AGENT);
;   }
; }
; DEV void phase25(const Params& p, const bool fuse) {
;     ...
;       for (int i = 0; i < 16; ++i) {
;         const int id = i * 64 + lane, r = id >> 4, pos = id & 15, c = pos ^ (r & 15);
;         const f32x4 v = *(const f32x4*)(lw + r * 256 + pos * 16);
;         const float rstd = rsqrtf(ssL[r] * (1.f / 512.f) + 1e-6f);
;         const int dv = 64 * wave + 4 * c;
;         *(u32x2*)(oa + (grow + r) * 2048 + h * 512 + dv) = pk4(v * rstd * ghv[i] * unpk4(sgv[i]));
;       }
;     }
;     __syncthreads();
;     if (fuse) panel_publish((unsigned*)(p.ws + OFF_MISC + 2048 + 512) + (b * 8 + (c >> 2)), tidx);
	v_pk_mul_f32 v[22:23], v[22:23], v[24:25] op_sel_hi:[1,0]
	v_pk_mul_f32 v[20:21], v[20:21], v[24:25] op_sel_hi:[1,0]
	ds_read_b32 v24, v119
	s_waitcnt vmcnt(18)
	v_pk_mul_f32 v[16:17], v[16:17], v[20:21]
	v_lshlrev_b32_e32 v20, 16, v72
	v_and_b32_e32 v21, 0xffff0000, v72
	v_pk_mul_f32 v[16:17], v[16:17], v[20:21]
	v_pk_mul_f32 v[18:19], v[18:19], v[22:23]
	v_cvt_pk_bf16_f32 v20, v16, v17
	s_waitcnt lgkmcnt(0)
	v_fmamk_f32 v16, v24, 0x3b000000, v178
	v_cmp_gt_f32_e32 vcc, s64, v16
	v_mul_f32_e32 v17, 0x4b800000, v16
	v_lshlrev_b32_e32 v22, 16, v73
	v_and_b32_e32 v23, 0xffff0000, v73
	v_cndmask_b32_e32 v16, v16, v17, vcc
	v_pk_mul_f32 v[18:19], v[18:19], v[22:23]
	v_rsq_f32_e32 v24, v16
	v_cvt_pk_bf16_f32 v21, v18, v19
	ds_read_b128 v[16:19], v239
	v_lshl_add_u64 v[22:23], s[90:91], 0, v[66:67]
	v_lshl_add_u64 v[22:23], v[22:23], 0, v[170:171]
	global_store_dwordx2 v[22:23], v[20:21], off sc1
	v_mul_f32_e32 v20, 0x45800000, v24
	v_cndmask_b32_e32 v20, v24, v20, vcc
	s_waitcnt lgkmcnt(0)
	v_pk_mul_f32 v[18:19], v[18:19], v[20:21] op_sel_hi:[1,0]
	v_pk_mul_f32 v[16:17], v[16:17], v[20:21] op_sel_hi:[1,0]
	ds_read_b32 v20, v121
	v_pk_mul_f32 v[4:5], v[4:5], v[16:17]
	s_waitcnt vmcnt(18)
	v_lshlrev_b32_e32 v16, 16, v68
	v_and_b32_e32 v17, 0xffff0000, v68
	v_pk_mul_f32 v[4:5], v[4:5], v[16:17]
	v_pk_mul_f32 v[6:7], v[6:7], v[18:19]
	v_cvt_pk_bf16_f32 v16, v4, v5
	s_waitcnt lgkmcnt(0)
	v_fmamk_f32 v4, v20, 0x3b000000, v178
	v_cmp_gt_f32_e32 vcc, s64, v4
	v_mul_f32_e32 v5, 0x4b800000, v4
	v_lshlrev_b32_e32 v18, 16, v69
	v_and_b32_e32 v19, 0xffff0000, v69
	v_cndmask_b32_e32 v4, v4, v5, vcc
	v_pk_mul_f32 v[6:7], v[6:7], v[18:19]
	v_rsq_f32_e32 v20, v4
	v_cvt_pk_bf16_f32 v17, v6, v7
	ds_read_b128 v[4:7], v240
	v_lshl_add_u64 v[18:19], s[90:91], 0, v[64:65]
	v_lshl_add_u64 v[18:19], v[18:19], 0, v[152:153]
	global_store_dwordx2 v[18:19], v[16:17], off sc1
	v_mul_f32_e32 v16, 0x45800000, v20
	v_cndmask_b32_e32 v16, v20, v16, vcc
	s_waitcnt lgkmcnt(0)
	v_pk_mul_f32 v[6:7], v[6:7], v[16:17] op_sel_hi:[1,0]
	v_pk_mul_f32 v[4:5], v[4:5], v[16:17] op_sel_hi:[1,0]
	ds_read_b32 v16, v212
	s_waitcnt vmcnt(17)
	v_pk_mul_f32 v[4:5], v[12:13], v[4:5]
	v_lshlrev_b32_e32 v12, 16, v62
	v_and_b32_e32 v13, 0xffff0000, v62
	v_pk_mul_f32 v[4:5], v[4:5], v[12:13]
	v_pk_mul_f32 v[6:7], v[14:15], v[6:7]
	v_cvt_pk_bf16_f32 v12, v4, v5
	s_waitcnt lgkmcnt(0)
	v_fmamk_f32 v4, v16, 0x3b000000, v178
	v_cmp_gt_f32_e32 vcc, s64, v4
	v_mul_f32_e32 v5, 0x4b800000, v4
	v_lshlrev_b32_e32 v14, 16, v63
	v_and_b32_e32 v15, 0xffff0000, v63
	v_cndmask_b32_e32 v4, v4, v5, vcc
	v_pk_mul_f32 v[6:7], v[6:7], v[14:15]
	v_rsq_f32_e32 v16, v4
	v_cvt_pk_bf16_f32 v13, v6, v7
	ds_read_b128 v[4:7], v241
	v_lshl_add_u64 v[14:15], s[90:91], 0, v[58:59]
	v_lshl_add_u64 v[14:15], v[14:15], 0, v[172:173]
	global_store_dwordx2 v[14:15], v[12:13], off sc1
	v_mul_f32_e32 v12, 0x45800000, v16
	v_cndmask_b32_e32 v12, v16, v12, vcc
	s_waitcnt lgkmcnt(0)
	v_pk_mul_f32 v[6:7], v[6:7], v[12:13] op_sel_hi:[1,0]
	v_pk_mul_f32 v[4:5], v[4:5], v[12:13] op_sel_hi:[1,0]
	s_waitcnt vmcnt(16)
	v_pk_mul_f32 v[6:7], v[10:11], v[6:7]
	v_lshlrev_b32_e32 v10, 16, v61
	v_and_b32_e32 v11, 0xffff0000, v61
	v_pk_mul_f32 v[6:7], v[6:7], v[10:11]
	ds_read_b32 v10, v213
	v_pk_mul_f32 v[4:5], v[8:9], v[4:5]
	v_lshlrev_b32_e32 v8, 16, v60
	v_and_b32_e32 v9, 0xffff0000, v60
	v_pk_mul_f32 v[4:5], v[4:5], v[8:9]
	s_waitcnt lgkmcnt(0)
	v_fmamk_f32 v8, v10, 0x3b000000, v178
	v_cmp_gt_f32_e32 vcc, s64, v8
	v_mul_f32_e32 v9, 0x4b800000, v8
	ds_read_b128 v[10:13], v242
	v_cndmask_b32_e32 v8, v8, v9, vcc
	v_rsq_f32_e32 v8, v8
	v_cvt_pk_bf16_f32 v4, v4, v5
	v_cvt_pk_bf16_f32 v5, v6, v7
	v_lshl_add_u64 v[6:7], s[90:91], 0, v[56:57]
	v_lshl_add_u64 v[6:7], v[6:7], 0, v[174:175]
	global_store_dwordx2 v[6:7], v[4:5], off sc1
	v_mul_f32_e32 v4, 0x45800000, v8
	v_cndmask_b32_e32 v4, v8, v4, vcc
	s_waitcnt lgkmcnt(0)
	v_pk_mul_f32 v[6:7], v[12:13], v[4:5] op_sel_hi:[1,0]
	v_pk_mul_f32 v[4:5], v[10:11], v[4:5] op_sel_hi:[1,0]
	s_waitcnt vmcnt(15)
	v_pk_mul_f32 v[2:3], v[2:3], v[6:7]
	v_pk_mul_f32 v[0:1], v[0:1], v[4:5]
	v_lshlrev_b32_e32 v4, 16, v54
	v_and_b32_e32 v5, 0xffff0000, v54
	v_lshlrev_b32_e32 v6, 16, v55
	v_and_b32_e32 v7, 0xffff0000, v55
	v_pk_mul_f32 v[2:3], v[2:3], v[6:7]
	v_pk_mul_f32 v[0:1], v[0:1], v[4:5]
	s_nop 0
	v_cvt_pk_bf16_f32 v0, v0, v1
	v_cvt_pk_bf16_f32 v1, v2, v3
	v_lshl_add_u64 v[2:3], s[90:91], 0, v[52:53]
	v_lshl_add_u64 v[2:3], v[2:3], 0, v[180:181]
	global_store_dwordx2 v[2:3], v[0:1], off sc1
	s_barrier
	s_waitcnt vmcnt(0)
	s_barrier
	s_and_saveexec_b64 s[64:65], s[0:1]
	s_xor_b64 s[64:65], exec, s[64:65]
	s_cbranch_execz .LBB0_1230
	s_mov_b64 s[66:67], exec
	s_waitcnt vmcnt(0)
	s_waitcnt vmcnt(0)
	v_mbcnt_lo_u32_b32 v0, s66, 0
	v_mbcnt_hi_u32_b32 v0, s67, v0
	s_mov_b32 s90, s71
	v_cmp_eq_u32_e32 vcc, 0, v0
	s_and_saveexec_b64 s[68:69], vcc
	s_xor_b64 s[68:69], exec, s[68:69]
	s_cbranch_execz .LBB0_1229
	s_lshl_b32 s8, s8, 3
	s_lshr_b32 s9, s88, 2
	s_or_b32 s8, s8, s9
	s_ashr_i32 s9, s8, 31
	s_lshl_b64 s[8:9], s[8:9], 2
	v_readlane_b32 s33, v253, 62
	s_add_u32 s8, s33, s8
	v_readlane_b32 s33, v253, 63
	s_addc_u32 s9, s33, s9
	s_bcnt1_i32_b64 s33, s[66:67]
	v_mov_b32_e32 v0, s33
	global_atomic_add v177, v0, s[8:9]
	s_branch .LBB0_1229

; DEV u32x2 pk4(f32x4 v) { u32x2 r = {pk_bf16(v[0], v[1]), pk_bf16(v[2], v[3])}; return r; }
; DEV f32x4 unpk4(u32x2 u) { f32x4 r = {bf_lo(u[0]), bf_hi(u[0]), bf_lo(u[1]), bf_hi(u[1])}; return r; }
; DEV void tile_rows_in(const bf16_t* __restrict__ src0, const size_t ld, const int tid) {
; #pragma unroll 1
;   for (int io = 0; io < 4; ++io) {
;     u32x4 v[4];
; #pragma unroll
;     for (int ii = 0; ii < 4; ++ii) {
;       const int id = (io * 4 + ii) * 512 + tid, r = id >> 5, pos = id & 31, c = pos ^ (r & 31);
;   DEV void operator()(f32x4 (&acc)[2][2][4][2], int brow, int bcol, int wr, int wc, int fr, int fq) const {
;     ...
;     u32x2* sp = (u32x2*)mg + ((size_t)((brow >> 8) * 8 + (bcol >> 8)) * 32) * 512 + tid;
;     tile_rows_in(gates + (size_t)brow * 6144 + gidx * 2048 + bcol, 6144, tid);
;     __syncthreads();
; #pragma unroll
;     for (int ai = 0; ai < 2; ++ai)
; #pragma unroll
;       for (int m = 0; m < 4; ++m) {
;         const int rl = ai * 128 + wr * 64 + m * 16 + fr, tok = brow + rl;
; #pragma unroll
;         for (int bj = 0; bj < 2; ++bj)
; #pragma unroll
;           for (int n = 0; n < 2; ++n) {
;             const int cl = bj * 128 + wc * 32 + n * 16 + fq * 4, col = bcol + cl;
;             const int f = ((ai * 4 + m) * 2 + bj) * 2 + n;
;             const f32x4 g = unpk4(tile_get4(rl, cl));
;             f32x4 v = acc[ai][bj][m][n] * g;
;             if (step == 0) sp[(size_t)f * 512] = pk4(v);
;             else if (step == 1) sp[(size_t)f * 512] = pk4(unpk4(sp[(size_t)f * 512]) + v);
;             else tile_put4(rl, cl, pk4(unpk4(sp[(size_t)f * 512]) + v));
.LBB0_1291:
	s_or_b64 exec, exec, s[20:21]
	s_cmp_lt_i32 s37, 1
	s_cbranch_scc1 .Lp3_nopf
	v_readlane_b32 s22, v253, 10
	s_ashr_i32 s21, s4, 5
	s_and_b32 s21, s21, -8
	s_ashr_i32 s20, s34, 8
	s_add_i32 s20, s21, s20
	s_ashr_i32 s21, s20, 31
	s_lshl_b64 s[20:21], s[20:21], 17
	s_add_u32 s20, s76, s20
	s_addc_u32 s21, s22, s21
	v_lshlrev_b32_e32 v158, 3, v140
	global_load_dwordx2 v[160:161], v158, s[20:21]
	v_add_u32_e32 v158, 0x1000, v158
	global_load_dwordx2 v[162:163], v158, s[20:21]
	v_add_u32_e32 v158, 0x1000, v158
	global_load_dwordx2 v[164:165], v158, s[20:21]
	v_add_u32_e32 v158, 0x1000, v158
	global_load_dwordx2 v[166:167], v158, s[20:21]
	v_add_u32_e32 v158, 0x1000, v158
	global_load_dwordx2 v[168:169], v158, s[20:21]
	v_add_u32_e32 v158, 0x1000, v158
	global_load_dwordx2 v[170:171], v158, s[20:21]
	v_add_u32_e32 v158, 0x1000, v158
	global_load_dwordx2 v[172:173], v158, s[20:21]
	v_add_u32_e32 v158, 0x1000, v158
	global_load_dwordx2 v[174:175], v158, s[20:21]
	v_add_u32_e32 v158, 0x1000, v158
	global_load_dwordx2 v[184:185], v158, s[20:21]
	v_add_u32_e32 v158, 0x1000, v158
	global_load_dwordx2 v[186:187], v158, s[20:21]
	v_add_u32_e32 v158, 0x1000, v158
	global_load_dwordx2 v[188:189], v158, s[20:21]
	v_add_u32_e32 v158, 0x1000, v158
	global_load_dwordx2 v[190:191], v158, s[20:21]
	v_add_u32_e32 v158, 0x1000, v158
	global_load_dwordx2 v[192:193], v158, s[20:21]
	v_add_u32_e32 v158, 0x1000, v158
	global_load_dwordx2 v[194:195], v158, s[20:21]
	v_add_u32_e32 v158, 0x1000, v158
	global_load_dwordx2 v[196:197], v158, s[20:21]
	v_add_u32_e32 v158, 0x1000, v158
	global_load_dwordx2 v[200:201], v158, s[20:21]
	v_add_u32_e32 v158, 0x1000, v158
	global_load_dwordx2 v[202:203], v158, s[20:21]
	v_add_u32_e32 v158, 0x1000, v158
	global_load_dwordx2 v[204:205], v158, s[20:21]
	v_add_u32_e32 v158, 0x1000, v158
	global_load_dwordx2 v[206:207], v158, s[20:21]
	v_add_u32_e32 v158, 0x1000, v158
	global_load_dwordx2 v[208:209], v158, s[20:21]
	v_add_u32_e32 v158, 0x1000, v158
	global_load_dwordx2 v[210:211], v158, s[20:21]
	v_add_u32_e32 v158, 0x1000, v158
	global_load_dwordx2 v[212:213], v158, s[20:21]
	v_add_u32_e32 v158, 0x1000, v158
	global_load_dwordx2 v[214:215], v158, s[20:21]
	v_add_u32_e32 v158, 0x1000, v158
	global_load_dwordx2 v[216:217], v158, s[20:21]
	v_add_u32_e32 v158, 0x1000, v158
	global_load_dwordx2 v[224:225], v158, s[20:21]
	v_add_u32_e32 v158, 0x1000, v158
	global_load_dwordx2 v[226:227], v158, s[20:21]
	v_add_u32_e32 v158, 0x1000, v158
	global_load_dwordx2 v[228:229], v158, s[20:21]
	v_add_u32_e32 v158, 0x1000, v158
	global_load_dwordx2 v[230:231], v158, s[20:21]
	v_add_u32_e32 v158, 0x1000, v158
	global_load_dwordx2 v[232:233], v158, s[20:21]
	v_add_u32_e32 v158, 0x1000, v158
	global_load_dwordx2 v[234:235], v158, s[20:21]
	v_add_u32_e32 v158, 0x1000, v158
	global_load_dwordx2 v[236:237], v158, s[20:21]
	v_add_u32_e32 v158, 0x1000, v158
	global_load_dwordx2 v[238:239], v158, s[20:21]
.Lp3_nopf:
	s_and_b64 s[16:17], s[16:17], exec
	s_mov_b32 s16, s4
	s_mov_b32 s20, s34
	s_cselect_b32 s21, 0x1000, 0
	v_bfe_u32 v134, v140, 6, 2
	v_bfe_u32 v135, v140, 4, 2
	v_and_b32_e32 v128, 0xffffff00, v140
	v_lshlrev_b32_e32 v130, 6, v134
	v_lshlrev_b32_e32 v131, 4, v135
	s_ashr_i32 s17, s16, 31
	v_readlane_b32 s2, v253, 8
	v_and_b32_e32 v138, 15, v140
	v_or3_b32 v132, v130, v128, v131
	v_readlane_b32 s3, v253, 9
	s_and_b64 s[18:19], s[18:19], exec
	v_or_b32_e32 v128, v132, v138
	v_mov_b64_e32 v[130:131], s[2:3]
	s_cselect_b32 s18, 0x800, s21
	v_mad_i64_i32 v[130:131], s[24:25], s16, v220, v[130:131]
	s_lshl_b32 s92, s18, 1
	s_ashr_i32 s21, s20, 31
	v_lshlrev_b32_e32 v136, 4, v128
	v_lshl_add_u64 v[130:131], v[130:131], 0, s[92:93]
	s_lshl_b64 s[18:19], s[20:21], 1
	v_and_b32_e32 v133, 0x1f0, v136
	s_mov_b32 s22, 0
	v_lshrrev_b32_e32 v129, 4, v140
	v_lshl_add_u64 v[130:131], v[130:131], 0, s[18:19]
	v_add_u32_e32 v133, 0, v133
; DEV u32x2 pk4(f32x4 v) { u32x2 r = {pk_bf16(v[0], v[1]), pk_bf16(v[2], v[3])}; return r; }
; DEV f32x4 unpk4(u32x2 u) { f32x4 r = {bf_lo(u[0]), bf_hi(u[0]), bf_lo(u[1]), bf_hi(u[1])}; return r; }
; DEV void tile_rows_in(const bf16_t* __restrict__ src0, const size_t ld, const int tid) {
; #pragma unroll 1
;   for (int io = 0; io < 4; ++io) {
;     u32x4 v[4];
; #pragma unroll
;     for (int ii = 0; ii < 4; ++ii) {
;       const int id = (io * 4 + ii) * 512 + tid, r = id >> 5, pos = id & 31, c = pos ^ (r & 31);
;       v[ii] = __builtin_nontemporal_load((const u32x4*)(src0 + (size_t)r * ld + 8 * c));
;     }
; #pragma unroll
;     for (int ii = 0; ii < 4; ++ii) {
;       const int id = (io * 4 + ii) * 512 + tid, r = id >> 5, pos = id & 31;
;       *(u32x4*)(smem + r * 512 + pos * 16) = v[ii];
;     }
;   }
; }
;   DEV void operator()(f32x4 (&acc)[2][2][4][2], int brow, int bcol, int wr, int wc, int fr, int fq) const {
;     ...
;     tile_rows_in(gates + (size_t)brow * 6144 + gidx * 2048 + bcol, 6144, tid);
;     __syncthreads();
; #pragma unroll
;     for (int ai = 0; ai < 2; ++ai)
; #pragma unroll
;       for (int m = 0; m < 4; ++m) {
;         const int rl = ai * 128 + wr * 64 + m * 16 + fr, tok = brow + rl;
; #pragma unroll
;         for (int bj = 0; bj < 2; ++bj)
; #pragma unroll
;           for (int n = 0; n < 2; ++n) {
;             const int cl = bj * 128 + wc * 32 + n * 16 + fq * 4, col = bcol + cl;
;             const int f = ((ai * 4 + m) * 2 + bj) * 2 + n;
;             const f32x4 g = unpk4(tile_get4(rl, cl));
;             f32x4 v = acc[ai][bj][m][n] * g;
;             if (step == 0) sp[(size_t)f * 512] = pk4(v);
;             else if (step == 1) sp[(size_t)f * 512] = pk4(unpk4(sp[(size_t)f * 512]) + v);
;             else tile_put4(rl, cl, pk4(unpk4(sp[(size_t)f * 512]) + v));
.LBB0_1292:
	v_add_u32_e32 v137, s22, v128
	v_ashrrev_i32_e32 v139, 5, v137
	v_add_u32_e32 v141, 0x200, v137
	v_add_u32_e32 v144, 0x400, v137
	v_add_u32_e32 v137, 0x600, v137
	v_xor_b32_e32 v145, v139, v128
	v_mad_i64_i32 v[142:143], s[24:25], v139, s73, v[130:131]
	v_ashrrev_i32_e32 v139, 5, v141
	v_ashrrev_i32_e32 v141, 5, v144
	v_ashrrev_i32_e32 v137, 5, v137
	v_lshlrev_b32_e32 v146, 4, v145
	v_xor_b32_e32 v147, v139, v128
	v_mad_i64_i32 v[144:145], s[24:25], v139, s73, v[130:131]
	v_xor_b32_e32 v139, v141, v128
	v_mad_i64_i32 v[150:151], s[24:25], v141, s73, v[130:131]
	v_xor_b32_e32 v141, v137, v128
	v_mad_i64_i32 v[152:153], s[24:25], v137, s73, v[130:131]
	v_and_b32_e32 v176, 0x1f0, v146
	v_lshlrev_b32_e32 v137, 4, v147
	v_lshlrev_b32_e32 v139, 4, v139
	v_lshl_add_u64 v[142:143], v[142:143], 0, v[176:177]
	v_and_b32_e32 v176, 0x1f0, v137
	v_lshlrev_b32_e32 v141, 4, v141
	v_lshl_add_u64 v[146:147], v[144:145], 0, v[176:177]
	v_and_b32_e32 v176, 0x1f0, v139
	v_lshl_add_u64 v[150:151], v[150:151], 0, v[176:177]
	v_and_b32_e32 v176, 0x1f0, v141
	v_lshl_add_u64 v[154:155], v[152:153], 0, v[176:177]
	global_load_dwordx4 v[142:145], v[142:143], off nt
	s_nop 0
	global_load_dwordx4 v[146:149], v[146:147], off nt
	s_nop 0
	global_load_dwordx4 v[150:153], v[150:151], off nt
	s_nop 0
	global_load_dwordx4 v[154:157], v[154:155], off nt
	v_and_b32_e32 v137, 0xfffffe00, v136
	s_addk_i32 s22, 0x800
	v_add_u32_e32 v136, 0x8000, v136
	v_add_u32_e32 v137, v133, v137
	s_cmpk_lg_i32 s22, 0x2000
	s_waitcnt vmcnt(0)
	ds_write_b128 v137, v[142:145]
	ds_write_b128 v137, v[146:149] offset:8192
	ds_write_b128 v137, v[150:153] offset:16384
	ds_write_b128 v137, v[154:157] offset:24576
	s_cbranch_scc1 .LBB0_1292
	v_lshlrev_b32_e32 v131, 2, v135
	v_lshrrev_b32_e32 v130, 2, v140
	s_mov_b32 s22, 0x7fffc0
	v_lshl_or_b32 v131, v134, 5, v131
	v_and_or_b32 v130, v130, s22, v138
	v_lshrrev_b32_e32 v139, 3, v131
	v_lshl_add_u32 v135, v130, 9, 0
	v_xor_b32_e32 v130, v139, v138
	v_lshlrev_b32_e32 v136, 4, v130
	v_lshlrev_b32_e32 v129, 3, v129
	v_add_u32_e32 v130, v135, v136
	v_and_b32_e32 v134, 8, v129
	s_ashr_i32 s21, s16, 5
	v_add_u32_e32 v137, v130, v134
	s_waitcnt lgkmcnt(0)
	s_barrier
	s_and_b32 s21, s21, -8
	s_ashr_i32 s20, s20, 8
	ds_read_b64 v[140:141], v137
	s_add_i32 s20, s21, s20
	s_ashr_i32 s21, s20, 31
	s_lshl_b64 s[20:21], s[20:21], 17
	s_add_u32 s20, s76, s20
	v_readlane_b32 s22, v253, 10
	v_ashrrev_i32_e32 v129, 31, v128
	s_addc_u32 s21, s22, s21
	s_waitcnt lgkmcnt(0)
	v_lshlrev_b32_e32 v142, 16, v140
	v_and_b32_e32 v143, 0xffff0000, v140
	v_lshlrev_b32_e32 v140, 16, v141
	v_and_b32_e32 v141, 0xffff0000, v141
	v_lshl_add_u64 v[130:131], v[128:129], 3, s[20:21]
	v_pk_mul_f32 v[126:127], v[126:127], v[140:141]
	v_pk_mul_f32 v[124:125], v[124:125], v[142:143]
	s_cmp_lt_i32 s37, 1
	s_mov_b64 s[20:21], -1
	s_cbranch_scc1 .LBB0_1299
	s_cmp_lg_u32 s37, 1
	s_cbranch_scc0 .LBB0_1296
	v_mov_b32_e32 v140, v160
	v_mov_b32_e32 v141, v161
	s_mov_b64 s[20:21], 0
	v_lshlrev_b32_e32 v142, 16, v140
	v_and_b32_e32 v143, 0xffff0000, v140
	v_lshlrev_b32_e32 v140, 16, v141
	v_and_b32_e32 v141, 0xffff0000, v141
	v_pk_add_f32 v[140:141], v[126:127], v[140:141]
	v_pk_add_f32 v[142:143], v[124:125], v[142:143]
	s_nop 0
	v_cvt_pk_bf16_f32 v142, v142, v143
	v_cvt_pk_bf16_f32 v143, v140, v141
	ds_write_b64 v137, v[142:143]
.LBB0_1296:
	s_andn2_b64 vcc, exec, s[20:21]
	s_cbranch_vccnz .LBB0_1298
	v_mov_b32_e32 v140, v160
	v_mov_b32_e32 v141, v161
	v_lshlrev_b32_e32 v142, 16, v140
	v_and_b32_e32 v143, 0xffff0000, v140
	v_lshlrev_b32_e32 v140, 16, v141
	v_and_b32_e32 v141, 0xffff0000, v141
	v_pk_add_f32 v[140:141], v[126:127], v[140:141]
	v_pk_add_f32 v[142:143], v[124:125], v[142:143]
	s_nop 0
	v_cvt_pk_bf16_f32 v142, v142, v143
	v_cvt_pk_bf16_f32 v143, v140, v141
	global_store_dwordx2 v[130:131], v[142:143], off

; DEV u32x2 pk4(f32x4 v) { u32x2 r = {pk_bf16(v[0], v[1]), pk_bf16(v[2], v[3])}; return r; }
; DEV f32x4 unpk4(u32x2 u) { f32x4 r = {bf_lo(u[0]), bf_hi(u[0]), bf_lo(u[1]), bf_hi(u[1])}; return r; }
;   DEV void operator()(f32x4 (&acc)[2][2][4][2], int brow, int bcol, int wr, int wc, int fr, int fq) const {
;     ...
;             const int cl = bj * 128 + wc * 32 + n * 16 + fq * 4, col = bcol + cl;
;             const int f = ((ai * 4 + m) * 2 + bj) * 2 + n;
;             const f32x4 g = unpk4(tile_get4(rl, cl));
;             f32x4 v = acc[ai][bj][m][n] * g;
;             if (step == 0) sp[(size_t)f * 512] = pk4(v);
;             else if (step == 1) sp[(size_t)f * 512] = pk4(unpk4(sp[(size_t)f * 512]) + v);
;             else tile_put4(rl, cl, pk4(unpk4(sp[(size_t)f * 512]) + v));
.LBB0_1301:
	v_bitop3_b32 v124, v139, v138, 2 bitop3:0x36
	v_lshlrev_b32_e32 v124, 4, v124
	v_add_u32_e32 v125, v135, v124
	v_add_u32_e32 v125, v125, v134
	ds_read_b64 v[126:127], v125
	s_cmp_lt_i32 s37, 1
	s_mov_b64 s[20:21], -1
	s_waitcnt lgkmcnt(0)
	v_lshlrev_b32_e32 v140, 16, v126
	v_and_b32_e32 v141, 0xffff0000, v126
	v_lshlrev_b32_e32 v126, 16, v127
	v_and_b32_e32 v127, 0xffff0000, v127
	v_pk_mul_f32 v[122:123], v[122:123], v[126:127]
	v_pk_mul_f32 v[120:121], v[120:121], v[140:141]
	s_cbranch_scc1 .LBB0_1307
	s_cmp_lg_u32 s37, 1
	s_cbranch_scc0 .LBB0_1304
	v_add_co_u32_e32 v126, vcc, 0x1000, v130
	s_mov_b64 s[20:21], 0
	s_nop 0
	v_addc_co_u32_e32 v127, vcc, 0, v131, vcc
	v_mov_b32_e32 v126, v162
	v_mov_b32_e32 v127, v163
	v_lshlrev_b32_e32 v140, 16, v126
	v_and_b32_e32 v141, 0xffff0000, v126
	v_lshlrev_b32_e32 v126, 16, v127
	v_and_b32_e32 v127, 0xffff0000, v127
	v_pk_add_f32 v[126:127], v[122:123], v[126:127]
	v_pk_add_f32 v[140:141], v[120:121], v[140:141]
	s_nop 0
	v_cvt_pk_bf16_f32 v140, v140, v141
	v_cvt_pk_bf16_f32 v141, v126, v127
	ds_write_b64 v125, v[140:141]
.LBB0_1304:
	s_andn2_b64 vcc, exec, s[20:21]
	s_cbranch_vccnz .LBB0_1306
	v_add_co_u32_e32 v126, vcc, 0x1000, v130
	s_nop 1
	v_addc_co_u32_e32 v127, vcc, 0, v131, vcc
	v_mov_b32_e32 v140, v162
	v_mov_b32_e32 v141, v163
	v_lshlrev_b32_e32 v142, 16, v140
	v_and_b32_e32 v143, 0xffff0000, v140
	v_lshlrev_b32_e32 v140, 16, v141
	v_and_b32_e32 v141, 0xffff0000, v141
	v_pk_add_f32 v[140:141], v[122:123], v[140:141]
	v_pk_add_f32 v[142:143], v[120:121], v[142:143]
	s_nop 0
	v_cvt_pk_bf16_f32 v142, v142, v143
	v_cvt_pk_bf16_f32 v143, v140, v141
	global_store_dwordx2 v[126:127], v[142:143], off

; DEV u32x2 pk4(f32x4 v) { u32x2 r = {pk_bf16(v[0], v[1]), pk_bf16(v[2], v[3])}; return r; }
; DEV f32x4 unpk4(u32x2 u) { f32x4 r = {bf_lo(u[0]), bf_hi(u[0]), bf_lo(u[1]), bf_hi(u[1])}; return r; }
;   DEV void operator()(f32x4 (&acc)[2][2][4][2], int brow, int bcol, int wr, int wc, int fr, int fq) const {
;     ...
;             const int cl = bj * 128 + wc * 32 + n * 16 + fq * 4, col = bcol + cl;
;             const int f = ((ai * 4 + m) * 2 + bj) * 2 + n;
;             const f32x4 g = unpk4(tile_get4(rl, cl));
;             f32x4 v = acc[ai][bj][m][n] * g;
;             if (step == 0) sp[(size_t)f * 512] = pk4(v);
;             else if (step == 1) sp[(size_t)f * 512] = pk4(unpk4(sp[(size_t)f * 512]) + v);
;             else tile_put4(rl, cl, pk4(unpk4(sp[(size_t)f * 512]) + v));
.LBB0_1309:
	v_bitop3_b32 v120, v139, v138, 16 bitop3:0x36
	v_lshlrev_b32_e32 v120, 4, v120
	v_add_u32_e32 v121, v135, v120
	v_add_u32_e32 v121, v121, v134
	ds_read_b64 v[126:127], v121
	v_or_b32_e32 v122, 2, v139
	s_cmp_lt_i32 s37, 1
	s_mov_b64 s[20:21], -1
	s_waitcnt lgkmcnt(0)
	v_lshlrev_b32_e32 v140, 16, v126
	v_and_b32_e32 v141, 0xffff0000, v126
	v_lshlrev_b32_e32 v126, 16, v127
	v_and_b32_e32 v127, 0xffff0000, v127
	v_pk_mul_f32 v[118:119], v[118:119], v[126:127]
	v_pk_mul_f32 v[116:117], v[116:117], v[140:141]
	s_cbranch_scc1 .LBB0_1315
	s_cmp_lg_u32 s37, 1
	s_cbranch_scc0 .LBB0_1312
	v_add_co_u32_e32 v126, vcc, 0x2000, v130
	s_mov_b64 s[20:21], 0
	s_nop 0
	v_addc_co_u32_e32 v127, vcc, 0, v131, vcc
	v_mov_b32_e32 v126, v164
	v_mov_b32_e32 v127, v165
	v_lshlrev_b32_e32 v140, 16, v126
	v_and_b32_e32 v141, 0xffff0000, v126
	v_lshlrev_b32_e32 v126, 16, v127
	v_and_b32_e32 v127, 0xffff0000, v127
	v_pk_add_f32 v[126:127], v[118:119], v[126:127]
	v_pk_add_f32 v[140:141], v[116:117], v[140:141]
	s_nop 0
	v_cvt_pk_bf16_f32 v140, v140, v141
	v_cvt_pk_bf16_f32 v141, v126, v127
	ds_write_b64 v121, v[140:141]
.LBB0_1312:
	s_andn2_b64 vcc, exec, s[20:21]
	s_cbranch_vccnz .LBB0_1314
	v_add_co_u32_e32 v126, vcc, 0x2000, v130
	s_nop 1
	v_addc_co_u32_e32 v127, vcc, 0, v131, vcc
	v_mov_b32_e32 v140, v164
	v_mov_b32_e32 v141, v165
	v_lshlrev_b32_e32 v142, 16, v140
	v_and_b32_e32 v143, 0xffff0000, v140
	v_lshlrev_b32_e32 v140, 16, v141
	v_and_b32_e32 v141, 0xffff0000, v141
	v_pk_add_f32 v[140:141], v[118:119], v[140:141]
	v_pk_add_f32 v[142:143], v[116:117], v[142:143]
	s_nop 0
	v_cvt_pk_bf16_f32 v142, v142, v143
	v_cvt_pk_bf16_f32 v143, v140, v141
	global_store_dwordx2 v[126:127], v[142:143], off

; DEV u32x2 pk4(f32x4 v) { u32x2 r = {pk_bf16(v[0], v[1]), pk_bf16(v[2], v[3])}; return r; }
; DEV f32x4 unpk4(u32x2 u) { f32x4 r = {bf_lo(u[0]), bf_hi(u[0]), bf_lo(u[1]), bf_hi(u[1])}; return r; }
;   DEV void operator()(f32x4 (&acc)[2][2][4][2], int brow, int bcol, int wr, int wc, int fr, int fq) const {
;     ...
;             const int cl = bj * 128 + wc * 32 + n * 16 + fq * 4, col = bcol + cl;
;             const int f = ((ai * 4 + m) * 2 + bj) * 2 + n;
;             const f32x4 g = unpk4(tile_get4(rl, cl));
;             f32x4 v = acc[ai][bj][m][n] * g;
;             if (step == 0) sp[(size_t)f * 512] = pk4(v);
;             else if (step == 1) sp[(size_t)f * 512] = pk4(unpk4(sp[(size_t)f * 512]) + v);
;             else tile_put4(rl, cl, pk4(unpk4(sp[(size_t)f * 512]) + v));
.LBB0_1317:
	v_bitop3_b32 v116, v139, v138, 18 bitop3:0x36
	v_lshlrev_b32_e32 v116, 4, v116
	v_add_u32_e32 v117, v135, v116
	v_add_u32_e32 v117, v117, v134
	ds_read_b64 v[126:127], v117
	v_or_b32_e32 v118, 16, v139
	s_cmp_lt_i32 s37, 1
	s_mov_b64 s[20:21], -1
	s_waitcnt lgkmcnt(0)
	v_lshlrev_b32_e32 v140, 16, v126
	v_and_b32_e32 v141, 0xffff0000, v126
	v_lshlrev_b32_e32 v126, 16, v127
	v_and_b32_e32 v127, 0xffff0000, v127
	v_pk_mul_f32 v[114:115], v[114:115], v[126:127]
	v_pk_mul_f32 v[112:113], v[112:113], v[140:141]
	s_cbranch_scc1 .LBB0_1323
	s_cmp_lg_u32 s37, 1
	s_cbranch_scc0 .LBB0_1320
	v_add_co_u32_e32 v126, vcc, 0x3000, v130
	s_mov_b64 s[20:21], 0
	s_nop 0
	v_addc_co_u32_e32 v127, vcc, 0, v131, vcc
	v_mov_b32_e32 v126, v166
	v_mov_b32_e32 v127, v167
	v_lshlrev_b32_e32 v140, 16, v126
	v_and_b32_e32 v141, 0xffff0000, v126
	v_lshlrev_b32_e32 v126, 16, v127
	v_and_b32_e32 v127, 0xffff0000, v127
	v_pk_add_f32 v[126:127], v[114:115], v[126:127]
	v_pk_add_f32 v[140:141], v[112:113], v[140:141]
	s_nop 0
	v_cvt_pk_bf16_f32 v140, v140, v141
	v_cvt_pk_bf16_f32 v141, v126, v127
	ds_write_b64 v117, v[140:141]
.LBB0_1320:
	s_andn2_b64 vcc, exec, s[20:21]
	s_cbranch_vccnz .LBB0_1322
	v_add_co_u32_e32 v126, vcc, 0x3000, v130
	s_nop 1
	v_addc_co_u32_e32 v127, vcc, 0, v131, vcc
	v_mov_b32_e32 v140, v166
	v_mov_b32_e32 v141, v167
	v_lshlrev_b32_e32 v142, 16, v140
	v_and_b32_e32 v143, 0xffff0000, v140
	v_lshlrev_b32_e32 v140, 16, v141
	v_and_b32_e32 v141, 0xffff0000, v141
	v_pk_add_f32 v[140:141], v[114:115], v[140:141]
	v_pk_add_f32 v[142:143], v[112:113], v[142:143]
	s_nop 0
	v_cvt_pk_bf16_f32 v142, v142, v143
	v_cvt_pk_bf16_f32 v143, v140, v141
	global_store_dwordx2 v[126:127], v[142:143], off

; DEV u32x2 pk4(f32x4 v) { u32x2 r = {pk_bf16(v[0], v[1]), pk_bf16(v[2], v[3])}; return r; }
; DEV f32x4 unpk4(u32x2 u) { f32x4 r = {bf_lo(u[0]), bf_hi(u[0]), bf_lo(u[1]), bf_hi(u[1])}; return r; }
;   DEV void operator()(f32x4 (&acc)[2][2][4][2], int brow, int bcol, int wr, int wc, int fr, int fq) const {
;     ...
;             const int cl = bj * 128 + wc * 32 + n * 16 + fq * 4, col = bcol + cl;
;             const int f = ((ai * 4 + m) * 2 + bj) * 2 + n;
;             const f32x4 g = unpk4(tile_get4(rl, cl));
;             f32x4 v = acc[ai][bj][m][n] * g;
;             if (step == 0) sp[(size_t)f * 512] = pk4(v);
;             else if (step == 1) sp[(size_t)f * 512] = pk4(unpk4(sp[(size_t)f * 512]) + v);
;             else tile_put4(rl, cl, pk4(unpk4(sp[(size_t)f * 512]) + v));
.LBB0_1325:
	v_bitop3_b32 v112, v139, v138, 16 bitop3:0x1e
	v_lshlrev_b32_e32 v112, 4, v112
	v_add_u32_e32 v113, v135, v112
	v_add_u32_e32 v113, v113, v134
	ds_read_b64 v[126:127], v113 offset:8192
	v_or_b32_e32 v114, 18, v139
	s_cmp_lt_i32 s37, 1
	s_mov_b64 s[20:21], -1
	s_waitcnt lgkmcnt(0)
	v_lshlrev_b32_e32 v140, 16, v126
	v_and_b32_e32 v141, 0xffff0000, v126
	v_lshlrev_b32_e32 v126, 16, v127
	v_and_b32_e32 v127, 0xffff0000, v127
	v_pk_mul_f32 v[110:111], v[110:111], v[126:127]
	v_pk_mul_f32 v[108:109], v[108:109], v[140:141]
	s_cbranch_scc1 .LBB0_1331
	s_cmp_lg_u32 s37, 1
	s_cbranch_scc0 .LBB0_1328
	v_add_co_u32_e32 v126, vcc, 0x4000, v130
	s_mov_b64 s[20:21], 0
	s_nop 0
	v_addc_co_u32_e32 v127, vcc, 0, v131, vcc
	v_mov_b32_e32 v126, v168
	v_mov_b32_e32 v127, v169
	v_lshlrev_b32_e32 v140, 16, v126
	v_and_b32_e32 v141, 0xffff0000, v126
	v_lshlrev_b32_e32 v126, 16, v127
	v_and_b32_e32 v127, 0xffff0000, v127
	v_pk_add_f32 v[126:127], v[110:111], v[126:127]
	v_pk_add_f32 v[140:141], v[108:109], v[140:141]
	s_nop 0
	v_cvt_pk_bf16_f32 v140, v140, v141
	v_cvt_pk_bf16_f32 v141, v126, v127
	ds_write_b64 v113, v[140:141] offset:8192
.LBB0_1328:
	s_andn2_b64 vcc, exec, s[20:21]
	s_cbranch_vccnz .LBB0_1330
	v_add_co_u32_e32 v126, vcc, 0x4000, v130
	s_nop 1
	v_addc_co_u32_e32 v127, vcc, 0, v131, vcc
	v_mov_b32_e32 v140, v168
	v_mov_b32_e32 v141, v169
	v_lshlrev_b32_e32 v142, 16, v140
	v_and_b32_e32 v143, 0xffff0000, v140
	v_lshlrev_b32_e32 v140, 16, v141
	v_and_b32_e32 v141, 0xffff0000, v141
	v_pk_add_f32 v[140:141], v[110:111], v[140:141]
	v_pk_add_f32 v[142:143], v[108:109], v[142:143]
	s_nop 0
	v_cvt_pk_bf16_f32 v142, v142, v143
	v_cvt_pk_bf16_f32 v143, v140, v141
	global_store_dwordx2 v[126:127], v[142:143], off

; DEV u32x2 pk4(f32x4 v) { u32x2 r = {pk_bf16(v[0], v[1]), pk_bf16(v[2], v[3])}; return r; }
; DEV f32x4 unpk4(u32x2 u) { f32x4 r = {bf_lo(u[0]), bf_hi(u[0]), bf_lo(u[1]), bf_hi(u[1])}; return r; }
;   DEV void operator()(f32x4 (&acc)[2][2][4][2], int brow, int bcol, int wr, int wc, int fr, int fq) const {
;     ...
;             const int cl = bj * 128 + wc * 32 + n * 16 + fq * 4, col = bcol + cl;
;             const int f = ((ai * 4 + m) * 2 + bj) * 2 + n;
;             const f32x4 g = unpk4(tile_get4(rl, cl));
;             f32x4 v = acc[ai][bj][m][n] * g;
;             if (step == 0) sp[(size_t)f * 512] = pk4(v);
;             else if (step == 1) sp[(size_t)f * 512] = pk4(unpk4(sp[(size_t)f * 512]) + v);
;             else tile_put4(rl, cl, pk4(unpk4(sp[(size_t)f * 512]) + v));
.LBB0_1333:
	v_or_b32_e32 v110, 16, v138
	v_xor_b32_e32 v108, v122, v110
	v_lshlrev_b32_e32 v108, 4, v108
	v_add_u32_e32 v109, v135, v108
	v_add_u32_e32 v109, v109, v134
	ds_read_b64 v[122:123], v109 offset:8192
	s_cmp_lt_i32 s37, 1
	s_mov_b64 s[20:21], -1
	s_waitcnt lgkmcnt(0)
	v_lshlrev_b32_e32 v126, 16, v122
	v_and_b32_e32 v127, 0xffff0000, v122
	v_lshlrev_b32_e32 v122, 16, v123
	v_and_b32_e32 v123, 0xffff0000, v123
	v_pk_mul_f32 v[106:107], v[106:107], v[122:123]
	v_pk_mul_f32 v[104:105], v[104:105], v[126:127]
	s_cbranch_scc1 .LBB0_1339
	s_cmp_lg_u32 s37, 1
	s_cbranch_scc0 .LBB0_1336
	v_add_co_u32_e32 v122, vcc, 0x5000, v130
	s_mov_b64 s[20:21], 0
	s_nop 0
	v_addc_co_u32_e32 v123, vcc, 0, v131, vcc
	v_mov_b32_e32 v122, v170
	v_mov_b32_e32 v123, v171
	v_lshlrev_b32_e32 v126, 16, v122
	v_and_b32_e32 v127, 0xffff0000, v122
	v_lshlrev_b32_e32 v122, 16, v123
	v_and_b32_e32 v123, 0xffff0000, v123
	v_pk_add_f32 v[122:123], v[106:107], v[122:123]
	v_pk_add_f32 v[126:127], v[104:105], v[126:127]
	s_nop 0
	v_cvt_pk_bf16_f32 v126, v126, v127
	v_cvt_pk_bf16_f32 v127, v122, v123
	ds_write_b64 v109, v[126:127] offset:8192
.LBB0_1336:
	s_andn2_b64 vcc, exec, s[20:21]
	s_cbranch_vccnz .LBB0_1338
	v_add_co_u32_e32 v122, vcc, 0x5000, v130
	s_nop 1
	v_addc_co_u32_e32 v123, vcc, 0, v131, vcc
	v_mov_b32_e32 v126, v170
	v_mov_b32_e32 v127, v171
	v_lshlrev_b32_e32 v138, 16, v126
	v_and_b32_e32 v139, 0xffff0000, v126
	v_lshlrev_b32_e32 v126, 16, v127
	v_and_b32_e32 v127, 0xffff0000, v127
	v_pk_add_f32 v[126:127], v[106:107], v[126:127]
	v_pk_add_f32 v[138:139], v[104:105], v[138:139]
	s_nop 0
	v_cvt_pk_bf16_f32 v138, v138, v139
	v_cvt_pk_bf16_f32 v139, v126, v127
	global_store_dwordx2 v[122:123], v[138:139], off

; DEV u32x2 pk4(f32x4 v) { u32x2 r = {pk_bf16(v[0], v[1]), pk_bf16(v[2], v[3])}; return r; }
; DEV f32x4 unpk4(u32x2 u) { f32x4 r = {bf_lo(u[0]), bf_hi(u[0]), bf_lo(u[1]), bf_hi(u[1])}; return r; }
;   DEV void operator()(f32x4 (&acc)[2][2][4][2], int brow, int bcol, int wr, int wc, int fr, int fq) const {
;     ...
;             const int cl = bj * 128 + wc * 32 + n * 16 + fq * 4, col = bcol + cl;
;             const int f = ((ai * 4 + m) * 2 + bj) * 2 + n;
;             const f32x4 g = unpk4(tile_get4(rl, cl));
;             f32x4 v = acc[ai][bj][m][n] * g;
;             if (step == 0) sp[(size_t)f * 512] = pk4(v);
;             else if (step == 1) sp[(size_t)f * 512] = pk4(unpk4(sp[(size_t)f * 512]) + v);
;             else tile_put4(rl, cl, pk4(unpk4(sp[(size_t)f * 512]) + v));
.LBB0_1341:
	v_xor_b32_e32 v104, v118, v110
	v_lshlrev_b32_e32 v104, 4, v104
	v_add_u32_e32 v105, v135, v104
	v_add_u32_e32 v105, v105, v134
	ds_read_b64 v[106:107], v105 offset:8192
	s_cmp_lt_i32 s37, 1
	s_mov_b64 s[20:21], -1
	s_waitcnt lgkmcnt(0)
	v_lshlrev_b32_e32 v118, 16, v106
	v_and_b32_e32 v119, 0xffff0000, v106
	v_lshlrev_b32_e32 v106, 16, v107
	v_and_b32_e32 v107, 0xffff0000, v107
	v_pk_mul_f32 v[102:103], v[102:103], v[106:107]
	v_pk_mul_f32 v[100:101], v[100:101], v[118:119]
	s_cbranch_scc1 .LBB0_1347
	s_cmp_lg_u32 s37, 1
	s_cbranch_scc0 .LBB0_1344
	v_add_co_u32_e32 v106, vcc, 0x6000, v130
	s_mov_b64 s[20:21], 0
	s_nop 0
	v_addc_co_u32_e32 v107, vcc, 0, v131, vcc
	v_mov_b32_e32 v106, v172
	v_mov_b32_e32 v107, v173
	v_lshlrev_b32_e32 v118, 16, v106
	v_and_b32_e32 v119, 0xffff0000, v106
	v_lshlrev_b32_e32 v106, 16, v107
	v_and_b32_e32 v107, 0xffff0000, v107
	v_pk_add_f32 v[106:107], v[102:103], v[106:107]
	v_pk_add_f32 v[118:119], v[100:101], v[118:119]
	s_nop 0
	v_cvt_pk_bf16_f32 v118, v118, v119
	v_cvt_pk_bf16_f32 v119, v106, v107
	ds_write_b64 v105, v[118:119] offset:8192
.LBB0_1344:
	s_andn2_b64 vcc, exec, s[20:21]
	s_cbranch_vccnz .LBB0_1346
	v_add_co_u32_e32 v106, vcc, 0x6000, v130
	s_nop 1
	v_addc_co_u32_e32 v107, vcc, 0, v131, vcc
	v_mov_b32_e32 v118, v172
	v_mov_b32_e32 v119, v173
	v_lshlrev_b32_e32 v122, 16, v118
	v_and_b32_e32 v123, 0xffff0000, v118
	v_lshlrev_b32_e32 v118, 16, v119
	v_and_b32_e32 v119, 0xffff0000, v119
	v_pk_add_f32 v[118:119], v[102:103], v[118:119]
	v_pk_add_f32 v[122:123], v[100:101], v[122:123]
	s_nop 0
	v_cvt_pk_bf16_f32 v122, v122, v123
	v_cvt_pk_bf16_f32 v123, v118, v119
	global_store_dwordx2 v[106:107], v[122:123], off

; DEV u32x2 pk4(f32x4 v) { u32x2 r = {pk_bf16(v[0], v[1]), pk_bf16(v[2], v[3])}; return r; }
; DEV f32x4 unpk4(u32x2 u) { f32x4 r = {bf_lo(u[0]), bf_hi(u[0]), bf_lo(u[1]), bf_hi(u[1])}; return r; }
;   DEV void operator()(f32x4 (&acc)[2][2][4][2], int brow, int bcol, int wr, int wc, int fr, int fq) const {
;     ...
;             const int cl = bj * 128 + wc * 32 + n * 16 + fq * 4, col = bcol + cl;
;             const int f = ((ai * 4 + m) * 2 + bj) * 2 + n;
;             const f32x4 g = unpk4(tile_get4(rl, cl));
;             f32x4 v = acc[ai][bj][m][n] * g;
;             if (step == 0) sp[(size_t)f * 512] = pk4(v);
;             else if (step == 1) sp[(size_t)f * 512] = pk4(unpk4(sp[(size_t)f * 512]) + v);
;             else tile_put4(rl, cl, pk4(unpk4(sp[(size_t)f * 512]) + v));
.LBB0_1349:
	v_xor_b32_e32 v100, v114, v110
	v_lshlrev_b32_e32 v100, 4, v100
	v_add_u32_e32 v101, v135, v100
	v_add_u32_e32 v101, v101, v134
	ds_read_b64 v[102:103], v101 offset:8192
	s_cmp_lt_i32 s37, 1
	s_mov_b64 s[20:21], -1
	s_waitcnt lgkmcnt(0)
	v_lshlrev_b32_e32 v106, 16, v102
	v_and_b32_e32 v107, 0xffff0000, v102
	v_lshlrev_b32_e32 v102, 16, v103
	v_and_b32_e32 v103, 0xffff0000, v103
	v_pk_mul_f32 v[98:99], v[98:99], v[102:103]
	v_pk_mul_f32 v[96:97], v[96:97], v[106:107]
	s_cbranch_scc1 .LBB0_1355
	s_cmp_lg_u32 s37, 1
	s_cbranch_scc0 .LBB0_1352
	v_add_co_u32_e32 v102, vcc, 0x7000, v130
	s_mov_b64 s[20:21], 0
	s_nop 0
	v_addc_co_u32_e32 v103, vcc, 0, v131, vcc
	v_mov_b32_e32 v102, v174
	v_mov_b32_e32 v103, v175
	v_lshlrev_b32_e32 v106, 16, v102
	v_and_b32_e32 v107, 0xffff0000, v102
	v_lshlrev_b32_e32 v102, 16, v103
	v_and_b32_e32 v103, 0xffff0000, v103
	v_pk_add_f32 v[102:103], v[98:99], v[102:103]
	v_pk_add_f32 v[106:107], v[96:97], v[106:107]
	s_nop 0
	v_cvt_pk_bf16_f32 v106, v106, v107
	v_cvt_pk_bf16_f32 v107, v102, v103
	ds_write_b64 v101, v[106:107] offset:8192
.LBB0_1352:
	s_andn2_b64 vcc, exec, s[20:21]
	s_cbranch_vccnz .LBB0_1354
	v_add_co_u32_e32 v102, vcc, 0x7000, v130
	s_nop 1
	v_addc_co_u32_e32 v103, vcc, 0, v131, vcc
	v_mov_b32_e32 v106, v174
	v_mov_b32_e32 v107, v175
	v_lshlrev_b32_e32 v110, 16, v106
	v_and_b32_e32 v111, 0xffff0000, v106
	v_lshlrev_b32_e32 v106, 16, v107
	v_and_b32_e32 v107, 0xffff0000, v107
	v_pk_add_f32 v[106:107], v[98:99], v[106:107]
	v_pk_add_f32 v[110:111], v[96:97], v[110:111]
	s_nop 0
	v_cvt_pk_bf16_f32 v110, v110, v111
	v_cvt_pk_bf16_f32 v111, v106, v107
	global_store_dwordx2 v[102:103], v[110:111], off

; DEV u32x2 pk4(f32x4 v) { u32x2 r = {pk_bf16(v[0], v[1]), pk_bf16(v[2], v[3])}; return r; }
; DEV f32x4 unpk4(u32x2 u) { f32x4 r = {bf_lo(u[0]), bf_hi(u[0]), bf_lo(u[1]), bf_hi(u[1])}; return r; }
;   DEV void operator()(f32x4 (&acc)[2][2][4][2], int brow, int bcol, int wr, int wc, int fr, int fq) const {
;     ...
;             const int cl = bj * 128 + wc * 32 + n * 16 + fq * 4, col = bcol + cl;
;             const int f = ((ai * 4 + m) * 2 + bj) * 2 + n;
;             const f32x4 g = unpk4(tile_get4(rl, cl));
;             f32x4 v = acc[ai][bj][m][n] * g;
;             if (step == 0) sp[(size_t)f * 512] = pk4(v);
;             else if (step == 1) sp[(size_t)f * 512] = pk4(unpk4(sp[(size_t)f * 512]) + v);
;             else tile_put4(rl, cl, pk4(unpk4(sp[(size_t)f * 512]) + v));
.LBB0_1357:
	ds_read_b64 v[96:97], v137 offset:16384
	s_cmp_lt_i32 s37, 1
	s_mov_b64 s[20:21], -1
	s_waitcnt lgkmcnt(0)
	v_lshlrev_b32_e32 v98, 16, v96
	v_and_b32_e32 v99, 0xffff0000, v96
	v_lshlrev_b32_e32 v96, 16, v97
	v_and_b32_e32 v97, 0xffff0000, v97
	v_pk_mul_f32 v[94:95], v[94:95], v[96:97]
	v_pk_mul_f32 v[92:93], v[92:93], v[98:99]
	s_cbranch_scc1 .LBB0_1363
	s_cmp_lg_u32 s37, 1
	s_cbranch_scc0 .LBB0_1360
	v_add_co_u32_e32 v96, vcc, 0x8000, v130
	s_mov_b64 s[20:21], 0
	s_nop 0
	v_addc_co_u32_e32 v97, vcc, 0, v131, vcc
	v_mov_b32_e32 v96, v184
	v_mov_b32_e32 v97, v185
	v_lshlrev_b32_e32 v98, 16, v96
	v_and_b32_e32 v99, 0xffff0000, v96
	v_lshlrev_b32_e32 v96, 16, v97
	v_and_b32_e32 v97, 0xffff0000, v97
	v_pk_add_f32 v[96:97], v[94:95], v[96:97]
	v_pk_add_f32 v[98:99], v[92:93], v[98:99]
	s_nop 0
	v_cvt_pk_bf16_f32 v98, v98, v99
	v_cvt_pk_bf16_f32 v99, v96, v97
	ds_write_b64 v137, v[98:99] offset:16384
.LBB0_1360:
	s_andn2_b64 vcc, exec, s[20:21]
	s_cbranch_vccnz .LBB0_1362
	v_add_co_u32_e32 v96, vcc, 0x8000, v130
	s_nop 1
	v_addc_co_u32_e32 v97, vcc, 0, v131, vcc
	v_mov_b32_e32 v98, v184
	v_mov_b32_e32 v99, v185
	v_lshlrev_b32_e32 v102, 16, v98
	v_and_b32_e32 v103, 0xffff0000, v98
	v_lshlrev_b32_e32 v98, 16, v99
	v_and_b32_e32 v99, 0xffff0000, v99
	v_pk_add_f32 v[98:99], v[94:95], v[98:99]
	v_pk_add_f32 v[102:103], v[92:93], v[102:103]
	s_nop 0
	v_cvt_pk_bf16_f32 v102, v102, v103
	v_cvt_pk_bf16_f32 v103, v98, v99
	global_store_dwordx2 v[96:97], v[102:103], off

; DEV u32x2 pk4(f32x4 v) { u32x2 r = {pk_bf16(v[0], v[1]), pk_bf16(v[2], v[3])}; return r; }
; DEV f32x4 unpk4(u32x2 u) { f32x4 r = {bf_lo(u[0]), bf_hi(u[0]), bf_lo(u[1]), bf_hi(u[1])}; return r; }
;   DEV void operator()(f32x4 (&acc)[2][2][4][2], int brow, int bcol, int wr, int wc, int fr, int fq) const {
;     ...
;             const int cl = bj * 128 + wc * 32 + n * 16 + fq * 4, col = bcol + cl;
;             const int f = ((ai * 4 + m) * 2 + bj) * 2 + n;
;             const f32x4 g = unpk4(tile_get4(rl, cl));
;             f32x4 v = acc[ai][bj][m][n] * g;
;             if (step == 0) sp[(size_t)f * 512] = pk4(v);
;             else if (step == 1) sp[(size_t)f * 512] = pk4(unpk4(sp[(size_t)f * 512]) + v);
;             else tile_put4(rl, cl, pk4(unpk4(sp[(size_t)f * 512]) + v));
.LBB0_1365:
	ds_read_b64 v[92:93], v125 offset:16384
	s_cmp_lt_i32 s37, 1
	s_mov_b64 s[20:21], -1
	s_waitcnt lgkmcnt(0)
	v_lshlrev_b32_e32 v94, 16, v92
	v_and_b32_e32 v95, 0xffff0000, v92
	v_lshlrev_b32_e32 v92, 16, v93
	v_and_b32_e32 v93, 0xffff0000, v93
	v_pk_mul_f32 v[90:91], v[90:91], v[92:93]
	v_pk_mul_f32 v[88:89], v[88:89], v[94:95]
	s_cbranch_scc1 .LBB0_1371
	s_cmp_lg_u32 s37, 1
	s_cbranch_scc0 .LBB0_1368
	v_add_co_u32_e32 v92, vcc, 0x9000, v130
	s_mov_b64 s[20:21], 0
	s_nop 0
	v_addc_co_u32_e32 v93, vcc, 0, v131, vcc
	v_mov_b32_e32 v92, v186
	v_mov_b32_e32 v93, v187
	v_lshlrev_b32_e32 v94, 16, v92
	v_and_b32_e32 v95, 0xffff0000, v92
	v_lshlrev_b32_e32 v92, 16, v93
	v_and_b32_e32 v93, 0xffff0000, v93
	v_pk_add_f32 v[92:93], v[90:91], v[92:93]
	v_pk_add_f32 v[94:95], v[88:89], v[94:95]
	s_nop 0
	v_cvt_pk_bf16_f32 v94, v94, v95
	v_cvt_pk_bf16_f32 v95, v92, v93
	ds_write_b64 v125, v[94:95] offset:16384
.LBB0_1368:
	s_andn2_b64 vcc, exec, s[20:21]
	s_cbranch_vccnz .LBB0_1370
	v_add_co_u32_e32 v92, vcc, 0x9000, v130
	s_nop 1
	v_addc_co_u32_e32 v93, vcc, 0, v131, vcc
	v_mov_b32_e32 v94, v186
	v_mov_b32_e32 v95, v187
	v_lshlrev_b32_e32 v96, 16, v94
	v_and_b32_e32 v97, 0xffff0000, v94
	v_lshlrev_b32_e32 v94, 16, v95
	v_and_b32_e32 v95, 0xffff0000, v95
	v_pk_add_f32 v[94:95], v[90:91], v[94:95]
	v_pk_add_f32 v[96:97], v[88:89], v[96:97]
	s_nop 0
	v_cvt_pk_bf16_f32 v96, v96, v97
	v_cvt_pk_bf16_f32 v97, v94, v95
	global_store_dwordx2 v[92:93], v[96:97], off

; DEV u32x2 pk4(f32x4 v) { u32x2 r = {pk_bf16(v[0], v[1]), pk_bf16(v[2], v[3])}; return r; }
; DEV f32x4 unpk4(u32x2 u) { f32x4 r = {bf_lo(u[0]), bf_hi(u[0]), bf_lo(u[1]), bf_hi(u[1])}; return r; }
;   DEV void operator()(f32x4 (&acc)[2][2][4][2], int brow, int bcol, int wr, int wc, int fr, int fq) const {
;     ...
;             const int cl = bj * 128 + wc * 32 + n * 16 + fq * 4, col = bcol + cl;
;             const int f = ((ai * 4 + m) * 2 + bj) * 2 + n;
;             const f32x4 g = unpk4(tile_get4(rl, cl));
;             f32x4 v = acc[ai][bj][m][n] * g;
;             if (step == 0) sp[(size_t)f * 512] = pk4(v);
;             else if (step == 1) sp[(size_t)f * 512] = pk4(unpk4(sp[(size_t)f * 512]) + v);
;             else tile_put4(rl, cl, pk4(unpk4(sp[(size_t)f * 512]) + v));
.LBB0_1373:
	ds_read_b64 v[88:89], v121 offset:16384
	s_cmp_lt_i32 s37, 1
	s_mov_b64 s[20:21], -1
	s_waitcnt lgkmcnt(0)
	v_lshlrev_b32_e32 v90, 16, v88
	v_and_b32_e32 v91, 0xffff0000, v88
	v_lshlrev_b32_e32 v88, 16, v89
	v_and_b32_e32 v89, 0xffff0000, v89
	v_pk_mul_f32 v[86:87], v[86:87], v[88:89]
	v_pk_mul_f32 v[84:85], v[84:85], v[90:91]
	s_cbranch_scc1 .LBB0_1379
	s_cmp_lg_u32 s37, 1
	s_cbranch_scc0 .LBB0_1376
	v_add_co_u32_e32 v88, vcc, 0xa000, v130
	s_mov_b64 s[20:21], 0
	s_nop 0
	v_addc_co_u32_e32 v89, vcc, 0, v131, vcc
	v_mov_b32_e32 v88, v188
	v_mov_b32_e32 v89, v189
	v_lshlrev_b32_e32 v90, 16, v88
	v_and_b32_e32 v91, 0xffff0000, v88
	v_lshlrev_b32_e32 v88, 16, v89
	v_and_b32_e32 v89, 0xffff0000, v89
	v_pk_add_f32 v[88:89], v[86:87], v[88:89]
	v_pk_add_f32 v[90:91], v[84:85], v[90:91]
	s_nop 0
	v_cvt_pk_bf16_f32 v90, v90, v91
	v_cvt_pk_bf16_f32 v91, v88, v89
	ds_write_b64 v121, v[90:91] offset:16384
.LBB0_1376:
	s_andn2_b64 vcc, exec, s[20:21]
	s_cbranch_vccnz .LBB0_1378
	v_add_co_u32_e32 v88, vcc, 0xa000, v130
	s_nop 1
	v_addc_co_u32_e32 v89, vcc, 0, v131, vcc
	v_mov_b32_e32 v90, v188
	v_mov_b32_e32 v91, v189
	v_lshlrev_b32_e32 v92, 16, v90
	v_and_b32_e32 v93, 0xffff0000, v90
	v_lshlrev_b32_e32 v90, 16, v91
	v_and_b32_e32 v91, 0xffff0000, v91
	v_pk_add_f32 v[90:91], v[86:87], v[90:91]
	v_pk_add_f32 v[92:93], v[84:85], v[92:93]
	s_nop 0
	v_cvt_pk_bf16_f32 v92, v92, v93
	v_cvt_pk_bf16_f32 v93, v90, v91
	global_store_dwordx2 v[88:89], v[92:93], off

; DEV u32x2 pk4(f32x4 v) { u32x2 r = {pk_bf16(v[0], v[1]), pk_bf16(v[2], v[3])}; return r; }
; DEV f32x4 unpk4(u32x2 u) { f32x4 r = {bf_lo(u[0]), bf_hi(u[0]), bf_lo(u[1]), bf_hi(u[1])}; return r; }
;   DEV void operator()(f32x4 (&acc)[2][2][4][2], int brow, int bcol, int wr, int wc, int fr, int fq) const {
;     ...
;             const int cl = bj * 128 + wc * 32 + n * 16 + fq * 4, col = bcol + cl;
;             const int f = ((ai * 4 + m) * 2 + bj) * 2 + n;
;             const f32x4 g = unpk4(tile_get4(rl, cl));
;             f32x4 v = acc[ai][bj][m][n] * g;
;             if (step == 0) sp[(size_t)f * 512] = pk4(v);
;             else if (step == 1) sp[(size_t)f * 512] = pk4(unpk4(sp[(size_t)f * 512]) + v);
;             else tile_put4(rl, cl, pk4(unpk4(sp[(size_t)f * 512]) + v));
.LBB0_1381:
	ds_read_b64 v[84:85], v117 offset:16384
	s_cmp_lt_i32 s37, 1
	s_mov_b64 s[20:21], -1
	s_waitcnt lgkmcnt(0)
	v_lshlrev_b32_e32 v86, 16, v84
	v_and_b32_e32 v87, 0xffff0000, v84
	v_lshlrev_b32_e32 v84, 16, v85
	v_and_b32_e32 v85, 0xffff0000, v85
	v_pk_mul_f32 v[82:83], v[82:83], v[84:85]
	v_pk_mul_f32 v[80:81], v[80:81], v[86:87]
	s_cbranch_scc1 .LBB0_1387
	s_cmp_lg_u32 s37, 1
	s_cbranch_scc0 .LBB0_1384
	v_add_co_u32_e32 v84, vcc, 0xb000, v130
	s_mov_b64 s[20:21], 0
	s_nop 0
	v_addc_co_u32_e32 v85, vcc, 0, v131, vcc
	v_mov_b32_e32 v84, v190
	v_mov_b32_e32 v85, v191
	v_lshlrev_b32_e32 v86, 16, v84
	v_and_b32_e32 v87, 0xffff0000, v84
	v_lshlrev_b32_e32 v84, 16, v85
	v_and_b32_e32 v85, 0xffff0000, v85
	v_pk_add_f32 v[84:85], v[82:83], v[84:85]
	v_pk_add_f32 v[86:87], v[80:81], v[86:87]
	s_nop 0
	v_cvt_pk_bf16_f32 v86, v86, v87
	v_cvt_pk_bf16_f32 v87, v84, v85
	ds_write_b64 v117, v[86:87] offset:16384
.LBB0_1384:
	s_andn2_b64 vcc, exec, s[20:21]
	s_cbranch_vccnz .LBB0_1386
	v_add_co_u32_e32 v84, vcc, 0xb000, v130
	s_nop 1
	v_addc_co_u32_e32 v85, vcc, 0, v131, vcc
	v_mov_b32_e32 v86, v190
	v_mov_b32_e32 v87, v191
	v_lshlrev_b32_e32 v88, 16, v86
	v_and_b32_e32 v89, 0xffff0000, v86
	v_lshlrev_b32_e32 v86, 16, v87
	v_and_b32_e32 v87, 0xffff0000, v87
	v_pk_add_f32 v[86:87], v[82:83], v[86:87]
	v_pk_add_f32 v[88:89], v[80:81], v[88:89]
	s_nop 0
	v_cvt_pk_bf16_f32 v88, v88, v89
	v_cvt_pk_bf16_f32 v89, v86, v87
	global_store_dwordx2 v[84:85], v[88:89], off

; DEV u32x2 pk4(f32x4 v) { u32x2 r = {pk_bf16(v[0], v[1]), pk_bf16(v[2], v[3])}; return r; }
; DEV f32x4 unpk4(u32x2 u) { f32x4 r = {bf_lo(u[0]), bf_hi(u[0]), bf_lo(u[1]), bf_hi(u[1])}; return r; }
;   DEV void operator()(f32x4 (&acc)[2][2][4][2], int brow, int bcol, int wr, int wc, int fr, int fq) const {
;     ...
;             const int cl = bj * 128 + wc * 32 + n * 16 + fq * 4, col = bcol + cl;
;             const int f = ((ai * 4 + m) * 2 + bj) * 2 + n;
;             const f32x4 g = unpk4(tile_get4(rl, cl));
;             f32x4 v = acc[ai][bj][m][n] * g;
;             if (step == 0) sp[(size_t)f * 512] = pk4(v);
;             else if (step == 1) sp[(size_t)f * 512] = pk4(unpk4(sp[(size_t)f * 512]) + v);
;             else tile_put4(rl, cl, pk4(unpk4(sp[(size_t)f * 512]) + v));
.LBB0_1389:
	ds_read_b64 v[80:81], v113 offset:24576
	s_cmp_lt_i32 s37, 1
	s_mov_b64 s[20:21], -1
	s_waitcnt lgkmcnt(0)
	v_lshlrev_b32_e32 v82, 16, v80
	v_and_b32_e32 v83, 0xffff0000, v80
	v_lshlrev_b32_e32 v80, 16, v81
	v_and_b32_e32 v81, 0xffff0000, v81
	v_pk_mul_f32 v[78:79], v[78:79], v[80:81]
	v_pk_mul_f32 v[76:77], v[76:77], v[82:83]
	s_cbranch_scc1 .LBB0_1395
	s_cmp_lg_u32 s37, 1
	s_cbranch_scc0 .LBB0_1392
	v_add_co_u32_e32 v80, vcc, 0xc000, v130
	s_mov_b64 s[20:21], 0
	s_nop 0
	v_addc_co_u32_e32 v81, vcc, 0, v131, vcc
	v_mov_b32_e32 v80, v192
	v_mov_b32_e32 v81, v193
	v_lshlrev_b32_e32 v82, 16, v80
	v_and_b32_e32 v83, 0xffff0000, v80
	v_lshlrev_b32_e32 v80, 16, v81
	v_and_b32_e32 v81, 0xffff0000, v81
	v_pk_add_f32 v[80:81], v[78:79], v[80:81]
	v_pk_add_f32 v[82:83], v[76:77], v[82:83]
	s_nop 0
	v_cvt_pk_bf16_f32 v82, v82, v83
	v_cvt_pk_bf16_f32 v83, v80, v81
	ds_write_b64 v113, v[82:83] offset:24576
.LBB0_1392:
	s_andn2_b64 vcc, exec, s[20:21]
	s_cbranch_vccnz .LBB0_1394
	v_add_co_u32_e32 v80, vcc, 0xc000, v130
	s_nop 1
	v_addc_co_u32_e32 v81, vcc, 0, v131, vcc
	v_mov_b32_e32 v82, v192
	v_mov_b32_e32 v83, v193
	v_lshlrev_b32_e32 v84, 16, v82
	v_and_b32_e32 v85, 0xffff0000, v82
	v_lshlrev_b32_e32 v82, 16, v83
	v_and_b32_e32 v83, 0xffff0000, v83
	v_pk_add_f32 v[82:83], v[78:79], v[82:83]
	v_pk_add_f32 v[84:85], v[76:77], v[84:85]
	s_nop 0
	v_cvt_pk_bf16_f32 v84, v84, v85
	v_cvt_pk_bf16_f32 v85, v82, v83
	global_store_dwordx2 v[80:81], v[84:85], off

; DEV u32x2 pk4(f32x4 v) { u32x2 r = {pk_bf16(v[0], v[1]), pk_bf16(v[2], v[3])}; return r; }
; DEV f32x4 unpk4(u32x2 u) { f32x4 r = {bf_lo(u[0]), bf_hi(u[0]), bf_lo(u[1]), bf_hi(u[1])}; return r; }
;   DEV void operator()(f32x4 (&acc)[2][2][4][2], int brow, int bcol, int wr, int wc, int fr, int fq) const {
;     ...
;             const int cl = bj * 128 + wc * 32 + n * 16 + fq * 4, col = bcol + cl;
;             const int f = ((ai * 4 + m) * 2 + bj) * 2 + n;
;             const f32x4 g = unpk4(tile_get4(rl, cl));
;             f32x4 v = acc[ai][bj][m][n] * g;
;             if (step == 0) sp[(size_t)f * 512] = pk4(v);
;             else if (step == 1) sp[(size_t)f * 512] = pk4(unpk4(sp[(size_t)f * 512]) + v);
;             else tile_put4(rl, cl, pk4(unpk4(sp[(size_t)f * 512]) + v));
.LBB0_1397:
	ds_read_b64 v[76:77], v109 offset:24576
	s_cmp_lt_i32 s37, 1
	s_mov_b64 s[20:21], -1
	s_waitcnt lgkmcnt(0)
	v_lshlrev_b32_e32 v78, 16, v76
	v_and_b32_e32 v79, 0xffff0000, v76
	v_lshlrev_b32_e32 v76, 16, v77
	v_and_b32_e32 v77, 0xffff0000, v77
	v_pk_mul_f32 v[74:75], v[74:75], v[76:77]
	v_pk_mul_f32 v[72:73], v[72:73], v[78:79]
	s_cbranch_scc1 .LBB0_1403
	s_cmp_lg_u32 s37, 1
	s_cbranch_scc0 .LBB0_1400
	v_add_co_u32_e32 v76, vcc, 0xd000, v130
	s_mov_b64 s[20:21], 0
	s_nop 0
	v_addc_co_u32_e32 v77, vcc, 0, v131, vcc
	v_mov_b32_e32 v76, v194
	v_mov_b32_e32 v77, v195
	v_lshlrev_b32_e32 v78, 16, v76
	v_and_b32_e32 v79, 0xffff0000, v76
	v_lshlrev_b32_e32 v76, 16, v77
	v_and_b32_e32 v77, 0xffff0000, v77
	v_pk_add_f32 v[76:77], v[74:75], v[76:77]
	v_pk_add_f32 v[78:79], v[72:73], v[78:79]
	s_nop 0
	v_cvt_pk_bf16_f32 v78, v78, v79
	v_cvt_pk_bf16_f32 v79, v76, v77
	ds_write_b64 v109, v[78:79] offset:24576
.LBB0_1400:
	s_andn2_b64 vcc, exec, s[20:21]
	s_cbranch_vccnz .LBB0_1402
	v_add_co_u32_e32 v76, vcc, 0xd000, v130
	s_nop 1
	v_addc_co_u32_e32 v77, vcc, 0, v131, vcc
	v_mov_b32_e32 v78, v194
	v_mov_b32_e32 v79, v195
	v_lshlrev_b32_e32 v80, 16, v78
	v_and_b32_e32 v81, 0xffff0000, v78
	v_lshlrev_b32_e32 v78, 16, v79
	v_and_b32_e32 v79, 0xffff0000, v79
	v_pk_add_f32 v[78:79], v[74:75], v[78:79]
	v_pk_add_f32 v[80:81], v[72:73], v[80:81]
	s_nop 0
	v_cvt_pk_bf16_f32 v80, v80, v81
	v_cvt_pk_bf16_f32 v81, v78, v79
	global_store_dwordx2 v[76:77], v[80:81], off

; DEV u32x2 pk4(f32x4 v) { u32x2 r = {pk_bf16(v[0], v[1]), pk_bf16(v[2], v[3])}; return r; }
; DEV f32x4 unpk4(u32x2 u) { f32x4 r = {bf_lo(u[0]), bf_hi(u[0]), bf_lo(u[1]), bf_hi(u[1])}; return r; }
;   DEV void operator()(f32x4 (&acc)[2][2][4][2], int brow, int bcol, int wr, int wc, int fr, int fq) const {
;     ...
;             const int cl = bj * 128 + wc * 32 + n * 16 + fq * 4, col = bcol + cl;
;             const int f = ((ai * 4 + m) * 2 + bj) * 2 + n;
;             const f32x4 g = unpk4(tile_get4(rl, cl));
;             f32x4 v = acc[ai][bj][m][n] * g;
;             if (step == 0) sp[(size_t)f * 512] = pk4(v);
;             else if (step == 1) sp[(size_t)f * 512] = pk4(unpk4(sp[(size_t)f * 512]) + v);
;             else tile_put4(rl, cl, pk4(unpk4(sp[(size_t)f * 512]) + v));
.LBB0_1405:
	ds_read_b64 v[72:73], v105 offset:24576
	s_cmp_lt_i32 s37, 1
	s_mov_b64 s[20:21], -1
	s_waitcnt lgkmcnt(0)
	v_lshlrev_b32_e32 v74, 16, v72
	v_and_b32_e32 v75, 0xffff0000, v72
	v_lshlrev_b32_e32 v72, 16, v73
	v_and_b32_e32 v73, 0xffff0000, v73
	v_pk_mul_f32 v[70:71], v[70:71], v[72:73]
	v_pk_mul_f32 v[68:69], v[68:69], v[74:75]
	s_cbranch_scc1 .LBB0_1411
	s_cmp_lg_u32 s37, 1
	s_cbranch_scc0 .LBB0_1408
	v_add_co_u32_e32 v72, vcc, 0xe000, v130
	s_mov_b64 s[20:21], 0
	s_nop 0
	v_addc_co_u32_e32 v73, vcc, 0, v131, vcc
	v_mov_b32_e32 v72, v196
	v_mov_b32_e32 v73, v197
	v_lshlrev_b32_e32 v74, 16, v72
	v_and_b32_e32 v75, 0xffff0000, v72
	v_lshlrev_b32_e32 v72, 16, v73
	v_and_b32_e32 v73, 0xffff0000, v73
	v_pk_add_f32 v[72:73], v[70:71], v[72:73]
	v_pk_add_f32 v[74:75], v[68:69], v[74:75]
	s_nop 0
	v_cvt_pk_bf16_f32 v74, v74, v75
	v_cvt_pk_bf16_f32 v75, v72, v73
	ds_write_b64 v105, v[74:75] offset:24576
.LBB0_1408:
	s_andn2_b64 vcc, exec, s[20:21]
	s_cbranch_vccnz .LBB0_1410
	v_add_co_u32_e32 v72, vcc, 0xe000, v130
	s_nop 1
	v_addc_co_u32_e32 v73, vcc, 0, v131, vcc
	v_mov_b32_e32 v74, v196
	v_mov_b32_e32 v75, v197
	v_lshlrev_b32_e32 v76, 16, v74
	v_and_b32_e32 v77, 0xffff0000, v74
	v_lshlrev_b32_e32 v74, 16, v75
	v_and_b32_e32 v75, 0xffff0000, v75
	v_pk_add_f32 v[74:75], v[70:71], v[74:75]
	v_pk_add_f32 v[76:77], v[68:69], v[76:77]
	s_nop 0
	v_cvt_pk_bf16_f32 v76, v76, v77
	v_cvt_pk_bf16_f32 v77, v74, v75
	global_store_dwordx2 v[72:73], v[76:77], off

; DEV u32x2 pk4(f32x4 v) { u32x2 r = {pk_bf16(v[0], v[1]), pk_bf16(v[2], v[3])}; return r; }
; DEV f32x4 unpk4(u32x2 u) { f32x4 r = {bf_lo(u[0]), bf_hi(u[0]), bf_lo(u[1]), bf_hi(u[1])}; return r; }
;   DEV void operator()(f32x4 (&acc)[2][2][4][2], int brow, int bcol, int wr, int wc, int fr, int fq) const {
;     ...
;             const int cl = bj * 128 + wc * 32 + n * 16 + fq * 4, col = bcol + cl;
;             const int f = ((ai * 4 + m) * 2 + bj) * 2 + n;
;             const f32x4 g = unpk4(tile_get4(rl, cl));
;             f32x4 v = acc[ai][bj][m][n] * g;
;             if (step == 0) sp[(size_t)f * 512] = pk4(v);
;             else if (step == 1) sp[(size_t)f * 512] = pk4(unpk4(sp[(size_t)f * 512]) + v);
;             else tile_put4(rl, cl, pk4(unpk4(sp[(size_t)f * 512]) + v));
.LBB0_1413:
	ds_read_b64 v[68:69], v101 offset:24576
	s_cmp_lt_i32 s37, 1
	s_mov_b64 s[20:21], -1
	s_waitcnt lgkmcnt(0)
	v_lshlrev_b32_e32 v70, 16, v68
	v_and_b32_e32 v71, 0xffff0000, v68
	v_lshlrev_b32_e32 v68, 16, v69
	v_and_b32_e32 v69, 0xffff0000, v69
	v_pk_mul_f32 v[66:67], v[66:67], v[68:69]
	v_pk_mul_f32 v[64:65], v[64:65], v[70:71]
	s_cbranch_scc1 .LBB0_1419
	s_cmp_lg_u32 s37, 1
	s_cbranch_scc0 .LBB0_1416
	v_add_co_u32_e32 v68, vcc, 0xf000, v130
	s_mov_b64 s[20:21], 0
	s_nop 0
	v_addc_co_u32_e32 v69, vcc, 0, v131, vcc
	v_mov_b32_e32 v68, v200
	v_mov_b32_e32 v69, v201
	v_lshlrev_b32_e32 v70, 16, v68
	v_and_b32_e32 v71, 0xffff0000, v68
	v_lshlrev_b32_e32 v68, 16, v69
	v_and_b32_e32 v69, 0xffff0000, v69
	v_pk_add_f32 v[68:69], v[66:67], v[68:69]
	v_pk_add_f32 v[70:71], v[64:65], v[70:71]
	s_nop 0
	v_cvt_pk_bf16_f32 v70, v70, v71
	v_cvt_pk_bf16_f32 v71, v68, v69
	ds_write_b64 v101, v[70:71] offset:24576
.LBB0_1416:
	s_andn2_b64 vcc, exec, s[20:21]
	s_cbranch_vccnz .LBB0_1418
	v_add_co_u32_e32 v68, vcc, 0xf000, v130
	s_nop 1
	v_addc_co_u32_e32 v69, vcc, 0, v131, vcc
	v_mov_b32_e32 v70, v200
	v_mov_b32_e32 v71, v201
	v_lshlrev_b32_e32 v72, 16, v70
	v_and_b32_e32 v73, 0xffff0000, v70
	v_lshlrev_b32_e32 v70, 16, v71
	v_and_b32_e32 v71, 0xffff0000, v71
	v_pk_add_f32 v[70:71], v[66:67], v[70:71]
	v_pk_add_f32 v[72:73], v[64:65], v[72:73]
	s_nop 0
	v_cvt_pk_bf16_f32 v72, v72, v73
	v_cvt_pk_bf16_f32 v73, v70, v71
	global_store_dwordx2 v[68:69], v[72:73], off

; DEV u32x2 pk4(f32x4 v) { u32x2 r = {pk_bf16(v[0], v[1]), pk_bf16(v[2], v[3])}; return r; }
; DEV f32x4 unpk4(u32x2 u) { f32x4 r = {bf_lo(u[0]), bf_hi(u[0]), bf_lo(u[1]), bf_hi(u[1])}; return r; }
;   DEV void operator()(f32x4 (&acc)[2][2][4][2], int brow, int bcol, int wr, int wc, int fr, int fq) const {
;     ...
;             const int cl = bj * 128 + wc * 32 + n * 16 + fq * 4, col = bcol + cl;
;             const int f = ((ai * 4 + m) * 2 + bj) * 2 + n;
;             const f32x4 g = unpk4(tile_get4(rl, cl));
;             f32x4 v = acc[ai][bj][m][n] * g;
;             if (step == 0) sp[(size_t)f * 512] = pk4(v);
;             else if (step == 1) sp[(size_t)f * 512] = pk4(unpk4(sp[(size_t)f * 512]) + v);
;             else tile_put4(rl, cl, pk4(unpk4(sp[(size_t)f * 512]) + v));
.LBB0_1421:
	v_add_u32_e32 v64, 0x10000, v135
	v_add_u32_e32 v65, v64, v136
	v_add_u32_e32 v65, v65, v134
	ds_read_b64 v[66:67], v65
	s_cmp_lt_i32 s37, 1
	s_mov_b64 s[20:21], -1
	s_waitcnt lgkmcnt(0)
	v_lshlrev_b32_e32 v68, 16, v66
	v_and_b32_e32 v69, 0xffff0000, v66
	v_lshlrev_b32_e32 v66, 16, v67
	v_and_b32_e32 v67, 0xffff0000, v67
	v_pk_mul_f32 v[62:63], v[62:63], v[66:67]
	v_pk_mul_f32 v[60:61], v[60:61], v[68:69]
	s_cbranch_scc1 .LBB0_1427
	s_cmp_lg_u32 s37, 1
	s_cbranch_scc0 .LBB0_1424
	v_add_co_u32_e32 v66, vcc, 0x10000, v130
	s_mov_b64 s[20:21], 0
	s_nop 0
	v_addc_co_u32_e32 v67, vcc, 0, v131, vcc
	v_mov_b32_e32 v66, v202
	v_mov_b32_e32 v67, v203
	v_lshlrev_b32_e32 v68, 16, v66
	v_and_b32_e32 v69, 0xffff0000, v66
	v_lshlrev_b32_e32 v66, 16, v67
	v_and_b32_e32 v67, 0xffff0000, v67
	v_pk_add_f32 v[66:67], v[62:63], v[66:67]
	v_pk_add_f32 v[68:69], v[60:61], v[68:69]
	s_nop 0
	v_cvt_pk_bf16_f32 v68, v68, v69
	v_cvt_pk_bf16_f32 v69, v66, v67
	ds_write_b64 v65, v[68:69]
.LBB0_1424:
	s_andn2_b64 vcc, exec, s[20:21]
	s_cbranch_vccnz .LBB0_1426
	v_add_co_u32_e32 v66, vcc, 0x10000, v130
	s_nop 1
	v_addc_co_u32_e32 v67, vcc, 0, v131, vcc
	v_mov_b32_e32 v68, v202
	v_mov_b32_e32 v69, v203
	v_lshlrev_b32_e32 v70, 16, v68
	v_and_b32_e32 v71, 0xffff0000, v68
	v_lshlrev_b32_e32 v68, 16, v69
	v_and_b32_e32 v69, 0xffff0000, v69
	v_pk_add_f32 v[68:69], v[62:63], v[68:69]
	v_pk_add_f32 v[70:71], v[60:61], v[70:71]
	s_nop 0
	v_cvt_pk_bf16_f32 v70, v70, v71
	v_cvt_pk_bf16_f32 v71, v68, v69
	global_store_dwordx2 v[66:67], v[70:71], off

; DEV u32x2 pk4(f32x4 v) { u32x2 r = {pk_bf16(v[0], v[1]), pk_bf16(v[2], v[3])}; return r; }
; DEV f32x4 unpk4(u32x2 u) { f32x4 r = {bf_lo(u[0]), bf_hi(u[0]), bf_lo(u[1]), bf_hi(u[1])}; return r; }
;   DEV void operator()(f32x4 (&acc)[2][2][4][2], int brow, int bcol, int wr, int wc, int fr, int fq) const {
;     ...
;             const int cl = bj * 128 + wc * 32 + n * 16 + fq * 4, col = bcol + cl;
;             const int f = ((ai * 4 + m) * 2 + bj) * 2 + n;
;             const f32x4 g = unpk4(tile_get4(rl, cl));
;             f32x4 v = acc[ai][bj][m][n] * g;
;             if (step == 0) sp[(size_t)f * 512] = pk4(v);
;             else if (step == 1) sp[(size_t)f * 512] = pk4(unpk4(sp[(size_t)f * 512]) + v);
;             else tile_put4(rl, cl, pk4(unpk4(sp[(size_t)f * 512]) + v));
.LBB0_1429:
	v_add_u32_e32 v60, v64, v124
	v_add_u32_e32 v60, v60, v134
	ds_read_b64 v[62:63], v60
	s_cmp_lt_i32 s37, 1
	s_mov_b64 s[20:21], -1
	s_waitcnt lgkmcnt(0)
	v_lshlrev_b32_e32 v66, 16, v62
	v_and_b32_e32 v67, 0xffff0000, v62
	v_lshlrev_b32_e32 v62, 16, v63
	v_and_b32_e32 v63, 0xffff0000, v63
	v_pk_mul_f32 v[58:59], v[58:59], v[62:63]
	v_pk_mul_f32 v[56:57], v[56:57], v[66:67]
	s_cbranch_scc1 .LBB0_1435
	s_cmp_lg_u32 s37, 1
	s_cbranch_scc0 .LBB0_1432
	v_add_co_u32_e32 v62, vcc, 0x11000, v130
	s_mov_b64 s[20:21], 0
	s_nop 0
	v_addc_co_u32_e32 v63, vcc, 0, v131, vcc
	v_mov_b32_e32 v62, v204
	v_mov_b32_e32 v63, v205
	v_lshlrev_b32_e32 v66, 16, v62
	v_and_b32_e32 v67, 0xffff0000, v62
	v_lshlrev_b32_e32 v62, 16, v63
	v_and_b32_e32 v63, 0xffff0000, v63
	v_pk_add_f32 v[62:63], v[58:59], v[62:63]
	v_pk_add_f32 v[66:67], v[56:57], v[66:67]
	s_nop 0
	v_cvt_pk_bf16_f32 v66, v66, v67
	v_cvt_pk_bf16_f32 v67, v62, v63
	ds_write_b64 v60, v[66:67]
.LBB0_1432:
	s_andn2_b64 vcc, exec, s[20:21]
	s_cbranch_vccnz .LBB0_1434
	v_add_co_u32_e32 v60, vcc, 0x11000, v130
	s_nop 1
	v_addc_co_u32_e32 v61, vcc, 0, v131, vcc
	v_mov_b32_e32 v62, v204
	v_mov_b32_e32 v63, v205
	v_lshlrev_b32_e32 v66, 16, v62
	v_and_b32_e32 v67, 0xffff0000, v62
	v_lshlrev_b32_e32 v62, 16, v63
	v_and_b32_e32 v63, 0xffff0000, v63
	v_pk_add_f32 v[62:63], v[58:59], v[62:63]
	v_pk_add_f32 v[66:67], v[56:57], v[66:67]
	s_nop 0
	v_cvt_pk_bf16_f32 v66, v66, v67
	v_cvt_pk_bf16_f32 v67, v62, v63
	global_store_dwordx2 v[60:61], v[66:67], off

; DEV u32x2 pk4(f32x4 v) { u32x2 r = {pk_bf16(v[0], v[1]), pk_bf16(v[2], v[3])}; return r; }
; DEV f32x4 unpk4(u32x2 u) { f32x4 r = {bf_lo(u[0]), bf_hi(u[0]), bf_lo(u[1]), bf_hi(u[1])}; return r; }
;   DEV void operator()(f32x4 (&acc)[2][2][4][2], int brow, int bcol, int wr, int wc, int fr, int fq) const {
;     ...
;             const int cl = bj * 128 + wc * 32 + n * 16 + fq * 4, col = bcol + cl;
;             const int f = ((ai * 4 + m) * 2 + bj) * 2 + n;
;             const f32x4 g = unpk4(tile_get4(rl, cl));
;             f32x4 v = acc[ai][bj][m][n] * g;
;             if (step == 0) sp[(size_t)f * 512] = pk4(v);
;             else if (step == 1) sp[(size_t)f * 512] = pk4(unpk4(sp[(size_t)f * 512]) + v);
;             else tile_put4(rl, cl, pk4(unpk4(sp[(size_t)f * 512]) + v));
.LBB0_1437:
	v_add_u32_e32 v56, v64, v120
	v_add_u32_e32 v56, v56, v134
	ds_read_b64 v[58:59], v56
	s_cmp_lt_i32 s37, 1
	s_mov_b64 s[20:21], -1
	s_waitcnt lgkmcnt(0)
	v_lshlrev_b32_e32 v60, 16, v58
	v_and_b32_e32 v61, 0xffff0000, v58
	v_lshlrev_b32_e32 v58, 16, v59
	v_and_b32_e32 v59, 0xffff0000, v59
	v_pk_mul_f32 v[54:55], v[54:55], v[58:59]
	v_pk_mul_f32 v[52:53], v[52:53], v[60:61]
	s_cbranch_scc1 .LBB0_1443
	s_cmp_lg_u32 s37, 1
	s_cbranch_scc0 .LBB0_1440
	v_add_co_u32_e32 v58, vcc, 0x12000, v130
	s_mov_b64 s[20:21], 0
	s_nop 0
	v_addc_co_u32_e32 v59, vcc, 0, v131, vcc
	v_mov_b32_e32 v58, v206
	v_mov_b32_e32 v59, v207
	v_lshlrev_b32_e32 v60, 16, v58
	v_and_b32_e32 v61, 0xffff0000, v58
	v_lshlrev_b32_e32 v58, 16, v59
	v_and_b32_e32 v59, 0xffff0000, v59
	v_pk_add_f32 v[58:59], v[54:55], v[58:59]
	v_pk_add_f32 v[60:61], v[52:53], v[60:61]
	s_nop 0
	v_cvt_pk_bf16_f32 v60, v60, v61
	v_cvt_pk_bf16_f32 v61, v58, v59
	ds_write_b64 v56, v[60:61]
.LBB0_1440:
	s_andn2_b64 vcc, exec, s[20:21]
	s_cbranch_vccnz .LBB0_1442
	v_add_co_u32_e32 v56, vcc, 0x12000, v130
	s_nop 1
	v_addc_co_u32_e32 v57, vcc, 0, v131, vcc
	v_mov_b32_e32 v58, v206
	v_mov_b32_e32 v59, v207
	v_lshlrev_b32_e32 v60, 16, v58
	v_and_b32_e32 v61, 0xffff0000, v58
	v_lshlrev_b32_e32 v58, 16, v59
	v_and_b32_e32 v59, 0xffff0000, v59
	v_pk_add_f32 v[58:59], v[54:55], v[58:59]
	v_pk_add_f32 v[60:61], v[52:53], v[60:61]
	s_nop 0
	v_cvt_pk_bf16_f32 v60, v60, v61
	v_cvt_pk_bf16_f32 v61, v58, v59
	global_store_dwordx2 v[56:57], v[60:61], off

; DEV u32x2 pk4(f32x4 v) { u32x2 r = {pk_bf16(v[0], v[1]), pk_bf16(v[2], v[3])}; return r; }
; DEV f32x4 unpk4(u32x2 u) { f32x4 r = {bf_lo(u[0]), bf_hi(u[0]), bf_lo(u[1]), bf_hi(u[1])}; return r; }
;   DEV void operator()(f32x4 (&acc)[2][2][4][2], int brow, int bcol, int wr, int wc, int fr, int fq) const {
;     ...
;             const int cl = bj * 128 + wc * 32 + n * 16 + fq * 4, col = bcol + cl;
;             const int f = ((ai * 4 + m) * 2 + bj) * 2 + n;
;             const f32x4 g = unpk4(tile_get4(rl, cl));
;             f32x4 v = acc[ai][bj][m][n] * g;
;             if (step == 0) sp[(size_t)f * 512] = pk4(v);
;             else if (step == 1) sp[(size_t)f * 512] = pk4(unpk4(sp[(size_t)f * 512]) + v);
;             else tile_put4(rl, cl, pk4(unpk4(sp[(size_t)f * 512]) + v));
.LBB0_1445:
	v_add_u32_e32 v52, v64, v116
	v_add_u32_e32 v52, v52, v134
	ds_read_b64 v[54:55], v52
	s_cmp_lt_i32 s37, 1
	s_mov_b64 s[20:21], -1
	s_waitcnt lgkmcnt(0)
	v_lshlrev_b32_e32 v56, 16, v54
	v_and_b32_e32 v57, 0xffff0000, v54
	v_lshlrev_b32_e32 v54, 16, v55
	v_and_b32_e32 v55, 0xffff0000, v55
	v_pk_mul_f32 v[50:51], v[50:51], v[54:55]
	v_pk_mul_f32 v[48:49], v[48:49], v[56:57]
	s_cbranch_scc1 .LBB0_1451
	s_cmp_lg_u32 s37, 1
	s_cbranch_scc0 .LBB0_1448
	v_add_co_u32_e32 v54, vcc, 0x13000, v130
	s_mov_b64 s[20:21], 0
	s_nop 0
	v_addc_co_u32_e32 v55, vcc, 0, v131, vcc
	v_mov_b32_e32 v54, v208
	v_mov_b32_e32 v55, v209
	v_lshlrev_b32_e32 v56, 16, v54
	v_and_b32_e32 v57, 0xffff0000, v54
	v_lshlrev_b32_e32 v54, 16, v55
	v_and_b32_e32 v55, 0xffff0000, v55
	v_pk_add_f32 v[54:55], v[50:51], v[54:55]
	v_pk_add_f32 v[56:57], v[48:49], v[56:57]
	s_nop 0
	v_cvt_pk_bf16_f32 v56, v56, v57
	v_cvt_pk_bf16_f32 v57, v54, v55
	ds_write_b64 v52, v[56:57]
.LBB0_1448:
	s_andn2_b64 vcc, exec, s[20:21]
	s_cbranch_vccnz .LBB0_1450
	v_add_co_u32_e32 v52, vcc, 0x13000, v130
	s_nop 1
	v_addc_co_u32_e32 v53, vcc, 0, v131, vcc
	v_mov_b32_e32 v54, v208
	v_mov_b32_e32 v55, v209
	v_lshlrev_b32_e32 v56, 16, v54
	v_and_b32_e32 v57, 0xffff0000, v54
	v_lshlrev_b32_e32 v54, 16, v55
	v_and_b32_e32 v55, 0xffff0000, v55
	v_pk_add_f32 v[54:55], v[50:51], v[54:55]
	v_pk_add_f32 v[56:57], v[48:49], v[56:57]
	s_nop 0
	v_cvt_pk_bf16_f32 v56, v56, v57
	v_cvt_pk_bf16_f32 v57, v54, v55
	global_store_dwordx2 v[52:53], v[56:57], off

; DEV u32x2 pk4(f32x4 v) { u32x2 r = {pk_bf16(v[0], v[1]), pk_bf16(v[2], v[3])}; return r; }
; DEV f32x4 unpk4(u32x2 u) { f32x4 r = {bf_lo(u[0]), bf_hi(u[0]), bf_lo(u[1]), bf_hi(u[1])}; return r; }
;   DEV void operator()(f32x4 (&acc)[2][2][4][2], int brow, int bcol, int wr, int wc, int fr, int fq) const {
;     ...
;             const int cl = bj * 128 + wc * 32 + n * 16 + fq * 4, col = bcol + cl;
;             const int f = ((ai * 4 + m) * 2 + bj) * 2 + n;
;             const f32x4 g = unpk4(tile_get4(rl, cl));
;             f32x4 v = acc[ai][bj][m][n] * g;
;             if (step == 0) sp[(size_t)f * 512] = pk4(v);
;             else if (step == 1) sp[(size_t)f * 512] = pk4(unpk4(sp[(size_t)f * 512]) + v);
;             else tile_put4(rl, cl, pk4(unpk4(sp[(size_t)f * 512]) + v));
.LBB0_1453:
	v_add_u32_e32 v48, 0x12000, v135
	v_add_u32_e32 v49, v48, v112
	v_add_u32_e32 v49, v49, v134
	ds_read_b64 v[50:51], v49
	s_cmp_lt_i32 s37, 1
	s_mov_b64 s[20:21], -1
	s_waitcnt lgkmcnt(0)
	v_lshlrev_b32_e32 v52, 16, v50
	v_and_b32_e32 v53, 0xffff0000, v50
	v_lshlrev_b32_e32 v50, 16, v51
	v_and_b32_e32 v51, 0xffff0000, v51
	v_pk_mul_f32 v[46:47], v[46:47], v[50:51]
	v_pk_mul_f32 v[44:45], v[44:45], v[52:53]
	s_cbranch_scc1 .LBB0_1459
	s_cmp_lg_u32 s37, 1
	s_cbranch_scc0 .LBB0_1456
	v_add_co_u32_e32 v50, vcc, 0x14000, v130
	s_mov_b64 s[20:21], 0
	s_nop 0
	v_addc_co_u32_e32 v51, vcc, 0, v131, vcc
	v_mov_b32_e32 v50, v210
	v_mov_b32_e32 v51, v211
	v_lshlrev_b32_e32 v52, 16, v50
	v_and_b32_e32 v53, 0xffff0000, v50
	v_lshlrev_b32_e32 v50, 16, v51
	v_and_b32_e32 v51, 0xffff0000, v51
	v_pk_add_f32 v[50:51], v[46:47], v[50:51]
	v_pk_add_f32 v[52:53], v[44:45], v[52:53]
	s_nop 0
	v_cvt_pk_bf16_f32 v52, v52, v53
	v_cvt_pk_bf16_f32 v53, v50, v51
	ds_write_b64 v49, v[52:53]
.LBB0_1456:
	s_andn2_b64 vcc, exec, s[20:21]
	s_cbranch_vccnz .LBB0_1458
	v_add_co_u32_e32 v50, vcc, 0x14000, v130
	s_nop 1
	v_addc_co_u32_e32 v51, vcc, 0, v131, vcc
	v_mov_b32_e32 v52, v210
	v_mov_b32_e32 v53, v211
	v_lshlrev_b32_e32 v54, 16, v52
	v_and_b32_e32 v55, 0xffff0000, v52
	v_lshlrev_b32_e32 v52, 16, v53
	v_and_b32_e32 v53, 0xffff0000, v53
	v_pk_add_f32 v[52:53], v[46:47], v[52:53]
	v_pk_add_f32 v[54:55], v[44:45], v[54:55]
	s_nop 0
	v_cvt_pk_bf16_f32 v54, v54, v55
	v_cvt_pk_bf16_f32 v55, v52, v53
	global_store_dwordx2 v[50:51], v[54:55], off

; DEV u32x2 pk4(f32x4 v) { u32x2 r = {pk_bf16(v[0], v[1]), pk_bf16(v[2], v[3])}; return r; }
; DEV f32x4 unpk4(u32x2 u) { f32x4 r = {bf_lo(u[0]), bf_hi(u[0]), bf_lo(u[1]), bf_hi(u[1])}; return r; }
;   DEV void operator()(f32x4 (&acc)[2][2][4][2], int brow, int bcol, int wr, int wc, int fr, int fq) const {
;     ...
;             const int cl = bj * 128 + wc * 32 + n * 16 + fq * 4, col = bcol + cl;
;             const int f = ((ai * 4 + m) * 2 + bj) * 2 + n;
;             const f32x4 g = unpk4(tile_get4(rl, cl));
;             f32x4 v = acc[ai][bj][m][n] * g;
;             if (step == 0) sp[(size_t)f * 512] = pk4(v);
;             else if (step == 1) sp[(size_t)f * 512] = pk4(unpk4(sp[(size_t)f * 512]) + v);
;             else tile_put4(rl, cl, pk4(unpk4(sp[(size_t)f * 512]) + v));
.LBB0_1461:
	v_add_u32_e32 v44, v48, v108
	v_add_u32_e32 v44, v44, v134
	ds_read_b64 v[46:47], v44
	s_cmp_lt_i32 s37, 1
	s_mov_b64 s[20:21], -1
	s_waitcnt lgkmcnt(0)
	v_lshlrev_b32_e32 v50, 16, v46
	v_and_b32_e32 v51, 0xffff0000, v46
	v_lshlrev_b32_e32 v46, 16, v47
	v_and_b32_e32 v47, 0xffff0000, v47
	v_pk_mul_f32 v[42:43], v[42:43], v[46:47]
	v_pk_mul_f32 v[40:41], v[40:41], v[50:51]
	s_cbranch_scc1 .LBB0_1467
	s_cmp_lg_u32 s37, 1
	s_cbranch_scc0 .LBB0_1464
	v_add_co_u32_e32 v46, vcc, 0x15000, v130
	s_mov_b64 s[20:21], 0
	s_nop 0
	v_addc_co_u32_e32 v47, vcc, 0, v131, vcc
	v_mov_b32_e32 v46, v212
	v_mov_b32_e32 v47, v213
	v_lshlrev_b32_e32 v50, 16, v46
	v_and_b32_e32 v51, 0xffff0000, v46
	v_lshlrev_b32_e32 v46, 16, v47
	v_and_b32_e32 v47, 0xffff0000, v47
	v_pk_add_f32 v[46:47], v[42:43], v[46:47]
	v_pk_add_f32 v[50:51], v[40:41], v[50:51]
	s_nop 0
	v_cvt_pk_bf16_f32 v50, v50, v51
	v_cvt_pk_bf16_f32 v51, v46, v47
	ds_write_b64 v44, v[50:51]
.LBB0_1464:
	s_andn2_b64 vcc, exec, s[20:21]
	s_cbranch_vccnz .LBB0_1466
	v_add_co_u32_e32 v44, vcc, 0x15000, v130
	s_nop 1
	v_addc_co_u32_e32 v45, vcc, 0, v131, vcc
	v_mov_b32_e32 v46, v212
	v_mov_b32_e32 v47, v213
	v_lshlrev_b32_e32 v50, 16, v46
	v_and_b32_e32 v51, 0xffff0000, v46
	v_lshlrev_b32_e32 v46, 16, v47
	v_and_b32_e32 v47, 0xffff0000, v47
	v_pk_add_f32 v[46:47], v[42:43], v[46:47]
	v_pk_add_f32 v[50:51], v[40:41], v[50:51]
	s_nop 0
	v_cvt_pk_bf16_f32 v50, v50, v51
	v_cvt_pk_bf16_f32 v51, v46, v47
	global_store_dwordx2 v[44:45], v[50:51], off

; DEV u32x2 pk4(f32x4 v) { u32x2 r = {pk_bf16(v[0], v[1]), pk_bf16(v[2], v[3])}; return r; }
; DEV f32x4 unpk4(u32x2 u) { f32x4 r = {bf_lo(u[0]), bf_hi(u[0]), bf_lo(u[1]), bf_hi(u[1])}; return r; }
;   DEV void operator()(f32x4 (&acc)[2][2][4][2], int brow, int bcol, int wr, int wc, int fr, int fq) const {
;     ...
;             const int cl = bj * 128 + wc * 32 + n * 16 + fq * 4, col = bcol + cl;
;             const int f = ((ai * 4 + m) * 2 + bj) * 2 + n;
;             const f32x4 g = unpk4(tile_get4(rl, cl));
;             f32x4 v = acc[ai][bj][m][n] * g;
;             if (step == 0) sp[(size_t)f * 512] = pk4(v);
;             else if (step == 1) sp[(size_t)f * 512] = pk4(unpk4(sp[(size_t)f * 512]) + v);
;             else tile_put4(rl, cl, pk4(unpk4(sp[(size_t)f * 512]) + v));
.LBB0_1469:
	v_add_u32_e32 v40, v48, v104
	v_add_u32_e32 v40, v40, v134
	ds_read_b64 v[42:43], v40
	s_cmp_lt_i32 s37, 1
	s_mov_b64 s[20:21], -1
	s_waitcnt lgkmcnt(0)
	v_lshlrev_b32_e32 v44, 16, v42
	v_and_b32_e32 v45, 0xffff0000, v42
	v_lshlrev_b32_e32 v42, 16, v43
	v_and_b32_e32 v43, 0xffff0000, v43
	v_pk_mul_f32 v[38:39], v[38:39], v[42:43]
	v_pk_mul_f32 v[36:37], v[36:37], v[44:45]
	s_cbranch_scc1 .LBB0_1475
	s_cmp_lg_u32 s37, 1
	s_cbranch_scc0 .LBB0_1472
	v_add_co_u32_e32 v42, vcc, 0x16000, v130
	s_mov_b64 s[20:21], 0
	s_nop 0
	v_addc_co_u32_e32 v43, vcc, 0, v131, vcc
	v_mov_b32_e32 v42, v214
	v_mov_b32_e32 v43, v215
	v_lshlrev_b32_e32 v44, 16, v42
	v_and_b32_e32 v45, 0xffff0000, v42
	v_lshlrev_b32_e32 v42, 16, v43
	v_and_b32_e32 v43, 0xffff0000, v43
	v_pk_add_f32 v[42:43], v[38:39], v[42:43]
	v_pk_add_f32 v[44:45], v[36:37], v[44:45]
	s_nop 0
	v_cvt_pk_bf16_f32 v44, v44, v45
	v_cvt_pk_bf16_f32 v45, v42, v43
	ds_write_b64 v40, v[44:45]
.LBB0_1472:
	s_andn2_b64 vcc, exec, s[20:21]
	s_cbranch_vccnz .LBB0_1474
	v_add_co_u32_e32 v40, vcc, 0x16000, v130
	s_nop 1
	v_addc_co_u32_e32 v41, vcc, 0, v131, vcc
	v_mov_b32_e32 v42, v214
	v_mov_b32_e32 v43, v215
	v_lshlrev_b32_e32 v44, 16, v42
	v_and_b32_e32 v45, 0xffff0000, v42
	v_lshlrev_b32_e32 v42, 16, v43
	v_and_b32_e32 v43, 0xffff0000, v43
	v_pk_add_f32 v[42:43], v[38:39], v[42:43]
	v_pk_add_f32 v[44:45], v[36:37], v[44:45]
	s_nop 0
	v_cvt_pk_bf16_f32 v44, v44, v45
	v_cvt_pk_bf16_f32 v45, v42, v43
	global_store_dwordx2 v[40:41], v[44:45], off

; DEV u32x2 pk4(f32x4 v) { u32x2 r = {pk_bf16(v[0], v[1]), pk_bf16(v[2], v[3])}; return r; }
; DEV f32x4 unpk4(u32x2 u) { f32x4 r = {bf_lo(u[0]), bf_hi(u[0]), bf_lo(u[1]), bf_hi(u[1])}; return r; }
;   DEV void operator()(f32x4 (&acc)[2][2][4][2], int brow, int bcol, int wr, int wc, int fr, int fq) const {
;     ...
;             const int cl = bj * 128 + wc * 32 + n * 16 + fq * 4, col = bcol + cl;
;             const int f = ((ai * 4 + m) * 2 + bj) * 2 + n;
;             const f32x4 g = unpk4(tile_get4(rl, cl));
;             f32x4 v = acc[ai][bj][m][n] * g;
;             if (step == 0) sp[(size_t)f * 512] = pk4(v);
;             else if (step == 1) sp[(size_t)f * 512] = pk4(unpk4(sp[(size_t)f * 512]) + v);
;             else tile_put4(rl, cl, pk4(unpk4(sp[(size_t)f * 512]) + v));
.LBB0_1477:
	v_add_u32_e32 v36, v48, v100
	v_add_u32_e32 v36, v36, v134
	ds_read_b64 v[38:39], v36
	s_cmp_lt_i32 s37, 1
	s_mov_b64 s[20:21], -1
	s_waitcnt lgkmcnt(0)
	v_lshlrev_b32_e32 v40, 16, v38
	v_and_b32_e32 v41, 0xffff0000, v38
	v_lshlrev_b32_e32 v38, 16, v39
	v_and_b32_e32 v39, 0xffff0000, v39
	v_pk_mul_f32 v[34:35], v[34:35], v[38:39]
	v_pk_mul_f32 v[32:33], v[32:33], v[40:41]
	s_cbranch_scc1 .LBB0_1483
	s_cmp_lg_u32 s37, 1
	s_cbranch_scc0 .LBB0_1480
	v_add_co_u32_e32 v38, vcc, 0x17000, v130
	s_mov_b64 s[20:21], 0
	s_nop 0
	v_addc_co_u32_e32 v39, vcc, 0, v131, vcc
	v_mov_b32_e32 v38, v216
	v_mov_b32_e32 v39, v217
	v_lshlrev_b32_e32 v40, 16, v38
	v_and_b32_e32 v41, 0xffff0000, v38
	v_lshlrev_b32_e32 v38, 16, v39
	v_and_b32_e32 v39, 0xffff0000, v39
	v_pk_add_f32 v[38:39], v[34:35], v[38:39]
	v_pk_add_f32 v[40:41], v[32:33], v[40:41]
	s_nop 0
	v_cvt_pk_bf16_f32 v40, v40, v41
	v_cvt_pk_bf16_f32 v41, v38, v39
	ds_write_b64 v36, v[40:41]
.LBB0_1480:
	s_andn2_b64 vcc, exec, s[20:21]
	s_cbranch_vccnz .LBB0_1482
	v_add_co_u32_e32 v36, vcc, 0x17000, v130
	s_nop 1
	v_addc_co_u32_e32 v37, vcc, 0, v131, vcc
	v_mov_b32_e32 v38, v216
	v_mov_b32_e32 v39, v217
	v_lshlrev_b32_e32 v40, 16, v38
	v_and_b32_e32 v41, 0xffff0000, v38
	v_lshlrev_b32_e32 v38, 16, v39
	v_and_b32_e32 v39, 0xffff0000, v39
	v_pk_add_f32 v[38:39], v[34:35], v[38:39]
	v_pk_add_f32 v[40:41], v[32:33], v[40:41]
	s_nop 0
	v_cvt_pk_bf16_f32 v40, v40, v41
	v_cvt_pk_bf16_f32 v41, v38, v39
	global_store_dwordx2 v[36:37], v[40:41], off

; DEV u32x2 pk4(f32x4 v) { u32x2 r = {pk_bf16(v[0], v[1]), pk_bf16(v[2], v[3])}; return r; }
; DEV f32x4 unpk4(u32x2 u) { f32x4 r = {bf_lo(u[0]), bf_hi(u[0]), bf_lo(u[1]), bf_hi(u[1])}; return r; }
;   DEV void operator()(f32x4 (&acc)[2][2][4][2], int brow, int bcol, int wr, int wc, int fr, int fq) const {
;     ...
;             const int cl = bj * 128 + wc * 32 + n * 16 + fq * 4, col = bcol + cl;
;             const int f = ((ai * 4 + m) * 2 + bj) * 2 + n;
;             const f32x4 g = unpk4(tile_get4(rl, cl));
;             f32x4 v = acc[ai][bj][m][n] * g;
;             if (step == 0) sp[(size_t)f * 512] = pk4(v);
;             else if (step == 1) sp[(size_t)f * 512] = pk4(unpk4(sp[(size_t)f * 512]) + v);
;             else tile_put4(rl, cl, pk4(unpk4(sp[(size_t)f * 512]) + v));
.LBB0_1485:
	v_add_u32_e32 v32, 0x14000, v135
	v_add_u32_e32 v33, v32, v136
	v_add_u32_e32 v33, v33, v134
	ds_read_b64 v[34:35], v33
	s_cmp_lt_i32 s37, 1
	s_mov_b64 s[20:21], -1
	s_waitcnt lgkmcnt(0)
	v_lshlrev_b32_e32 v36, 16, v34
	v_and_b32_e32 v37, 0xffff0000, v34
	v_lshlrev_b32_e32 v34, 16, v35
	v_and_b32_e32 v35, 0xffff0000, v35
	v_pk_mul_f32 v[30:31], v[30:31], v[34:35]
	v_pk_mul_f32 v[28:29], v[28:29], v[36:37]
	s_cbranch_scc1 .LBB0_1491
	s_cmp_lg_u32 s37, 1
	s_cbranch_scc0 .LBB0_1488
	v_add_co_u32_e32 v34, vcc, 0x18000, v130
	s_mov_b64 s[20:21], 0
	s_nop 0
	v_addc_co_u32_e32 v35, vcc, 0, v131, vcc
	v_mov_b32_e32 v34, v224
	v_mov_b32_e32 v35, v225
	v_lshlrev_b32_e32 v36, 16, v34
	v_and_b32_e32 v37, 0xffff0000, v34
	v_lshlrev_b32_e32 v34, 16, v35
	v_and_b32_e32 v35, 0xffff0000, v35
	v_pk_add_f32 v[34:35], v[30:31], v[34:35]
	v_pk_add_f32 v[36:37], v[28:29], v[36:37]
	s_nop 0
	v_cvt_pk_bf16_f32 v36, v36, v37
	v_cvt_pk_bf16_f32 v37, v34, v35
	ds_write_b64 v33, v[36:37]
.LBB0_1488:
	s_andn2_b64 vcc, exec, s[20:21]
	s_cbranch_vccnz .LBB0_1490
	v_add_co_u32_e32 v34, vcc, 0x18000, v130
	s_nop 1
	v_addc_co_u32_e32 v35, vcc, 0, v131, vcc
	v_mov_b32_e32 v36, v224
	v_mov_b32_e32 v37, v225
	v_lshlrev_b32_e32 v38, 16, v36
	v_and_b32_e32 v39, 0xffff0000, v36
	v_lshlrev_b32_e32 v36, 16, v37
	v_and_b32_e32 v37, 0xffff0000, v37
	v_pk_add_f32 v[36:37], v[30:31], v[36:37]
	v_pk_add_f32 v[38:39], v[28:29], v[38:39]
	s_nop 0
	v_cvt_pk_bf16_f32 v38, v38, v39
	v_cvt_pk_bf16_f32 v39, v36, v37
	global_store_dwordx2 v[34:35], v[38:39], off

; DEV u32x2 pk4(f32x4 v) { u32x2 r = {pk_bf16(v[0], v[1]), pk_bf16(v[2], v[3])}; return r; }
; DEV f32x4 unpk4(u32x2 u) { f32x4 r = {bf_lo(u[0]), bf_hi(u[0]), bf_lo(u[1]), bf_hi(u[1])}; return r; }
;   DEV void operator()(f32x4 (&acc)[2][2][4][2], int brow, int bcol, int wr, int wc, int fr, int fq) const {
;     ...
;             const int cl = bj * 128 + wc * 32 + n * 16 + fq * 4, col = bcol + cl;
;             const int f = ((ai * 4 + m) * 2 + bj) * 2 + n;
;             const f32x4 g = unpk4(tile_get4(rl, cl));
;             f32x4 v = acc[ai][bj][m][n] * g;
;             if (step == 0) sp[(size_t)f * 512] = pk4(v);
;             else if (step == 1) sp[(size_t)f * 512] = pk4(unpk4(sp[(size_t)f * 512]) + v);
;             else tile_put4(rl, cl, pk4(unpk4(sp[(size_t)f * 512]) + v));
.LBB0_1493:
	v_add_u32_e32 v28, v32, v124
	v_add_u32_e32 v28, v28, v134
	ds_read_b64 v[30:31], v28
	s_cmp_lt_i32 s37, 1
	s_mov_b64 s[20:21], -1
	s_waitcnt lgkmcnt(0)
	v_lshlrev_b32_e32 v34, 16, v30
	v_and_b32_e32 v35, 0xffff0000, v30
	v_lshlrev_b32_e32 v30, 16, v31
	v_and_b32_e32 v31, 0xffff0000, v31
	v_pk_mul_f32 v[26:27], v[26:27], v[30:31]
	v_pk_mul_f32 v[24:25], v[24:25], v[34:35]
	s_cbranch_scc1 .LBB0_1499
	s_cmp_lg_u32 s37, 1
	s_cbranch_scc0 .LBB0_1496
	v_add_co_u32_e32 v30, vcc, 0x19000, v130
	s_mov_b64 s[20:21], 0
	s_nop 0
	v_addc_co_u32_e32 v31, vcc, 0, v131, vcc
	v_mov_b32_e32 v30, v226
	v_mov_b32_e32 v31, v227
	v_lshlrev_b32_e32 v34, 16, v30
	v_and_b32_e32 v35, 0xffff0000, v30
	v_lshlrev_b32_e32 v30, 16, v31
	v_and_b32_e32 v31, 0xffff0000, v31
	v_pk_add_f32 v[30:31], v[26:27], v[30:31]
	v_pk_add_f32 v[34:35], v[24:25], v[34:35]
	s_nop 0
	v_cvt_pk_bf16_f32 v34, v34, v35
	v_cvt_pk_bf16_f32 v35, v30, v31
	ds_write_b64 v28, v[34:35]
.LBB0_1496:
	s_andn2_b64 vcc, exec, s[20:21]
	s_cbranch_vccnz .LBB0_1498
	v_add_co_u32_e32 v28, vcc, 0x19000, v130
	s_nop 1
	v_addc_co_u32_e32 v29, vcc, 0, v131, vcc
	v_mov_b32_e32 v30, v226
	v_mov_b32_e32 v31, v227
	v_lshlrev_b32_e32 v34, 16, v30
	v_and_b32_e32 v35, 0xffff0000, v30
	v_lshlrev_b32_e32 v30, 16, v31
	v_and_b32_e32 v31, 0xffff0000, v31
	v_pk_add_f32 v[30:31], v[26:27], v[30:31]
	v_pk_add_f32 v[34:35], v[24:25], v[34:35]
	s_nop 0
	v_cvt_pk_bf16_f32 v34, v34, v35
	v_cvt_pk_bf16_f32 v35, v30, v31
	global_store_dwordx2 v[28:29], v[34:35], off

; DEV u32x2 pk4(f32x4 v) { u32x2 r = {pk_bf16(v[0], v[1]), pk_bf16(v[2], v[3])}; return r; }
; DEV f32x4 unpk4(u32x2 u) { f32x4 r = {bf_lo(u[0]), bf_hi(u[0]), bf_lo(u[1]), bf_hi(u[1])}; return r; }
;   DEV void operator()(f32x4 (&acc)[2][2][4][2], int brow, int bcol, int wr, int wc, int fr, int fq) const {
;     ...
;             const int cl = bj * 128 + wc * 32 + n * 16 + fq * 4, col = bcol + cl;
;             const int f = ((ai * 4 + m) * 2 + bj) * 2 + n;
;             const f32x4 g = unpk4(tile_get4(rl, cl));
;             f32x4 v = acc[ai][bj][m][n] * g;
;             if (step == 0) sp[(size_t)f * 512] = pk4(v);
;             else if (step == 1) sp[(size_t)f * 512] = pk4(unpk4(sp[(size_t)f * 512]) + v);
;             else tile_put4(rl, cl, pk4(unpk4(sp[(size_t)f * 512]) + v));
.LBB0_1501:
	v_add_u32_e32 v24, v32, v120
	v_add_u32_e32 v24, v24, v134
	ds_read_b64 v[26:27], v24
	s_cmp_lt_i32 s37, 1
	s_mov_b64 s[20:21], -1
	s_waitcnt lgkmcnt(0)
	v_lshlrev_b32_e32 v28, 16, v26
	v_and_b32_e32 v29, 0xffff0000, v26
	v_lshlrev_b32_e32 v26, 16, v27
	v_and_b32_e32 v27, 0xffff0000, v27
	v_pk_mul_f32 v[22:23], v[22:23], v[26:27]
	v_pk_mul_f32 v[20:21], v[20:21], v[28:29]
	s_cbranch_scc1 .LBB0_1507
	s_cmp_lg_u32 s37, 1
	s_cbranch_scc0 .LBB0_1504
	v_add_co_u32_e32 v26, vcc, 0x1a000, v130
	s_mov_b64 s[20:21], 0
	s_nop 0
	v_addc_co_u32_e32 v27, vcc, 0, v131, vcc
	v_mov_b32_e32 v26, v228
	v_mov_b32_e32 v27, v229
	v_lshlrev_b32_e32 v28, 16, v26
	v_and_b32_e32 v29, 0xffff0000, v26
	v_lshlrev_b32_e32 v26, 16, v27
	v_and_b32_e32 v27, 0xffff0000, v27
	v_pk_add_f32 v[26:27], v[22:23], v[26:27]
	v_pk_add_f32 v[28:29], v[20:21], v[28:29]
	s_nop 0
	v_cvt_pk_bf16_f32 v28, v28, v29
	v_cvt_pk_bf16_f32 v29, v26, v27
	ds_write_b64 v24, v[28:29]
.LBB0_1504:
	s_andn2_b64 vcc, exec, s[20:21]
	s_cbranch_vccnz .LBB0_1506
	v_add_co_u32_e32 v24, vcc, 0x1a000, v130
	s_nop 1
	v_addc_co_u32_e32 v25, vcc, 0, v131, vcc
	v_mov_b32_e32 v26, v228
	v_mov_b32_e32 v27, v229
	v_lshlrev_b32_e32 v28, 16, v26
	v_and_b32_e32 v29, 0xffff0000, v26
	v_lshlrev_b32_e32 v26, 16, v27
	v_and_b32_e32 v27, 0xffff0000, v27
	v_pk_add_f32 v[26:27], v[22:23], v[26:27]
	v_pk_add_f32 v[28:29], v[20:21], v[28:29]
	s_nop 0
	v_cvt_pk_bf16_f32 v28, v28, v29
	v_cvt_pk_bf16_f32 v29, v26, v27
	global_store_dwordx2 v[24:25], v[28:29], off

; DEV u32x2 pk4(f32x4 v) { u32x2 r = {pk_bf16(v[0], v[1]), pk_bf16(v[2], v[3])}; return r; }
; DEV f32x4 unpk4(u32x2 u) { f32x4 r = {bf_lo(u[0]), bf_hi(u[0]), bf_lo(u[1]), bf_hi(u[1])}; return r; }
;   DEV void operator()(f32x4 (&acc)[2][2][4][2], int brow, int bcol, int wr, int wc, int fr, int fq) const {
;     ...
;             const int cl = bj * 128 + wc * 32 + n * 16 + fq * 4, col = bcol + cl;
;             const int f = ((ai * 4 + m) * 2 + bj) * 2 + n;
;             const f32x4 g = unpk4(tile_get4(rl, cl));
;             f32x4 v = acc[ai][bj][m][n] * g;
;             if (step == 0) sp[(size_t)f * 512] = pk4(v);
;             else if (step == 1) sp[(size_t)f * 512] = pk4(unpk4(sp[(size_t)f * 512]) + v);
;             else tile_put4(rl, cl, pk4(unpk4(sp[(size_t)f * 512]) + v));
.LBB0_1509:
	v_add_u32_e32 v20, v32, v116
	v_add_u32_e32 v20, v20, v134
	ds_read_b64 v[22:23], v20
	s_cmp_lt_i32 s37, 1
	s_mov_b64 s[20:21], -1
	s_waitcnt lgkmcnt(0)
	v_lshlrev_b32_e32 v24, 16, v22
	v_and_b32_e32 v25, 0xffff0000, v22
	v_lshlrev_b32_e32 v22, 16, v23
	v_and_b32_e32 v23, 0xffff0000, v23
	v_pk_mul_f32 v[18:19], v[18:19], v[22:23]
	v_pk_mul_f32 v[16:17], v[16:17], v[24:25]
	s_cbranch_scc1 .LBB0_1515
	s_cmp_lg_u32 s37, 1
	s_cbranch_scc0 .LBB0_1512
	v_add_co_u32_e32 v22, vcc, 0x1b000, v130
	s_mov_b64 s[20:21], 0
	s_nop 0
	v_addc_co_u32_e32 v23, vcc, 0, v131, vcc
	v_mov_b32_e32 v22, v230
	v_mov_b32_e32 v23, v231
	v_lshlrev_b32_e32 v24, 16, v22
	v_and_b32_e32 v25, 0xffff0000, v22
	v_lshlrev_b32_e32 v22, 16, v23
	v_and_b32_e32 v23, 0xffff0000, v23
	v_pk_add_f32 v[22:23], v[18:19], v[22:23]
	v_pk_add_f32 v[24:25], v[16:17], v[24:25]
	s_nop 0
	v_cvt_pk_bf16_f32 v24, v24, v25
	v_cvt_pk_bf16_f32 v25, v22, v23
	ds_write_b64 v20, v[24:25]
.LBB0_1512:
	s_andn2_b64 vcc, exec, s[20:21]
	s_cbranch_vccnz .LBB0_1514
	v_add_co_u32_e32 v20, vcc, 0x1b000, v130
	s_nop 1
	v_addc_co_u32_e32 v21, vcc, 0, v131, vcc
	v_mov_b32_e32 v22, v230
	v_mov_b32_e32 v23, v231
	v_lshlrev_b32_e32 v24, 16, v22
	v_and_b32_e32 v25, 0xffff0000, v22
	v_lshlrev_b32_e32 v22, 16, v23
	v_and_b32_e32 v23, 0xffff0000, v23
	v_pk_add_f32 v[22:23], v[18:19], v[22:23]
	v_pk_add_f32 v[24:25], v[16:17], v[24:25]
	s_nop 0
	v_cvt_pk_bf16_f32 v24, v24, v25
	v_cvt_pk_bf16_f32 v25, v22, v23
	global_store_dwordx2 v[20:21], v[24:25], off

; DEV u32x2 pk4(f32x4 v) { u32x2 r = {pk_bf16(v[0], v[1]), pk_bf16(v[2], v[3])}; return r; }
; DEV f32x4 unpk4(u32x2 u) { f32x4 r = {bf_lo(u[0]), bf_hi(u[0]), bf_lo(u[1]), bf_hi(u[1])}; return r; }
;   DEV void operator()(f32x4 (&acc)[2][2][4][2], int brow, int bcol, int wr, int wc, int fr, int fq) const {
;     ...
;             const int cl = bj * 128 + wc * 32 + n * 16 + fq * 4, col = bcol + cl;
;             const int f = ((ai * 4 + m) * 2 + bj) * 2 + n;
;             const f32x4 g = unpk4(tile_get4(rl, cl));
;             f32x4 v = acc[ai][bj][m][n] * g;
;             if (step == 0) sp[(size_t)f * 512] = pk4(v);
;             else if (step == 1) sp[(size_t)f * 512] = pk4(unpk4(sp[(size_t)f * 512]) + v);
;             else tile_put4(rl, cl, pk4(unpk4(sp[(size_t)f * 512]) + v));
.LBB0_1517:
	v_add_u32_e32 v16, 0x16000, v135
	v_add_u32_e32 v17, v16, v112
	v_add_u32_e32 v17, v17, v134
	ds_read_b64 v[18:19], v17
	s_cmp_lt_i32 s37, 1
	s_mov_b64 s[20:21], -1
	s_waitcnt lgkmcnt(0)
	v_lshlrev_b32_e32 v20, 16, v18
	v_and_b32_e32 v21, 0xffff0000, v18
	v_lshlrev_b32_e32 v18, 16, v19
	v_and_b32_e32 v19, 0xffff0000, v19
	v_pk_mul_f32 v[14:15], v[14:15], v[18:19]
	v_pk_mul_f32 v[12:13], v[12:13], v[20:21]
	s_cbranch_scc1 .LBB0_1523
	s_cmp_lg_u32 s37, 1
	s_cbranch_scc0 .LBB0_1520
	v_add_co_u32_e32 v18, vcc, 0x1c000, v130
	s_mov_b64 s[20:21], 0
	s_nop 0
	v_addc_co_u32_e32 v19, vcc, 0, v131, vcc
	v_mov_b32_e32 v18, v232
	v_mov_b32_e32 v19, v233
	v_lshlrev_b32_e32 v20, 16, v18
	v_and_b32_e32 v21, 0xffff0000, v18
	v_lshlrev_b32_e32 v18, 16, v19
	v_and_b32_e32 v19, 0xffff0000, v19
	v_pk_add_f32 v[18:19], v[14:15], v[18:19]
	v_pk_add_f32 v[20:21], v[12:13], v[20:21]
	s_nop 0
	v_cvt_pk_bf16_f32 v20, v20, v21
	v_cvt_pk_bf16_f32 v21, v18, v19
	ds_write_b64 v17, v[20:21]
.LBB0_1520:
	s_andn2_b64 vcc, exec, s[20:21]
	s_cbranch_vccnz .LBB0_1522
	v_add_co_u32_e32 v18, vcc, 0x1c000, v130
	s_nop 1
	v_addc_co_u32_e32 v19, vcc, 0, v131, vcc
	v_mov_b32_e32 v20, v232
	v_mov_b32_e32 v21, v233
	v_lshlrev_b32_e32 v22, 16, v20
	v_and_b32_e32 v23, 0xffff0000, v20
	v_lshlrev_b32_e32 v20, 16, v21
	v_and_b32_e32 v21, 0xffff0000, v21
	v_pk_add_f32 v[20:21], v[14:15], v[20:21]
	v_pk_add_f32 v[22:23], v[12:13], v[22:23]
	s_nop 0
	v_cvt_pk_bf16_f32 v22, v22, v23
	v_cvt_pk_bf16_f32 v23, v20, v21
	global_store_dwordx2 v[18:19], v[22:23], off

; DEV u32x2 pk4(f32x4 v) { u32x2 r = {pk_bf16(v[0], v[1]), pk_bf16(v[2], v[3])}; return r; }
; DEV f32x4 unpk4(u32x2 u) { f32x4 r = {bf_lo(u[0]), bf_hi(u[0]), bf_lo(u[1]), bf_hi(u[1])}; return r; }
;   DEV void operator()(f32x4 (&acc)[2][2][4][2], int brow, int bcol, int wr, int wc, int fr, int fq) const {
;     ...
;             const int cl = bj * 128 + wc * 32 + n * 16 + fq * 4, col = bcol + cl;
;             const int f = ((ai * 4 + m) * 2 + bj) * 2 + n;
;             const f32x4 g = unpk4(tile_get4(rl, cl));
;             f32x4 v = acc[ai][bj][m][n] * g;
;             if (step == 0) sp[(size_t)f * 512] = pk4(v);
;             else if (step == 1) sp[(size_t)f * 512] = pk4(unpk4(sp[(size_t)f * 512]) + v);
;             else tile_put4(rl, cl, pk4(unpk4(sp[(size_t)f * 512]) + v));
.LBB0_1525:
	v_add_u32_e32 v12, v16, v108
	v_add_u32_e32 v12, v12, v134
	ds_read_b64 v[14:15], v12
	s_cmp_lt_i32 s37, 1
	s_mov_b64 s[20:21], -1
	s_waitcnt lgkmcnt(0)
	v_lshlrev_b32_e32 v18, 16, v14
	v_and_b32_e32 v19, 0xffff0000, v14
	v_lshlrev_b32_e32 v14, 16, v15
	v_and_b32_e32 v15, 0xffff0000, v15
	v_pk_mul_f32 v[10:11], v[10:11], v[14:15]
	v_pk_mul_f32 v[8:9], v[8:9], v[18:19]
	s_cbranch_scc1 .LBB0_1531
	s_cmp_lg_u32 s37, 1
	s_cbranch_scc0 .LBB0_1528
	v_add_co_u32_e32 v14, vcc, 0x1d000, v130
	s_mov_b64 s[20:21], 0
	s_nop 0
	v_addc_co_u32_e32 v15, vcc, 0, v131, vcc
	v_mov_b32_e32 v14, v234
	v_mov_b32_e32 v15, v235
	v_lshlrev_b32_e32 v18, 16, v14
	v_and_b32_e32 v19, 0xffff0000, v14
	v_lshlrev_b32_e32 v14, 16, v15
	v_and_b32_e32 v15, 0xffff0000, v15
	v_pk_add_f32 v[14:15], v[10:11], v[14:15]
	v_pk_add_f32 v[18:19], v[8:9], v[18:19]
	s_nop 0
	v_cvt_pk_bf16_f32 v18, v18, v19
	v_cvt_pk_bf16_f32 v19, v14, v15
	ds_write_b64 v12, v[18:19]
.LBB0_1528:
	s_andn2_b64 vcc, exec, s[20:21]
	s_cbranch_vccnz .LBB0_1530
	v_add_co_u32_e32 v12, vcc, 0x1d000, v130
	s_nop 1
	v_addc_co_u32_e32 v13, vcc, 0, v131, vcc
	v_mov_b32_e32 v14, v234
	v_mov_b32_e32 v15, v235
	v_lshlrev_b32_e32 v18, 16, v14
	v_and_b32_e32 v19, 0xffff0000, v14
	v_lshlrev_b32_e32 v14, 16, v15
	v_and_b32_e32 v15, 0xffff0000, v15
	v_pk_add_f32 v[14:15], v[10:11], v[14:15]
	v_pk_add_f32 v[18:19], v[8:9], v[18:19]
	s_nop 0
	v_cvt_pk_bf16_f32 v18, v18, v19
	v_cvt_pk_bf16_f32 v19, v14, v15
	global_store_dwordx2 v[12:13], v[18:19], off

; DEV u32x2 pk4(f32x4 v) { u32x2 r = {pk_bf16(v[0], v[1]), pk_bf16(v[2], v[3])}; return r; }
; DEV f32x4 unpk4(u32x2 u) { f32x4 r = {bf_lo(u[0]), bf_hi(u[0]), bf_lo(u[1]), bf_hi(u[1])}; return r; }
;   DEV void operator()(f32x4 (&acc)[2][2][4][2], int brow, int bcol, int wr, int wc, int fr, int fq) const {
;     ...
;             const int cl = bj * 128 + wc * 32 + n * 16 + fq * 4, col = bcol + cl;
;             const int f = ((ai * 4 + m) * 2 + bj) * 2 + n;
;             const f32x4 g = unpk4(tile_get4(rl, cl));
;             f32x4 v = acc[ai][bj][m][n] * g;
;             if (step == 0) sp[(size_t)f * 512] = pk4(v);
;             else if (step == 1) sp[(size_t)f * 512] = pk4(unpk4(sp[(size_t)f * 512]) + v);
;             else tile_put4(rl, cl, pk4(unpk4(sp[(size_t)f * 512]) + v));
.LBB0_1533:
	v_add_u32_e32 v8, v16, v104
	v_add_u32_e32 v8, v8, v134
	ds_read_b64 v[10:11], v8
	s_cmp_lt_i32 s37, 1
	s_mov_b64 s[20:21], -1
	s_waitcnt lgkmcnt(0)
	v_lshlrev_b32_e32 v12, 16, v10
	v_and_b32_e32 v13, 0xffff0000, v10
	v_lshlrev_b32_e32 v10, 16, v11
	v_and_b32_e32 v11, 0xffff0000, v11
	v_pk_mul_f32 v[6:7], v[6:7], v[10:11]
	v_pk_mul_f32 v[4:5], v[4:5], v[12:13]
	s_cbranch_scc1 .LBB0_1539
	s_cmp_lg_u32 s37, 1
	s_cbranch_scc0 .LBB0_1536
	v_add_co_u32_e32 v10, vcc, 0x1e000, v130
	s_mov_b64 s[20:21], 0
	s_nop 0
	v_addc_co_u32_e32 v11, vcc, 0, v131, vcc
	v_mov_b32_e32 v10, v236
	v_mov_b32_e32 v11, v237
	v_lshlrev_b32_e32 v12, 16, v10
	v_and_b32_e32 v13, 0xffff0000, v10
	v_lshlrev_b32_e32 v10, 16, v11
	v_and_b32_e32 v11, 0xffff0000, v11
	v_pk_add_f32 v[10:11], v[6:7], v[10:11]
	v_pk_add_f32 v[12:13], v[4:5], v[12:13]
	s_nop 0
	v_cvt_pk_bf16_f32 v12, v12, v13
	v_cvt_pk_bf16_f32 v13, v10, v11
	ds_write_b64 v8, v[12:13]
.LBB0_1536:
	s_andn2_b64 vcc, exec, s[20:21]
	s_cbranch_vccnz .LBB0_1538
	v_add_co_u32_e32 v8, vcc, 0x1e000, v130
	s_nop 1
	v_addc_co_u32_e32 v9, vcc, 0, v131, vcc
	v_mov_b32_e32 v10, v236
	v_mov_b32_e32 v11, v237
	v_lshlrev_b32_e32 v12, 16, v10
	v_and_b32_e32 v13, 0xffff0000, v10
	v_lshlrev_b32_e32 v10, 16, v11
	v_and_b32_e32 v11, 0xffff0000, v11
	v_pk_add_f32 v[10:11], v[6:7], v[10:11]
	v_pk_add_f32 v[12:13], v[4:5], v[12:13]
	s_nop 0
	v_cvt_pk_bf16_f32 v12, v12, v13
	v_cvt_pk_bf16_f32 v13, v10, v11
	global_store_dwordx2 v[8:9], v[12:13], off

; DEV u32x2 pk4(f32x4 v) { u32x2 r = {pk_bf16(v[0], v[1]), pk_bf16(v[2], v[3])}; return r; }
; DEV f32x4 unpk4(u32x2 u) { f32x4 r = {bf_lo(u[0]), bf_hi(u[0]), bf_lo(u[1]), bf_hi(u[1])}; return r; }
;   DEV void operator()(f32x4 (&acc)[2][2][4][2], int brow, int bcol, int wr, int wc, int fr, int fq) const {
;     ...
;             const int cl = bj * 128 + wc * 32 + n * 16 + fq * 4, col = bcol + cl;
;             const int f = ((ai * 4 + m) * 2 + bj) * 2 + n;
;             const f32x4 g = unpk4(tile_get4(rl, cl));
;             f32x4 v = acc[ai][bj][m][n] * g;
;             if (step == 0) sp[(size_t)f * 512] = pk4(v);
;             else if (step == 1) sp[(size_t)f * 512] = pk4(unpk4(sp[(size_t)f * 512]) + v);
;             else tile_put4(rl, cl, pk4(unpk4(sp[(size_t)f * 512]) + v));
.LBB0_1541:
	v_add_u32_e32 v4, v16, v100
	v_add_u32_e32 v4, v4, v134
	ds_read_b64 v[6:7], v4
	s_cmp_lt_i32 s37, 1
	s_mov_b64 s[20:21], -1
	s_waitcnt lgkmcnt(0)
	v_lshlrev_b32_e32 v8, 16, v6
	v_and_b32_e32 v9, 0xffff0000, v6
	v_lshlrev_b32_e32 v6, 16, v7
	v_and_b32_e32 v7, 0xffff0000, v7
	v_pk_mul_f32 v[2:3], v[2:3], v[6:7]
	v_pk_mul_f32 v[0:1], v[0:1], v[8:9]
	s_cbranch_scc1 .LBB0_1548
	s_cmp_lg_u32 s37, 1
	s_cbranch_scc0 .LBB0_1544
	v_add_co_u32_e32 v6, vcc, 0x1f000, v130
	s_mov_b64 s[20:21], 0
	s_nop 0
	v_addc_co_u32_e32 v7, vcc, 0, v131, vcc
	v_mov_b32_e32 v6, v238
	v_mov_b32_e32 v7, v239
	v_lshlrev_b32_e32 v8, 16, v6
	v_and_b32_e32 v9, 0xffff0000, v6
	v_lshlrev_b32_e32 v6, 16, v7
	v_and_b32_e32 v7, 0xffff0000, v7
	v_pk_add_f32 v[6:7], v[2:3], v[6:7]
	v_pk_add_f32 v[8:9], v[0:1], v[8:9]
	s_nop 0
	v_cvt_pk_bf16_f32 v8, v8, v9
	v_cvt_pk_bf16_f32 v9, v6, v7
	ds_write_b64 v4, v[8:9]
.LBB0_1544:
	s_andn2_b64 vcc, exec, s[20:21]
	s_cbranch_vccnz .LBB0_1546
	v_add_co_u32_e32 v4, vcc, 0x1f000, v130
	s_nop 1
	v_addc_co_u32_e32 v5, vcc, 0, v131, vcc
	v_mov_b32_e32 v6, v238
	v_mov_b32_e32 v7, v239
	v_lshlrev_b32_e32 v8, 16, v6
	v_and_b32_e32 v9, 0xffff0000, v6
	v_lshlrev_b32_e32 v6, 16, v7
	v_and_b32_e32 v7, 0xffff0000, v7
	v_pk_add_f32 v[6:7], v[2:3], v[6:7]
	v_pk_add_f32 v[8:9], v[0:1], v[8:9]
	s_nop 0
	v_cvt_pk_bf16_f32 v8, v8, v9
	v_cvt_pk_bf16_f32 v9, v6, v7
	global_store_dwordx2 v[4:5], v[8:9], off

; template <bool NT = false>
; DEV void tile_rows_out(bf16_t* __restrict__ out0, const size_t ld, const int tid) {
;     ...
;   for (int i = 0; i < 16; ++i) {
;     const int id = i * 512 + tid, r = id >> 5, pos = id & 31, c = pos ^ (r & 31);
;     const u32x4 v = *(const u32x4*)(smem + r * 512 + pos * 16);
;     if (NT) __builtin_nontemporal_store(v, (u32x4*)(out0 + (size_t)r * ld + 8 * c)); else *(u32x4*)(out0 + (size_t)r * ld + 8 * c) = v;
;   }
.LBB0_1550:
	s_lshl_b64 s[14:15], s[16:17], 12
	v_ashrrev_i32_e32 v4, 5, v132
	s_add_u32 s14, s79, s14
	v_lshl_add_u32 v0, v4, 9, v133
	s_waitcnt lgkmcnt(0)
	s_barrier
	s_addc_u32 s15, s89, s15
	ds_read_b128 v[0:3], v0
	s_add_u32 s14, s14, s18
	v_xor_b32_e32 v6, v4, v128
	v_ashrrev_i32_e32 v5, 31, v4
	s_addc_u32 s15, s15, s19
	v_lshlrev_b64 v[4:5], 12, v[4:5]
	v_lshlrev_b32_e32 v6, 4, v6
	v_lshl_add_u64 v[4:5], s[14:15], 0, v[4:5]
	v_and_b32_e32 v176, 0x1f0, v6
	v_lshl_add_u64 v[4:5], v[4:5], 0, v[176:177]
	s_waitcnt lgkmcnt(0)
	global_store_dwordx4 v[4:5], v[0:3], off sc1
	s_nop 1
	v_add_u32_e32 v0, 0x200, v132
	v_ashrrev_i32_e32 v4, 5, v0
	v_lshl_add_u32 v0, v4, 9, v133
	ds_read_b128 v[0:3], v0
	v_xor_b32_e32 v6, v4, v128
	v_ashrrev_i32_e32 v5, 31, v4
	v_lshlrev_b64 v[4:5], 12, v[4:5]
	v_lshlrev_b32_e32 v6, 4, v6
	v_lshl_add_u64 v[4:5], s[14:15], 0, v[4:5]
	v_and_b32_e32 v176, 0x1f0, v6
	v_lshl_add_u64 v[4:5], v[4:5], 0, v[176:177]
	s_waitcnt lgkmcnt(0)
	global_store_dwordx4 v[4:5], v[0:3], off sc1
	s_nop 1
	v_add_u32_e32 v0, 0x400, v132
	v_ashrrev_i32_e32 v4, 5, v0
	v_lshl_add_u32 v0, v4, 9, v133
	ds_read_b128 v[0:3], v0
	v_xor_b32_e32 v6, v4, v128
	v_ashrrev_i32_e32 v5, 31, v4
	v_lshlrev_b64 v[4:5], 12, v[4:5]
	v_lshlrev_b32_e32 v6, 4, v6
	v_lshl_add_u64 v[4:5], s[14:15], 0, v[4:5]
	v_and_b32_e32 v176, 0x1f0, v6
	v_lshl_add_u64 v[4:5], v[4:5], 0, v[176:177]
	s_waitcnt lgkmcnt(0)
	global_store_dwordx4 v[4:5], v[0:3], off sc1
	s_nop 1
	v_add_u32_e32 v0, 0x600, v132
	v_ashrrev_i32_e32 v4, 5, v0
	v_lshl_add_u32 v0, v4, 9, v133
	ds_read_b128 v[0:3], v0
	v_xor_b32_e32 v6, v4, v128
	v_ashrrev_i32_e32 v5, 31, v4
	v_lshlrev_b64 v[4:5], 12, v[4:5]
	v_lshlrev_b32_e32 v6, 4, v6
	v_lshl_add_u64 v[4:5], s[14:15], 0, v[4:5]
	v_and_b32_e32 v176, 0x1f0, v6
	v_lshl_add_u64 v[4:5], v[4:5], 0, v[176:177]
	s_waitcnt lgkmcnt(0)
	global_store_dwordx4 v[4:5], v[0:3], off sc1
	s_nop 1
	v_add_u32_e32 v0, 0x800, v132
	v_ashrrev_i32_e32 v4, 5, v0
	v_lshl_add_u32 v0, v4, 9, v133
	ds_read_b128 v[0:3], v0
	v_xor_b32_e32 v6, v4, v128
	v_ashrrev_i32_e32 v5, 31, v4
	v_lshlrev_b64 v[4:5], 12, v[4:5]
	v_lshlrev_b32_e32 v6, 4, v6
	v_lshl_add_u64 v[4:5], s[14:15], 0, v[4:5]
	v_and_b32_e32 v176, 0x1f0, v6
	v_lshl_add_u64 v[4:5], v[4:5], 0, v[176:177]
	s_waitcnt lgkmcnt(0)
	global_store_dwordx4 v[4:5], v[0:3], off sc1
	s_nop 1
	v_add_u32_e32 v0, 0xa00, v132
	v_ashrrev_i32_e32 v4, 5, v0
	v_lshl_add_u32 v0, v4, 9, v133
	ds_read_b128 v[0:3], v0
	v_xor_b32_e32 v6, v4, v128
	v_ashrrev_i32_e32 v5, 31, v4
	v_lshlrev_b64 v[4:5], 12, v[4:5]
	v_lshlrev_b32_e32 v6, 4, v6
	v_lshl_add_u64 v[4:5], s[14:15], 0, v[4:5]
	v_and_b32_e32 v176, 0x1f0, v6
	v_lshl_add_u64 v[4:5], v[4:5], 0, v[176:177]
	s_waitcnt lgkmcnt(0)
	global_store_dwordx4 v[4:5], v[0:3], off sc1
	s_nop 1
	v_add_u32_e32 v0, 0xc00, v132
	v_ashrrev_i32_e32 v4, 5, v0
	v_lshl_add_u32 v0, v4, 9, v133
	ds_read_b128 v[0:3], v0
	v_xor_b32_e32 v6, v4, v128
	v_ashrrev_i32_e32 v5, 31, v4
	v_lshlrev_b64 v[4:5], 12, v[4:5]
	v_lshlrev_b32_e32 v6, 4, v6
	v_lshl_add_u64 v[4:5], s[14:15], 0, v[4:5]
	v_and_b32_e32 v176, 0x1f0, v6
	v_lshl_add_u64 v[4:5], v[4:5], 0, v[176:177]
	s_waitcnt lgkmcnt(0)
	global_store_dwordx4 v[4:5], v[0:3], off sc1
	s_nop 1
	v_add_u32_e32 v0, 0xe00, v132
	v_ashrrev_i32_e32 v4, 5, v0
	v_lshl_add_u32 v0, v4, 9, v133
	ds_read_b128 v[0:3], v0
	v_xor_b32_e32 v6, v4, v128
	v_ashrrev_i32_e32 v5, 31, v4
	v_lshlrev_b64 v[4:5], 12, v[4:5]
	v_lshlrev_b32_e32 v6, 4, v6
	v_lshl_add_u64 v[4:5], s[14:15], 0, v[4:5]
	v_and_b32_e32 v176, 0x1f0, v6
	v_lshl_add_u64 v[4:5], v[4:5], 0, v[176:177]
	s_waitcnt lgkmcnt(0)
	global_store_dwordx4 v[4:5], v[0:3], off sc1
	s_nop 1
	v_add_u32_e32 v0, 0x1000, v132
	v_ashrrev_i32_e32 v4, 5, v0
	v_lshl_add_u32 v0, v4, 9, v133
	ds_read_b128 v[0:3], v0
	v_xor_b32_e32 v6, v4, v128
	v_ashrrev_i32_e32 v5, 31, v4
	v_lshlrev_b64 v[4:5], 12, v[4:5]
	v_lshlrev_b32_e32 v6, 4, v6
	v_lshl_add_u64 v[4:5], s[14:15], 0, v[4:5]
	v_and_b32_e32 v176, 0x1f0, v6
	v_lshl_add_u64 v[4:5], v[4:5], 0, v[176:177]
	s_waitcnt lgkmcnt(0)
; template <bool NT = false>
; DEV void tile_rows_out(bf16_t* __restrict__ out0, const size_t ld, const int tid) {
;     ...
;   for (int i = 0; i < 16; ++i) {
;     const int id = i * 512 + tid, r = id >> 5, pos = id & 31, c = pos ^ (r & 31);
;     const u32x4 v = *(const u32x4*)(smem + r * 512 + pos * 16);
;     if (NT) __builtin_nontemporal_store(v, (u32x4*)(out0 + (size_t)r * ld + 8 * c)); else *(u32x4*)(out0 + (size_t)r * ld + 8 * c) = v;
;   }
; DEV void panel_publish(unsigned* cnt, const int tidx) {
;   asm volatile("s_waitcnt vmcnt(0)" ::: "memory");
;   __syncthreads();
;   if (tidx == 0) {
;     __builtin_amdgcn_fence(__ATOMIC_RELEASE, "agent");
;     asm volatile("s_waitcnt vmcnt(0)" ::: "memory");
;     __hip_atomic_fetch_add(cnt, 1u, __ATOMIC_RELAXED, __HIP_MEMORY_SCOPE_AGENT);
;   }
; }
	global_store_dwordx4 v[4:5], v[0:3], off sc1
	s_nop 1
	v_add_u32_e32 v0, 0x1200, v132
	v_ashrrev_i32_e32 v4, 5, v0
	v_lshl_add_u32 v0, v4, 9, v133
	ds_read_b128 v[0:3], v0
	v_xor_b32_e32 v6, v4, v128
	v_ashrrev_i32_e32 v5, 31, v4
	v_lshlrev_b64 v[4:5], 12, v[4:5]
	v_lshlrev_b32_e32 v6, 4, v6
	v_lshl_add_u64 v[4:5], s[14:15], 0, v[4:5]
	v_and_b32_e32 v176, 0x1f0, v6
	v_lshl_add_u64 v[4:5], v[4:5], 0, v[176:177]
	s_waitcnt lgkmcnt(0)
	global_store_dwordx4 v[4:5], v[0:3], off sc1
	s_nop 1
	v_add_u32_e32 v0, 0x1400, v132
	v_ashrrev_i32_e32 v4, 5, v0
	v_lshl_add_u32 v0, v4, 9, v133
	ds_read_b128 v[0:3], v0
	v_xor_b32_e32 v6, v4, v128
	v_ashrrev_i32_e32 v5, 31, v4
	v_lshlrev_b64 v[4:5], 12, v[4:5]
	v_lshlrev_b32_e32 v6, 4, v6
	v_lshl_add_u64 v[4:5], s[14:15], 0, v[4:5]
	v_and_b32_e32 v176, 0x1f0, v6
	v_lshl_add_u64 v[4:5], v[4:5], 0, v[176:177]
	s_waitcnt lgkmcnt(0)
	global_store_dwordx4 v[4:5], v[0:3], off sc1
	s_nop 1
	v_add_u32_e32 v0, 0x1600, v132
	v_ashrrev_i32_e32 v4, 5, v0
	v_lshl_add_u32 v0, v4, 9, v133
	ds_read_b128 v[0:3], v0
	v_xor_b32_e32 v6, v4, v128
	v_ashrrev_i32_e32 v5, 31, v4
	v_lshlrev_b64 v[4:5], 12, v[4:5]
	v_lshlrev_b32_e32 v6, 4, v6
	v_lshl_add_u64 v[4:5], s[14:15], 0, v[4:5]
	v_and_b32_e32 v176, 0x1f0, v6
	v_lshl_add_u64 v[4:5], v[4:5], 0, v[176:177]
	s_waitcnt lgkmcnt(0)
	global_store_dwordx4 v[4:5], v[0:3], off sc1
	s_nop 1
	v_add_u32_e32 v0, 0x1800, v132
	v_ashrrev_i32_e32 v4, 5, v0
	v_lshl_add_u32 v0, v4, 9, v133
	ds_read_b128 v[0:3], v0
	v_xor_b32_e32 v6, v4, v128
	v_ashrrev_i32_e32 v5, 31, v4
	v_lshlrev_b64 v[4:5], 12, v[4:5]
	v_lshlrev_b32_e32 v6, 4, v6
	v_lshl_add_u64 v[4:5], s[14:15], 0, v[4:5]
	v_and_b32_e32 v176, 0x1f0, v6
	v_lshl_add_u64 v[4:5], v[4:5], 0, v[176:177]
	s_waitcnt lgkmcnt(0)
	global_store_dwordx4 v[4:5], v[0:3], off sc1
	s_nop 1
	v_add_u32_e32 v0, 0x1a00, v132
	v_ashrrev_i32_e32 v4, 5, v0
	v_lshl_add_u32 v0, v4, 9, v133
	ds_read_b128 v[0:3], v0
	v_xor_b32_e32 v6, v4, v128
	v_ashrrev_i32_e32 v5, 31, v4
	v_lshlrev_b64 v[4:5], 12, v[4:5]
	v_lshlrev_b32_e32 v6, 4, v6
	v_lshl_add_u64 v[4:5], s[14:15], 0, v[4:5]
	v_and_b32_e32 v176, 0x1f0, v6
	v_lshl_add_u64 v[4:5], v[4:5], 0, v[176:177]
	s_waitcnt lgkmcnt(0)
	global_store_dwordx4 v[4:5], v[0:3], off sc1
	s_nop 1
	v_add_u32_e32 v0, 0x1c00, v132
	v_ashrrev_i32_e32 v4, 5, v0
	v_lshl_add_u32 v0, v4, 9, v133
	ds_read_b128 v[0:3], v0
	v_xor_b32_e32 v6, v4, v128
	v_ashrrev_i32_e32 v5, 31, v4
	v_lshlrev_b64 v[4:5], 12, v[4:5]
	v_lshlrev_b32_e32 v6, 4, v6
	v_lshl_add_u64 v[4:5], s[14:15], 0, v[4:5]
	v_and_b32_e32 v176, 0x1f0, v6
	v_lshl_add_u64 v[4:5], v[4:5], 0, v[176:177]
	s_waitcnt lgkmcnt(0)
	global_store_dwordx4 v[4:5], v[0:3], off sc1
	s_nop 1
	v_add_u32_e32 v0, 0x1e00, v132
	v_ashrrev_i32_e32 v4, 5, v0
	v_lshl_add_u32 v0, v4, 9, v133
	ds_read_b128 v[0:3], v0
	v_xor_b32_e32 v6, v4, v128
	v_ashrrev_i32_e32 v5, 31, v4
	v_lshlrev_b64 v[4:5], 12, v[4:5]
	v_lshlrev_b32_e32 v6, 4, v6
	v_lshl_add_u64 v[4:5], s[14:15], 0, v[4:5]
	v_and_b32_e32 v176, 0x1f0, v6
	v_lshl_add_u64 v[4:5], v[4:5], 0, v[176:177]
	s_waitcnt lgkmcnt(0)
	global_store_dwordx4 v[4:5], v[0:3], off sc1
	s_branch .LBB0_1272
.LBB0_1551:
	v_mov_b32_e32 v0, v179
	s_waitcnt vmcnt(0)
	s_waitcnt lgkmcnt(0)
	v_cmp_eq_u32_e32 vcc, 0, v0
	s_barrier
	s_and_saveexec_b64 s[4:5], vcc
	s_cbranch_execz .LBB0_1270
	s_mov_b64 s[6:7], exec
	v_mbcnt_lo_u32_b32 v0, s6, 0
	s_waitcnt vmcnt(0)
	s_waitcnt vmcnt(0)
	v_mbcnt_hi_u32_b32 v0, s7, v0
	v_cmp_eq_u32_e32 vcc, 0, v0
	s_and_b64 s[8:9], exec, vcc
	s_mov_b64 exec, s[8:9]
	s_cbranch_execz .LBB0_1270
	v_readlane_b32 s8, v254, 0
	s_add_u32 s0, s8, s0
	v_readlane_b32 s8, v254, 1
	s_addc_u32 s1, s8, s1
	s_bcnt1_i32_b64 s6, s[6:7]
	v_mov_b32_e32 v0, s6
	global_atomic_add v177, v0, s[0:1]
	s_branch .LBB0_1270

; DEV u32x2 pk4(f32x4 v) { u32x2 r = {pk_bf16(v[0], v[1]), pk_bf16(v[2], v[3])}; return r; }
;   DEV void operator()(f32x4 (&acc)[2][2][4][2], int brow, int bcol, int wr, int wc, int fr, int fq) const {
;     ...
;     for (int ai = 0; ai < 2; ++ai)
; #pragma unroll
;       for (int m = 0; m < 4; ++m) {
;         const int rl = ai * 128 + wr * 64 + m * 16 + fr, tok = brow + rl;
;         float ss = 0.f;
; #pragma unroll
;         for (int bj = 0; bj < 2; ++bj)
; #pragma unroll
;           for (int n = 0; n < 2; ++n) {
;             const int cl = bj * 128 + wc * 32 + n * 16 + fq * 4;
;             const f32x4 v = acc[ai][bj][m][n];
;             tile_put4(rl, cl, pk4(v));
;             ss += v[0] * v[0] + v[1] * v[1] + v[2] * v[2] + v[3] * v[3];
;           }
;         ss += __shfl_xor(ss, 16); ss += __shfl_xor(ss, 32);
;         if (fq == 0) part[(size_t)((bcol >> 8) * 4 + wc) * NTOK + tok] = ss;
.LBB0_2165:
	s_or_b64 exec, exec, s[4:5]
	v_cvt_pk_bf16_f32 v144, v124, v125
	v_mul_f32_e32 v125, v125, v125
	v_fmac_f32_e32 v125, v124, v124
	v_cvt_pk_bf16_f32 v145, v126, v127
	v_fmac_f32_e32 v125, v126, v126
	v_cvt_pk_bf16_f32 v126, v116, v117
	v_mul_f32_e32 v117, v117, v117
	s_lshl_b32 s10, s21, 8
	s_mov_b32 s12, s6
	v_fmac_f32_e32 v117, v116, v116
	v_fmac_f32_e32 v125, v127, v127
	v_bfe_u32 v135, v141, 4, 2
	v_cvt_pk_bf16_f32 v127, v118, v119
	v_fmac_f32_e32 v117, v118, v118
	v_cvt_pk_bf16_f32 v118, v120, v121
	v_mul_f32_e32 v121, v121, v121
	v_bfe_u32 v134, v141, 6, 2
	v_lshlrev_b32_e32 v130, 2, v135
	v_and_b32_e32 v131, 64, v219
	v_fmac_f32_e32 v121, v120, v120
	v_mul_f32_e32 v120, v113, v113
	v_lshl_or_b32 v138, v134, 5, v130
	v_xor_b32_e32 v130, 16, v219
	v_add_u32_e32 v132, 64, v131
	v_fmac_f32_e32 v117, v119, v119
	v_fmac_f32_e32 v121, v122, v122
	v_fmac_f32_e32 v120, v112, v112
	v_cmp_lt_i32_e32 vcc, v130, v132
	v_add_f32_e32 v117, v125, v117
	v_fmac_f32_e32 v121, v123, v123
	v_fmac_f32_e32 v120, v114, v114
	v_cndmask_b32_e32 v130, v219, v130, vcc
	v_add_f32_e32 v117, v117, v121
	v_fmac_f32_e32 v120, v115, v115
	v_lshlrev_b32_e32 v130, 2, v130
	v_add_f32_e32 v117, v117, v120
	ds_bpermute_b32 v120, v130, v117
	v_lshrrev_b32_e32 v129, 6, v141
	v_xor_b32_e32 v131, 32, v219
	s_ashr_i32 s7, s10, 6
	v_cmp_lt_i32_e32 vcc, v131, v132
	v_bfi_b32 v136, -4, s7, v129
	v_ashrrev_i32_e32 v137, 31, v136
	v_cndmask_b32_e32 v131, v219, v131, vcc
	v_lshrrev_b32_e32 v129, 3, v138
	v_and_b32_e32 v133, 15, v141
	v_ashrrev_i32_e32 v128, 2, v141
	s_movk_i32 s4, 0xffc0
	v_lshlrev_b32_e32 v131, 2, v131
	v_lshlrev_b64 v[142:143], 15, v[136:137]
	v_bitop3_b32 v136, v129, v141, 15 bitop3:0x78
	v_cvt_pk_bf16_f32 v112, v112, v113
	v_cvt_pk_bf16_f32 v113, v114, v115
	s_waitcnt lgkmcnt(0)
	v_add_f32_e32 v115, v117, v120
	v_and_or_b32 v128, v128, s4, v133
	v_lshlrev_b32_e32 v138, 4, v136
	v_lshrrev_b32_e32 v136, 1, v141
	v_bitop3_b32 v116, v129, v133, 16 bitop3:0x36
	ds_bpermute_b32 v117, v131, v115
	v_lshl_add_u32 v137, v128, 9, 0
	v_and_b32_e32 v136, 8, v136
	v_lshlrev_b32_e32 v116, 4, v116
	v_bitop3_b32 v114, v129, v133, 18 bitop3:0x36
	v_bitop3_b32 v124, v129, v133, 2 bitop3:0x36
	v_cvt_pk_bf16_f32 v119, v122, v123
	v_add3_u32 v125, v137, v116, v136
	v_lshlrev_b32_e32 v114, 4, v114
	v_readlane_b32 s14, v253, 2
	v_add3_u32 v139, v137, v138, v136
	v_lshlrev_b32_e32 v124, 4, v124
	ds_write_b64 v125, v[118:119]
	v_add3_u32 v118, v137, v114, v136
	v_readlane_b32 s15, v253, 3
	v_cmp_ne_u32_e32 vcc, 0, v135
	v_cmp_eq_u32_e64 s[4:5], 0, v135
	ds_write_b64 v139, v[144:145]
	v_add3_u32 v139, v137, v124, v136
	ds_write_b64 v118, v[112:113]
	v_lshl_add_u64 v[112:113], s[14:15], 0, v[142:143]
	ds_write_b64 v139, v[126:127]
	s_and_saveexec_b64 s[14:15], s[4:5]
	s_cbranch_execz .LBB0_2167
	v_add_u32_e32 v118, s12, v128
	v_ashrrev_i32_e32 v119, 31, v118
	v_lshl_add_u64 v[118:119], v[118:119], 2, v[112:113]
	s_waitcnt lgkmcnt(0)
	v_add_f32_e32 v115, v115, v117
	global_store_dword v[118:119], v115, off sc1
.LBB0_2167:
	s_or_b64 exec, exec, s[14:15]
	v_cvt_pk_bf16_f32 v118, v108, v109
	v_mul_f32_e32 v109, v109, v109
	v_fmac_f32_e32 v109, v108, v108
	v_cvt_pk_bf16_f32 v119, v110, v111
	v_fmac_f32_e32 v109, v110, v110
	v_cvt_pk_bf16_f32 v110, v100, v101
	v_mul_f32_e32 v101, v101, v101
	v_fmac_f32_e32 v101, v100, v100
	v_fmac_f32_e32 v109, v111, v111
	v_cvt_pk_bf16_f32 v111, v102, v103
	v_fmac_f32_e32 v101, v102, v102
	v_cvt_pk_bf16_f32 v102, v104, v105
	v_mul_f32_e32 v105, v105, v105
	v_fmac_f32_e32 v105, v104, v104
	v_mul_f32_e32 v104, v97, v97
	v_fmac_f32_e32 v101, v103, v103
	v_fmac_f32_e32 v105, v106, v106
	v_fmac_f32_e32 v104, v96, v96
	v_add_f32_e32 v101, v109, v101
	v_fmac_f32_e32 v105, v107, v107
	v_fmac_f32_e32 v104, v98, v98
	v_add_f32_e32 v101, v101, v105
	v_fmac_f32_e32 v104, v99, v99
	v_add_f32_e32 v101, v101, v104
	ds_bpermute_b32 v104, v130, v101
	v_or_b32_e32 v120, 16, v129
	v_bitop3_b32 v100, v120, v133, 16 bitop3:0x1e
	v_add_u32_e32 v122, 0x2000, v137
	v_lshlrev_b32_e32 v100, 4, v100
	v_cvt_pk_bf16_f32 v103, v106, v107
	v_add3_u32 v109, v122, v100, v136
	ds_write_b64 v109, v[102:103]
	v_cvt_pk_bf16_f32 v102, v96, v97
	s_waitcnt lgkmcnt(0)
	v_add_f32_e32 v97, v101, v104
	v_cvt_pk_bf16_f32 v103, v98, v99
	ds_bpermute_b32 v98, v131, v97
	v_or_b32_e32 v117, 2, v129
	v_or_b32_e32 v121, 18, v129
	v_bitop3_b32 v115, v129, v133, 16 bitop3:0x1e
	v_bitop3_b32 v108, v117, v133, 16 bitop3:0x1e
	v_bitop3_b32 v96, v121, v133, 16 bitop3:0x1e
	v_lshlrev_b32_e32 v115, 4, v115
	v_lshlrev_b32_e32 v108, 4, v108
	v_lshlrev_b32_e32 v96, 4, v96
	v_add3_u32 v123, v122, v115, v136
	v_add3_u32 v117, v122, v108, v136
	v_add3_u32 v99, v122, v96, v136
	v_ashrrev_i32_e32 v129, 31, v128
	ds_write_b64 v123, v[118:119]
	ds_write_b64 v117, v[110:111]
	ds_write_b64 v99, v[102:103]
	s_and_saveexec_b64 s[14:15], s[4:5]
	s_cbranch_execz .LBB0_2169
	s_ashr_i32 s13, s12, 31
	v_lshl_add_u64 v[102:103], v[128:129], 0, s[12:13]
	v_lshl_add_u64 v[102:103], v[102:103], 2, v[112:113]
	s_waitcnt lgkmcnt(0)
	v_add_f32_e32 v97, v97, v98
	global_store_dword v[102:103], v97, off offset:64 sc1
; DEV u32x2 pk4(f32x4 v) { u32x2 r = {pk_bf16(v[0], v[1]), pk_bf16(v[2], v[3])}; return r; }
;   DEV void operator()(f32x4 (&acc)[2][2][4][2], int brow, int bcol, int wr, int wc, int fr, int fq) const {
;     ...
;     for (int ai = 0; ai < 2; ++ai)
; #pragma unroll
;       for (int m = 0; m < 4; ++m) {
;         const int rl = ai * 128 + wr * 64 + m * 16 + fr, tok = brow + rl;
;         float ss = 0.f;
; #pragma unroll
;         for (int bj = 0; bj < 2; ++bj)
; #pragma unroll
;           for (int n = 0; n < 2; ++n) {
;             const int cl = bj * 128 + wc * 32 + n * 16 + fq * 4;
;             const f32x4 v = acc[ai][bj][m][n];
;             tile_put4(rl, cl, pk4(v));
;             ss += v[0] * v[0] + v[1] * v[1] + v[2] * v[2] + v[3] * v[3];
;           }
;         ss += __shfl_xor(ss, 16); ss += __shfl_xor(ss, 32);
;         if (fq == 0) part[(size_t)((bcol >> 8) * 4 + wc) * NTOK + tok] = ss;
.LBB0_2169:
	s_or_b64 exec, exec, s[14:15]
	v_add_u32_e32 v97, 0x4000, v137
	s_waitcnt lgkmcnt(0)
	v_cvt_pk_bf16_f32 v98, v92, v93
	v_cvt_pk_bf16_f32 v99, v94, v95
	v_add3_u32 v101, v97, v138, v136
	ds_write_b64 v101, v[98:99]
	v_mul_f32_e32 v98, v93, v93
	v_fmac_f32_e32 v98, v92, v92
	v_cvt_pk_bf16_f32 v92, v88, v89
	v_mul_f32_e32 v89, v89, v89
	v_fmac_f32_e32 v89, v88, v88
	v_fmac_f32_e32 v98, v94, v94
	v_fmac_f32_e32 v89, v90, v90
	v_fmac_f32_e32 v98, v95, v95
	v_fmac_f32_e32 v89, v91, v91
	v_add_f32_e32 v88, v98, v89
	v_mul_f32_e32 v89, v85, v85
	v_fmac_f32_e32 v89, v84, v84
	v_fmac_f32_e32 v89, v86, v86
	v_fmac_f32_e32 v89, v87, v87
	v_add_f32_e32 v88, v88, v89
	v_mul_f32_e32 v89, v81, v81
	v_fmac_f32_e32 v89, v80, v80
	v_fmac_f32_e32 v89, v82, v82
	v_fmac_f32_e32 v89, v83, v83
	v_add_f32_e32 v88, v88, v89
	ds_bpermute_b32 v89, v130, v88
	v_cvt_pk_bf16_f32 v84, v84, v85
	v_cvt_pk_bf16_f32 v85, v86, v87
	v_add3_u32 v86, v97, v116, v136
	ds_write_b64 v86, v[84:85]
	s_waitcnt lgkmcnt(0)
	v_add_f32_e32 v84, v88, v89
	ds_bpermute_b32 v85, v131, v84
	v_cvt_pk_bf16_f32 v93, v90, v91
	v_add3_u32 v94, v97, v124, v136
	v_cvt_pk_bf16_f32 v80, v80, v81
	v_cvt_pk_bf16_f32 v81, v82, v83
	v_add3_u32 v82, v97, v114, v136
	ds_write_b64 v94, v[92:93]
	ds_write_b64 v82, v[80:81]
	s_and_saveexec_b64 s[14:15], s[4:5]
	s_cbranch_execz .LBB0_2171
	s_ashr_i32 s13, s12, 31
	v_lshl_add_u64 v[80:81], v[128:129], 0, s[12:13]
	v_lshl_add_u64 v[80:81], v[80:81], 2, v[112:113]
	s_waitcnt lgkmcnt(0)
	v_add_f32_e32 v82, v84, v85
	global_store_dword v[80:81], v82, off offset:128 sc1
.LBB0_2171:
	s_or_b64 exec, exec, s[14:15]
	v_add_u32_e32 v82, 0x6000, v137
	v_cvt_pk_bf16_f32 v80, v76, v77
	v_cvt_pk_bf16_f32 v81, v78, v79
	v_add3_u32 v83, v82, v115, v136
	ds_write_b64 v83, v[80:81]
	v_mul_f32_e32 v80, v77, v77
	v_fmac_f32_e32 v80, v76, v76
	v_cvt_pk_bf16_f32 v76, v72, v73
	v_mul_f32_e32 v73, v73, v73
	v_fmac_f32_e32 v73, v72, v72
	v_fmac_f32_e32 v80, v78, v78
	v_fmac_f32_e32 v73, v74, v74
	v_fmac_f32_e32 v80, v79, v79
	v_fmac_f32_e32 v73, v75, v75
	v_add_f32_e32 v72, v80, v73
	v_mul_f32_e32 v73, v69, v69
	v_fmac_f32_e32 v73, v68, v68
	v_fmac_f32_e32 v73, v70, v70
	v_fmac_f32_e32 v73, v71, v71
	v_add_f32_e32 v72, v72, v73
	v_mul_f32_e32 v73, v65, v65
	v_fmac_f32_e32 v73, v64, v64
	v_fmac_f32_e32 v73, v66, v66
	v_fmac_f32_e32 v73, v67, v67
	v_add_f32_e32 v72, v72, v73
	ds_bpermute_b32 v73, v130, v72
	v_cvt_pk_bf16_f32 v68, v68, v69
	v_cvt_pk_bf16_f32 v69, v70, v71
	v_add3_u32 v70, v82, v100, v136
	ds_write_b64 v70, v[68:69]
	s_waitcnt lgkmcnt(0)
	v_add_f32_e32 v68, v72, v73
	ds_bpermute_b32 v69, v131, v68
	v_cvt_pk_bf16_f32 v77, v74, v75
	v_add3_u32 v78, v82, v108, v136
	v_cvt_pk_bf16_f32 v64, v64, v65
	v_cvt_pk_bf16_f32 v65, v66, v67
	v_add3_u32 v66, v82, v96, v136
	ds_write_b64 v78, v[76:77]
	ds_write_b64 v66, v[64:65]
	s_and_saveexec_b64 s[14:15], s[4:5]
	s_cbranch_execz .LBB0_2173
	s_ashr_i32 s13, s12, 31
	v_lshl_add_u64 v[64:65], v[128:129], 0, s[12:13]
	v_lshl_add_u64 v[64:65], v[64:65], 2, v[112:113]
	s_waitcnt lgkmcnt(0)
	v_add_f32_e32 v66, v68, v69
	global_store_dword v[64:65], v66, off offset:192 sc1
.LBB0_2173:
	s_or_b64 exec, exec, s[14:15]
	v_add_u32_e32 v66, 0x10000, v137
	v_cvt_pk_bf16_f32 v64, v60, v61
	v_cvt_pk_bf16_f32 v65, v62, v63
	v_add3_u32 v67, v66, v138, v136
	ds_write_b64 v67, v[64:65]
	v_mul_f32_e32 v64, v61, v61
	v_fmac_f32_e32 v64, v60, v60
	v_cvt_pk_bf16_f32 v60, v56, v57
	v_mul_f32_e32 v57, v57, v57
	v_fmac_f32_e32 v57, v56, v56
	v_fmac_f32_e32 v64, v62, v62
	v_fmac_f32_e32 v57, v58, v58
	v_fmac_f32_e32 v64, v63, v63
	v_fmac_f32_e32 v57, v59, v59
	v_add_f32_e32 v56, v64, v57
	v_mul_f32_e32 v57, v53, v53
	v_fmac_f32_e32 v57, v52, v52
	v_fmac_f32_e32 v57, v54, v54
	v_fmac_f32_e32 v57, v55, v55
	v_add_f32_e32 v56, v56, v57
	v_mul_f32_e32 v57, v49, v49
	v_fmac_f32_e32 v57, v48, v48
	v_fmac_f32_e32 v57, v50, v50
	v_fmac_f32_e32 v57, v51, v51
	v_add_f32_e32 v56, v56, v57
	ds_bpermute_b32 v57, v130, v56
	v_cvt_pk_bf16_f32 v52, v52, v53
	v_cvt_pk_bf16_f32 v53, v54, v55
	v_add3_u32 v54, v66, v116, v136
	ds_write_b64 v54, v[52:53]
	s_waitcnt lgkmcnt(0)
	v_add_f32_e32 v52, v56, v57
	ds_bpermute_b32 v53, v131, v52
	v_cvt_pk_bf16_f32 v61, v58, v59
	v_add3_u32 v62, v66, v124, v136
	v_cvt_pk_bf16_f32 v48, v48, v49
	v_cvt_pk_bf16_f32 v49, v50, v51
	v_add3_u32 v50, v66, v114, v136
	ds_write_b64 v62, v[60:61]
	ds_write_b64 v50, v[48:49]
	s_and_saveexec_b64 s[14:15], s[4:5]
	s_cbranch_execz .LBB0_2175
	s_ashr_i32 s13, s12, 31
	v_lshl_add_u64 v[48:49], v[128:129], 0, s[12:13]
	v_lshl_add_u64 v[48:49], v[48:49], 2, v[112:113]
	s_waitcnt lgkmcnt(0)
	v_add_f32_e32 v50, v52, v53
	global_store_dword v[48:49], v50, off offset:512 sc1
.LBB0_2175:
	s_or_b64 exec, exec, s[14:15]
	v_add_u32_e32 v50, 0x12000, v137
	v_cvt_pk_bf16_f32 v48, v44, v45
	v_cvt_pk_bf16_f32 v49, v46, v47
	v_add3_u32 v51, v50, v115, v136
	ds_write_b64 v51, v[48:49]
	v_mul_f32_e32 v48, v45, v45
	v_fmac_f32_e32 v48, v44, v44
	v_cvt_pk_bf16_f32 v44, v40, v41
	v_mul_f32_e32 v41, v41, v41
	v_fmac_f32_e32 v41, v40, v40
	v_fmac_f32_e32 v48, v46, v46
	v_fmac_f32_e32 v41, v42, v42
	v_fmac_f32_e32 v48, v47, v47
	v_fmac_f32_e32 v41, v43, v43
	v_add_f32_e32 v40, v48, v41
	v_mul_f32_e32 v41, v37, v37
	v_fmac_f32_e32 v41, v36, v36
	v_fmac_f32_e32 v41, v38, v38
	v_fmac_f32_e32 v41, v39, v39
	v_add_f32_e32 v40, v40, v41
	v_mul_f32_e32 v41, v33, v33
	v_fmac_f32_e32 v41, v32, v32
	v_fmac_f32_e32 v41, v34, v34
	v_fmac_f32_e32 v41, v35, v35
	v_add_f32_e32 v40, v40, v41
	ds_bpermute_b32 v41, v130, v40
	v_cvt_pk_bf16_f32 v36, v36, v37
	v_cvt_pk_bf16_f32 v37, v38, v39
	v_add3_u32 v38, v50, v100, v136
	ds_write_b64 v38, v[36:37]
	s_waitcnt lgkmcnt(0)
	v_add_f32_e32 v36, v40, v41
	ds_bpermute_b32 v37, v131, v36
	v_cvt_pk_bf16_f32 v45, v42, v43
	v_add3_u32 v46, v50, v108, v136
	v_cvt_pk_bf16_f32 v32, v32, v33
	v_cvt_pk_bf16_f32 v33, v34, v35
	v_add3_u32 v34, v50, v96, v136
	ds_write_b64 v46, v[44:45]
	ds_write_b64 v34, v[32:33]
	s_and_saveexec_b64 s[14:15], s[4:5]
	s_cbranch_execz .LBB0_2177
	s_ashr_i32 s13, s12, 31
	v_lshl_add_u64 v[32:33], v[128:129], 0, s[12:13]
	v_lshl_add_u64 v[32:33], v[32:33], 2, v[112:113]
	s_waitcnt lgkmcnt(0)
	v_add_f32_e32 v34, v36, v37
	global_store_dword v[32:33], v34, off offset:576 sc1
; DEV u32x2 pk4(f32x4 v) { u32x2 r = {pk_bf16(v[0], v[1]), pk_bf16(v[2], v[3])}; return r; }
; template <bool NT = false>
; DEV void tile_rows_out(bf16_t* __restrict__ out0, const size_t ld, const int tid) {
;     ...
;   for (int i = 0; i < 16; ++i) {
;     const int id = i * 512 + tid, r = id >> 5, pos = id & 31, c = pos ^ (r & 31);
;     const u32x4 v = *(const u32x4*)(smem + r * 512 + pos * 16);
;     if (NT) __builtin_nontemporal_store(v, (u32x4*)(out0 + (size_t)r * ld + 8 * c)); else *(u32x4*)(out0 + (size_t)r * ld + 8 * c) = v;
;   }
;   DEV void operator()(f32x4 (&acc)[2][2][4][2], int brow, int bcol, int wr, int wc, int fr, int fq) const {
;     ...
;     for (int ai = 0; ai < 2; ++ai)
; #pragma unroll
;       for (int m = 0; m < 4; ++m) {
;         const int rl = ai * 128 + wr * 64 + m * 16 + fr, tok = brow + rl;
;         float ss = 0.f;
; #pragma unroll
;         for (int bj = 0; bj < 2; ++bj)
; #pragma unroll
;           for (int n = 0; n < 2; ++n) {
;             const int cl = bj * 128 + wc * 32 + n * 16 + fq * 4;
;             const f32x4 v = acc[ai][bj][m][n];
;             tile_put4(rl, cl, pk4(v));
;             ss += v[0] * v[0] + v[1] * v[1] + v[2] * v[2] + v[3] * v[3];
;           }
;         ss += __shfl_xor(ss, 16); ss += __shfl_xor(ss, 32);
;         if (fq == 0) part[(size_t)((bcol >> 8) * 4 + wc) * NTOK + tok] = ss;
;       }
;     __syncthreads();
.LBB0_2177:
	s_or_b64 exec, exec, s[14:15]
	v_add_u32_e32 v34, 0x14000, v137
	v_cvt_pk_bf16_f32 v32, v28, v29
	v_cvt_pk_bf16_f32 v33, v30, v31
	v_add3_u32 v35, v34, v138, v136
	ds_write_b64 v35, v[32:33]
	v_mul_f32_e32 v32, v29, v29
	v_fmac_f32_e32 v32, v28, v28
	v_cvt_pk_bf16_f32 v28, v24, v25
	v_mul_f32_e32 v25, v25, v25
	v_fmac_f32_e32 v25, v24, v24
	v_fmac_f32_e32 v32, v30, v30
	v_fmac_f32_e32 v25, v26, v26
	v_fmac_f32_e32 v32, v31, v31
	v_fmac_f32_e32 v25, v27, v27
	v_add_f32_e32 v24, v32, v25
	v_mul_f32_e32 v25, v21, v21
	v_fmac_f32_e32 v25, v20, v20
	v_fmac_f32_e32 v25, v22, v22
	v_fmac_f32_e32 v25, v23, v23
	v_add_f32_e32 v24, v24, v25
	v_mul_f32_e32 v25, v17, v17
	v_fmac_f32_e32 v25, v16, v16
	v_fmac_f32_e32 v25, v18, v18
	v_fmac_f32_e32 v25, v19, v19
	v_add_f32_e32 v24, v24, v25
	ds_bpermute_b32 v25, v130, v24
	v_cvt_pk_bf16_f32 v20, v20, v21
	v_cvt_pk_bf16_f32 v21, v22, v23
	v_add3_u32 v22, v34, v116, v136
	ds_write_b64 v22, v[20:21]
	s_waitcnt lgkmcnt(0)
	v_add_f32_e32 v20, v24, v25
	ds_bpermute_b32 v21, v131, v20
	v_cvt_pk_bf16_f32 v29, v26, v27
	v_add3_u32 v30, v34, v124, v136
	v_cvt_pk_bf16_f32 v16, v16, v17
	v_cvt_pk_bf16_f32 v17, v18, v19
	v_add3_u32 v18, v34, v114, v136
	ds_write_b64 v30, v[28:29]
	ds_write_b64 v18, v[16:17]
	s_and_saveexec_b64 s[14:15], s[4:5]
	s_cbranch_execz .LBB0_2179
	s_ashr_i32 s13, s12, 31
	v_lshl_add_u64 v[16:17], v[128:129], 0, s[12:13]
	v_lshl_add_u64 v[16:17], v[16:17], 2, v[112:113]
	s_waitcnt lgkmcnt(0)
	v_add_f32_e32 v18, v20, v21
	global_store_dword v[16:17], v18, off offset:640 sc1
.LBB0_2179:
	s_or_b64 exec, exec, s[14:15]
	v_add_u32_e32 v18, 0x16000, v137
	v_cvt_pk_bf16_f32 v16, v12, v13
	v_cvt_pk_bf16_f32 v17, v14, v15
	v_add3_u32 v19, v18, v115, v136
	ds_write_b64 v19, v[16:17]
	v_mul_f32_e32 v16, v13, v13
	v_fmac_f32_e32 v16, v12, v12
	v_cvt_pk_bf16_f32 v12, v8, v9
	v_mul_f32_e32 v9, v9, v9
	v_fmac_f32_e32 v9, v8, v8
	v_fmac_f32_e32 v16, v14, v14
	v_fmac_f32_e32 v9, v10, v10
	v_fmac_f32_e32 v16, v15, v15
	v_fmac_f32_e32 v9, v11, v11
	v_add_f32_e32 v8, v16, v9
	v_mul_f32_e32 v9, v5, v5
	v_fmac_f32_e32 v9, v4, v4
	v_fmac_f32_e32 v9, v6, v6
	v_fmac_f32_e32 v9, v7, v7
	v_add_f32_e32 v8, v8, v9
	v_mul_f32_e32 v9, v1, v1
	v_fmac_f32_e32 v9, v0, v0
	v_fmac_f32_e32 v9, v2, v2
	v_fmac_f32_e32 v9, v3, v3
	v_add_f32_e32 v8, v8, v9
	ds_bpermute_b32 v9, v130, v8
	v_cvt_pk_bf16_f32 v4, v4, v5
	v_cvt_pk_bf16_f32 v5, v6, v7
	v_add3_u32 v6, v18, v100, v136
	ds_write_b64 v6, v[4:5]
	s_waitcnt lgkmcnt(0)
	v_add_f32_e32 v4, v8, v9
	ds_bpermute_b32 v5, v131, v4
	v_cvt_pk_bf16_f32 v13, v10, v11
	v_add3_u32 v14, v18, v108, v136
	v_cvt_pk_bf16_f32 v0, v0, v1
	v_cvt_pk_bf16_f32 v1, v2, v3
	v_add3_u32 v2, v18, v96, v136
	ds_write_b64 v14, v[12:13]
	ds_write_b64 v2, v[0:1]
	s_and_saveexec_b64 s[4:5], vcc
	s_xor_b64 s[4:5], exec, s[4:5]
	s_ashr_i32 s13, s12, 31
	s_or_saveexec_b64 s[4:5], s[4:5]
	v_mov_b64_e32 v[0:1], s[12:13]
	s_xor_b64 exec, exec, s[4:5]
	s_cbranch_execz .LBB0_2183
	s_ashr_i32 s13, s12, 31
	v_lshl_add_u64 v[0:1], v[128:129], 0, s[12:13]
	v_lshl_add_u64 v[0:1], v[0:1], 2, v[112:113]
	s_waitcnt lgkmcnt(0)
	v_add_f32_e32 v2, v4, v5
	global_store_dword v[0:1], v2, off offset:704 sc1
	v_mov_b64_e32 v[0:1], s[12:13]
.LBB0_2183:
	s_or_b64 exec, exec, s[4:5]
	v_and_b32_e32 v2, 0xffffff00, v141
	v_lshlrev_b32_e32 v3, 6, v134
	v_lshlrev_b32_e32 v4, 4, v135
	v_or3_b32 v8, v3, v2, v4
	v_or_b32_e32 v2, v8, v133
	v_lshlrev_b32_e32 v2, 4, v2
	v_and_b32_e32 v2, 0x1f0, v2
	v_add_u32_e32 v9, 0, v2
	v_ashrrev_i32_e32 v6, 5, v8
	v_readlane_b32 s4, v253, 0
	v_lshl_add_u32 v2, v6, 9, v9
	s_waitcnt vmcnt(0) lgkmcnt(0)
	s_barrier
	v_lshlrev_b64 v[0:1], 12, v[0:1]
	v_readlane_b32 s5, v253, 1
	ds_read_b128 v[2:5], v2
	s_ashr_i32 s11, s10, 31
	v_lshl_add_u64 v[0:1], s[4:5], 0, v[0:1]
	v_bitop3_b32 v10, v6, v8, v133 bitop3:0x1e
	v_ashrrev_i32_e32 v7, 31, v6
	v_lshl_add_u64 v[0:1], s[10:11], 1, v[0:1]
	v_lshlrev_b64 v[6:7], 12, v[6:7]
	v_lshlrev_b32_e32 v10, 4, v10
	v_lshl_add_u64 v[6:7], v[0:1], 0, v[6:7]
	v_and_b32_e32 v176, 0x1f0, v10
	v_lshl_add_u64 v[6:7], v[6:7], 0, v[176:177]
	s_waitcnt lgkmcnt(0)
	global_store_dwordx4 v[6:7], v[2:5], off sc1
	s_nop 1
	v_add_u32_e32 v2, 0x200, v8
	v_ashrrev_i32_e32 v6, 5, v2
	v_lshl_add_u32 v2, v6, 9, v9
	ds_read_b128 v[2:5], v2
	v_bitop3_b32 v10, v6, v8, v133 bitop3:0x1e
	v_ashrrev_i32_e32 v7, 31, v6
	v_lshlrev_b64 v[6:7], 12, v[6:7]
	v_lshlrev_b32_e32 v10, 4, v10
	v_lshl_add_u64 v[6:7], v[0:1], 0, v[6:7]
	v_and_b32_e32 v176, 0x1f0, v10
	v_lshl_add_u64 v[6:7], v[6:7], 0, v[176:177]
	s_waitcnt lgkmcnt(0)
	global_store_dwordx4 v[6:7], v[2:5], off sc1
	s_nop 1
	v_add_u32_e32 v2, 0x400, v8
	v_ashrrev_i32_e32 v6, 5, v2
	v_lshl_add_u32 v2, v6, 9, v9
	ds_read_b128 v[2:5], v2
	v_bitop3_b32 v10, v6, v8, v133 bitop3:0x1e
	v_ashrrev_i32_e32 v7, 31, v6
	v_lshlrev_b64 v[6:7], 12, v[6:7]
	v_lshlrev_b32_e32 v10, 4, v10
	v_lshl_add_u64 v[6:7], v[0:1], 0, v[6:7]
	v_and_b32_e32 v176, 0x1f0, v10
	v_lshl_add_u64 v[6:7], v[6:7], 0, v[176:177]
	s_waitcnt lgkmcnt(0)
	global_store_dwordx4 v[6:7], v[2:5], off sc1
	s_nop 1
	v_add_u32_e32 v2, 0x600, v8
	v_ashrrev_i32_e32 v6, 5, v2
	v_lshl_add_u32 v2, v6, 9, v9
	ds_read_b128 v[2:5], v2
	v_bitop3_b32 v10, v6, v8, v133 bitop3:0x1e
	v_ashrrev_i32_e32 v7, 31, v6
	v_lshlrev_b64 v[6:7], 12, v[6:7]
	v_lshlrev_b32_e32 v10, 4, v10
	v_lshl_add_u64 v[6:7], v[0:1], 0, v[6:7]
	v_and_b32_e32 v176, 0x1f0, v10
	v_lshl_add_u64 v[6:7], v[6:7], 0, v[176:177]
	s_waitcnt lgkmcnt(0)
; template <bool NT = false>
; DEV void tile_rows_out(bf16_t* __restrict__ out0, const size_t ld, const int tid) {
;     ...
;   for (int i = 0; i < 16; ++i) {
;     const int id = i * 512 + tid, r = id >> 5, pos = id & 31, c = pos ^ (r & 31);
;     const u32x4 v = *(const u32x4*)(smem + r * 512 + pos * 16);
;     if (NT) __builtin_nontemporal_store(v, (u32x4*)(out0 + (size_t)r * ld + 8 * c)); else *(u32x4*)(out0 + (size_t)r * ld + 8 * c) = v;
;   }
; DEV void panel_publish(unsigned* cnt, const int tidx) {
;   asm volatile("s_waitcnt vmcnt(0)" ::: "memory");
;   __syncthreads();
;   if (tidx == 0) {
;     __builtin_amdgcn_fence(__ATOMIC_RELEASE, "agent");
;     asm volatile("s_waitcnt vmcnt(0)" ::: "memory");
;     __hip_atomic_fetch_add(cnt, 1u, __ATOMIC_RELAXED, __HIP_MEMORY_SCOPE_AGENT);
;   }
; }
	global_store_dwordx4 v[6:7], v[2:5], off sc1
	s_nop 1
	v_add_u32_e32 v2, 0x800, v8
	v_ashrrev_i32_e32 v6, 5, v2
	v_lshl_add_u32 v2, v6, 9, v9
	ds_read_b128 v[2:5], v2
	v_bitop3_b32 v10, v6, v8, v133 bitop3:0x1e
	v_ashrrev_i32_e32 v7, 31, v6
	v_lshlrev_b64 v[6:7], 12, v[6:7]
	v_lshlrev_b32_e32 v10, 4, v10
	v_lshl_add_u64 v[6:7], v[0:1], 0, v[6:7]
	v_and_b32_e32 v176, 0x1f0, v10
	v_lshl_add_u64 v[6:7], v[6:7], 0, v[176:177]
	s_waitcnt lgkmcnt(0)
	global_store_dwordx4 v[6:7], v[2:5], off sc1
	s_nop 1
	v_add_u32_e32 v2, 0xa00, v8
	v_ashrrev_i32_e32 v6, 5, v2
	v_lshl_add_u32 v2, v6, 9, v9
	ds_read_b128 v[2:5], v2
	v_bitop3_b32 v10, v6, v8, v133 bitop3:0x1e
	v_ashrrev_i32_e32 v7, 31, v6
	v_lshlrev_b64 v[6:7], 12, v[6:7]
	v_lshlrev_b32_e32 v10, 4, v10
	v_lshl_add_u64 v[6:7], v[0:1], 0, v[6:7]
	v_and_b32_e32 v176, 0x1f0, v10
	v_lshl_add_u64 v[6:7], v[6:7], 0, v[176:177]
	s_waitcnt lgkmcnt(0)
	global_store_dwordx4 v[6:7], v[2:5], off sc1
	s_nop 1
	v_add_u32_e32 v2, 0xc00, v8
	v_ashrrev_i32_e32 v6, 5, v2
	v_lshl_add_u32 v2, v6, 9, v9
	ds_read_b128 v[2:5], v2
	v_bitop3_b32 v10, v6, v8, v133 bitop3:0x1e
	v_ashrrev_i32_e32 v7, 31, v6
	v_lshlrev_b64 v[6:7], 12, v[6:7]
	v_lshlrev_b32_e32 v10, 4, v10
	v_lshl_add_u64 v[6:7], v[0:1], 0, v[6:7]
	v_and_b32_e32 v176, 0x1f0, v10
	v_lshl_add_u64 v[6:7], v[6:7], 0, v[176:177]
	s_waitcnt lgkmcnt(0)
	global_store_dwordx4 v[6:7], v[2:5], off sc1
	s_nop 1
	v_add_u32_e32 v2, 0xe00, v8
	v_ashrrev_i32_e32 v6, 5, v2
	v_lshl_add_u32 v2, v6, 9, v9
	ds_read_b128 v[2:5], v2
	v_bitop3_b32 v10, v6, v8, v133 bitop3:0x1e
	v_ashrrev_i32_e32 v7, 31, v6
	v_lshlrev_b64 v[6:7], 12, v[6:7]
	v_lshlrev_b32_e32 v10, 4, v10
	v_lshl_add_u64 v[6:7], v[0:1], 0, v[6:7]
	v_and_b32_e32 v176, 0x1f0, v10
	v_lshl_add_u64 v[6:7], v[6:7], 0, v[176:177]
	s_waitcnt lgkmcnt(0)
	global_store_dwordx4 v[6:7], v[2:5], off sc1
	s_nop 1
	v_add_u32_e32 v2, 0x1000, v8
	v_ashrrev_i32_e32 v6, 5, v2
	v_lshl_add_u32 v2, v6, 9, v9
	ds_read_b128 v[2:5], v2
	v_bitop3_b32 v10, v6, v8, v133 bitop3:0x1e
	v_ashrrev_i32_e32 v7, 31, v6
	v_lshlrev_b64 v[6:7], 12, v[6:7]
	v_lshlrev_b32_e32 v10, 4, v10
	v_lshl_add_u64 v[6:7], v[0:1], 0, v[6:7]
	v_and_b32_e32 v176, 0x1f0, v10
	v_lshl_add_u64 v[6:7], v[6:7], 0, v[176:177]
	s_waitcnt lgkmcnt(0)
	global_store_dwordx4 v[6:7], v[2:5], off sc1
	s_nop 1
	v_add_u32_e32 v2, 0x1200, v8
	v_ashrrev_i32_e32 v6, 5, v2
	v_lshl_add_u32 v2, v6, 9, v9
	ds_read_b128 v[2:5], v2
	v_bitop3_b32 v10, v6, v8, v133 bitop3:0x1e
	v_ashrrev_i32_e32 v7, 31, v6
	v_lshlrev_b64 v[6:7], 12, v[6:7]
	v_lshlrev_b32_e32 v10, 4, v10
	v_lshl_add_u64 v[6:7], v[0:1], 0, v[6:7]
	v_and_b32_e32 v176, 0x1f0, v10
	v_lshl_add_u64 v[6:7], v[6:7], 0, v[176:177]
	s_waitcnt lgkmcnt(0)
	global_store_dwordx4 v[6:7], v[2:5], off sc1
	s_nop 1
	v_add_u32_e32 v2, 0x1400, v8
	v_ashrrev_i32_e32 v6, 5, v2
	v_lshl_add_u32 v2, v6, 9, v9
	ds_read_b128 v[2:5], v2
	v_bitop3_b32 v10, v6, v8, v133 bitop3:0x1e
	v_ashrrev_i32_e32 v7, 31, v6
	v_lshlrev_b64 v[6:7], 12, v[6:7]
	v_lshlrev_b32_e32 v10, 4, v10
	v_lshl_add_u64 v[6:7], v[0:1], 0, v[6:7]
	v_and_b32_e32 v176, 0x1f0, v10
	v_lshl_add_u64 v[6:7], v[6:7], 0, v[176:177]
	s_waitcnt lgkmcnt(0)
	global_store_dwordx4 v[6:7], v[2:5], off sc1
	s_nop 1
	v_add_u32_e32 v2, 0x1600, v8
	v_ashrrev_i32_e32 v6, 5, v2
	v_lshl_add_u32 v2, v6, 9, v9
	ds_read_b128 v[2:5], v2
	v_bitop3_b32 v10, v6, v8, v133 bitop3:0x1e
	v_ashrrev_i32_e32 v7, 31, v6
	v_lshlrev_b64 v[6:7], 12, v[6:7]
	v_lshlrev_b32_e32 v10, 4, v10
	v_lshl_add_u64 v[6:7], v[0:1], 0, v[6:7]
	v_and_b32_e32 v176, 0x1f0, v10
	v_lshl_add_u64 v[6:7], v[6:7], 0, v[176:177]
	s_waitcnt lgkmcnt(0)
	global_store_dwordx4 v[6:7], v[2:5], off sc1
	s_nop 1
	v_add_u32_e32 v2, 0x1800, v8
	v_ashrrev_i32_e32 v6, 5, v2
	v_lshl_add_u32 v2, v6, 9, v9
	ds_read_b128 v[2:5], v2
	v_bitop3_b32 v10, v6, v8, v133 bitop3:0x1e
	v_ashrrev_i32_e32 v7, 31, v6
	v_lshlrev_b64 v[6:7], 12, v[6:7]
	v_lshlrev_b32_e32 v10, 4, v10
	v_lshl_add_u64 v[6:7], v[0:1], 0, v[6:7]
	v_and_b32_e32 v176, 0x1f0, v10
	v_lshl_add_u64 v[6:7], v[6:7], 0, v[176:177]
	s_waitcnt lgkmcnt(0)
	global_store_dwordx4 v[6:7], v[2:5], off sc1
	s_nop 1
	v_add_u32_e32 v2, 0x1a00, v8
	v_ashrrev_i32_e32 v6, 5, v2
	v_lshl_add_u32 v2, v6, 9, v9
	ds_read_b128 v[2:5], v2
	v_bitop3_b32 v10, v6, v8, v133 bitop3:0x1e
	v_ashrrev_i32_e32 v7, 31, v6
	v_lshlrev_b64 v[6:7], 12, v[6:7]
	v_lshlrev_b32_e32 v10, 4, v10
	v_lshl_add_u64 v[6:7], v[0:1], 0, v[6:7]
	v_and_b32_e32 v176, 0x1f0, v10
	v_lshl_add_u64 v[6:7], v[6:7], 0, v[176:177]
	s_waitcnt lgkmcnt(0)
	global_store_dwordx4 v[6:7], v[2:5], off sc1
	s_nop 1
	v_add_u32_e32 v2, 0x1c00, v8
	v_ashrrev_i32_e32 v6, 5, v2
	v_lshl_add_u32 v2, v6, 9, v9
	ds_read_b128 v[2:5], v2
	v_bitop3_b32 v10, v6, v8, v133 bitop3:0x1e
	v_ashrrev_i32_e32 v7, 31, v6
	v_lshlrev_b64 v[6:7], 12, v[6:7]
	v_lshlrev_b32_e32 v10, 4, v10
	v_lshl_add_u64 v[6:7], v[0:1], 0, v[6:7]
	v_and_b32_e32 v176, 0x1f0, v10
	v_lshl_add_u64 v[6:7], v[6:7], 0, v[176:177]
	s_waitcnt lgkmcnt(0)
	global_store_dwordx4 v[6:7], v[2:5], off sc1
	s_nop 1
	v_add_u32_e32 v2, 0x1e00, v8
	v_ashrrev_i32_e32 v6, 5, v2
	v_lshl_add_u32 v2, v6, 9, v9
	ds_read_b128 v[2:5], v2
	v_ashrrev_i32_e32 v7, 31, v6
	v_bitop3_b32 v8, v6, v8, v133 bitop3:0x1e
	v_lshlrev_b64 v[6:7], 12, v[6:7]
	v_lshl_add_u64 v[0:1], v[0:1], 0, v[6:7]
	v_lshlrev_b32_e32 v6, 4, v8
	v_and_b32_e32 v176, 0x1f0, v6
	v_lshl_add_u64 v[0:1], v[0:1], 0, v[176:177]
	s_waitcnt lgkmcnt(0)
	global_store_dwordx4 v[0:1], v[2:5], off sc1
	s_waitcnt vmcnt(0)
	s_barrier
	s_and_saveexec_b64 s[4:5], s[0:1]
	s_cbranch_execz .LBB0_2189
	s_mov_b64 s[10:11], exec
	s_lshl_b64 s[0:1], s[8:9], 2
	v_readlane_b32 s7, v254, 4
	s_waitcnt vmcnt(0)
	s_waitcnt vmcnt(0)
	v_mbcnt_lo_u32_b32 v0, s10, 0
	s_add_u32 s0, s7, s0
	v_readlane_b32 s7, v254, 5
	v_mbcnt_hi_u32_b32 v0, s11, v0
	s_addc_u32 s1, s7, s1
	v_cmp_eq_u32_e32 vcc, 0, v0
	s_and_saveexec_b64 s[8:9], vcc
	s_cbranch_execz .LBB0_2186
	s_bcnt1_i32_b64 s7, s[10:11]
	v_mov_b32_e32 v0, s7
	global_atomic_add v177, v0, s[0:1]
